# replace IEEE f32 division chains by v_rcp_f32 (350 sites: sigmoid/silu/gelu)
# speedup vs baseline: 1.0368x; 1.0368x over previous
; __device__ __forceinline__ void hy_hdn_row(const float* w1, const float* b1, const float* fq, const float* w2, const float* b2, float* hdn2, int t, int lane) {
;     ...
;     for (int m = 0; m < 16; ++m) { const float fr = 1e-4f + (float)m * ((15.f - 1e-4f) / 15.f); const float ang = fr * w;
;         pre += cosf(ang) * w1c[m] - sinf(ang) * w1s[m]; }
.LBB0_272:
	v_mul_f32_e32 v162, v161, v161
	v_fmamk_f32 v163, v162, 0xb94c1982, v217
	v_fmaak_f32 v163, v162, v163, 0xbe2aaa9d
	v_mul_f32_e32 v163, v162, v163
	v_fmac_f32_e32 v161, v161, v163
	v_fmamk_f32 v163, v162, 0x37d75334, v218
	v_fmaak_f32 v163, v162, v163, 0x3d2aabf7
	v_fmaak_f32 v163, v162, v163, 0xbf000004
	v_fma_f32 v162, v162, v163, 1.0
	v_and_b32_e32 v163, 1, v158
	v_cmp_eq_u32_e32 vcc, 0, v163
	v_lshlrev_b32_e32 v158, 30, v158
	v_and_b32_e32 v158, 0x80000000, v158
	v_cndmask_b32_e64 v161, -v161, v162, vcc
	v_xor_b32_e32 v158, v158, v161
	v_mul_f32_e32 v161, v160, v160
	v_fmamk_f32 v162, v161, 0xb94c1982, v217
	v_fmaak_f32 v162, v161, v162, 0xbe2aaa9d
	v_mul_f32_e32 v162, v161, v162
	v_fmac_f32_e32 v160, v160, v162
	v_fmamk_f32 v162, v161, 0x37d75334, v218
	v_fmaak_f32 v162, v161, v162, 0x3d2aabf7
	v_fmaak_f32 v162, v161, v162, 0xbf000004
	v_fma_f32 v161, v161, v162, 1.0
	v_and_b32_e32 v162, 1, v159
	v_cmp_eq_u32_e32 vcc, 0, v162
	v_lshlrev_b32_e32 v159, 30, v159
	v_and_b32_e32 v159, 0x80000000, v159
	v_cndmask_b32_e64 v160, -v160, v161, vcc
	v_xor_b32_e32 v159, v159, v160
	v_mul_f32_e32 v160, v155, v155
	v_fmamk_f32 v161, v160, 0xb94c1982, v217
	v_fmaak_f32 v161, v160, v161, 0xbe2aaa9d
	v_mul_f32_e32 v161, v160, v161
	v_fmac_f32_e32 v155, v155, v161
	v_fmamk_f32 v161, v160, 0x37d75334, v218
	v_fmaak_f32 v161, v160, v161, 0x3d2aabf7
	v_fmaak_f32 v161, v160, v161, 0xbf000004
	v_fma_f32 v160, v160, v161, 1.0
	v_and_b32_e32 v161, 1, v154
	v_cmp_eq_u32_e32 vcc, 0, v161
	v_lshlrev_b32_e32 v154, 30, v154
	v_and_b32_e32 v154, 0x80000000, v154
	v_cndmask_b32_e64 v155, -v155, v160, vcc
	v_xor_b32_e32 v154, v154, v155
	v_mul_f32_e32 v155, v151, v151
	v_fmamk_f32 v160, v155, 0xb94c1982, v217
	v_fmaak_f32 v160, v155, v160, 0xbe2aaa9d
	v_mul_f32_e32 v160, v155, v160
	v_fmac_f32_e32 v151, v151, v160
	v_fmamk_f32 v160, v155, 0x37d75334, v218
	v_fmaak_f32 v160, v155, v160, 0x3d2aabf7
	v_fmaak_f32 v160, v155, v160, 0xbf000004
	v_fma_f32 v155, v155, v160, 1.0
	v_and_b32_e32 v160, 1, v150
	v_cmp_eq_u32_e32 vcc, 0, v160
	v_lshlrev_b32_e32 v150, 30, v150
	v_and_b32_e32 v150, 0x80000000, v150
	v_cndmask_b32_e64 v151, -v151, v155, vcc
	v_xor_b32_e32 v150, v150, v151
	v_mul_f32_e32 v151, v146, v146
	v_fmamk_f32 v155, v151, 0xb94c1982, v217
	v_fmaak_f32 v155, v151, v155, 0xbe2aaa9d
	v_mul_f32_e32 v155, v151, v155
	v_fmac_f32_e32 v146, v146, v155
	v_fmamk_f32 v155, v151, 0x37d75334, v218
	v_fmaak_f32 v155, v151, v155, 0x3d2aabf7
	v_fmaak_f32 v155, v151, v155, 0xbf000004
	v_fma_f32 v151, v151, v155, 1.0
	v_and_b32_e32 v155, 1, v145
	v_cmp_eq_u32_e32 vcc, 0, v155
	v_lshlrev_b32_e32 v145, 30, v145
	v_and_b32_e32 v145, 0x80000000, v145
	v_cndmask_b32_e64 v146, -v146, v151, vcc
	v_xor_b32_e32 v145, v145, v146
	v_mul_f32_e32 v146, v139, v139
	v_fmamk_f32 v151, v146, 0xb94c1982, v217
	v_fmaak_f32 v151, v146, v151, 0xbe2aaa9d
	v_mul_f32_e32 v151, v146, v151
	v_fmac_f32_e32 v139, v139, v151
	v_fmamk_f32 v151, v146, 0x37d75334, v218
	v_fmaak_f32 v151, v146, v151, 0x3d2aabf7
	v_fmaak_f32 v151, v146, v151, 0xbf000004
	v_fma_f32 v146, v146, v151, 1.0
	v_and_b32_e32 v151, 1, v138
	v_cmp_eq_u32_e32 vcc, 0, v151
	v_lshlrev_b32_e32 v138, 30, v138
	v_and_b32_e32 v138, 0x80000000, v138
	v_cndmask_b32_e64 v139, -v139, v146, vcc
	v_xor_b32_e32 v138, v138, v139
	v_mul_f32_e32 v139, v133, v133
	v_fmamk_f32 v146, v139, 0xb94c1982, v217
	v_fmaak_f32 v146, v139, v146, 0xbe2aaa9d
	v_mul_f32_e32 v146, v139, v146
	v_fmac_f32_e32 v133, v133, v146
	v_fmamk_f32 v146, v139, 0x37d75334, v218
	v_fmaak_f32 v146, v139, v146, 0x3d2aabf7
	v_fmaak_f32 v146, v139, v146, 0xbf000004
	v_fma_f32 v139, v139, v146, 1.0
	v_and_b32_e32 v146, 1, v132
	v_cmp_eq_u32_e32 vcc, 0, v146
	v_lshlrev_b32_e32 v132, 30, v132
	v_and_b32_e32 v132, 0x80000000, v132
	v_cndmask_b32_e64 v133, -v133, v139, vcc
	v_xor_b32_e32 v132, v132, v133
	v_mul_f32_e32 v133, v128, v128
	v_fmamk_f32 v139, v133, 0xb94c1982, v217
	v_fmaak_f32 v139, v133, v139, 0xbe2aaa9d
	v_mul_f32_e32 v139, v133, v139
	v_fmac_f32_e32 v128, v128, v139
	v_fmamk_f32 v139, v133, 0x37d75334, v218
	v_fmaak_f32 v139, v133, v139, 0x3d2aabf7
	v_fmaak_f32 v139, v133, v139, 0xbf000004
	v_fma_f32 v133, v133, v139, 1.0
	v_and_b32_e32 v139, 1, v127
	v_cmp_eq_u32_e32 vcc, 0, v139
	v_lshlrev_b32_e32 v127, 30, v127
	v_and_b32_e32 v127, 0x80000000, v127
	v_cndmask_b32_e64 v128, -v128, v133, vcc
	v_xor_b32_e32 v127, v127, v128
	v_mul_f32_e32 v128, v123, v123
	v_fmamk_f32 v133, v128, 0xb94c1982, v217
	v_fmaak_f32 v133, v128, v133, 0xbe2aaa9d
	v_mul_f32_e32 v133, v128, v133
	v_fmac_f32_e32 v123, v123, v133
	v_fmamk_f32 v133, v128, 0x37d75334, v218
	v_fmaak_f32 v133, v128, v133, 0x3d2aabf7
	v_fmaak_f32 v133, v128, v133, 0xbf000004
	v_fma_f32 v128, v128, v133, 1.0
	v_and_b32_e32 v133, 1, v122
	v_cmp_eq_u32_e32 vcc, 0, v133
	v_lshlrev_b32_e32 v122, 30, v122
	v_and_b32_e32 v122, 0x80000000, v122
	v_cndmask_b32_e64 v123, -v123, v128, vcc
	v_xor_b32_e32 v122, v122, v123
	v_mul_f32_e32 v123, v118, v118
	v_fmamk_f32 v128, v123, 0xb94c1982, v217
	v_fmaak_f32 v128, v123, v128, 0xbe2aaa9d
	v_mul_f32_e32 v128, v123, v128
	v_fmac_f32_e32 v118, v118, v128
	v_fmamk_f32 v128, v123, 0x37d75334, v218
	v_fmaak_f32 v128, v123, v128, 0x3d2aabf7
	v_fmaak_f32 v128, v123, v128, 0xbf000004
	v_fma_f32 v123, v123, v128, 1.0
	v_and_b32_e32 v128, 1, v117
	v_cmp_eq_u32_e32 vcc, 0, v128
	v_lshlrev_b32_e32 v117, 30, v117
	v_and_b32_e32 v117, 0x80000000, v117
	v_cndmask_b32_e64 v118, -v118, v123, vcc
	v_xor_b32_e32 v117, v117, v118
	v_mul_f32_e32 v118, v113, v113
	v_fmamk_f32 v123, v118, 0xb94c1982, v217
	v_fmaak_f32 v123, v118, v123, 0xbe2aaa9d
	v_mul_f32_e32 v123, v118, v123
	v_fmac_f32_e32 v113, v113, v123
; __device__ __forceinline__ void hy_hdn_row(const float* w1, const float* b1, const float* fq, const float* w2, const float* b2, float* hdn2, int t, int lane) {
;     const float zt = (float)t / 4095.f;
;     const float w = 6.283185307179586f * (float)t / 4096.f;
;     float pre = b1[lane] + zt * w1[lane];
;     float w1c[16], w1s[16];
; #pragma unroll
;     for (int m = 0; m < 16; ++m) { w1c[m] = w1[(1 + m) * 64 + lane]; w1s[m] = w1[(17 + m) * 64 + lane]; }
; #pragma unroll
;     for (int m = 0; m < 16; ++m) { const float fr = 1e-4f + (float)m * ((15.f - 1e-4f) / 15.f); const float ang = fr * w;
;         pre += cosf(ang) * w1c[m] - sinf(ang) * w1s[m]; }
	v_fmamk_f32 v123, v118, 0x37d75334, v218
	v_fmaak_f32 v123, v118, v123, 0x3d2aabf7
	v_fmaak_f32 v123, v118, v123, 0xbf000004
	v_fma_f32 v118, v118, v123, 1.0
	v_and_b32_e32 v123, 1, v112
	v_cmp_eq_u32_e32 vcc, 0, v123
	v_lshlrev_b32_e32 v112, 30, v112
	v_and_b32_e32 v112, 0x80000000, v112
	v_cndmask_b32_e64 v113, -v113, v118, vcc
	v_xor_b32_e32 v112, v112, v113
	v_mul_f32_e32 v113, v108, v108
	v_fmamk_f32 v118, v113, 0xb94c1982, v217
	v_fmaak_f32 v118, v113, v118, 0xbe2aaa9d
	v_mul_f32_e32 v118, v113, v118
	v_fmac_f32_e32 v108, v108, v118
	v_fmamk_f32 v118, v113, 0x37d75334, v218
	v_fmaak_f32 v118, v113, v118, 0x3d2aabf7
	v_fmaak_f32 v118, v113, v118, 0xbf000004
	v_fma_f32 v113, v113, v118, 1.0
	v_and_b32_e32 v118, 1, v107
	v_cmp_eq_u32_e32 vcc, 0, v118
	v_lshlrev_b32_e32 v107, 30, v107
	v_and_b32_e32 v107, 0x80000000, v107
	v_cndmask_b32_e64 v108, -v108, v113, vcc
	v_xor_b32_e32 v107, v107, v108
	v_mul_f32_e32 v108, v102, v102
	v_fmamk_f32 v113, v108, 0xb94c1982, v217
	v_fmaak_f32 v113, v108, v113, 0xbe2aaa9d
	v_mul_f32_e32 v113, v108, v113
	v_fmac_f32_e32 v102, v102, v113
	v_fmamk_f32 v113, v108, 0x37d75334, v218
	v_fmaak_f32 v113, v108, v113, 0x3d2aabf7
	v_fmaak_f32 v113, v108, v113, 0xbf000004
	v_fma_f32 v108, v108, v113, 1.0
	v_and_b32_e32 v113, 1, v101
	v_cmp_eq_u32_e32 vcc, 0, v113
	v_lshlrev_b32_e32 v101, 30, v101
	v_and_b32_e32 v101, 0x80000000, v101
	v_cndmask_b32_e64 v102, -v102, v108, vcc
	v_xor_b32_e32 v101, v101, v102
	v_mul_f32_e32 v102, v95, v95
	v_fmamk_f32 v108, v102, 0xb94c1982, v217
	v_fmaak_f32 v108, v102, v108, 0xbe2aaa9d
	v_mul_f32_e32 v108, v102, v108
	v_fmac_f32_e32 v95, v95, v108
	v_fmamk_f32 v108, v102, 0x37d75334, v218
	v_fmaak_f32 v108, v102, v108, 0x3d2aabf7
	v_fmaak_f32 v108, v102, v108, 0xbf000004
	v_fma_f32 v102, v102, v108, 1.0
	v_and_b32_e32 v108, 1, v94
	v_cmp_eq_u32_e32 vcc, 0, v108
	v_lshlrev_b32_e32 v94, 30, v94
	v_and_b32_e32 v94, 0x80000000, v94
	v_cndmask_b32_e64 v95, -v95, v102, vcc
	v_xor_b32_e32 v94, v94, v95
	v_mul_f32_e32 v95, v89, v89
	v_fmamk_f32 v102, v95, 0xb94c1982, v217
	v_fmaak_f32 v102, v95, v102, 0xbe2aaa9d
	v_mul_f32_e32 v102, v95, v102
	v_fmac_f32_e32 v89, v89, v102
	v_fmamk_f32 v102, v95, 0x37d75334, v218
	v_fmaak_f32 v102, v95, v102, 0x3d2aabf7
	v_fmaak_f32 v102, v95, v102, 0xbf000004
	v_fma_f32 v95, v95, v102, 1.0
	v_and_b32_e32 v102, 1, v88
	v_cmp_eq_u32_e32 vcc, 0, v102
	v_lshlrev_b32_e32 v88, 30, v88
	v_and_b32_e32 v88, 0x80000000, v88
	v_cndmask_b32_e64 v89, -v89, v95, vcc
	v_xor_b32_e32 v88, v88, v89
	v_mul_f32_e32 v89, v84, v84
	v_fmamk_f32 v95, v89, 0xb94c1982, v217
	v_fmaak_f32 v95, v89, v95, 0xbe2aaa9d
	v_mul_f32_e32 v95, v89, v95
	v_fmac_f32_e32 v84, v84, v95
	v_fmamk_f32 v95, v89, 0x37d75334, v218
	v_fmaak_f32 v95, v89, v95, 0x3d2aabf7
	v_fmaak_f32 v95, v89, v95, 0xbf000004
	v_fma_f32 v89, v89, v95, 1.0
	v_and_b32_e32 v95, 1, v83
	v_cmp_eq_u32_e32 vcc, 0, v95
	s_mov_b32 s30, 0x457ff000
	v_lshlrev_b32_e32 v83, 30, v83
	v_cndmask_b32_e64 v84, -v84, v89, vcc
	v_and_b32_e32 v83, 0x80000000, v83
	v_xor_b32_e32 v83, v83, v84
	s_movk_i32 s22, 0x1f8
	v_rcp_f32_e32 v84, s30
	s_nop 0
	v_mul_f32_e32 v82, v82, v84
	s_waitcnt vmcnt(0)
	v_fmac_f32_e32 v77, v82, v80
	v_mul_f32_e32 v80, v86, v86
	v_fmamk_f32 v82, v80, 0xb94c1982, v217
	v_fmaak_f32 v82, v80, v82, 0xbe2aaa9d
	v_mul_f32_e32 v82, v80, v82
	v_fmac_f32_e32 v86, v86, v82
	v_fmamk_f32 v82, v80, 0x37d75334, v218
	v_fmaak_f32 v82, v80, v82, 0x3d2aabf7
	v_fmaak_f32 v82, v80, v82, 0xbf000004
	v_fma_f32 v80, v80, v82, 1.0
	v_and_b32_e32 v82, 1, v85
	v_cmp_eq_u32_e32 vcc, 0, v82
	v_lshlrev_b32_e32 v82, 30, v85
	v_cmp_class_f32_e64 s[50:51], v81, s22
	v_and_b32_e32 v82, 0x80000000, v82
	v_xor_b32_e32 v81, s36, v81
	v_cndmask_b32_e32 v80, v80, v86, vcc
	v_xor_b32_e32 v81, v81, v82
	v_xor_b32_e32 v80, v81, v80
	v_cndmask_b32_e64 v80, v222, v80, s[50:51]
	v_cndmask_b32_e64 v83, v222, v83, s[50:51]
	v_mul_f32_e32 v79, v79, v80
	v_fma_f32 v78, v78, v83, -v79
	v_add_f32_e32 v77, v77, v78
	v_mul_f32_e32 v78, v91, v91
	v_fmamk_f32 v79, v78, 0xb94c1982, v217
	v_fmaak_f32 v79, v78, v79, 0xbe2aaa9d
	v_mul_f32_e32 v79, v78, v79
	v_fmac_f32_e32 v91, v91, v79
	v_fmamk_f32 v79, v78, 0x37d75334, v218
	v_fmaak_f32 v79, v78, v79, 0x3d2aabf7
	v_fmaak_f32 v79, v78, v79, 0xbf000004
	v_fma_f32 v78, v78, v79, 1.0
	v_and_b32_e32 v79, 1, v90
	v_cmp_eq_u32_e32 vcc, 0, v79
	v_lshlrev_b32_e32 v79, 30, v90
	v_and_b32_e32 v79, 0x80000000, v79
	v_xor_b32_e32 v80, s53, v87
	v_cndmask_b32_e32 v78, v78, v91, vcc
	v_xor_b32_e32 v79, v80, v79
	v_cmp_class_f32_e64 s[48:49], v87, s22
	v_xor_b32_e32 v78, v79, v78
	v_cmp_class_f32_e64 s[46:47], v92, s22
	v_cndmask_b32_e64 v78, v222, v78, s[48:49]
	v_cndmask_b32_e64 v88, v222, v88, s[48:49]
	v_mul_f32_e32 v76, v76, v78
	v_fma_f32 v75, v75, v88, -v76
	v_mul_f32_e32 v76, v97, v97
	v_add_f32_e32 v75, v77, v75
	v_fmamk_f32 v77, v76, 0xb94c1982, v217
	v_fmaak_f32 v77, v76, v77, 0xbe2aaa9d
	v_mul_f32_e32 v77, v76, v77
	v_fmac_f32_e32 v97, v97, v77
	v_fmamk_f32 v77, v76, 0x37d75334, v218
	v_fmaak_f32 v77, v76, v77, 0x3d2aabf7
	v_fmaak_f32 v77, v76, v77, 0xbf000004
	v_fma_f32 v76, v76, v77, 1.0
	v_and_b32_e32 v77, 1, v96
	v_cmp_eq_u32_e32 vcc, 0, v77
	v_lshlrev_b32_e32 v77, 30, v96
	v_and_b32_e32 v77, 0x80000000, v77
	v_xor_b32_e32 v78, s68, v92
	v_cndmask_b32_e32 v76, v76, v97, vcc
	v_xor_b32_e32 v77, v78, v77
	v_xor_b32_e32 v76, v77, v76
	v_cndmask_b32_e64 v76, v222, v76, s[46:47]
	v_cndmask_b32_e64 v94, v222, v94, s[46:47]
	v_mul_f32_e32 v74, v74, v76
	v_fma_f32 v73, v73, v94, -v74
	v_mul_f32_e32 v74, v100, v100
	v_add_f32_e32 v73, v75, v73
	v_fmamk_f32 v75, v74, 0xb94c1982, v217
	v_fmaak_f32 v75, v74, v75, 0xbe2aaa9d
; __device__ __forceinline__ void hy_hdn_row(const float* w1, const float* b1, const float* fq, const float* w2, const float* b2, float* hdn2, int t, int lane) {
;     ...
;     for (int m = 0; m < 16; ++m) { const float fr = 1e-4f + (float)m * ((15.f - 1e-4f) / 15.f); const float ang = fr * w;
;         pre += cosf(ang) * w1c[m] - sinf(ang) * w1s[m]; }
	v_mul_f32_e32 v75, v74, v75
	v_fmac_f32_e32 v100, v100, v75
	v_fmamk_f32 v75, v74, 0x37d75334, v218
	v_fmaak_f32 v75, v74, v75, 0x3d2aabf7
	v_fmaak_f32 v75, v74, v75, 0xbf000004
	v_fma_f32 v74, v74, v75, 1.0
	v_and_b32_e32 v75, 1, v99
	v_cmp_eq_u32_e32 vcc, 0, v75
	v_lshlrev_b32_e32 v75, 30, v99
	v_and_b32_e32 v75, 0x80000000, v75
	v_xor_b32_e32 v76, s69, v98
	v_cndmask_b32_e32 v74, v74, v100, vcc
	v_xor_b32_e32 v75, v76, v75
	v_cmp_class_f32_e64 s[44:45], v98, s22
	v_xor_b32_e32 v74, v75, v74
	v_cmp_class_f32_e64 s[42:43], v103, s22
	v_cndmask_b32_e64 v74, v222, v74, s[44:45]
	v_cndmask_b32_e64 v101, v222, v101, s[44:45]
	v_mul_f32_e32 v72, v72, v74
	v_fma_f32 v71, v71, v101, -v72
	v_mul_f32_e32 v72, v105, v105
	v_add_f32_e32 v71, v73, v71
	v_fmamk_f32 v73, v72, 0xb94c1982, v217
	v_fmaak_f32 v73, v72, v73, 0xbe2aaa9d
	v_mul_f32_e32 v73, v72, v73
	v_fmac_f32_e32 v105, v105, v73
	v_fmamk_f32 v73, v72, 0x37d75334, v218
	v_fmaak_f32 v73, v72, v73, 0x3d2aabf7
	v_fmaak_f32 v73, v72, v73, 0xbf000004
	v_fma_f32 v72, v72, v73, 1.0
	v_and_b32_e32 v73, 1, v104
	v_cmp_eq_u32_e32 vcc, 0, v73
	v_lshlrev_b32_e32 v73, 30, v104
	v_and_b32_e32 v73, 0x80000000, v73
	v_xor_b32_e32 v74, s70, v103
	v_cndmask_b32_e32 v72, v72, v105, vcc
	v_xor_b32_e32 v73, v74, v73
	v_xor_b32_e32 v72, v73, v72
	v_cndmask_b32_e64 v72, v222, v72, s[42:43]
	v_cndmask_b32_e64 v107, v222, v107, s[42:43]
	v_mul_f32_e32 v70, v70, v72
	v_fma_f32 v69, v69, v107, -v70
	v_mul_f32_e32 v70, v110, v110
	v_add_f32_e32 v69, v71, v69
	v_fmamk_f32 v71, v70, 0xb94c1982, v217
	v_fmaak_f32 v71, v70, v71, 0xbe2aaa9d
	v_mul_f32_e32 v71, v70, v71
	v_fmac_f32_e32 v110, v110, v71
	v_fmamk_f32 v71, v70, 0x37d75334, v218
	v_fmaak_f32 v71, v70, v71, 0x3d2aabf7
	v_fmaak_f32 v71, v70, v71, 0xbf000004
	v_fma_f32 v70, v70, v71, 1.0
	v_and_b32_e32 v71, 1, v109
	v_cmp_eq_u32_e32 vcc, 0, v71
	v_lshlrev_b32_e32 v71, 30, v109
	v_and_b32_e32 v71, 0x80000000, v71
	v_xor_b32_e32 v72, s71, v106
	v_cndmask_b32_e32 v70, v70, v110, vcc
	v_xor_b32_e32 v71, v72, v71
	v_cmp_class_f32_e64 s[40:41], v106, s22
	v_xor_b32_e32 v70, v71, v70
	v_cmp_class_f32_e64 s[38:39], v111, s22
	v_cndmask_b32_e64 v70, v222, v70, s[40:41]
	v_cndmask_b32_e64 v112, v222, v112, s[40:41]
	v_mul_f32_e32 v68, v68, v70
	v_fma_f32 v67, v67, v112, -v68
	v_mul_f32_e32 v68, v115, v115
	v_add_f32_e32 v67, v69, v67
	v_fmamk_f32 v69, v68, 0xb94c1982, v217
	v_fmaak_f32 v69, v68, v69, 0xbe2aaa9d
	v_mul_f32_e32 v69, v68, v69
	v_fmac_f32_e32 v115, v115, v69
	v_fmamk_f32 v69, v68, 0x37d75334, v218
	v_fmaak_f32 v69, v68, v69, 0x3d2aabf7
	v_fmaak_f32 v69, v68, v69, 0xbf000004
	v_fma_f32 v68, v68, v69, 1.0
	v_and_b32_e32 v69, 1, v114
	v_cmp_eq_u32_e32 vcc, 0, v69
	v_lshlrev_b32_e32 v69, 30, v114
	v_and_b32_e32 v69, 0x80000000, v69
	v_xor_b32_e32 v70, s72, v111
	v_cndmask_b32_e32 v68, v68, v115, vcc
	v_xor_b32_e32 v69, v70, v69
	v_xor_b32_e32 v68, v69, v68
	v_cndmask_b32_e64 v68, v222, v68, s[38:39]
	v_cndmask_b32_e64 v117, v222, v117, s[38:39]
	v_mul_f32_e32 v66, v66, v68
	v_fma_f32 v64, v64, v117, -v66
	v_mul_f32_e32 v66, v120, v120
	v_add_f32_e32 v64, v67, v64
	v_fmamk_f32 v67, v66, 0xb94c1982, v217
	v_fmaak_f32 v67, v66, v67, 0xbe2aaa9d
	v_mul_f32_e32 v67, v66, v67
	v_fmac_f32_e32 v120, v120, v67
	v_fmamk_f32 v67, v66, 0x37d75334, v218
	v_fmaak_f32 v67, v66, v67, 0x3d2aabf7
	v_fmaak_f32 v67, v66, v67, 0xbf000004
	v_fma_f32 v66, v66, v67, 1.0
	v_and_b32_e32 v67, 1, v119
	v_cmp_eq_u32_e32 vcc, 0, v67
	v_lshlrev_b32_e32 v67, 30, v119
	v_and_b32_e32 v67, 0x80000000, v67
	v_xor_b32_e32 v68, s73, v116
	v_cndmask_b32_e32 v66, v66, v120, vcc
	v_xor_b32_e32 v67, v68, v67
	v_cmp_class_f32_e64 s[20:21], v116, s22
	v_xor_b32_e32 v66, v67, v66
	v_cmp_class_f32_e64 s[18:19], v121, s22
	v_cndmask_b32_e64 v66, v222, v66, s[20:21]
	v_cndmask_b32_e64 v122, v222, v122, s[20:21]
	v_mul_f32_e32 v63, v63, v66
	v_fma_f32 v62, v62, v122, -v63
	v_mul_f32_e32 v63, v125, v125
	v_add_f32_e32 v62, v64, v62
	v_fmamk_f32 v64, v63, 0xb94c1982, v217
	v_fmaak_f32 v64, v63, v64, 0xbe2aaa9d
	v_mul_f32_e32 v64, v63, v64
	v_fmac_f32_e32 v125, v125, v64
	v_fmamk_f32 v64, v63, 0x37d75334, v218
	v_fmaak_f32 v64, v63, v64, 0x3d2aabf7
	v_fmaak_f32 v64, v63, v64, 0xbf000004
	v_fma_f32 v63, v63, v64, 1.0
	v_and_b32_e32 v64, 1, v124
	v_cmp_eq_u32_e32 vcc, 0, v64
	v_lshlrev_b32_e32 v64, 30, v124
	v_and_b32_e32 v64, 0x80000000, v64
	v_xor_b32_e32 v66, s74, v121
	v_cndmask_b32_e32 v63, v63, v125, vcc
	v_xor_b32_e32 v64, v66, v64
	v_xor_b32_e32 v63, v64, v63
	v_cndmask_b32_e64 v63, v222, v63, s[18:19]
	v_cndmask_b32_e64 v127, v222, v127, s[18:19]
	v_mul_f32_e32 v61, v61, v63
	v_fma_f32 v60, v60, v127, -v61
	v_mul_f32_e32 v61, v130, v130
	v_add_f32_e32 v60, v62, v60
	v_fmamk_f32 v62, v61, 0xb94c1982, v217
	v_fmaak_f32 v62, v61, v62, 0xbe2aaa9d
	v_mul_f32_e32 v62, v61, v62
	v_fmac_f32_e32 v130, v130, v62
	v_fmamk_f32 v62, v61, 0x37d75334, v218
	v_fmaak_f32 v62, v61, v62, 0x3d2aabf7
	v_fmaak_f32 v62, v61, v62, 0xbf000004
	v_fma_f32 v61, v61, v62, 1.0
	v_and_b32_e32 v62, 1, v129
	v_cmp_eq_u32_e32 vcc, 0, v62
	v_lshlrev_b32_e32 v62, 30, v129
	v_and_b32_e32 v62, 0x80000000, v62
	v_xor_b32_e32 v63, s67, v126
	v_cndmask_b32_e32 v61, v61, v130, vcc
	v_xor_b32_e32 v62, v63, v62
	v_cmp_class_f32_e64 s[16:17], v126, s22
	v_xor_b32_e32 v61, v62, v61
	v_cmp_class_f32_e64 s[14:15], v131, s22
	v_cndmask_b32_e64 v61, v222, v61, s[16:17]
	v_cndmask_b32_e64 v132, v222, v132, s[16:17]
	v_mul_f32_e32 v59, v59, v61
	v_fma_f32 v58, v58, v132, -v59
	v_mul_f32_e32 v59, v135, v135
	v_add_f32_e32 v58, v60, v58
	v_fmamk_f32 v60, v59, 0xb94c1982, v217
	v_fmaak_f32 v60, v59, v60, 0xbe2aaa9d
	v_mul_f32_e32 v60, v59, v60
; __device__ __forceinline__ void hy_hdn_row(const float* w1, const float* b1, const float* fq, const float* w2, const float* b2, float* hdn2, int t, int lane) {
;     ...
;     for (int m = 0; m < 16; ++m) { const float fr = 1e-4f + (float)m * ((15.f - 1e-4f) / 15.f); const float ang = fr * w;
;         pre += cosf(ang) * w1c[m] - sinf(ang) * w1s[m]; }
;     const float f = fq[lane];
;     const float h1 = sinf(f * pre);
	v_fmac_f32_e32 v135, v135, v60
	v_fmamk_f32 v60, v59, 0x37d75334, v218
	v_fmaak_f32 v60, v59, v60, 0x3d2aabf7
	v_fmaak_f32 v60, v59, v60, 0xbf000004
	v_fma_f32 v59, v59, v60, 1.0
	v_and_b32_e32 v60, 1, v134
	v_cmp_eq_u32_e32 vcc, 0, v60
	v_lshlrev_b32_e32 v60, 30, v134
	v_and_b32_e32 v60, 0x80000000, v60
	v_xor_b32_e32 v61, s75, v131
	v_cndmask_b32_e32 v59, v59, v135, vcc
	v_xor_b32_e32 v60, v61, v60
	v_xor_b32_e32 v59, v60, v59
	v_cndmask_b32_e64 v59, v222, v59, s[14:15]
	v_cndmask_b32_e64 v138, v222, v138, s[14:15]
	v_mul_f32_e32 v57, v57, v59
	v_fma_f32 v56, v56, v138, -v57
	v_mul_f32_e32 v57, v141, v141
	v_add_f32_e32 v56, v58, v56
	v_fmamk_f32 v58, v57, 0xb94c1982, v217
	v_fmaak_f32 v58, v57, v58, 0xbe2aaa9d
	v_mul_f32_e32 v58, v57, v58
	v_fmac_f32_e32 v141, v141, v58
	v_fmamk_f32 v58, v57, 0x37d75334, v218
	v_fmaak_f32 v58, v57, v58, 0x3d2aabf7
	v_fmaak_f32 v58, v57, v58, 0xbf000004
	v_fma_f32 v57, v57, v58, 1.0
	v_and_b32_e32 v58, 1, v140
	v_cmp_eq_u32_e32 vcc, 0, v58
	v_lshlrev_b32_e32 v58, 30, v140
	v_and_b32_e32 v58, 0x80000000, v58
	v_xor_b32_e32 v59, s76, v136
	v_cndmask_b32_e32 v57, v57, v141, vcc
	v_xor_b32_e32 v58, v59, v58
	v_cmp_class_f32_e64 s[12:13], v136, s22
	v_xor_b32_e32 v57, v58, v57
	v_xor_b32_e32 v58, s77, v137
	v_cndmask_b32_e64 v57, v222, v57, s[12:13]
	v_cndmask_b32_e64 v145, v222, v145, s[12:13]
	v_mul_f32_e32 v55, v55, v57
	v_fma_f32 v54, v54, v145, -v55
	v_add_f32_e32 v55, v56, v54
	v_mul_f32_e32 v56, v143, v143
	v_fmamk_f32 v54, v56, 0xb94c1982, v217
	v_fmaak_f32 v54, v56, v54, 0xbe2aaa9d
	v_mul_f32_e32 v54, v56, v54
	v_fmac_f32_e32 v143, v143, v54
	global_load_dword v54, v[38:39], off
	v_fmamk_f32 v57, v56, 0x37d75334, v218
	v_fmaak_f32 v57, v56, v57, 0x3d2aabf7
	v_fmaak_f32 v57, v56, v57, 0xbf000004
	v_fma_f32 v56, v56, v57, 1.0
	v_and_b32_e32 v57, 1, v142
	v_cmp_eq_u32_e32 vcc, 0, v57
	v_lshlrev_b32_e32 v57, 30, v142
	v_and_b32_e32 v57, 0x80000000, v57
	v_cndmask_b32_e32 v56, v56, v143, vcc
	v_xor_b32_e32 v57, v58, v57
	v_cmp_class_f32_e64 s[10:11], v137, s22
	v_xor_b32_e32 v56, v57, v56
	v_cmp_class_f32_e64 s[8:9], v144, s22
	v_cndmask_b32_e64 v56, v222, v56, s[10:11]
	v_cndmask_b32_e64 v150, v222, v150, s[10:11]
	v_mul_f32_e32 v53, v53, v56
	v_fma_f32 v52, v52, v150, -v53
	v_mul_f32_e32 v53, v148, v148
	v_add_f32_e32 v52, v55, v52
	v_fmamk_f32 v55, v53, 0xb94c1982, v217
	v_fmaak_f32 v55, v53, v55, 0xbe2aaa9d
	v_mul_f32_e32 v55, v53, v55
	v_fmac_f32_e32 v148, v148, v55
	v_fmamk_f32 v55, v53, 0x37d75334, v218
	v_fmaak_f32 v55, v53, v55, 0x3d2aabf7
	v_fmaak_f32 v55, v53, v55, 0xbf000004
	v_fma_f32 v53, v53, v55, 1.0
	v_and_b32_e32 v55, 1, v147
	v_cmp_eq_u32_e32 vcc, 0, v55
	v_lshlrev_b32_e32 v55, 30, v147
	v_and_b32_e32 v55, 0x80000000, v55
	v_xor_b32_e32 v56, s78, v144
	v_cndmask_b32_e32 v53, v53, v148, vcc
	v_xor_b32_e32 v55, v56, v55
	v_xor_b32_e32 v53, v55, v53
	v_cndmask_b32_e64 v53, v222, v53, s[8:9]
	v_cndmask_b32_e64 v154, v222, v154, s[8:9]
	v_mul_f32_e32 v51, v51, v53
	v_fma_f32 v50, v50, v154, -v51
	v_mul_f32_e32 v51, v153, v153
	v_add_f32_e32 v50, v52, v50
	v_fmamk_f32 v52, v51, 0xb94c1982, v217
	v_fmaak_f32 v52, v51, v52, 0xbe2aaa9d
	v_mul_f32_e32 v52, v51, v52
	v_fmac_f32_e32 v153, v153, v52
	v_fmamk_f32 v52, v51, 0x37d75334, v218
	v_fmaak_f32 v52, v51, v52, 0x3d2aabf7
	v_fmaak_f32 v52, v51, v52, 0xbf000004
	v_fma_f32 v51, v51, v52, 1.0
	v_and_b32_e32 v52, 1, v152
	v_cmp_eq_u32_e32 vcc, 0, v52
	v_lshlrev_b32_e32 v52, 30, v152
	v_and_b32_e32 v52, 0x80000000, v52
	v_xor_b32_e32 v53, s79, v149
	v_cndmask_b32_e32 v51, v51, v153, vcc
	v_xor_b32_e32 v52, v53, v52
	v_cmp_class_f32_e64 s[6:7], v149, s22
	v_xor_b32_e32 v51, v52, v51
	v_cmp_class_f32_e64 s[4:5], v93, s22
	v_cndmask_b32_e64 v51, v222, v51, s[6:7]
	v_cndmask_b32_e64 v159, v222, v159, s[6:7]
	v_mul_f32_e32 v49, v49, v51
	v_fma_f32 v48, v48, v159, -v49
	v_mul_f32_e32 v49, v157, v157
	v_add_f32_e32 v48, v50, v48
	v_fmamk_f32 v50, v49, 0xb94c1982, v217
	v_fmaak_f32 v50, v49, v50, 0xbe2aaa9d
	v_mul_f32_e32 v50, v49, v50
	v_fmac_f32_e32 v157, v157, v50
	v_fmamk_f32 v50, v49, 0x37d75334, v218
	v_fmaak_f32 v50, v49, v50, 0x3d2aabf7
	v_fmaak_f32 v50, v49, v50, 0xbf000004
	v_fma_f32 v49, v49, v50, 1.0
	v_and_b32_e32 v50, 1, v156
	v_cmp_eq_u32_e32 vcc, 0, v50
	v_lshlrev_b32_e32 v50, 30, v156
	v_and_b32_e32 v50, 0x80000000, v50
	v_xor_b32_e32 v51, s80, v93
	v_cndmask_b32_e32 v49, v49, v157, vcc
	v_xor_b32_e32 v50, v51, v50
	v_xor_b32_e32 v49, v50, v49
	v_cndmask_b32_e64 v49, v222, v49, s[4:5]
	v_cndmask_b32_e64 v158, v222, v158, s[4:5]
	v_mul_f32_e32 v45, v45, v49
	v_fma_f32 v44, v44, v158, -v45
	v_add_f32_e32 v44, v48, v44
	s_waitcnt vmcnt(0)
	v_mul_f32_e32 v44, v54, v44
	s_brev_b32 s19, 18
	s_movk_i32 s23, 0x1f8
	v_and_b32_e32 v45, 0x7fffffff, v44
	v_cmp_nlt_f32_e64 s[4:5], |v44|, s19
	s_and_saveexec_b64 s[6:7], s[4:5]
	s_xor_b64 s[10:11], exec, s[6:7]
	s_mov_b32 s20, 0x3fc90fda
	s_cbranch_execz .LBB0_274
; __device__ __forceinline__ void hy_hdn_row(const float* w1, const float* b1, const float* fq, const float* w2, const float* b2, float* hdn2, int t, int lane) {
;     ...
;     const float h1 = sinf(f * pre);
	v_lshrrev_b32_e32 v48, 23, v45
	v_add_u32_e32 v48, 0xffffff88, v48
	v_cmp_lt_u32_e32 vcc, 63, v48
	v_not_b32_e32 v49, 63
	v_not_b32_e32 v50, 31
	v_cndmask_b32_e32 v49, 0, v49, vcc
	v_add_u32_e32 v48, v49, v48
	v_cmp_lt_u32_e64 s[4:5], 31, v48
	s_mov_b32 s8, 0xfe5163ab
	s_nop 0
	v_cndmask_b32_e64 v49, 0, v50, s[4:5]
	v_add_u32_e32 v48, v49, v48
	v_cmp_lt_u32_e64 s[6:7], 31, v48
	s_nop 1
	v_cndmask_b32_e64 v49, 0, v50, s[6:7]
	v_add_u32_e32 v55, v49, v48
	v_and_b32_e32 v48, 0x7fffff, v45
	v_or_b32_e32 v62, 0x800000, v48
	v_mad_u64_u32 v[48:49], s[8:9], v62, s8, 0
	v_mov_b32_e32 v64, v49
	s_mov_b32 s8, 0x3c439041
	v_mad_u64_u32 v[50:51], s[8:9], v62, s8, v[64:65]
	v_mov_b32_e32 v64, v51
	s_mov_b32 s8, 0xdb629599
	v_mad_u64_u32 v[52:53], s[8:9], v62, s8, v[64:65]
	v_mov_b32_e32 v64, v53
	s_mov_b32 s8, 0xf534ddc0
	v_mad_u64_u32 v[56:57], s[8:9], v62, s8, v[64:65]
	v_mov_b32_e32 v64, v57
	s_mov_b32 s8, 0xfc2757d1
	v_mad_u64_u32 v[58:59], s[8:9], v62, s8, v[64:65]
	v_mov_b32_e32 v64, v59
	s_mov_b32 s8, 0x4e441529
	v_mad_u64_u32 v[60:61], s[8:9], v62, s8, v[64:65]
	v_mov_b32_e32 v64, v61
	s_mov_b32 s8, 0xa2f9836e
	v_mad_u64_u32 v[62:63], s[8:9], v62, s8, v[64:65]
	v_cndmask_b32_e32 v49, v60, v56, vcc
	v_cndmask_b32_e32 v51, v62, v58, vcc
	v_cndmask_b32_e32 v57, v63, v60, vcc
	v_cndmask_b32_e64 v53, v51, v49, s[4:5]
	v_cndmask_b32_e64 v51, v57, v51, s[4:5]
	v_cndmask_b32_e32 v57, v58, v52, vcc
	v_cndmask_b32_e64 v49, v49, v57, s[4:5]
	v_cndmask_b32_e32 v50, v56, v50, vcc
	v_cndmask_b32_e64 v51, v51, v53, s[6:7]
	v_cndmask_b32_e64 v53, v53, v49, s[6:7]
	v_sub_u32_e32 v58, 32, v55
	v_cmp_eq_u32_e64 s[8:9], 0, v55
	v_cndmask_b32_e64 v55, v57, v50, s[4:5]
	v_alignbit_b32 v59, v51, v53, v58
	v_cndmask_b32_e64 v49, v49, v55, s[6:7]
	v_cndmask_b32_e64 v51, v59, v51, s[8:9]
	v_alignbit_b32 v56, v53, v49, v58
	v_cndmask_b32_e32 v48, v52, v48, vcc
	v_cndmask_b32_e64 v53, v56, v53, s[8:9]
	v_bfe_u32 v59, v51, 29, 1
	v_cndmask_b32_e64 v48, v50, v48, s[4:5]
	v_alignbit_b32 v56, v51, v53, 30
	v_sub_u32_e32 v60, 0, v59
	v_cndmask_b32_e64 v48, v55, v48, s[6:7]
	v_xor_b32_e32 v56, v56, v60
	v_alignbit_b32 v50, v49, v48, v58
	v_cndmask_b32_e64 v49, v50, v49, s[8:9]
	v_ffbh_u32_e32 v52, v56
	v_alignbit_b32 v50, v53, v49, 30
	v_min_u32_e32 v52, 32, v52
	v_alignbit_b32 v48, v49, v48, 30
	v_xor_b32_e32 v50, v50, v60
	v_sub_u32_e32 v53, 31, v52
	v_xor_b32_e32 v48, v48, v60
	v_alignbit_b32 v55, v56, v50, v53
	v_alignbit_b32 v48, v50, v48, v53
	v_alignbit_b32 v49, v55, v48, 9
	v_ffbh_u32_e32 v50, v49
	v_min_u32_e32 v50, 32, v50
	v_lshrrev_b32_e32 v57, 29, v51
	v_not_b32_e32 v53, v50
	v_alignbit_b32 v48, v49, v48, v53
	v_lshlrev_b32_e32 v49, 31, v57
	v_or_b32_e32 v53, 0x33000000, v49
	v_add_lshl_u32 v50, v50, v52, 23
	v_lshrrev_b32_e32 v48, 9, v48
	v_sub_u32_e32 v50, v53, v50
	v_or_b32_e32 v49, 0.5, v49
	v_lshlrev_b32_e32 v52, 23, v52
	v_or_b32_e32 v48, v50, v48
	v_lshrrev_b32_e32 v50, 9, v55
	v_sub_u32_e32 v49, v49, v52
	v_or_b32_e32 v49, v50, v49
	v_mul_f32_e32 v50, 0x3fc90fda, v49
	v_fma_f32 v52, v49, s20, -v50
	v_fmac_f32_e32 v52, 0x33a22168, v49
	v_fmac_f32_e32 v52, 0x3fc90fda, v48
	v_lshrrev_b32_e32 v48, 30, v51
	v_add_f32_e32 v49, v50, v52
	v_add_u32_e32 v48, v59, v48

; __device__ __forceinline__ bf16_t f2bf(float f) { return (bf16_t)(cvt_pk_bf16(f, 0.f) & 0xffffu); }
; __device__ __forceinline__ float bf2f(bf16_t b) { return __uint_as_float(((unsigned)b) << 16); }
; __device__ __forceinline__ float sigmoidf_(float x) { return 1.0f / (1.0f + __expf(-x)); }
; template <bool FINAL>
; __device__ __forceinline__ void lru_item(const Ctx& C, int l, int item) {
;     ...
;             for (int dt = 0; dt < 4; ++dt) {
;                 f32x4 Da = {0.f, 0.f, 0.f, 0.f}, Dx = {0.f, 0.f, 0.f, 0.f};
;                 Da = __builtin_amdgcn_mfma_f32_16x16x32_bf16(xa0, Bw[0][dt][0], Da, 0, 0, 0); Da = __builtin_amdgcn_mfma_f32_16x16x32_bf16(xa1, Bw[0][dt][1], Da, 0, 0, 0);
;                 Dx = __builtin_amdgcn_mfma_f32_16x16x32_bf16(xa0, Bw[1][dt][0], Dx, 0, 0, 0); Dx = __builtin_amdgcn_mfma_f32_16x16x32_bf16(xa1, Bw[1][dt][1], Dx, 0, 0, 0);
; #pragma unroll
;                 for (int r = 0; r < 4; ++r) { const int tloc = 4 * quad + r, d = 16 * dt + fr;
;                     const float rg = sigmoidf_(Da[r] + bav[dt]), ig = sigmoidf_(Dx[r] + bxv[dt]), la = -8.0f * rg * spv[dt], a = __expf(la);
;                     const float x = bf2f(xc[(16 * tt + tloc) * XCP + n * 64 + d]);
;                     Al[tloc * 68 + d] = a; Ul[tloc * 68 + d] = f2bf(sqrtf(fmaxf(1.0f - a * a, 0.f)) * ig * x); }
.LBB0_466:
	s_and_b64 s[0:1], s[4:5], exec
	s_cselect_b32 s0, s19, s20
	s_lshl_b32 s21, s0, 4
	v_or_b32_e32 v66, s21, v93
	v_mad_u64_u32 v[66:67], s[0:1], v66, s58, v[92:93]
	ds_read_b128 v[70:73], v66
	ds_read_b128 v[66:69], v66 offset:64
	s_add_i32 s19, s19, 1
	s_add_i32 s20, s20, -1
	s_waitcnt lgkmcnt(1)
	v_mfma_f32_16x16x32_bf16 v[74:77], v[70:73], v[0:3], 0
	s_cmp_lg_u32 s19, 4
	s_waitcnt lgkmcnt(0)
	v_mfma_f32_16x16x32_bf16 v[74:77], v[66:69], v[16:19], v[74:77]
	v_mfma_f32_16x16x32_bf16 v[98:101], v[70:73], v[32:35], 0
	v_mfma_f32_16x16x32_bf16 v[168:171], v[66:69], v[48:51], v[98:101]
	s_nop 5
	v_add_f32_e32 v74, v64, v74
	v_mul_f32_e32 v74, 0xbfb8aa3b, v74
	v_exp_f32_e32 v74, v74
	s_nop 0
	v_add_f32_e32 v74, 1.0, v74
	s_nop 0
	v_rcp_f32_e32 v74, v74
	v_add_f32_e32 v98, v155, v168
	v_mul_f32_e32 v98, 0xbfb8aa3b, v98
	v_exp_f32_e32 v98, v98
	v_mul_f32_e32 v74, 0xc1000000, v74
	v_mul_f32_e32 v74, v156, v74
	v_mul_f32_e32 v74, 0x3fb8aa3b, v74
	v_add_f32_e32 v98, 1.0, v98
	v_exp_f32_e32 v74, v74
	ds_write_b32 v108, v74 offset:33792
	v_fma_f32 v74, -v74, v74, 1.0
	v_max_f32_e32 v74, 0, v74
	v_cmp_gt_f32_e32 vcc, s59, v74
	v_mul_f32_e32 v100, 0x4f800000, v74
	v_rcp_f32_e32 v98, v98
	v_cndmask_b32_e32 v74, v74, v100, vcc
	v_sqrt_f32_e32 v100, v74
	v_or_b32_e32 v99, s21, v106
	v_mad_u64_u32 v[104:105], s[0:1], v99, s58, v[96:97]
	v_add_u32_e32 v101, -1, v100
	v_fma_f32 v102, -v101, v100, v74
	v_cmp_ge_f32_e64 s[0:1], 0, v102
	v_add_u32_e32 v102, 1, v100
	ds_read_u16 v99, v104
	v_cndmask_b32_e64 v101, v100, v101, s[0:1]
	v_fma_f32 v100, -v102, v100, v74
	v_cmp_lt_f32_e64 s[0:1], 0, v100
	s_waitcnt lgkmcnt(0)
	v_lshlrev_b32_e32 v99, 16, v99
	v_cndmask_b32_e64 v100, v101, v102, s[0:1]
	v_mul_f32_e32 v101, 0x37800000, v100
	v_cndmask_b32_e32 v100, v100, v101, vcc
	v_cmp_class_f32_e32 vcc, v74, v220
	s_nop 1
	v_cndmask_b32_e32 v74, v100, v74, vcc
	v_mul_f32_e32 v74, v98, v74
	v_mul_f32_e32 v74, v74, v99
	v_cvt_pk_bf16_f32 v74, v74, s0
	ds_write_b16 v136, v74 offset:38144
	v_add_f32_e32 v74, v64, v75
	v_mul_f32_e32 v74, 0xbfb8aa3b, v74
	v_exp_f32_e32 v74, v74
	s_nop 0
	v_add_f32_e32 v74, 1.0, v74
	s_nop 0
	v_rcp_f32_e32 v74, v74
	v_add_f32_e32 v75, v155, v169
	v_mul_f32_e32 v75, 0xbfb8aa3b, v75
	v_exp_f32_e32 v75, v75
	v_mul_f32_e32 v74, 0xc1000000, v74
	v_mul_f32_e32 v74, v156, v74
	v_mul_f32_e32 v74, 0x3fb8aa3b, v74
	v_add_f32_e32 v75, 1.0, v75
	v_exp_f32_e32 v74, v74
	ds_write_b32 v110, v74 offset:33792
	v_fma_f32 v74, -v74, v74, 1.0
	v_max_f32_e32 v74, 0, v74
	v_cmp_gt_f32_e32 vcc, s59, v74
	v_mul_f32_e32 v99, 0x4f800000, v74
	v_rcp_f32_e32 v75, v75
	v_cndmask_b32_e32 v74, v74, v99, vcc
	v_sqrt_f32_e32 v99, v74
	v_or_b32_e32 v98, s21, v109
	v_mad_u64_u32 v[102:103], s[0:1], v98, s58, v[96:97]
	v_add_u32_e32 v100, -1, v99
	v_fma_f32 v101, -v100, v99, v74
	v_cmp_ge_f32_e64 s[0:1], 0, v101
	v_add_u32_e32 v101, 1, v99
	ds_read_u16 v98, v102
	v_cndmask_b32_e64 v100, v99, v100, s[0:1]
	v_fma_f32 v99, -v101, v99, v74
	v_cmp_lt_f32_e64 s[0:1], 0, v99
	s_waitcnt lgkmcnt(0)
	v_lshlrev_b32_e32 v98, 16, v98
	v_cndmask_b32_e64 v99, v100, v101, s[0:1]
	v_mul_f32_e32 v100, 0x37800000, v99
	v_cndmask_b32_e32 v99, v99, v100, vcc
	v_cmp_class_f32_e32 vcc, v74, v220
	s_nop 1
	v_cndmask_b32_e32 v74, v99, v74, vcc
	v_mul_f32_e32 v74, v75, v74
	v_mul_f32_e32 v74, v74, v98
	v_cvt_pk_bf16_f32 v74, v74, s0
	ds_write_b16 v137, v74 offset:38144
	v_add_f32_e32 v74, v64, v76
	v_mul_f32_e32 v74, 0xbfb8aa3b, v74
	v_exp_f32_e32 v74, v74
	s_nop 0
	v_add_f32_e32 v74, 1.0, v74
	s_nop 0
	v_rcp_f32_e32 v74, v74
	v_add_f32_e32 v75, v155, v170
	v_mul_f32_e32 v75, 0xbfb8aa3b, v75
	v_exp_f32_e32 v75, v75
	v_mul_f32_e32 v74, 0xc1000000, v74
	v_mul_f32_e32 v74, v156, v74
	v_mul_f32_e32 v74, 0x3fb8aa3b, v74
	v_add_f32_e32 v75, 1.0, v75
	v_exp_f32_e32 v74, v74
	ds_write_b32 v112, v74 offset:33792
	v_fma_f32 v74, -v74, v74, 1.0
	v_max_f32_e32 v74, 0, v74
	v_cmp_gt_f32_e32 vcc, s59, v74
	v_mul_f32_e32 v98, 0x4f800000, v74
	v_rcp_f32_e32 v75, v75
	v_cndmask_b32_e32 v74, v74, v98, vcc
	v_sqrt_f32_e32 v98, v74
	v_or_b32_e32 v76, s21, v111
	v_mad_u64_u32 v[100:101], s[0:1], v76, s58, v[96:97]
	v_add_u32_e32 v99, -1, v98
	v_fma_f32 v101, -v99, v98, v74
	v_cmp_ge_f32_e64 s[0:1], 0, v101
	v_add_u32_e32 v101, 1, v98
	ds_read_u16 v76, v100
	v_cndmask_b32_e64 v99, v98, v99, s[0:1]
	v_fma_f32 v98, -v101, v98, v74
	v_cmp_lt_f32_e64 s[0:1], 0, v98
	s_waitcnt lgkmcnt(0)
	v_lshlrev_b32_e32 v76, 16, v76
	v_cndmask_b32_e64 v98, v99, v101, s[0:1]
	v_mul_f32_e32 v99, 0x37800000, v98
	v_cndmask_b32_e32 v98, v98, v99, vcc
	v_cmp_class_f32_e32 vcc, v74, v220
	s_nop 1
	v_cndmask_b32_e32 v74, v98, v74, vcc
	v_mul_f32_e32 v74, v75, v74
	v_mul_f32_e32 v74, v74, v76
	v_cvt_pk_bf16_f32 v74, v74, s0
	ds_write_b16 v138, v74 offset:38144
	v_add_f32_e32 v74, v64, v77
	v_mul_f32_e32 v74, 0xbfb8aa3b, v74
	v_exp_f32_e32 v74, v74
	s_nop 0
	v_add_f32_e32 v74, 1.0, v74
	s_nop 0
	v_rcp_f32_e32 v74, v74
	v_add_f32_e32 v75, v155, v171
	v_mul_f32_e32 v75, 0xbfb8aa3b, v75
	v_exp_f32_e32 v75, v75
	v_mul_f32_e32 v74, 0xc1000000, v74
	v_mul_f32_e32 v74, v156, v74
	v_mul_f32_e32 v74, 0x3fb8aa3b, v74
	v_add_f32_e32 v75, 1.0, v75
	v_exp_f32_e32 v74, v74
	v_mfma_f32_16x16x32_bf16 v[168:171], v[70:73], v[36:39], 0
	ds_write_b32 v114, v74 offset:33792
	v_fma_f32 v74, -v74, v74, 1.0
	v_max_f32_e32 v74, 0, v74
	v_cmp_gt_f32_e32 vcc, s59, v74
	v_mul_f32_e32 v77, 0x4f800000, v74
	v_rcp_f32_e32 v75, v75
	v_cndmask_b32_e32 v74, v74, v77, vcc
	v_sqrt_f32_e32 v77, v74
	v_or_b32_e32 v76, s21, v113
	v_mad_u64_u32 v[98:99], s[0:1], v76, s58, v[96:97]
	v_add_u32_e32 v99, -1, v77
	v_fma_f32 v101, -v99, v77, v74
	v_cmp_ge_f32_e64 s[0:1], 0, v101
	v_add_u32_e32 v101, 1, v77
	ds_read_u16 v76, v98
	v_cndmask_b32_e64 v99, v77, v99, s[0:1]
	v_fma_f32 v77, -v101, v77, v74
	v_cmp_lt_f32_e64 s[0:1], 0, v77
	v_mfma_f32_16x16x32_bf16 v[168:171], v[66:69], v[52:55], v[168:171]
	s_waitcnt lgkmcnt(0)
; __device__ __forceinline__ bf16_t f2bf(float f) { return (bf16_t)(cvt_pk_bf16(f, 0.f) & 0xffffu); }
; __device__ __forceinline__ float bf2f(bf16_t b) { return __uint_as_float(((unsigned)b) << 16); }
; __device__ __forceinline__ float sigmoidf_(float x) { return 1.0f / (1.0f + __expf(-x)); }
; template <bool FINAL>
; __device__ __forceinline__ void lru_item(const Ctx& C, int l, int item) {
;     ...
;             for (int dt = 0; dt < 4; ++dt) {
;                 f32x4 Da = {0.f, 0.f, 0.f, 0.f}, Dx = {0.f, 0.f, 0.f, 0.f};
;                 Da = __builtin_amdgcn_mfma_f32_16x16x32_bf16(xa0, Bw[0][dt][0], Da, 0, 0, 0); Da = __builtin_amdgcn_mfma_f32_16x16x32_bf16(xa1, Bw[0][dt][1], Da, 0, 0, 0);
;                 Dx = __builtin_amdgcn_mfma_f32_16x16x32_bf16(xa0, Bw[1][dt][0], Dx, 0, 0, 0); Dx = __builtin_amdgcn_mfma_f32_16x16x32_bf16(xa1, Bw[1][dt][1], Dx, 0, 0, 0);
; #pragma unroll
;                 for (int r = 0; r < 4; ++r) { const int tloc = 4 * quad + r, d = 16 * dt + fr;
;                     const float rg = sigmoidf_(Da[r] + bav[dt]), ig = sigmoidf_(Dx[r] + bxv[dt]), la = -8.0f * rg * spv[dt], a = __expf(la);
;                     const float x = bf2f(xc[(16 * tt + tloc) * XCP + n * 64 + d]);
;                     Al[tloc * 68 + d] = a; Ul[tloc * 68 + d] = f2bf(sqrtf(fmaxf(1.0f - a * a, 0.f)) * ig * x); }
	v_lshlrev_b32_e32 v76, 16, v76
	v_cndmask_b32_e64 v77, v99, v101, s[0:1]
	v_mul_f32_e32 v99, 0x37800000, v77
	v_cndmask_b32_e32 v77, v77, v99, vcc
	v_cmp_class_f32_e32 vcc, v74, v220
	s_nop 1
	v_cndmask_b32_e32 v74, v77, v74, vcc
	v_mul_f32_e32 v74, v75, v74
	v_mul_f32_e32 v74, v74, v76
	v_cvt_pk_bf16_f32 v74, v74, s0
	ds_write_b16 v139, v74 offset:38144
	v_mfma_f32_16x16x32_bf16 v[74:77], v[70:73], v[4:7], 0
	v_mfma_f32_16x16x32_bf16 v[74:77], v[66:69], v[20:23], v[74:77]
	s_nop 7
	v_add_f32_e32 v74, v157, v74
	v_mul_f32_e32 v74, 0xbfb8aa3b, v74
	v_exp_f32_e32 v74, v74
	s_nop 0
	v_add_f32_e32 v74, 1.0, v74
	s_nop 0
	v_rcp_f32_e32 v74, v74
	v_add_f32_e32 v99, v158, v168
	v_mul_f32_e32 v99, 0xbfb8aa3b, v99
	v_exp_f32_e32 v99, v99
	v_mul_f32_e32 v74, 0xc1000000, v74
	v_mul_f32_e32 v74, v159, v74
	v_mul_f32_e32 v74, 0x3fb8aa3b, v74
	v_add_f32_e32 v99, 1.0, v99
	v_exp_f32_e32 v74, v74
	ds_write_b32 v108, v74 offset:33856
	v_fma_f32 v74, -v74, v74, 1.0
	v_max_f32_e32 v74, 0, v74
	v_cmp_gt_f32_e32 vcc, s59, v74
	v_mul_f32_e32 v103, 0x4f800000, v74
	v_rcp_f32_e32 v99, v99
	v_cndmask_b32_e32 v74, v74, v103, vcc
	v_sqrt_f32_e32 v103, v74
	ds_read_u16 v101, v104 offset:32
	v_add_u32_e32 v105, -1, v103
	v_fma_f32 v168, -v105, v103, v74
	v_cmp_ge_f32_e64 s[0:1], 0, v168
	v_add_u32_e32 v168, 1, v103
	s_waitcnt lgkmcnt(0)
	v_lshlrev_b32_e32 v101, 16, v101
	v_cndmask_b32_e64 v105, v103, v105, s[0:1]
	v_fma_f32 v103, -v168, v103, v74
	v_cmp_lt_f32_e64 s[0:1], 0, v103
	s_nop 1
	v_cndmask_b32_e64 v103, v105, v168, s[0:1]
	v_mul_f32_e32 v105, 0x37800000, v103
	v_cndmask_b32_e32 v103, v103, v105, vcc
	v_cmp_class_f32_e32 vcc, v74, v220
	s_nop 1
	v_cndmask_b32_e32 v74, v103, v74, vcc
	v_mul_f32_e32 v74, v99, v74
	v_mul_f32_e32 v74, v74, v101
	v_cvt_pk_bf16_f32 v74, v74, s0
	ds_write_b16 v115, v74 offset:38176
	v_add_f32_e32 v74, v157, v75
	v_mul_f32_e32 v74, 0xbfb8aa3b, v74
	v_exp_f32_e32 v74, v74
	s_nop 0
	v_add_f32_e32 v74, 1.0, v74
	s_nop 0
	v_rcp_f32_e32 v74, v74
	v_add_f32_e32 v75, v158, v169
	v_mul_f32_e32 v75, 0xbfb8aa3b, v75
	v_exp_f32_e32 v75, v75
	v_mul_f32_e32 v74, 0xc1000000, v74
	v_mul_f32_e32 v74, v159, v74
	v_mul_f32_e32 v74, 0x3fb8aa3b, v74
	v_add_f32_e32 v75, 1.0, v75
	v_exp_f32_e32 v74, v74
	ds_write_b32 v110, v74 offset:33856
	v_fma_f32 v74, -v74, v74, 1.0
	v_max_f32_e32 v74, 0, v74
	v_cmp_gt_f32_e32 vcc, s59, v74
	v_mul_f32_e32 v101, 0x4f800000, v74
	v_rcp_f32_e32 v75, v75
	v_cndmask_b32_e32 v74, v74, v101, vcc
	v_sqrt_f32_e32 v101, v74
	ds_read_u16 v99, v102 offset:32
	v_add_u32_e32 v103, -1, v101
	v_fma_f32 v105, -v103, v101, v74
	v_cmp_ge_f32_e64 s[0:1], 0, v105
	v_add_u32_e32 v105, 1, v101
	s_waitcnt lgkmcnt(0)
	v_lshlrev_b32_e32 v99, 16, v99
	v_cndmask_b32_e64 v103, v101, v103, s[0:1]
	v_fma_f32 v101, -v105, v101, v74
	v_cmp_lt_f32_e64 s[0:1], 0, v101
	s_nop 1
	v_cndmask_b32_e64 v101, v103, v105, s[0:1]
	v_mul_f32_e32 v103, 0x37800000, v101
	v_cndmask_b32_e32 v101, v101, v103, vcc
	v_cmp_class_f32_e32 vcc, v74, v220
	s_nop 1
	v_cndmask_b32_e32 v74, v101, v74, vcc
	v_mul_f32_e32 v74, v75, v74
	v_mul_f32_e32 v74, v74, v99
	v_cvt_pk_bf16_f32 v74, v74, s0
	ds_write_b16 v116, v74 offset:38176
	v_add_f32_e32 v74, v157, v76
	v_mul_f32_e32 v74, 0xbfb8aa3b, v74
	v_exp_f32_e32 v74, v74
	s_nop 0
	v_add_f32_e32 v74, 1.0, v74
	s_nop 0
	v_rcp_f32_e32 v74, v74
	v_add_f32_e32 v75, v158, v170
	v_mul_f32_e32 v75, 0xbfb8aa3b, v75
	v_exp_f32_e32 v75, v75
	v_mul_f32_e32 v74, 0xc1000000, v74
	v_mul_f32_e32 v74, v159, v74
	v_mul_f32_e32 v74, 0x3fb8aa3b, v74
	v_add_f32_e32 v75, 1.0, v75
	v_exp_f32_e32 v74, v74
	ds_write_b32 v112, v74 offset:33856
	v_fma_f32 v74, -v74, v74, 1.0
	v_max_f32_e32 v74, 0, v74
	v_cmp_gt_f32_e32 vcc, s59, v74
	v_mul_f32_e32 v99, 0x4f800000, v74
	v_rcp_f32_e32 v75, v75
	v_cndmask_b32_e32 v74, v74, v99, vcc
	v_sqrt_f32_e32 v99, v74
	ds_read_u16 v76, v100 offset:32
	v_add_u32_e32 v101, -1, v99
	v_fma_f32 v103, -v101, v99, v74
	v_cmp_ge_f32_e64 s[0:1], 0, v103
	v_add_u32_e32 v103, 1, v99
	s_waitcnt lgkmcnt(0)
	v_lshlrev_b32_e32 v76, 16, v76
	v_cndmask_b32_e64 v101, v99, v101, s[0:1]
	v_fma_f32 v99, -v103, v99, v74
	v_cmp_lt_f32_e64 s[0:1], 0, v99
	s_nop 1
	v_cndmask_b32_e64 v99, v101, v103, s[0:1]
	v_mul_f32_e32 v101, 0x37800000, v99
	v_cndmask_b32_e32 v99, v99, v101, vcc
	v_cmp_class_f32_e32 vcc, v74, v220
	s_nop 1
	v_cndmask_b32_e32 v74, v99, v74, vcc
	v_mul_f32_e32 v74, v75, v74
	v_mul_f32_e32 v74, v74, v76
	v_cvt_pk_bf16_f32 v74, v74, s0
	ds_write_b16 v117, v74 offset:38176
	v_add_f32_e32 v74, v157, v77
	v_mul_f32_e32 v74, 0xbfb8aa3b, v74
	v_exp_f32_e32 v74, v74
	s_nop 0
	v_add_f32_e32 v74, 1.0, v74
	s_nop 0
	v_rcp_f32_e32 v74, v74
	v_add_f32_e32 v75, v158, v171
	v_mul_f32_e32 v75, 0xbfb8aa3b, v75
	v_exp_f32_e32 v75, v75
	v_mul_f32_e32 v74, 0xc1000000, v74
	v_mul_f32_e32 v74, v159, v74
	v_mul_f32_e32 v74, 0x3fb8aa3b, v74
	v_add_f32_e32 v75, 1.0, v75
	v_exp_f32_e32 v74, v74
	v_mfma_f32_16x16x32_bf16 v[168:171], v[70:73], v[40:43], 0
	ds_write_b32 v114, v74 offset:33856
	v_fma_f32 v74, -v74, v74, 1.0
	v_max_f32_e32 v74, 0, v74
	v_cmp_gt_f32_e32 vcc, s59, v74
	v_mul_f32_e32 v77, 0x4f800000, v74
	v_rcp_f32_e32 v75, v75
	v_cndmask_b32_e32 v74, v74, v77, vcc
	v_sqrt_f32_e32 v77, v74
	ds_read_u16 v76, v98 offset:32
	v_mfma_f32_16x16x32_bf16 v[168:171], v[66:69], v[56:59], v[168:171]
	v_add_u32_e32 v99, -1, v77
	v_fma_f32 v101, -v99, v77, v74
	v_cmp_ge_f32_e64 s[0:1], 0, v101
	v_add_u32_e32 v101, 1, v77
	s_waitcnt lgkmcnt(0)
; __device__ __forceinline__ bf16_t f2bf(float f) { return (bf16_t)(cvt_pk_bf16(f, 0.f) & 0xffffu); }
; __device__ __forceinline__ float bf2f(bf16_t b) { return __uint_as_float(((unsigned)b) << 16); }
; __device__ __forceinline__ float sigmoidf_(float x) { return 1.0f / (1.0f + __expf(-x)); }
; template <bool FINAL>
; __device__ __forceinline__ void lru_item(const Ctx& C, int l, int item) {
;     ...
;             for (int dt = 0; dt < 4; ++dt) {
;                 f32x4 Da = {0.f, 0.f, 0.f, 0.f}, Dx = {0.f, 0.f, 0.f, 0.f};
;                 Da = __builtin_amdgcn_mfma_f32_16x16x32_bf16(xa0, Bw[0][dt][0], Da, 0, 0, 0); Da = __builtin_amdgcn_mfma_f32_16x16x32_bf16(xa1, Bw[0][dt][1], Da, 0, 0, 0);
;                 Dx = __builtin_amdgcn_mfma_f32_16x16x32_bf16(xa0, Bw[1][dt][0], Dx, 0, 0, 0); Dx = __builtin_amdgcn_mfma_f32_16x16x32_bf16(xa1, Bw[1][dt][1], Dx, 0, 0, 0);
; #pragma unroll
;                 for (int r = 0; r < 4; ++r) { const int tloc = 4 * quad + r, d = 16 * dt + fr;
;                     const float rg = sigmoidf_(Da[r] + bav[dt]), ig = sigmoidf_(Dx[r] + bxv[dt]), la = -8.0f * rg * spv[dt], a = __expf(la);
;                     const float x = bf2f(xc[(16 * tt + tloc) * XCP + n * 64 + d]);
;                     Al[tloc * 68 + d] = a; Ul[tloc * 68 + d] = f2bf(sqrtf(fmaxf(1.0f - a * a, 0.f)) * ig * x); }
	v_lshlrev_b32_e32 v76, 16, v76
	v_cndmask_b32_e64 v99, v77, v99, s[0:1]
	v_fma_f32 v77, -v101, v77, v74
	v_cmp_lt_f32_e64 s[0:1], 0, v77
	s_nop 1
	v_cndmask_b32_e64 v77, v99, v101, s[0:1]
	v_mul_f32_e32 v99, 0x37800000, v77
	v_cndmask_b32_e32 v77, v77, v99, vcc
	v_cmp_class_f32_e32 vcc, v74, v220
	s_nop 1
	v_cndmask_b32_e32 v74, v77, v74, vcc
	v_mul_f32_e32 v74, v75, v74
	v_mul_f32_e32 v74, v74, v76
	v_cvt_pk_bf16_f32 v74, v74, s0
	ds_write_b16 v118, v74 offset:38176
	v_mfma_f32_16x16x32_bf16 v[74:77], v[70:73], v[8:11], 0
	v_mfma_f32_16x16x32_bf16 v[74:77], v[66:69], v[24:27], v[74:77]
	s_nop 7
	v_add_f32_e32 v74, v160, v74
	v_mul_f32_e32 v74, 0xbfb8aa3b, v74
	v_exp_f32_e32 v74, v74
	s_nop 0
	v_add_f32_e32 v74, 1.0, v74
	s_nop 0
	v_rcp_f32_e32 v74, v74
	v_add_f32_e32 v99, v161, v168
	v_mul_f32_e32 v99, 0xbfb8aa3b, v99
	v_exp_f32_e32 v99, v99
	v_mul_f32_e32 v74, 0xc1000000, v74
	v_mul_f32_e32 v74, v162, v74
	v_mul_f32_e32 v74, 0x3fb8aa3b, v74
	v_add_f32_e32 v99, 1.0, v99
	v_exp_f32_e32 v74, v74
	ds_write_b32 v108, v74 offset:33920
	v_fma_f32 v74, -v74, v74, 1.0
	v_max_f32_e32 v74, 0, v74
	v_cmp_gt_f32_e32 vcc, s59, v74
	v_mul_f32_e32 v103, 0x4f800000, v74
	v_rcp_f32_e32 v99, v99
	v_cndmask_b32_e32 v74, v74, v103, vcc
	v_sqrt_f32_e32 v103, v74
	ds_read_u16 v101, v104 offset:64
	v_add_u32_e32 v105, -1, v103
	v_fma_f32 v168, -v105, v103, v74
	v_cmp_ge_f32_e64 s[0:1], 0, v168
	v_add_u32_e32 v168, 1, v103
	s_waitcnt lgkmcnt(0)
	v_lshlrev_b32_e32 v101, 16, v101
	v_cndmask_b32_e64 v105, v103, v105, s[0:1]
	v_fma_f32 v103, -v168, v103, v74
	v_cmp_lt_f32_e64 s[0:1], 0, v103
	s_nop 1
	v_cndmask_b32_e64 v103, v105, v168, s[0:1]
	v_mul_f32_e32 v105, 0x37800000, v103
	v_cndmask_b32_e32 v103, v103, v105, vcc
	v_cmp_class_f32_e32 vcc, v74, v220
	s_nop 1
	v_cndmask_b32_e32 v74, v103, v74, vcc
	v_mul_f32_e32 v74, v99, v74
	v_mul_f32_e32 v74, v74, v101
	v_cvt_pk_bf16_f32 v74, v74, s0
	ds_write_b16 v115, v74 offset:38208
	v_add_f32_e32 v74, v160, v75
	v_mul_f32_e32 v74, 0xbfb8aa3b, v74
	v_exp_f32_e32 v74, v74
	s_nop 0
	v_add_f32_e32 v74, 1.0, v74
	s_nop 0
	v_rcp_f32_e32 v74, v74
	v_add_f32_e32 v75, v161, v169
	v_mul_f32_e32 v75, 0xbfb8aa3b, v75
	v_exp_f32_e32 v75, v75
	v_mul_f32_e32 v74, 0xc1000000, v74
	v_mul_f32_e32 v74, v162, v74
	v_mul_f32_e32 v74, 0x3fb8aa3b, v74
	v_add_f32_e32 v75, 1.0, v75
	v_exp_f32_e32 v74, v74
	ds_write_b32 v110, v74 offset:33920
	v_fma_f32 v74, -v74, v74, 1.0
	v_max_f32_e32 v74, 0, v74
	v_cmp_gt_f32_e32 vcc, s59, v74
	v_mul_f32_e32 v101, 0x4f800000, v74
	v_rcp_f32_e32 v75, v75
	v_cndmask_b32_e32 v74, v74, v101, vcc
	v_sqrt_f32_e32 v101, v74
	ds_read_u16 v99, v102 offset:64
	v_add_u32_e32 v103, -1, v101
	v_fma_f32 v105, -v103, v101, v74
	v_cmp_ge_f32_e64 s[0:1], 0, v105
	v_add_u32_e32 v105, 1, v101
	s_waitcnt lgkmcnt(0)
	v_lshlrev_b32_e32 v99, 16, v99
	v_cndmask_b32_e64 v103, v101, v103, s[0:1]
	v_fma_f32 v101, -v105, v101, v74
	v_cmp_lt_f32_e64 s[0:1], 0, v101
	s_nop 1
	v_cndmask_b32_e64 v101, v103, v105, s[0:1]
	v_mul_f32_e32 v103, 0x37800000, v101
	v_cndmask_b32_e32 v101, v101, v103, vcc
	v_cmp_class_f32_e32 vcc, v74, v220
	s_nop 1
	v_cndmask_b32_e32 v74, v101, v74, vcc
	v_mul_f32_e32 v74, v75, v74
	v_mul_f32_e32 v74, v74, v99
	v_cvt_pk_bf16_f32 v74, v74, s0
	ds_write_b16 v116, v74 offset:38208
	v_add_f32_e32 v74, v160, v76
	v_mul_f32_e32 v74, 0xbfb8aa3b, v74
	v_exp_f32_e32 v74, v74
	s_nop 0
	v_add_f32_e32 v74, 1.0, v74
	s_nop 0
	v_rcp_f32_e32 v74, v74
	v_add_f32_e32 v75, v161, v170
	v_mul_f32_e32 v75, 0xbfb8aa3b, v75
	v_exp_f32_e32 v75, v75
	v_mul_f32_e32 v74, 0xc1000000, v74
	v_mul_f32_e32 v74, v162, v74
	v_mul_f32_e32 v74, 0x3fb8aa3b, v74
	v_add_f32_e32 v75, 1.0, v75
	v_exp_f32_e32 v74, v74
	ds_write_b32 v112, v74 offset:33920
	v_fma_f32 v74, -v74, v74, 1.0
	v_max_f32_e32 v74, 0, v74
	v_cmp_gt_f32_e32 vcc, s59, v74
	v_mul_f32_e32 v99, 0x4f800000, v74
	v_rcp_f32_e32 v75, v75
	v_cndmask_b32_e32 v74, v74, v99, vcc
	v_sqrt_f32_e32 v99, v74
	ds_read_u16 v76, v100 offset:64
	v_add_u32_e32 v101, -1, v99
	v_fma_f32 v103, -v101, v99, v74
	v_cmp_ge_f32_e64 s[0:1], 0, v103
	v_add_u32_e32 v103, 1, v99
	s_waitcnt lgkmcnt(0)
	v_lshlrev_b32_e32 v76, 16, v76
	v_cndmask_b32_e64 v101, v99, v101, s[0:1]
	v_fma_f32 v99, -v103, v99, v74
	v_cmp_lt_f32_e64 s[0:1], 0, v99
	s_nop 1
	v_cndmask_b32_e64 v99, v101, v103, s[0:1]
	v_mul_f32_e32 v101, 0x37800000, v99
	v_cndmask_b32_e32 v99, v99, v101, vcc
	v_cmp_class_f32_e32 vcc, v74, v220
	s_nop 1
	v_cndmask_b32_e32 v74, v99, v74, vcc
	v_mul_f32_e32 v74, v75, v74
	v_mul_f32_e32 v74, v74, v76
	v_cvt_pk_bf16_f32 v74, v74, s0
	ds_write_b16 v117, v74 offset:38208
	v_add_f32_e32 v74, v160, v77
	v_mul_f32_e32 v74, 0xbfb8aa3b, v74
	v_exp_f32_e32 v74, v74
	s_nop 0
	v_add_f32_e32 v74, 1.0, v74
	s_nop 0
	v_rcp_f32_e32 v74, v74
	v_add_f32_e32 v75, v161, v171
	v_mul_f32_e32 v75, 0xbfb8aa3b, v75
	v_exp_f32_e32 v75, v75
	v_mul_f32_e32 v74, 0xc1000000, v74
	v_mul_f32_e32 v74, v162, v74
	v_mul_f32_e32 v74, 0x3fb8aa3b, v74
	v_add_f32_e32 v75, 1.0, v75
	v_exp_f32_e32 v74, v74
	ds_write_b32 v114, v74 offset:33920
	v_fma_f32 v74, -v74, v74, 1.0
	v_max_f32_e32 v74, 0, v74
	v_cmp_gt_f32_e32 vcc, s59, v74
	v_mul_f32_e32 v77, 0x4f800000, v74
	v_rcp_f32_e32 v75, v75
	v_cndmask_b32_e32 v74, v74, v77, vcc
	v_sqrt_f32_e32 v77, v74
	ds_read_u16 v76, v98 offset:64
	v_add_u32_e32 v99, -1, v77
	v_fma_f32 v101, -v99, v77, v74
	v_cmp_ge_f32_e64 s[0:1], 0, v101
	v_add_u32_e32 v101, 1, v77
	s_waitcnt lgkmcnt(0)
; __device__ __forceinline__ bf16_t f2bf(float f) { return (bf16_t)(cvt_pk_bf16(f, 0.f) & 0xffffu); }
; __device__ __forceinline__ float bf2f(bf16_t b) { return __uint_as_float(((unsigned)b) << 16); }
; __device__ __forceinline__ float sigmoidf_(float x) { return 1.0f / (1.0f + __expf(-x)); }
; template <bool FINAL>
; __device__ __forceinline__ void lru_item(const Ctx& C, int l, int item) {
;     ...
;             for (int dt = 0; dt < 4; ++dt) {
;                 f32x4 Da = {0.f, 0.f, 0.f, 0.f}, Dx = {0.f, 0.f, 0.f, 0.f};
;                 Da = __builtin_amdgcn_mfma_f32_16x16x32_bf16(xa0, Bw[0][dt][0], Da, 0, 0, 0); Da = __builtin_amdgcn_mfma_f32_16x16x32_bf16(xa1, Bw[0][dt][1], Da, 0, 0, 0);
;                 Dx = __builtin_amdgcn_mfma_f32_16x16x32_bf16(xa0, Bw[1][dt][0], Dx, 0, 0, 0); Dx = __builtin_amdgcn_mfma_f32_16x16x32_bf16(xa1, Bw[1][dt][1], Dx, 0, 0, 0);
; #pragma unroll
;                 for (int r = 0; r < 4; ++r) { const int tloc = 4 * quad + r, d = 16 * dt + fr;
;                     const float rg = sigmoidf_(Da[r] + bav[dt]), ig = sigmoidf_(Dx[r] + bxv[dt]), la = -8.0f * rg * spv[dt], a = __expf(la);
;                     const float x = bf2f(xc[(16 * tt + tloc) * XCP + n * 64 + d]);
;                     Al[tloc * 68 + d] = a; Ul[tloc * 68 + d] = f2bf(sqrtf(fmaxf(1.0f - a * a, 0.f)) * ig * x); }
	v_lshlrev_b32_e32 v76, 16, v76
	v_cndmask_b32_e64 v99, v77, v99, s[0:1]
	v_fma_f32 v77, -v101, v77, v74
	v_cmp_lt_f32_e64 s[0:1], 0, v77
	s_nop 1
	v_cndmask_b32_e64 v77, v99, v101, s[0:1]
	v_mul_f32_e32 v99, 0x37800000, v77
	v_cndmask_b32_e32 v77, v77, v99, vcc
	v_cmp_class_f32_e32 vcc, v74, v220
	s_nop 1
	v_cndmask_b32_e32 v74, v77, v74, vcc
	v_mul_f32_e32 v74, v75, v74
	v_mul_f32_e32 v74, v74, v76
	v_cvt_pk_bf16_f32 v74, v74, s0
	ds_write_b16 v118, v74 offset:38208
	v_mfma_f32_16x16x32_bf16 v[74:77], v[70:73], v[12:15], 0
	v_mfma_f32_16x16x32_bf16 v[74:77], v[66:69], v[28:31], v[74:77]
	v_mfma_f32_16x16x32_bf16 v[70:73], v[70:73], v[44:47], 0
	v_mfma_f32_16x16x32_bf16 v[66:69], v[66:69], v[60:63], v[70:73]
	s_waitcnt vmcnt(1)
	s_nop 5
	v_add_f32_e32 v70, v163, v74
	v_mul_f32_e32 v70, 0xbfb8aa3b, v70
	v_exp_f32_e32 v70, v70
	s_waitcnt vmcnt(0)
	v_add_f32_e32 v66, v164, v66
	v_mul_f32_e32 v66, 0xbfb8aa3b, v66
	v_exp_f32_e32 v66, v66
	v_add_f32_e32 v70, 1.0, v70
	v_add_f32_e32 v66, 1.0, v66
	v_add_f32_e32 v67, v164, v67
	v_mul_f32_e32 v67, 0xbfb8aa3b, v67
	v_rcp_f32_e32 v70, v70
	s_nop 0
	v_mul_f32_e32 v70, 0xc1000000, v70
	v_mul_f32_e32 v70, v165, v70
	v_mul_f32_e32 v70, 0x3fb8aa3b, v70
	v_exp_f32_e32 v70, v70
	ds_write_b32 v108, v70 offset:33984
	v_fma_f32 v70, -v70, v70, 1.0
	v_max_f32_e32 v70, 0, v70
	v_cmp_gt_f32_e32 vcc, s59, v70
	v_mul_f32_e32 v72, 0x4f800000, v70
	v_rcp_f32_e32 v66, v66
	v_cndmask_b32_e32 v70, v70, v72, vcc
	v_sqrt_f32_e32 v72, v70
	ds_read_u16 v71, v104 offset:96
	v_exp_f32_e32 v67, v67
	v_add_u32_e32 v73, -1, v72
	v_fma_f32 v74, -v73, v72, v70
	v_cmp_ge_f32_e64 s[0:1], 0, v74
	v_add_u32_e32 v74, 1, v72
	s_waitcnt lgkmcnt(0)
	v_lshlrev_b32_e32 v71, 16, v71
	v_cndmask_b32_e64 v73, v72, v73, s[0:1]
	v_fma_f32 v72, -v74, v72, v70
	v_cmp_lt_f32_e64 s[0:1], 0, v72
	v_add_f32_e32 v67, 1.0, v67
	s_nop 0
	v_cndmask_b32_e64 v72, v73, v74, s[0:1]
	v_mul_f32_e32 v73, 0x37800000, v72
	v_cndmask_b32_e32 v72, v72, v73, vcc
	v_cmp_class_f32_e32 vcc, v70, v220
	s_nop 1
	v_cndmask_b32_e32 v70, v72, v70, vcc
	v_mul_f32_e32 v66, v66, v70
	v_mul_f32_e32 v66, v66, v71
	v_cvt_pk_bf16_f32 v66, v66, s0
	ds_write_b16 v115, v66 offset:38240
	v_add_f32_e32 v66, v163, v75
	v_mul_f32_e32 v66, 0xbfb8aa3b, v66
	v_exp_f32_e32 v66, v66
	s_nop 0
	v_add_f32_e32 v66, 1.0, v66
	s_nop 0
	v_rcp_f32_e32 v66, v66
	s_nop 0
	v_mul_f32_e32 v66, 0xc1000000, v66
	v_mul_f32_e32 v66, v165, v66
	v_mul_f32_e32 v66, 0x3fb8aa3b, v66
	v_exp_f32_e32 v66, v66
	ds_write_b32 v110, v66 offset:33984
	v_fma_f32 v66, -v66, v66, 1.0
	v_max_f32_e32 v66, 0, v66
	v_cmp_gt_f32_e32 vcc, s59, v66
	v_mul_f32_e32 v71, 0x4f800000, v66
	v_rcp_f32_e32 v67, v67
	v_cndmask_b32_e32 v66, v66, v71, vcc
	v_sqrt_f32_e32 v71, v66
	ds_read_u16 v70, v102 offset:96
	v_add_u32_e32 v72, -1, v71
	v_fma_f32 v73, -v72, v71, v66
	v_cmp_ge_f32_e64 s[0:1], 0, v73
	v_add_u32_e32 v73, 1, v71
	s_waitcnt lgkmcnt(0)
	v_lshlrev_b32_e32 v70, 16, v70
	v_cndmask_b32_e64 v72, v71, v72, s[0:1]
	v_fma_f32 v71, -v73, v71, v66
	v_cmp_lt_f32_e64 s[0:1], 0, v71
	s_nop 1
	v_cndmask_b32_e64 v71, v72, v73, s[0:1]
	v_mul_f32_e32 v72, 0x37800000, v71
	v_cndmask_b32_e32 v71, v71, v72, vcc
	v_cmp_class_f32_e32 vcc, v66, v220
	s_nop 1
	v_cndmask_b32_e32 v66, v71, v66, vcc
	v_mul_f32_e32 v66, v67, v66
	v_mul_f32_e32 v66, v66, v70
	v_cvt_pk_bf16_f32 v66, v66, s0
	ds_write_b16 v116, v66 offset:38240
	v_add_f32_e32 v66, v163, v76
	v_mul_f32_e32 v66, 0xbfb8aa3b, v66
	v_exp_f32_e32 v66, v66
	s_nop 0
	v_add_f32_e32 v66, 1.0, v66
	s_nop 0
	v_rcp_f32_e32 v66, v66
	v_add_f32_e32 v67, v164, v68
	v_mul_f32_e32 v67, 0xbfb8aa3b, v67
	v_exp_f32_e32 v67, v67
	v_mul_f32_e32 v66, 0xc1000000, v66
	v_mul_f32_e32 v66, v165, v66
	v_mul_f32_e32 v66, 0x3fb8aa3b, v66
	v_add_f32_e32 v67, 1.0, v67
	v_exp_f32_e32 v66, v66
	ds_write_b32 v112, v66 offset:33984
	v_fma_f32 v66, -v66, v66, 1.0
	v_max_f32_e32 v66, 0, v66
	v_cmp_gt_f32_e32 vcc, s59, v66
	v_mul_f32_e32 v70, 0x4f800000, v66
	v_rcp_f32_e32 v67, v67
	v_cndmask_b32_e32 v66, v66, v70, vcc
	v_sqrt_f32_e32 v70, v66
	ds_read_u16 v68, v100 offset:96
	v_add_u32_e32 v71, -1, v70
	v_fma_f32 v72, -v71, v70, v66
	v_cmp_ge_f32_e64 s[0:1], 0, v72
	v_add_u32_e32 v72, 1, v70
	s_waitcnt lgkmcnt(0)
	v_lshlrev_b32_e32 v68, 16, v68
	v_cndmask_b32_e64 v71, v70, v71, s[0:1]
	v_fma_f32 v70, -v72, v70, v66
	v_cmp_lt_f32_e64 s[0:1], 0, v70
	s_nop 1
	v_cndmask_b32_e64 v70, v71, v72, s[0:1]
	v_mul_f32_e32 v71, 0x37800000, v70
	v_cndmask_b32_e32 v70, v70, v71, vcc
	v_cmp_class_f32_e32 vcc, v66, v220
	s_nop 1
	v_cndmask_b32_e32 v66, v70, v66, vcc
	v_mul_f32_e32 v66, v67, v66
	v_mul_f32_e32 v66, v66, v68
	v_cvt_pk_bf16_f32 v66, v66, s0
	ds_write_b16 v117, v66 offset:38240
	v_add_f32_e32 v66, v163, v77
	v_mul_f32_e32 v66, 0xbfb8aa3b, v66
	v_exp_f32_e32 v66, v66
	s_nop 0
	v_add_f32_e32 v66, 1.0, v66
	s_nop 0
	v_rcp_f32_e32 v66, v66
	v_add_f32_e32 v67, v164, v69
	v_mul_f32_e32 v67, 0xbfb8aa3b, v67
	v_exp_f32_e32 v67, v67
	v_mul_f32_e32 v66, 0xc1000000, v66
	v_mul_f32_e32 v66, v165, v66
	v_mul_f32_e32 v66, 0x3fb8aa3b, v66
	v_add_f32_e32 v67, 1.0, v67
	v_exp_f32_e32 v66, v66
	ds_write_b32 v114, v66 offset:33984
	v_fma_f32 v66, -v66, v66, 1.0
	v_max_f32_e32 v66, 0, v66
	v_cmp_gt_f32_e32 vcc, s59, v66
	v_mul_f32_e32 v69, 0x4f800000, v66
	v_rcp_f32_e32 v67, v67
	v_cndmask_b32_e32 v66, v66, v69, vcc
	v_sqrt_f32_e32 v69, v66
	ds_read_u16 v68, v98 offset:96
	v_add_u32_e32 v70, -1, v69
	v_fma_f32 v71, -v70, v69, v66
	v_cmp_ge_f32_e64 s[0:1], 0, v71
	v_add_u32_e32 v71, 1, v69
	s_waitcnt lgkmcnt(0)
; __device__ __forceinline__ bf16_t f2bf(float f) { return (bf16_t)(cvt_pk_bf16(f, 0.f) & 0xffffu); }
; __device__ __forceinline__ float bf2f(bf16_t b) { return __uint_as_float(((unsigned)b) << 16); }
; __device__ __forceinline__ float sigmoidf_(float x) { return 1.0f / (1.0f + __expf(-x)); }
; __device__ __forceinline__ void wave_lds_fence() { asm volatile("s_waitcnt lgkmcnt(0)" ::: "memory"); __builtin_amdgcn_wave_barrier(); }
;     __device__ __forceinline__ float* fp(size_t off) const { return (float*)(ws + off); }
; template <bool FINAL>
; __device__ __forceinline__ void lru_item(const Ctx& C, int l, int item) {
;     ...
;                 for (int r = 0; r < 4; ++r) { const int tloc = 4 * quad + r, d = 16 * dt + fr;
;                     const float rg = sigmoidf_(Da[r] + bav[dt]), ig = sigmoidf_(Dx[r] + bxv[dt]), la = -8.0f * rg * spv[dt], a = __expf(la);
;                     const float x = bf2f(xc[(16 * tt + tloc) * XCP + n * 64 + d]);
;                     Al[tloc * 68 + d] = a; Ul[tloc * 68 + d] = f2bf(sqrtf(fmaxf(1.0f - a * a, 0.f)) * ig * x); }
;             }
;             wave_lds_fence();
; #pragma unroll
;             for (int j = 0; j < 16; ++j) { const int tloc = z ? 15 - j : j;
;                 const float a = Al[tloc * 68 + lane], u = bf2f(Ul[tloc * 68 + lane]);
;                 h = fmaf(a, h, u); Ap *= a;
;                 if (FINAL) Hz[(16 * tt + tloc) * 256 + n * 64 + lane] = f2bf(h); }
;             wave_lds_fence();
;         }
;         if (!FINAL) { C.fp(OFF_CARA)[cidx] = Ap; C.fp(OFF_CARH)[cidx] = h; }
	v_lshlrev_b32_e32 v68, 16, v68
	v_cndmask_b32_e64 v70, v69, v70, s[0:1]
	v_fma_f32 v69, -v71, v69, v66
	v_cmp_lt_f32_e64 s[0:1], 0, v69
	s_nop 1
	v_cndmask_b32_e64 v69, v70, v71, s[0:1]
	v_mul_f32_e32 v70, 0x37800000, v69
	v_cndmask_b32_e32 v69, v69, v70, vcc
	v_cmp_class_f32_e32 vcc, v66, v220
	s_nop 1
	v_cndmask_b32_e32 v66, v69, v66, vcc
	v_mul_f32_e32 v66, v67, v66
	v_mul_f32_e32 v66, v66, v68
	v_cvt_pk_bf16_f32 v66, v66, s0
	ds_write_b16 v118, v66 offset:38240
	s_waitcnt lgkmcnt(0)
	ds_read_b32 v66, v107 offset:33792
	ds_read_u16 v67, v119 offset:38144
	ds_read_b32 v68, v120 offset:33792
	ds_read_u16 v69, v140 offset:38144
	s_waitcnt lgkmcnt(2)
	v_lshlrev_b32_e32 v67, 16, v67
	v_fmac_f32_e32 v67, v66, v166
	v_mul_f32_e32 v66, v167, v66
	s_waitcnt lgkmcnt(0)
	v_lshlrev_b32_e32 v69, 16, v69
	v_fmac_f32_e32 v69, v68, v67
	v_mul_f32_e32 v66, v66, v68
	ds_read_b32 v67, v121 offset:33792
	ds_read_u16 v68, v141 offset:38144
	s_waitcnt lgkmcnt(1)
	v_mul_f32_e32 v66, v66, v67
	s_waitcnt lgkmcnt(0)
	v_lshlrev_b32_e32 v68, 16, v68
	v_fmac_f32_e32 v68, v67, v69
	ds_read_b32 v67, v122 offset:33792
	ds_read_u16 v69, v142 offset:38144
	s_waitcnt lgkmcnt(1)
	v_mul_f32_e32 v66, v66, v67
	s_waitcnt lgkmcnt(0)
	v_lshlrev_b32_e32 v69, 16, v69
	v_fmac_f32_e32 v69, v67, v68
	ds_read_b32 v67, v123 offset:33792
	ds_read_u16 v68, v143 offset:38144
	s_waitcnt lgkmcnt(1)
	v_mul_f32_e32 v66, v66, v67
	s_waitcnt lgkmcnt(0)
	v_lshlrev_b32_e32 v68, 16, v68
	v_fmac_f32_e32 v68, v67, v69
	ds_read_b32 v67, v124 offset:33792
	ds_read_u16 v69, v144 offset:38144
	s_waitcnt lgkmcnt(1)
	v_mul_f32_e32 v66, v66, v67
	s_waitcnt lgkmcnt(0)
	v_lshlrev_b32_e32 v69, 16, v69
	v_fmac_f32_e32 v69, v67, v68
	ds_read_b32 v67, v125 offset:33792
	ds_read_u16 v68, v145 offset:38144
	s_waitcnt lgkmcnt(1)
	v_mul_f32_e32 v66, v66, v67
	s_waitcnt lgkmcnt(0)
	v_lshlrev_b32_e32 v68, 16, v68
	v_fmac_f32_e32 v68, v67, v69
	ds_read_b32 v67, v126 offset:33792
	ds_read_u16 v69, v146 offset:38144
	s_waitcnt lgkmcnt(1)
	v_mul_f32_e32 v66, v66, v67
	s_waitcnt lgkmcnt(0)
	v_lshlrev_b32_e32 v69, 16, v69
	v_fmac_f32_e32 v69, v67, v68
	ds_read_b32 v67, v127 offset:33792
	ds_read_u16 v68, v147 offset:38144
	s_waitcnt lgkmcnt(1)
	v_mul_f32_e32 v66, v66, v67
	s_waitcnt lgkmcnt(0)
	v_lshlrev_b32_e32 v68, 16, v68
	v_fmac_f32_e32 v68, v67, v69
	ds_read_b32 v67, v128 offset:33792
	ds_read_u16 v69, v148 offset:38144
	s_waitcnt lgkmcnt(1)
	v_mul_f32_e32 v66, v66, v67
	s_waitcnt lgkmcnt(0)
	v_lshlrev_b32_e32 v69, 16, v69
	v_fmac_f32_e32 v69, v67, v68
	ds_read_b32 v67, v129 offset:33792
	ds_read_u16 v68, v149 offset:38144
	s_waitcnt lgkmcnt(1)
	v_mul_f32_e32 v66, v66, v67
	s_waitcnt lgkmcnt(0)
	v_lshlrev_b32_e32 v68, 16, v68
	v_fmac_f32_e32 v68, v67, v69
	ds_read_b32 v67, v130 offset:33792
	ds_read_u16 v69, v150 offset:38144
	s_waitcnt lgkmcnt(1)
	v_mul_f32_e32 v66, v66, v67
	s_waitcnt lgkmcnt(0)
	v_lshlrev_b32_e32 v69, 16, v69
	v_fmac_f32_e32 v69, v67, v68
	ds_read_b32 v67, v131 offset:33792
	ds_read_u16 v68, v151 offset:38144
	s_waitcnt lgkmcnt(1)
	v_mul_f32_e32 v66, v66, v67
	s_waitcnt lgkmcnt(0)
	v_lshlrev_b32_e32 v68, 16, v68
	v_fmac_f32_e32 v68, v67, v69
	ds_read_b32 v67, v132 offset:33792
	ds_read_u16 v69, v152 offset:38144
	s_waitcnt lgkmcnt(1)
	v_mul_f32_e32 v66, v66, v67
	s_waitcnt lgkmcnt(0)
	v_lshlrev_b32_e32 v69, 16, v69
	v_fmac_f32_e32 v69, v67, v68
	ds_read_b32 v67, v133 offset:33792
	ds_read_u16 v68, v153 offset:38144
	s_waitcnt lgkmcnt(1)
	v_mul_f32_e32 v66, v66, v67
	s_waitcnt lgkmcnt(0)
	v_lshlrev_b32_e32 v68, 16, v68
	v_fmac_f32_e32 v68, v67, v69
	ds_read_b32 v67, v134 offset:33792
	ds_read_u16 v69, v154 offset:38144
	s_waitcnt lgkmcnt(0)
	s_waitcnt lgkmcnt(1)
	v_mul_f32_e32 v167, v66, v67
	s_waitcnt lgkmcnt(0)
	v_lshlrev_b32_e32 v166, 16, v69
	v_fmac_f32_e32 v166, v67, v68
	s_cbranch_scc1 .LBB0_466
	s_and_b32 s0, s17, 0xffffffc0
	s_add_i32 s0, s0, s14
	s_or_b32 s0, s0, s18
	s_ashr_i32 s1, s0, 31
	s_lshl_b64 s[0:1], s[0:1], 10
	v_lshl_or_b32 v0, v94, 2, s0
	v_readlane_b32 s0, v254, 27
	v_mov_b32_e32 v1, s1
	s_add_i32 s17, s17, s26
	s_add_i32 s16, s16, s26
	s_add_i32 s15, s15, s0
	v_lshl_add_u64 v[2:3], s[6:7], 0, v[0:1]
	v_lshl_add_u64 v[0:1], s[8:9], 0, v[0:1]
	s_cmpk_gt_i32 s17, 0x1ff
	global_store_dword v[2:3], v167, off
	global_store_dword v[0:1], v166, off
	s_barrier
	s_cbranch_scc0 .LBB0_435

; __device__ __forceinline__ float hgrn_lb(const Ctx& C, int l, int ch) {
;     if (l == 0) return 0.f;
;     const float a0 = C.P->in[3][ch], a1 = C.P->in[3][256 + ch];
;     return 1.0f / (1.0f + __expf(a0 - a1));
; }
.LBB0_470:
	s_lshl_b32 s0, s18, 1
	s_and_b32 s4, s0, 0xc0
	v_readlane_b32 s0, v255, 1
	v_readlane_b32 s1, v255, 2
	v_or_b32_e32 v2, s4, v64
	s_and_b64 vcc, exec, s[0:1]
	s_cbranch_vccz .LBB0_472
	v_readlane_b32 s68, v251, 4
	v_lshlrev_b32_e32 v0, 2, v2
	v_readlane_b32 s74, v251, 10
	v_readlane_b32 s75, v251, 11
	s_nop 4
	global_load_dword v1, v0, s[74:75]
	s_nop 0
	global_load_dword v0, v0, s[74:75] offset:1024
	v_readlane_b32 s69, v251, 5
	v_readlane_b32 s70, v251, 6
	v_readlane_b32 s71, v251, 7
	v_readlane_b32 s72, v251, 8
	v_readlane_b32 s73, v251, 9
	v_readlane_b32 s76, v251, 12
	v_readlane_b32 s77, v251, 13
	v_readlane_b32 s78, v251, 14
	v_readlane_b32 s79, v251, 15
	v_readlane_b32 s80, v251, 16
	v_readlane_b32 s81, v251, 17
	v_readlane_b32 s82, v251, 18
	v_readlane_b32 s83, v251, 19
	v_readlane_b32 s22, v253, 26
	s_waitcnt vmcnt(0)
	v_sub_f32_e32 v0, v1, v0
	v_mul_f32_e32 v0, 0x3fb8aa3b, v0
	v_exp_f32_e32 v0, v0
	s_nop 0
	v_add_f32_e32 v0, 1.0, v0
	v_rcp_f32_e32 v130, v0
	s_cbranch_execz .LBB0_473
	s_branch .LBB0_474

; __device__ __forceinline__ bf16_t f2bf(float f) { return (bf16_t)(cvt_pk_bf16(f, 0.f) & 0xffffu); }
; __device__ __forceinline__ float bf2f(bf16_t b) { return __uint_as_float(((unsigned)b) << 16); }
; __device__ __forceinline__ float sigmoidf_(float x) { return 1.0f / (1.0f + __expf(-x)); }
; template <int MODE>
; __device__ __forceinline__ void hgrn_mfma(const Ctx& C, int l, int z, int b, int hd, int c, f32x4 (&Sacc)[4][4], float& dectot, unsigned char* wl, float lb) {
;     ...
;             for (int t = 0; t < 16; ++t) { const bf16_t* row = row0 + rstep * t; fv[t] = row[fcol]; vv[t] = row[vcol]; if (MODE != 0) qv[t] = row[qcol]; }
; #pragma unroll
;             for (int t = 0; t < 16; ++t) {
;                 const float fl = bf2f(fv[t]);
;                 const float sg = sigmoidf_(fl);
;                 const float f = lb + (1.0f - lb) * sg, kk = (1.0f - lb) * (1.0f - sg);
;                 bacc += __logf(fmaxf(f, 1e-30f));
;                 Kb[(g8 * 16 + t) * HPT + lane] = f2bf(kk * __expf(fminf(-bacc, 80.f)));
;                 if (MODE != 0) Qt[(g8 * 16 + t) * HPT + lane] = f2bf(bf2f(qv[t]) * __expf(fmaxf(bacc, -80.f)));
;                 Vv[(g8 * 16 + t) * HPT + lane] = vv[t];
.LBB0_476:
	s_lshl_b32 s0, s70, 4
	s_or_b32 s6, s0, s67
	v_cndmask_b32_e64 v67, 0, 1, s[44:45]
	s_mul_i32 s1, s70, 0x480
	s_sub_i32 s7, 0xfff, s6
	v_cmp_ne_u32_e64 s[4:5], 1, v67
	v_or_b32_e32 v67, s1, v64
	s_and_b64 s[0:1], s[38:39], exec
	s_cselect_b32 s0, s6, s7
	s_add_i32 s0, s0, s68
	s_mul_i32 s36, s0, 0x500
	s_lshl_b64 s[0:1], s[36:37], 1
	s_add_u32 s0, s47, s0
	s_addc_u32 s1, s48, s1
	global_load_ushort v68, v132, s[0:1]
	global_load_ushort v69, v133, s[0:1] offset:1536
	s_add_u32 s0, s0, s42
	s_addc_u32 s1, s1, s43
	global_load_ushort v70, v132, s[0:1]
	global_load_ushort v71, v133, s[0:1] offset:1536
	s_add_u32 s0, s0, s42
	s_addc_u32 s1, s1, s43
	global_load_ushort v72, v132, s[0:1]
	global_load_ushort v73, v133, s[0:1] offset:1536
	s_add_u32 s0, s0, s42
	s_addc_u32 s1, s1, s43
	global_load_ushort v74, v132, s[0:1]
	global_load_ushort v75, v133, s[0:1] offset:1536
	s_add_u32 s0, s0, s42
	s_addc_u32 s1, s1, s43
	global_load_ushort v76, v132, s[0:1]
	global_load_ushort v77, v133, s[0:1] offset:1536
	s_add_u32 s0, s0, s42
	s_addc_u32 s1, s1, s43
	global_load_ushort v78, v132, s[0:1]
	global_load_ushort v79, v133, s[0:1] offset:1536
	s_add_u32 s0, s0, s42
	s_addc_u32 s1, s1, s43
	s_add_u32 s6, s0, s42
	s_addc_u32 s7, s1, s43
	global_load_ushort v80, v133, s[0:1] offset:1536
	global_load_ushort v81, v132, s[0:1]
	global_load_ushort v134, v133, s[6:7] offset:1536
	global_load_ushort v135, v132, s[6:7]
	s_add_u32 s0, s6, s42
	s_addc_u32 s1, s7, s43
	s_add_u32 s6, s0, s42
	global_load_ushort v136, v133, s[0:1] offset:1536
	global_load_ushort v137, v132, s[0:1]
	s_addc_u32 s7, s1, s43
	global_load_ushort v138, v133, s[6:7] offset:1536
	global_load_ushort v139, v132, s[6:7]
	s_add_u32 s0, s6, s42
	s_addc_u32 s1, s7, s43
	global_load_ushort v140, v133, s[0:1] offset:1536
	global_load_ushort v141, v132, s[0:1]
	s_add_u32 s6, s0, s42
	s_addc_u32 s7, s1, s43
	s_add_u32 s0, s6, s42
	global_load_ushort v142, v133, s[6:7] offset:1536
	global_load_ushort v143, v132, s[6:7]
	s_addc_u32 s1, s7, s43
	global_load_ushort v144, v133, s[0:1] offset:1536
	global_load_ushort v145, v132, s[0:1]
	s_add_u32 s6, s0, s42
	s_addc_u32 s7, s1, s43
	global_load_ushort v146, v133, s[6:7] offset:1536
	global_load_ushort v147, v132, s[6:7]
	s_add_u32 s0, s6, s42
	s_addc_u32 s1, s7, s43
	global_load_ushort v148, v133, s[0:1] offset:1536
	global_load_ushort v149, v132, s[0:1]
	s_add_u32 s6, s0, s42
	s_addc_u32 s7, s1, s43
	global_load_ushort v150, v133, s[6:7] offset:1536
	global_load_ushort v151, v132, s[6:7]
	v_lshl_add_u32 v67, v67, 1, s46
	s_mov_b64 s[44:45], 0
	s_mov_b32 s70, 1
	s_waitcnt vmcnt(31)
	v_lshlrev_b32_e32 v68, 16, v68
	v_mul_f32_e32 v68, 0xbfb8aa3b, v68
	v_exp_f32_e32 v68, v68
	s_waitcnt vmcnt(30)
	ds_write_b16 v67, v69 offset:9216
	s_waitcnt vmcnt(29)
	v_lshlrev_b32_e32 v69, 16, v70
	v_mul_f32_e32 v69, 0xbfb8aa3b, v69
	v_exp_f32_e32 v69, v69
	s_waitcnt vmcnt(27)
	v_lshlrev_b32_e32 v70, 16, v72
	v_mul_f32_e32 v70, 0xbfb8aa3b, v70
	v_add_f32_e32 v68, 1.0, v68
	ds_write_b16 v67, v71 offset:9360
	v_exp_f32_e32 v70, v70
	s_waitcnt vmcnt(25)
	v_lshlrev_b32_e32 v71, 16, v74
	v_mul_f32_e32 v71, 0xbfb8aa3b, v71
	v_add_f32_e32 v69, 1.0, v69
	v_exp_f32_e32 v71, v71
	s_waitcnt vmcnt(24)
	ds_write_b16 v67, v75 offset:9648
	s_waitcnt vmcnt(23)
	v_lshlrev_b32_e32 v75, 16, v76
	v_mul_f32_e32 v75, 0xbfb8aa3b, v75
	v_add_f32_e32 v70, 1.0, v70
	s_waitcnt vmcnt(21)
	v_lshlrev_b32_e32 v78, 16, v78
	v_exp_f32_e32 v75, v75
	s_waitcnt vmcnt(20)
	ds_write_b16 v67, v79 offset:9936
	v_mul_f32_e32 v78, 0xbfb8aa3b, v78
	ds_write_b16 v67, v73 offset:9504
	v_add_f32_e32 v71, 1.0, v71
	v_exp_f32_e32 v78, v78
	s_waitcnt vmcnt(19)
	ds_write_b16 v67, v80 offset:10080
	s_waitcnt vmcnt(16)
	v_lshlrev_b32_e32 v135, 16, v135
	ds_write_b16 v67, v134 offset:10224
	v_mul_f32_e32 v135, 0xbfb8aa3b, v135
	ds_write_b16 v67, v77 offset:9792
	v_lshlrev_b32_e32 v81, 16, v81
	v_add_f32_e32 v75, 1.0, v75
	v_exp_f32_e32 v135, v135
	v_mul_f32_e32 v81, 0xbfb8aa3b, v81
	v_add_f32_e32 v78, 1.0, v78
	s_waitcnt vmcnt(14)
	v_lshlrev_b32_e32 v137, 16, v137
	v_exp_f32_e32 v81, v81
	ds_write_b16 v67, v136 offset:10368
	v_mul_f32_e32 v137, 0xbfb8aa3b, v137
	v_exp_f32_e32 v137, v137
	s_waitcnt vmcnt(12)
	v_lshlrev_b32_e32 v139, 16, v139
	v_rcp_f32_e32 v68, v68
	v_mul_f32_e32 v74, 0xbfb8aa3b, v139
	v_fma_f32 v139, v131, v68, v130
	v_sub_f32_e32 v68, 1.0, v68
	v_add_f32_e32 v135, 1.0, v135
	v_mul_f32_e32 v76, v131, v68
	v_max_f32_e32 v68, 0xda24260, v139
	v_add_f32_e32 v81, 1.0, v81
	v_exp_f32_e32 v163, v74
	s_waitcnt vmcnt(10)
	v_lshlrev_b32_e32 v74, 16, v141
	v_rcp_f32_e32 v69, v69
	v_cmp_gt_f32_e64 s[0:1], s54, v68
	v_mul_f32_e32 v74, 0xbfb8aa3b, v74
	s_nop 0
	v_cndmask_b32_e64 v141, 0, 32, s[0:1]
	v_fma_f32 v152, v131, v69, v130
	v_sub_f32_e32 v69, 1.0, v69
	v_add_f32_e32 v137, 1.0, v137
	v_exp_f32_e32 v155, v74
	v_ldexp_f32 v68, v68, v141
	v_cndmask_b32_e64 v141, 0, v225, s[0:1]
	v_mul_f32_e32 v74, v131, v69
	v_max_f32_e32 v69, 0xda24260, v152
	v_rcp_f32_e32 v70, v70
	v_cmp_gt_f32_e64 s[0:1], s54, v69
	s_waitcnt vmcnt(8)
	v_lshlrev_b32_e32 v143, 16, v143
	v_log_f32_e32 v152, v68
	v_cndmask_b32_e64 v68, 0, 32, s[0:1]
	v_fma_f32 v154, v131, v70, v130
	v_add_f32_e32 v163, 1.0, v163
	v_mul_f32_e32 v143, 0xbfb8aa3b, v143
	v_sub_f32_e32 v70, 1.0, v70
	s_waitcnt vmcnt(7)
	ds_write_b16 v67, v144 offset:10944
	v_ldexp_f32 v68, v69, v68
	v_cndmask_b32_e64 v144, 0, v225, s[0:1]
	v_max_f32_e32 v69, 0xda24260, v154
	v_exp_f32_e32 v143, v143
	v_mul_f32_e32 v72, v131, v70
	v_rcp_f32_e32 v70, v71
	v_cmp_gt_f32_e64 s[0:1], s54, v69
	ds_write_b16 v67, v138 offset:10512
	s_waitcnt vmcnt(6)
; __device__ __forceinline__ bf16_t f2bf(float f) { return (bf16_t)(cvt_pk_bf16(f, 0.f) & 0xffffu); }
; __device__ __forceinline__ float bf2f(bf16_t b) { return __uint_as_float(((unsigned)b) << 16); }
; __device__ __forceinline__ float sigmoidf_(float x) { return 1.0f / (1.0f + __expf(-x)); }
; template <int MODE>
; __device__ __forceinline__ void hgrn_mfma(const Ctx& C, int l, int z, int b, int hd, int c, f32x4 (&Sacc)[4][4], float& dectot, unsigned char* wl, float lb) {
;     ...
;             for (int t = 0; t < 16; ++t) {
;                 const float fl = bf2f(fv[t]);
;                 const float sg = sigmoidf_(fl);
;                 const float f = lb + (1.0f - lb) * sg, kk = (1.0f - lb) * (1.0f - sg);
;                 bacc += __logf(fmaxf(f, 1e-30f));
;                 Kb[(g8 * 16 + t) * HPT + lane] = f2bf(kk * __expf(fminf(-bacc, 80.f)));
;                 if (MODE != 0) Qt[(g8 * 16 + t) * HPT + lane] = f2bf(bf2f(qv[t]) * __expf(fmaxf(bacc, -80.f)));
	v_lshlrev_b32_e32 v145, 16, v145
	v_log_f32_e32 v158, v68
	v_cndmask_b32_e64 v68, 0, 32, s[0:1]
	v_fma_f32 v159, v131, v70, v130
	v_sub_f32_e32 v70, 1.0, v70
	v_add_f32_e32 v155, 1.0, v155
	v_mul_f32_e32 v145, 0xbfb8aa3b, v145
	s_waitcnt vmcnt(5)
	ds_write_b16 v67, v146 offset:11088
	v_ldexp_f32 v68, v69, v68
	v_cndmask_b32_e64 v146, 0, v225, s[0:1]
	v_mul_f32_e32 v71, v131, v70
	v_max_f32_e32 v69, 0xda24260, v159
	v_rcp_f32_e32 v70, v75
	v_exp_f32_e32 v145, v145
	s_waitcnt vmcnt(4)
	v_lshlrev_b32_e32 v147, 16, v147
	v_cmp_gt_f32_e64 s[0:1], s54, v69
	ds_write_b16 v67, v140 offset:10656
	v_mul_f32_e32 v147, 0xbfb8aa3b, v147
	v_mul_f32_e32 v160, 0x3f317217, v152
	v_log_f32_e32 v161, v68
	v_cndmask_b32_e64 v68, 0, 32, s[0:1]
	v_fma_f32 v166, v131, v70, v130
	v_sub_f32_e32 v70, 1.0, v70
	v_add_f32_e32 v143, 1.0, v143
	v_exp_f32_e32 v147, v147
	s_waitcnt vmcnt(3)
	ds_write_b16 v67, v148 offset:11232
	v_fma_f32 v148, v152, s56, -v160
	v_ldexp_f32 v68, v69, v68
	v_cndmask_b32_e64 v160, 0, v225, s[0:1]
	v_mul_f32_e32 v69, v131, v70
	v_max_f32_e32 v70, 0xda24260, v166
	ds_write_b16 v67, v142 offset:10800
	s_waitcnt vmcnt(2)
	v_lshlrev_b32_e32 v149, 16, v149
	v_rcp_f32_e32 v73, v78
	v_cmp_gt_f32_e64 s[0:1], s54, v70
	v_mul_f32_e32 v80, 0xbfb8aa3b, v149
	v_fmac_f32_e32 v148, 0x3377d1cf, v152
	v_mul_f32_e32 v149, 0x3f317217, v158
	v_log_f32_e32 v167, v68
	v_cndmask_b32_e64 v68, 0, 32, s[0:1]
	v_fma_f32 v168, v131, v73, v130
	v_sub_f32_e32 v73, 1.0, v73
	v_add_f32_e32 v78, 1.0, v145
	v_exp_f32_e32 v80, v80
	s_waitcnt vmcnt(1)
	ds_write_b16 v67, v150 offset:11376
	v_fmac_f32_e32 v148, 0x3f317217, v152
	v_fma_f32 v149, v158, s56, -v149
	v_ldexp_f32 v70, v70, v68
	v_cndmask_b32_e64 v150, 0, v225, s[0:1]
	v_mul_f32_e32 v68, v131, v73
	v_max_f32_e32 v73, 0xda24260, v168
	v_rcp_f32_e32 v77, v81
	v_cmp_lt_f32_e64 vcc, |v152|, s57
	s_waitcnt vmcnt(0)
	v_lshlrev_b32_e32 v145, 16, v151
	v_cndmask_b32_e32 v148, v152, v148, vcc
	v_fmac_f32_e32 v149, 0x3377d1cf, v158
	v_mul_f32_e32 v152, 0x3f317217, v161
	v_cmp_gt_f32_e64 s[0:1], s54, v73
	v_fma_f32 v168, v131, v77, v130
	v_sub_f32_e32 v170, 1.0, v77
	v_add_f32_e32 v77, 1.0, v147
	v_mul_f32_e32 v145, 0xbfb8aa3b, v145
	v_log_f32_e32 v162, v70
	v_cndmask_b32_e64 v70, 0, 32, s[0:1]
	v_sub_f32_e32 v141, v148, v141
	v_fmac_f32_e32 v149, 0x3f317217, v158
	v_cmp_lt_f32_e64 vcc, |v158|, s57
	v_fma_f32 v147, v161, s56, -v152
	v_cndmask_b32_e64 v148, 0, v225, s[0:1]
	v_max_f32_e32 v152, 0xda24260, v168
	v_exp_f32_e32 v145, v145
	v_ldexp_f32 v73, v73, v70
	v_rcp_f32_e32 v75, v135
	v_add_f32_e32 v141, v66, v141
	v_cndmask_b32_e32 v66, v158, v149, vcc
	v_cmp_gt_f32_e64 s[0:1], s54, v152
	v_log_f32_e32 v158, v73
	s_nop 0
	v_cndmask_b32_e64 v73, 0, 32, s[0:1]
	v_fma_f32 v168, v131, v75, v130
	v_sub_f32_e32 v75, 1.0, v75
	v_add_f32_e32 v79, 1.0, v80
	v_fmac_f32_e32 v147, 0x3377d1cf, v161
	v_mul_f32_e32 v149, 0x3f317217, v167
	v_sub_f32_e32 v144, v66, v144
	v_ldexp_f32 v73, v152, v73
	v_cndmask_b32_e64 v152, 0, v225, s[0:1]
	v_mul_f32_e32 v66, v131, v75
	v_max_f32_e32 v75, 0xda24260, v168
	v_rcp_f32_e32 v134, v137
	v_min_f32_e64 v80, -v141, s60
	v_fmac_f32_e32 v147, 0x3f317217, v161
	v_cmp_lt_f32_e64 vcc, |v161|, s57
	v_fma_f32 v149, v167, s56, -v149
	v_cmp_gt_f32_e64 s[0:1], s54, v75
	v_mul_f32_e32 v70, v131, v170
	v_mul_f32_e32 v168, 0x3fb8aa3b, v80
	v_add_f32_e32 v141, v141, v144
	v_cndmask_b32_e32 v144, v161, v147, vcc
	v_fmac_f32_e32 v149, 0x3377d1cf, v167
	v_mul_f32_e32 v147, 0x3f317217, v162
	v_log_f32_e32 v161, v73
	v_cndmask_b32_e64 v73, 0, 32, s[0:1]
	v_fma_f32 v171, v131, v134, v130
	v_sub_f32_e32 v134, 1.0, v134
	v_add_f32_e32 v80, 1.0, v145
	v_sub_f32_e32 v144, v144, v146
	v_fmac_f32_e32 v149, 0x3f317217, v167
	v_cmp_lt_f32_e64 vcc, |v167|, s57
	v_fma_f32 v146, v162, s56, -v147
	v_ldexp_f32 v75, v75, v73
	v_cndmask_b32_e64 v147, 0, v225, s[0:1]
	v_mul_f32_e32 v73, v131, v134
	v_max_f32_e32 v134, 0xda24260, v171
	v_exp_f32_e32 v145, v168
	v_min_f32_e64 v168, -v141, s60
	v_rcp_f32_e32 v81, v163
	v_add_f32_e32 v141, v141, v144
	v_cndmask_b32_e32 v144, v167, v149, vcc
	v_fmac_f32_e32 v146, 0x3377d1cf, v162
	v_cmp_gt_f32_e64 s[0:1], s54, v134
	v_mul_f32_e32 v168, 0x3fb8aa3b, v168
	v_mul_f32_e32 v149, 0x3f317217, v158
	v_log_f32_e32 v167, v75
	v_cndmask_b32_e64 v75, 0, 32, s[0:1]
	v_fma_f32 v171, v131, v81, v130
	v_sub_f32_e32 v81, 1.0, v81
	v_sub_f32_e32 v144, v144, v160
	v_fmac_f32_e32 v146, 0x3f317217, v162
	v_cmp_lt_f32_e64 vcc, |v162|, s57
	v_exp_f32_e32 v168, v168
	v_min_f32_e64 v172, -v141, s60
	v_fma_f32 v149, v158, s56, -v149
	v_ldexp_f32 v134, v134, v75
	v_mul_f32_e32 v75, v131, v81
	v_max_f32_e32 v81, 0xda24260, v171
	v_add_f32_e32 v141, v141, v144
	v_cndmask_b32_e32 v144, v162, v146, vcc
	v_cndmask_b32_e64 v160, 0, v225, s[0:1]
	v_rcp_f32_e32 v135, v155
	v_fmac_f32_e32 v149, 0x3377d1cf, v158
	v_mul_f32_e32 v146, 0x3f317217, v161
	v_cmp_gt_f32_e64 s[0:1], s54, v81
	v_mul_f32_e32 v156, 0x3fb8aa3b, v172
	v_log_f32_e32 v134, v134
	v_cndmask_b32_e64 v162, 0, 32, s[0:1]
	v_fma_f32 v166, v131, v135, v130
	v_sub_f32_e32 v135, 1.0, v135
	v_mul_f32_e32 v145, v76, v145
	v_sub_f32_e32 v144, v144, v150
	v_fmac_f32_e32 v149, 0x3f317217, v158
	v_cmp_lt_f32_e64 vcc, |v158|, s57
	v_fma_f32 v146, v161, s56, -v146
	v_rcp_f32_e32 v137, v143
	v_exp_f32_e32 v156, v156
	v_min_f32_e64 v169, -v141, s60
	v_ldexp_f32 v81, v81, v162
	v_mul_f32_e32 v76, v131, v135
	v_max_f32_e32 v135, 0xda24260, v166
	v_cvt_pk_bf16_f32 v145, v145, s0
	v_add_f32_e32 v141, v141, v144
	v_cndmask_b32_e32 v144, v158, v149, vcc
	v_fmac_f32_e32 v146, 0x3377d1cf, v161
	v_fma_f32 v158, v131, v137, v130
	v_sub_f32_e32 v137, 1.0, v137
	v_cndmask_b32_e64 v150, 0, v225, s[0:1]
; __device__ __forceinline__ bf16_t f2bf(float f) { return (bf16_t)(cvt_pk_bf16(f, 0.f) & 0xffffu); }
; __device__ __forceinline__ float bf2f(bf16_t b) { return __uint_as_float(((unsigned)b) << 16); }
; __device__ __forceinline__ float sigmoidf_(float x) { return 1.0f / (1.0f + __expf(-x)); }
; template <int MODE>
; __device__ __forceinline__ void hgrn_mfma(const Ctx& C, int l, int z, int b, int hd, int c, f32x4 (&Sacc)[4][4], float& dectot, unsigned char* wl, float lb) {
;     ...
;             for (int t = 0; t < 16; ++t) {
;                 const float fl = bf2f(fv[t]);
;                 const float sg = sigmoidf_(fl);
;                 const float f = lb + (1.0f - lb) * sg, kk = (1.0f - lb) * (1.0f - sg);
;                 bacc += __logf(fmaxf(f, 1e-30f));
;                 Kb[(g8 * 16 + t) * HPT + lane] = f2bf(kk * __expf(fminf(-bacc, 80.f)));
;                 if (MODE != 0) Qt[(g8 * 16 + t) * HPT + lane] = f2bf(bf2f(qv[t]) * __expf(fmaxf(bacc, -80.f)));
	v_mul_f32_e32 v151, 0x3fb8aa3b, v169
	v_mul_f32_e32 v149, 0x3f317217, v167
	v_log_f32_e32 v81, v81
	v_cmp_gt_f32_e64 s[0:1], s54, v135
	ds_write_b16 v67, v145 offset:4608
	v_mul_f32_e32 v145, v74, v168
	v_sub_f32_e32 v144, v144, v148
	v_fmac_f32_e32 v146, 0x3f317217, v161
	v_cmp_lt_f32_e64 vcc, |v161|, s57
	v_mul_f32_e32 v74, v131, v137
	v_max_f32_e32 v137, 0xda24260, v158
	v_cndmask_b32_e64 v155, 0, 32, s[0:1]
	v_exp_f32_e32 v151, v151
	v_min_f32_e64 v153, -v141, s60
	v_fma_f32 v148, v167, s56, -v149
	v_cndmask_b32_e64 v149, 0, v225, s[0:1]
	v_rcp_f32_e32 v78, v78
	v_cvt_pk_bf16_f32 v142, v145, s0
	v_add_f32_e32 v141, v141, v144
	v_cndmask_b32_e32 v144, v161, v146, vcc
	v_cmp_gt_f32_e64 s[0:1], s54, v137
	v_mul_f32_e32 v143, 0x3fb8aa3b, v153
	v_fmac_f32_e32 v148, 0x3377d1cf, v167
	v_mul_f32_e32 v145, 0x3f317217, v134
	v_cndmask_b32_e64 v146, 0, 32, s[0:1]
	v_fma_f32 v153, v131, v78, v130
	v_ldexp_f32 v135, v135, v155
	ds_write_b16 v67, v142 offset:4752
	v_mul_f32_e32 v72, v72, v156
	v_exp_f32_e32 v139, v143
	v_min_f32_e64 v142, -v141, s60
	v_sub_f32_e32 v143, v144, v152
	v_fmac_f32_e32 v148, 0x3f317217, v167
	v_cmp_lt_f32_e64 vcc, |v167|, s57
	v_fma_f32 v144, v134, s56, -v145
	v_ldexp_f32 v137, v137, v146
	v_max_f32_e32 v146, 0xda24260, v153
	v_rcp_f32_e32 v77, v77
	v_log_f32_e32 v135, v135
	v_cndmask_b32_e64 v145, 0, v225, s[0:1]
	v_cvt_pk_bf16_f32 v72, v72, s0
	v_mul_f32_e32 v142, 0x3fb8aa3b, v142
	v_add_f32_e32 v141, v141, v143
	v_cndmask_b32_e32 v143, v167, v148, vcc
	v_fmac_f32_e32 v144, 0x3377d1cf, v134
	v_mul_f32_e32 v148, 0x3f317217, v81
	v_cmp_gt_f32_e64 s[0:1], s54, v146
	v_fma_f32 v155, v131, v77, v130
	s_nop 0
	v_cndmask_b32_e64 v153, 0, 32, s[0:1]
	ds_write_b16 v67, v72 offset:4896
	v_mul_f32_e32 v71, v71, v151
	v_exp_f32_e32 v72, v142
	v_sub_f32_e32 v142, v143, v147
	v_fmac_f32_e32 v144, 0x3f317217, v134
	v_cmp_lt_f32_e64 vcc, |v134|, s57
	v_fma_f32 v143, v81, s56, -v148
	v_max_f32_e32 v148, 0xda24260, v155
	v_log_f32_e32 v137, v137
	v_min_f32_e64 v140, -v141, s60
	v_ldexp_f32 v146, v146, v153
	v_cndmask_b32_e64 v147, 0, v225, s[0:1]
	v_rcp_f32_e32 v79, v79
	v_cvt_pk_bf16_f32 v71, v71, s0
	v_cndmask_b32_e32 v134, v134, v144, vcc
	v_cmp_gt_f32_e64 s[0:1], s54, v148
	v_mul_f32_e32 v140, 0x3fb8aa3b, v140
	v_fmac_f32_e32 v143, 0x3377d1cf, v81
	v_log_f32_e32 v144, v146
	v_cndmask_b32_e64 v146, 0, 32, s[0:1]
	v_fma_f32 v151, v131, v79, v130
	v_add_f32_e32 v141, v141, v142
	v_mul_f32_e32 v142, 0x3f317217, v135
	s_and_b64 vcc, exec, s[4:5]
	ds_write_b16 v67, v71 offset:5040
	v_mul_f32_e32 v69, v69, v139
	v_exp_f32_e32 v71, v140
	v_fmac_f32_e32 v143, 0x3f317217, v81
	v_cmp_lt_f32_e64 s[4:5], |v81|, s57
	v_ldexp_f32 v140, v148, v146
	v_max_f32_e32 v146, 0xda24260, v151
	v_rcp_f32_e32 v80, v80
	v_min_f32_e64 v138, -v141, s60
	v_sub_f32_e32 v134, v134, v160
	v_fma_f32 v139, v135, s56, -v142
	v_cndmask_b32_e64 v142, 0, v225, s[0:1]
	v_cvt_pk_bf16_f32 v69, v69, s0
	v_cndmask_b32_e64 v81, v81, v143, s[4:5]
	v_cmp_gt_f32_e64 s[0:1], s54, v146
	v_fma_f32 v143, v131, v80, v130
	v_mul_f32_e32 v136, 0x3fb8aa3b, v138
	v_add_f32_e32 v134, v141, v134
	v_fmac_f32_e32 v139, 0x3377d1cf, v135
	v_mul_f32_e32 v138, 0x3f317217, v137
	v_log_f32_e32 v140, v140
	v_cndmask_b32_e64 v141, 0, 32, s[0:1]
	v_mul_f32_e32 v68, v68, v72
	v_max_f32_e32 v143, 0xda24260, v143
	ds_write_b16 v67, v69 offset:5184
	v_exp_f32_e32 v69, v136
	v_min_f32_e64 v72, -v134, s60
	v_sub_f32_e32 v81, v81, v150
	v_fmac_f32_e32 v139, 0x3f317217, v135
	v_cmp_lt_f32_e64 s[4:5], |v135|, s57
	v_fma_f32 v136, v137, s56, -v138
	v_ldexp_f32 v138, v146, v141
	v_cndmask_b32_e64 v141, 0, v225, s[0:1]
	v_cvt_pk_bf16_f32 v68, v68, s0
	v_cmp_gt_f32_e64 s[0:1], s54, v143
	v_mul_f32_e32 v72, 0x3fb8aa3b, v72
	v_add_f32_e32 v81, v134, v81
	v_cndmask_b32_e64 v134, v135, v139, s[4:5]
	v_fmac_f32_e32 v136, 0x3377d1cf, v137
	v_mul_f32_e32 v135, 0x3f317217, v144
	v_log_f32_e32 v138, v138
	v_cndmask_b32_e64 v139, 0, 32, s[0:1]
	ds_write_b16 v67, v68 offset:5328
	v_mul_f32_e32 v68, v70, v71
	v_exp_f32_e32 v70, v72
	v_min_f32_e64 v71, -v81, s60
	v_sub_f32_e32 v72, v134, v149
	v_fmac_f32_e32 v136, 0x3f317217, v137
	v_cmp_lt_f32_e64 s[4:5], |v137|, s57
	v_fma_f32 v134, v144, s56, -v135
	v_ldexp_f32 v135, v143, v139
	v_cvt_pk_bf16_f32 v68, v68, s0
	v_mul_f32_e32 v71, 0x3fb8aa3b, v71
	v_add_f32_e32 v72, v81, v72
	v_cndmask_b32_e64 v81, v137, v136, s[4:5]
	v_fmac_f32_e32 v134, 0x3377d1cf, v144
	v_mul_f32_e32 v136, 0x3f317217, v140
	v_log_f32_e32 v135, v135
	v_cndmask_b32_e64 v139, 0, v225, s[0:1]
	ds_write_b16 v67, v68 offset:5472
	v_mul_f32_e32 v66, v66, v69
	v_exp_f32_e32 v68, v71
	v_min_f32_e64 v69, -v72, s60
	v_sub_f32_e32 v71, v81, v145
	v_fmac_f32_e32 v134, 0x3f317217, v144
	v_cmp_lt_f32_e64 s[0:1], |v144|, s57
	v_fma_f32 v81, v140, s56, -v136
	v_mul_f32_e32 v69, 0x3fb8aa3b, v69
	v_cvt_pk_bf16_f32 v66, v66, s0
	v_add_f32_e32 v71, v72, v71
	v_cndmask_b32_e64 v72, v144, v134, s[0:1]
	v_fmac_f32_e32 v81, 0x3377d1cf, v140
	v_mul_f32_e32 v134, 0x3f317217, v138
	ds_write_b16 v67, v66 offset:5616
	v_mul_f32_e32 v66, v73, v70
	v_exp_f32_e32 v69, v69
	v_min_f32_e64 v70, -v71, s60
	v_sub_f32_e32 v72, v72, v147
	v_fmac_f32_e32 v81, 0x3f317217, v140
	v_cmp_lt_f32_e64 s[0:1], |v140|, s57
	v_fma_f32 v73, v138, s56, -v134
	v_mul_f32_e32 v70, 0x3fb8aa3b, v70
	v_cvt_pk_bf16_f32 v66, v66, s0
	v_add_f32_e32 v71, v71, v72
	v_cndmask_b32_e64 v72, v140, v81, s[0:1]
	v_fmac_f32_e32 v73, 0x3377d1cf, v138
	v_mul_f32_e32 v81, 0x3f317217, v135
	ds_write_b16 v67, v66 offset:5760
	v_mul_f32_e32 v66, v75, v68
	v_exp_f32_e32 v68, v70
	v_min_f32_e64 v70, -v71, s60
	v_sub_f32_e32 v72, v72, v142
	v_fmac_f32_e32 v73, 0x3f317217, v138
; __device__ __forceinline__ bf16_t f2bf(float f) { return (bf16_t)(cvt_pk_bf16(f, 0.f) & 0xffffu); }
; __device__ __forceinline__ float bf2f(bf16_t b) { return __uint_as_float(((unsigned)b) << 16); }
; template <int MODE>
; __device__ __forceinline__ void hgrn_mfma(const Ctx& C, int l, int z, int b, int hd, int c, f32x4 (&Sacc)[4][4], float& dectot, unsigned char* wl, float lb) {
;     ...
;                 Kb[(g8 * 16 + t) * HPT + lane] = f2bf(kk * __expf(fminf(-bacc, 80.f)));
;                 if (MODE != 0) Qt[(g8 * 16 + t) * HPT + lane] = f2bf(bf2f(qv[t]) * __expf(fmaxf(bacc, -80.f)));
;                 Vv[(g8 * 16 + t) * HPT + lane] = vv[t];
;             }
;         }
;         { const float eb = __expf(bacc); dl[lane] = eb; dectot *= eb; }
;     ...
;         {
;             bf16x8 vB[4];
; #pragma unroll
;             for (int vt = 0; vt < 4; ++vt) { const bf16_t* vp = Vv + (8 * quad + (fr >> 2)) * HPT + 16 * vt + 4 * (fr & 3);
;                 union { bf16x8 v; s16x4 h[2]; } vb; vb.h[0] = lds_tr(vp); vb.h[1] = lds_tr(vp + 4 * HPT); vB[vt] = vb.v; }
; #pragma unroll
;             for (int kt = 0; kt < 4; ++kt) { const bf16_t* kp = Kb + (8 * quad + (fr >> 2)) * HPT + 16 * kt + 4 * (fr & 3);
;                 union { bf16x8 v; s16x4 h[2]; } ka; ka.h[0] = lds_tr(kp); ka.h[1] = lds_tr(kp + 4 * HPT);
;                 const f32x4 d4 = *(const f32x4*)(dl + 16 * kt + 4 * quad);
; #pragma unroll
;                 for (int vt = 0; vt < 4; ++vt) { Sacc[kt][vt] = __builtin_amdgcn_mfma_f32_16x16x32_bf16(ka.v, vB[vt], Sacc[kt][vt], 0, 0, 0); Sacc[kt][vt] *= d4; } }
;         }
	v_cmp_lt_f32_e64 s[0:1], |v138|, s57
	v_fma_f32 v75, v135, s56, -v81
	v_mul_f32_e32 v70, 0x3fb8aa3b, v70
	v_cvt_pk_bf16_f32 v66, v66, s0
	v_add_f32_e32 v71, v71, v72
	v_cndmask_b32_e64 v72, v138, v73, s[0:1]
	v_fmac_f32_e32 v75, 0x3377d1cf, v135
	ds_write_b16 v67, v66 offset:5904
	v_mul_f32_e32 v66, v76, v69
	v_exp_f32_e32 v69, v70
	v_min_f32_e64 v70, -v71, s60
	v_sub_f32_e32 v72, v72, v141
	v_fmac_f32_e32 v75, 0x3f317217, v135
	v_cmp_lt_f32_e64 s[0:1], |v135|, s57
	v_mul_f32_e32 v70, 0x3fb8aa3b, v70
	v_add_f32_e32 v71, v71, v72
	v_cvt_pk_bf16_f32 v66, v66, s0
	v_cndmask_b32_e64 v72, v135, v75, s[0:1]
	v_sub_f32_e32 v78, 1.0, v78
	ds_write_b16 v67, v66 offset:6048
	v_mul_f32_e32 v66, v74, v68
	v_exp_f32_e32 v68, v70
	v_min_f32_e64 v70, -v71, s60
	v_sub_f32_e32 v72, v72, v139
	v_mul_f32_e32 v78, v131, v78
	v_cvt_pk_bf16_f32 v73, v66, s0
	v_mul_f32_e32 v70, 0x3fb8aa3b, v70
	v_add_f32_e32 v66, v71, v72
	v_sub_f32_e32 v77, 1.0, v77
	v_mul_f32_e32 v69, v78, v69
	v_exp_f32_e32 v70, v70
	v_min_f32_e64 v71, -v66, s60
	v_mul_f32_e32 v77, v131, v77
	v_cvt_pk_bf16_f32 v69, v69, s0
	v_mul_f32_e32 v71, 0x3fb8aa3b, v71
	v_sub_f32_e32 v79, 1.0, v79
	ds_write_b16 v67, v69 offset:6336
	v_mul_f32_e32 v68, v77, v68
	v_exp_f32_e32 v69, v71
	v_mul_f32_e32 v79, v131, v79
	v_cvt_pk_bf16_f32 v68, v68, s0
	v_sub_f32_e32 v80, 1.0, v80
	ds_write_b16 v67, v68 offset:6480
	v_mul_f32_e32 v68, v79, v70
	v_mul_f32_e32 v80, v131, v80
	v_cvt_pk_bf16_f32 v68, v68, s0
	ds_write_b16 v67, v68 offset:6624
	v_mul_f32_e32 v68, v80, v69
	v_cvt_pk_bf16_f32 v68, v68, s0
	ds_write_b16 v67, v73 offset:6192
	ds_write_b16 v67, v68 offset:6768
	s_cbranch_vccz .LBB0_476
	v_mul_f32_e32 v66, 0x3fb8aa3b, v66
	v_exp_f32_e32 v66, v66
	s_add_i32 s69, s69, 1
	s_cmp_eq_u32 s69, 4
	ds_write_b32 v82, v66 offset:13824
	v_mul_f32_e32 v129, v129, v66
	s_waitcnt lgkmcnt(0)
	ds_read_b64_tr_b16 v[78:79], v83 offset:9216
	ds_read_b64_tr_b16 v[80:81], v83 offset:9792
	ds_read_b64_tr_b16 v[74:75], v83 offset:9248
	ds_read_b64_tr_b16 v[76:77], v83 offset:9824
	ds_read_b64_tr_b16 v[70:71], v83 offset:9280
	ds_read_b64_tr_b16 v[72:73], v83 offset:9856
	ds_read_b64_tr_b16 v[66:67], v83 offset:9312
	ds_read_b64_tr_b16 v[68:69], v83 offset:9888
	ds_read_b64_tr_b16 v[136:137], v83 offset:5184
	ds_read_b64_tr_b16 v[134:135], v83 offset:4608
	ds_read_b64_tr_b16 v[138:139], v83 offset:4640
	ds_read_b128 v[140:143], v84 offset:13824
	s_waitcnt lgkmcnt(2)
	v_mfma_f32_16x16x32_bf16 v[60:63], v[134:137], v[78:81], v[60:63]
	v_mfma_f32_16x16x32_bf16 v[56:59], v[134:137], v[74:77], v[56:59]
	s_waitcnt lgkmcnt(0)
	s_nop 5
	v_pk_mul_f32 v[60:61], v[140:141], v[60:61]
	v_pk_mul_f32 v[62:63], v[142:143], v[62:63]
	v_mfma_f32_16x16x32_bf16 v[52:55], v[134:137], v[70:73], v[52:55]
	v_mfma_f32_16x16x32_bf16 v[48:51], v[134:137], v[66:69], v[48:51]
	v_mul_f32_e64 v56, v140, v56
	v_mul_f32_e64 v57, v141, v57
	s_nop 4
	v_pk_mul_f32 v[52:53], v[140:141], v[52:53]
	v_pk_mul_f32 v[58:59], v[142:143], v[58:59]
	v_pk_mul_f32 v[54:55], v[142:143], v[54:55]
	v_pk_mul_f32 v[48:49], v[140:141], v[48:49]
	ds_read_b64_tr_b16 v[140:141], v83 offset:5216
	ds_read_b128 v[134:137], v84 offset:13888
	s_waitcnt lgkmcnt(1)
	v_mfma_f32_16x16x32_bf16 v[44:47], v[138:141], v[78:81], v[44:47]
	v_mul_f32_e64 v50, v142, v50
	v_mul_f32_e64 v51, v143, v51
	v_mfma_f32_16x16x32_bf16 v[40:43], v[138:141], v[74:77], v[40:43]
	s_waitcnt lgkmcnt(0)
	s_nop 3
	v_pk_mul_f32 v[46:47], v[136:137], v[46:47]
	v_pk_mul_f32 v[44:45], v[134:135], v[44:45]
	v_mfma_f32_16x16x32_bf16 v[36:39], v[138:141], v[70:73], v[36:39]
	v_mfma_f32_16x16x32_bf16 v[32:35], v[138:141], v[66:69], v[32:35]
	v_mul_f32_e64 v42, v136, v42
	v_mul_f32_e64 v43, v137, v43
	v_pk_mul_f32 v[40:41], v[134:135], v[40:41]
	s_nop 3
	v_pk_mul_f32 v[38:39], v[136:137], v[38:39]
	v_pk_mul_f32 v[36:37], v[134:135], v[36:37]
	v_pk_mul_f32 v[34:35], v[136:137], v[34:35]
	v_pk_mul_f32 v[32:33], v[134:135], v[32:33]
	ds_read_b64_tr_b16 v[134:135], v83 offset:4672
	ds_read_b64_tr_b16 v[136:137], v83 offset:5248
	ds_read_b128 v[138:141], v84 offset:13952
	s_waitcnt lgkmcnt(1)
	v_mfma_f32_16x16x32_bf16 v[28:31], v[134:137], v[78:81], v[28:31]
	v_mfma_f32_16x16x32_bf16 v[24:27], v[134:137], v[74:77], v[24:27]
	s_waitcnt lgkmcnt(0)
	s_nop 5
	v_pk_mul_f32 v[30:31], v[140:141], v[30:31]
	v_pk_mul_f32 v[28:29], v[138:139], v[28:29]
	v_mfma_f32_16x16x32_bf16 v[20:23], v[134:137], v[70:73], v[20:23]
	v_mfma_f32_16x16x32_bf16 v[16:19], v[134:137], v[66:69], v[16:19]
	v_mul_f32_e64 v26, v140, v26
	v_mul_f32_e64 v27, v141, v27
	v_pk_mul_f32 v[24:25], v[138:139], v[24:25]
	s_nop 3
	v_pk_mul_f32 v[22:23], v[140:141], v[22:23]
	v_pk_mul_f32 v[20:21], v[138:139], v[20:21]
	v_pk_mul_f32 v[18:19], v[140:141], v[18:19]
	v_pk_mul_f32 v[16:17], v[138:139], v[16:17]
	ds_read_b64_tr_b16 v[134:135], v83 offset:4704
	ds_read_b64_tr_b16 v[136:137], v83 offset:5280
	ds_read_b128 v[138:141], v84 offset:14016
	s_waitcnt lgkmcnt(1)
	v_mfma_f32_16x16x32_bf16 v[8:11], v[134:137], v[78:81], v[8:11]
	s_waitcnt lgkmcnt(0)
	v_mfma_f32_16x16x32_bf16 v[12:15], v[134:137], v[74:77], v[12:15]
	s_waitcnt lgkmcnt(0)
	s_nop 5
	v_pk_mul_f32 v[10:11], v[140:141], v[10:11]
	v_pk_mul_f32 v[8:9], v[138:139], v[8:9]
	v_mfma_f32_16x16x32_bf16 v[4:7], v[134:137], v[70:73], v[4:7]
	v_mfma_f32_16x16x32_bf16 v[0:3], v[134:137], v[66:69], v[0:3]
	v_mul_f32_e64 v14, v140, v14
	v_mul_f32_e64 v15, v141, v15
	v_pk_mul_f32 v[12:13], v[138:139], v[12:13]
	s_nop 3
	v_pk_mul_f32 v[6:7], v[140:141], v[6:7]
	v_pk_mul_f32 v[4:5], v[138:139], v[4:5]
	v_pk_mul_f32 v[2:3], v[140:141], v[2:3]
	v_pk_mul_f32 v[0:1], v[138:139], v[0:1]
	s_cbranch_scc0 .LBB0_475
;     __device__ __forceinline__ float* fp(size_t off) const { return (float*)(ws + off); }
; __device__ __forceinline__ void hgrn_pass1_item(const Ctx& C, int l, int item) {
;     ...
;     float* sb = C.fp(OFF_S) + (size_t)item * 4096;
;     const int fr = C.lane & 15, quad = C.lane >> 4;
; #pragma unroll
;     for (int kt = 0; kt < 4; ++kt)
; #pragma unroll
;         for (int vt = 0; vt < 4; ++vt)
; #pragma unroll
;             for (int r = 0; r < 4; ++r) sb[(16 * kt + 4 * quad + r) * 64 + 16 * vt + fr] = Sacc[kt][vt][r];
;     C.fp(OFF_DEC)[item * 64 + C.lane] = dectot;
	s_ashr_i32 s19, s18, 31
	s_lshl_b64 s[0:1], s[18:19], 14
	s_add_u32 s0, s49, s0
	s_addc_u32 s1, s53, s1
	global_store_dword v85, v60, s[0:1]
	global_store_dword v85, v61, s[0:1] offset:256
	global_store_dword v85, v62, s[0:1] offset:512
	global_store_dword v86, v63, s[0:1]
	global_store_dword v85, v56, s[0:1] offset:64
	global_store_dword v87, v57, s[0:1] offset:256
	global_store_dword v87, v58, s[0:1] offset:512
	global_store_dword v86, v59, s[0:1] offset:64
	global_store_dword v85, v52, s[0:1] offset:128
	global_store_dword v88, v53, s[0:1] offset:256
	global_store_dword v88, v54, s[0:1] offset:512
	global_store_dword v86, v55, s[0:1] offset:128
	global_store_dword v85, v48, s[0:1] offset:192
	global_store_dword v89, v49, s[0:1] offset:256
	global_store_dword v89, v50, s[0:1] offset:512
	global_store_dword v86, v51, s[0:1] offset:192
	global_store_dword v90, v44, s[0:1]
	global_store_dword v91, v45, s[0:1]
	global_store_dword v92, v46, s[0:1]
	global_store_dword v93, v47, s[0:1]
	global_store_dword v94, v40, s[0:1]
	global_store_dword v95, v41, s[0:1]
	global_store_dword v96, v42, s[0:1]
	global_store_dword v93, v43, s[0:1] offset:64
	global_store_dword v97, v36, s[0:1]
	global_store_dword v98, v37, s[0:1]
	global_store_dword v99, v38, s[0:1]
	global_store_dword v93, v39, s[0:1] offset:128
	global_store_dword v100, v32, s[0:1]
	global_store_dword v101, v33, s[0:1]
	global_store_dword v102, v34, s[0:1]
	global_store_dword v93, v35, s[0:1] offset:192
	global_store_dword v103, v28, s[0:1]
	global_store_dword v104, v29, s[0:1]
	global_store_dword v105, v30, s[0:1]
	global_store_dword v106, v31, s[0:1]
	global_store_dword v107, v24, s[0:1]
	global_store_dword v108, v25, s[0:1]
	global_store_dword v109, v26, s[0:1]
	global_store_dword v106, v27, s[0:1] offset:64
	global_store_dword v110, v20, s[0:1]
	global_store_dword v111, v21, s[0:1]
	global_store_dword v112, v22, s[0:1]
	global_store_dword v106, v23, s[0:1] offset:128
	global_store_dword v113, v16, s[0:1]
	global_store_dword v114, v17, s[0:1]
	global_store_dword v115, v18, s[0:1]
	global_store_dword v106, v19, s[0:1] offset:192
	global_store_dword v116, v8, s[0:1]
	global_store_dword v117, v9, s[0:1]
	global_store_dword v118, v10, s[0:1]
	global_store_dword v119, v11, s[0:1]
	global_store_dword v120, v12, s[0:1]
	global_store_dword v121, v13, s[0:1]
	global_store_dword v122, v14, s[0:1]
	global_store_dword v119, v15, s[0:1] offset:64
	global_store_dword v123, v4, s[0:1]
	global_store_dword v124, v5, s[0:1]
	global_store_dword v125, v6, s[0:1]
	global_store_dword v119, v7, s[0:1] offset:128
	global_store_dword v126, v0, s[0:1]
	global_store_dword v127, v1, s[0:1]
	global_store_dword v128, v2, s[0:1]
	global_store_dword v119, v3, s[0:1] offset:192
	v_lshl_or_b32 v0, s18, 6, v64
	v_readlane_b32 s0, v254, 20
	v_ashrrev_i32_e32 v1, 31, v0
	s_add_i32 s18, s18, s0
	v_lshl_add_u64 v[0:1], v[0:1], 2, s[20:21]
	s_cmpk_gt_i32 s18, 0x7ff
	v_readlane_b32 s1, v254, 21
	global_store_dword v[0:1], v129, off
	s_cbranch_scc0 .LBB0_470

; __device__ __forceinline__ void hy_conv_item(const Ctx& C, int l, int c) {
;     ...
;     for (int k = 0; k < 8; ++k) { const int t = tid + NTHR * k; const f32x4* hr = (const f32x4*)(hdn + (size_t)t * 64);
;         float a0 = 0.f, a1 = 0.f, a2 = 0.f, a3 = 0.f;
; #pragma unroll 1
;         for (int j8 = 0; j8 < 16; j8 += 8) {
;         f32x4 hrow[8];
; #pragma unroll
;         for (int j4 = 0; j4 < 8; ++j4) hrow[j4] = hr[j8 + j4];
; #pragma unroll
;         for (int jj4 = 0; jj4 < 8; ++jj4) { const f32x4 hv = hrow[jj4]; const int j4 = j8 + jj4;
;             const f32x4 q0 = *(const f32x4*)(w3s + 4 * j4), q1 = *(const f32x4*)(w3s + 64 + 4 * j4), q2 = *(const f32x4*)(w3s + 128 + 4 * j4), q3 = *(const f32x4*)(w3s + 192 + 4 * j4);
;             a0 += hv.x * q0.x + hv.y * q0.y + hv.z * q0.z + hv.w * q0.w; a1 += hv.x * q1.x + hv.y * q1.y + hv.z * q1.z + hv.w * q1.w;
;             a2 += hv.x * q2.x + hv.y * q2.y + hv.z * q2.z + hv.w * q2.w; a3 += hv.x * q3.x + hv.y * q3.y + hv.z * q3.z + hv.w * q3.w; } }
.LBB0_613:
	v_cndmask_b32_e64 v0, 0, 1, s[0:1]
	v_lshl_add_u64 v[42:43], s[36:37], 4, v[10:11]
	v_cmp_ne_u32_e32 vcc, 1, v0
	global_load_dwordx4 v[18:21], v[42:43], off offset:48
	global_load_dwordx4 v[22:25], v[42:43], off offset:32
	global_load_dwordx4 v[26:29], v[42:43], off offset:16
	global_load_dwordx4 v[30:33], v[42:43], off
	global_load_dwordx4 v[0:3], v[42:43], off offset:112
	global_load_dwordx4 v[34:37], v[42:43], off offset:96
	global_load_dwordx4 v[38:41], v[42:43], off offset:80
	s_nop 0
	global_load_dwordx4 v[42:45], v[42:43], off offset:64
	s_lshl_b32 s0, s36, 4
	s_add_i32 s80, s61, s0
	s_add_i32 s79, s63, s0
	v_mov_b32_e32 v9, s80
	s_add_i32 s78, s64, s0
	ds_read_b128 v[46:49], v9
	v_mov_b32_e32 v9, s79
	s_add_i32 s77, s65, s0
	ds_read_b128 v[50:53], v9
	v_mov_b32_e32 v9, s78
	ds_read_b128 v[54:57], v9
	v_mov_b32_e32 v9, s77
	ds_read_b128 v[58:61], v9
	s_or_b32 s1, s0, 16
	s_add_i32 s76, s61, s1
	s_add_i32 s75, s63, s1
	s_waitcnt lgkmcnt(1)
	v_mov_b32_e32 v66, v54
	s_waitcnt lgkmcnt(0)
	v_mov_b32_e32 v67, v59
	v_mov_b32_e32 v9, s76
	s_add_i32 s74, s64, s1
	v_mov_b32_e32 v62, v46
	v_mov_b32_e32 v63, v51
	s_add_i32 s72, s65, s1
	s_or_b32 s1, s0, 32
	v_mov_b32_e32 v46, v47
	v_mov_b32_e32 v47, v50
	s_add_i32 s73, s61, s1
	v_mov_b32_e32 v50, v48
	v_mov_b32_e32 v51, v52
	s_add_i32 s71, s63, s1
	v_mov_b32_e32 v52, v49
	s_add_i32 s70, s64, s1
	s_add_i32 s68, s65, s1
	s_or_b32 s1, s0, 48
	s_add_i32 s69, s61, s1
	s_add_i32 s67, s63, s1
	s_add_i32 s53, s64, s1
	s_add_i32 s38, s65, s1
	s_or_b32 s1, s0, 64
	s_add_i32 s39, s61, s1
	s_add_i32 s21, s63, s1
	s_add_i32 s20, s64, s1
	s_add_i32 s18, s65, s1
	s_or_b32 s1, s0, 0x50
	s_add_i32 s19, s61, s1
	s_add_i32 s17, s63, s1
	s_add_i32 s16, s64, s1
	s_add_i32 s14, s65, s1
	s_or_b32 s1, s0, 0x60
	s_add_i32 s15, s61, s1
	s_add_i32 s13, s63, s1
	s_add_i32 s11, s64, s1
	s_add_i32 s9, s65, s1
	s_or_b32 s0, s0, 0x70
	s_add_i32 s10, s61, s0
	s_add_i32 s8, s63, s0
	s_add_i32 s1, s64, s0
	s_add_i32 s0, s65, s0
	s_mov_b32 s36, 8
	s_and_b64 vcc, exec, vcc
	s_waitcnt vmcnt(7)
	v_mov_b32_e32 v54, v21
	s_waitcnt vmcnt(4)
	v_pk_mul_f32 v[248:249], v[30:31], v[66:67]
	ds_read_b128 v[66:69], v9
	v_mov_b32_e32 v9, s75
	ds_read_b128 v[70:73], v9
	v_pk_mul_f32 v[62:63], v[30:31], v[62:63]
	v_mov_b32_e32 v9, s74
	ds_read_b128 v[74:77], v9
	v_mov_b32_e32 v9, s72
	v_pk_fma_f32 v[46:47], v[30:31], v[46:47], v[62:63] op_sel:[1,0,0] op_sel_hi:[0,1,1]
	ds_read_b128 v[78:81], v9
	v_mov_b32_e32 v9, s73
	v_pk_fma_f32 v[46:47], v[32:33], v[50:51], v[46:47] op_sel_hi:[0,1,1]
	v_mov_b32_e32 v48, v33
	ds_read_b128 v[82:85], v9
	v_mov_b32_e32 v9, s71
	v_pk_fma_f32 v[46:47], v[48:49], v[52:53], v[46:47] op_sel_hi:[0,1,1]
	ds_read_b128 v[110:113], v9
	v_pk_add_f32 v[14:15], v[14:15], v[46:47]
	s_waitcnt lgkmcnt(5)
	v_mov_b32_e32 v46, v67
	s_waitcnt lgkmcnt(4)
	v_mov_b32_e32 v67, v71
	v_mov_b32_e32 v9, s70
	v_mov_b32_e32 v47, v70
	v_pk_mul_f32 v[50:51], v[26:27], v[66:67]
	ds_read_b128 v[142:145], v9
	v_mov_b32_e32 v9, s68
	v_pk_fma_f32 v[46:47], v[26:27], v[46:47], v[50:51] op_sel:[1,0,0] op_sel_hi:[0,1,1]
	v_mov_b32_e32 v50, v68
	v_mov_b32_e32 v51, v72
	ds_read_b128 v[146:149], v9
	v_mov_b32_e32 v9, s69
	v_pk_fma_f32 v[46:47], v[28:29], v[50:51], v[46:47] op_sel_hi:[0,1,1]
	v_mov_b32_e32 v50, v29
	v_mov_b32_e32 v72, v69
	ds_read_b128 v[150:153], v9
	v_mov_b32_e32 v9, s67
	v_pk_fma_f32 v[46:47], v[50:51], v[72:73], v[46:47] op_sel_hi:[0,1,1]
	ds_read_b128 v[154:157], v9
	v_pk_add_f32 v[14:15], v[14:15], v[46:47]
	s_waitcnt lgkmcnt(5)
	v_mov_b32_e32 v46, v83
	s_waitcnt lgkmcnt(4)
	v_mov_b32_e32 v83, v111
	v_mov_b32_e32 v9, s53
	v_mov_b32_e32 v47, v110
	v_pk_mul_f32 v[52:53], v[22:23], v[82:83]
	ds_read_b128 v[158:161], v9
	v_mov_b32_e32 v9, s38
	v_pk_fma_f32 v[46:47], v[22:23], v[46:47], v[52:53] op_sel:[1,0,0] op_sel_hi:[0,1,1]
	v_mov_b32_e32 v52, v84
	v_mov_b32_e32 v53, v112
	ds_read_b128 v[162:165], v9
	v_mov_b32_e32 v9, s39
	v_pk_fma_f32 v[46:47], v[24:25], v[52:53], v[46:47] op_sel_hi:[0,1,1]
	v_mov_b32_e32 v52, v25
	v_mov_b32_e32 v112, v85
	ds_read_b128 v[166:169], v9
	v_mov_b32_e32 v9, s21
	v_pk_fma_f32 v[46:47], v[52:53], v[112:113], v[46:47] op_sel_hi:[0,1,1]
	ds_read_b128 v[170:173], v9
	v_pk_add_f32 v[14:15], v[14:15], v[46:47]
	s_waitcnt lgkmcnt(5)
	v_mov_b32_e32 v46, v151
	s_waitcnt lgkmcnt(4)
	v_mov_b32_e32 v151, v155
	v_mov_b32_e32 v9, s20
	v_mov_b32_e32 v47, v154
	v_pk_mul_f32 v[62:63], v[18:19], v[150:151]
	ds_read_b128 v[174:177], v9
	v_mov_b32_e32 v9, s18
	v_pk_fma_f32 v[46:47], v[18:19], v[46:47], v[62:63] op_sel:[1,0,0] op_sel_hi:[0,1,1]
	v_mov_b32_e32 v62, v152
	v_mov_b32_e32 v63, v156
	ds_read_b128 v[192:195], v9
	v_mov_b32_e32 v9, s19
	v_pk_fma_f32 v[46:47], v[20:21], v[62:63], v[46:47] op_sel_hi:[0,1,1]
	v_mov_b32_e32 v156, v153
	ds_read_b128 v[196:199], v9
	v_mov_b32_e32 v9, s17
	v_pk_fma_f32 v[46:47], v[54:55], v[156:157], v[46:47] op_sel_hi:[0,1,1]
	ds_read_b128 v[200:203], v9
	v_pk_add_f32 v[14:15], v[14:15], v[46:47]
	s_waitcnt lgkmcnt(5)
	v_mov_b32_e32 v46, v167
	s_waitcnt lgkmcnt(4)
	v_mov_b32_e32 v167, v171
	v_mov_b32_e32 v9, s16
	v_mov_b32_e32 v47, v170
	s_waitcnt vmcnt(0)
	v_pk_mul_f32 v[62:63], v[42:43], v[166:167]
	ds_read_b128 v[204:207], v9
	v_mov_b32_e32 v9, s14
	v_pk_fma_f32 v[46:47], v[42:43], v[46:47], v[62:63] op_sel:[1,0,0] op_sel_hi:[0,1,1]
	v_mov_b32_e32 v62, v168
	v_mov_b32_e32 v63, v172
	ds_read_b128 v[208:211], v9
	v_mov_b32_e32 v9, s15
	v_pk_fma_f32 v[46:47], v[44:45], v[62:63], v[46:47] op_sel_hi:[0,1,1]
	v_mov_b32_e32 v62, v45
	v_mov_b32_e32 v172, v169
	ds_read_b128 v[212:215], v9
	v_mov_b32_e32 v9, s13
	v_pk_fma_f32 v[46:47], v[62:63], v[172:173], v[46:47] op_sel_hi:[0,1,1]
	ds_read_b128 v[228:231], v9
	v_pk_add_f32 v[14:15], v[14:15], v[46:47]
	s_waitcnt lgkmcnt(5)
; __device__ __forceinline__ void hy_conv_item(const Ctx& C, int l, int c) {
;     ...
;         for (int j4 = 0; j4 < 8; ++j4) hrow[j4] = hr[j8 + j4];
; #pragma unroll
;         for (int jj4 = 0; jj4 < 8; ++jj4) { const f32x4 hv = hrow[jj4]; const int j4 = j8 + jj4;
;             const f32x4 q0 = *(const f32x4*)(w3s + 4 * j4), q1 = *(const f32x4*)(w3s + 64 + 4 * j4), q2 = *(const f32x4*)(w3s + 128 + 4 * j4), q3 = *(const f32x4*)(w3s + 192 + 4 * j4);
;             a0 += hv.x * q0.x + hv.y * q0.y + hv.z * q0.z + hv.w * q0.w; a1 += hv.x * q1.x + hv.y * q1.y + hv.z * q1.z + hv.w * q1.w;
;             a2 += hv.x * q2.x + hv.y * q2.y + hv.z * q2.z + hv.w * q2.w; a3 += hv.x * q3.x + hv.y * q3.y + hv.z * q3.z + hv.w * q3.w; } }
;         const float dec = __expf(-((float)t / 4095.f) * adelta);
;         a0 *= dec; a1 *= dec; a2 *= dec; a3 *= dec;
;         hft[t] = a0; hft[4096 + t] = a1; hft[8192 + t] = a2; hft[12288 + t] = a3;
;         ss[0] += a0 * a0; ss[1] += a1 * a1; ss[2] += a2 * a2; ss[3] += a3 * a3; }
; #pragma unroll
;     for (int q = 0; q < 4; ++q) { const float s_ = wave_sum(ss[q]); if (lane == 0) red[w * 4 + q] = s_; }
	v_mov_b32_e32 v46, v197
	s_waitcnt lgkmcnt(4)
	v_mov_b32_e32 v197, v201
	v_mov_b32_e32 v9, s11
	v_mov_b32_e32 v47, v200
	v_pk_mul_f32 v[66:67], v[38:39], v[196:197]
	ds_read_b128 v[232:235], v9
	v_mov_b32_e32 v9, s9
	v_pk_fma_f32 v[46:47], v[38:39], v[46:47], v[66:67] op_sel:[1,0,0] op_sel_hi:[0,1,1]
	v_mov_b32_e32 v66, v198
	v_mov_b32_e32 v67, v202
	ds_read_b128 v[236:239], v9
	v_mov_b32_e32 v9, s10
	v_pk_fma_f32 v[46:47], v[40:41], v[66:67], v[46:47] op_sel_hi:[0,1,1]
	v_mov_b32_e32 v66, v41
	v_mov_b32_e32 v202, v199
	ds_read_b128 v[240:243], v9
	v_mov_b32_e32 v9, s8
	v_pk_fma_f32 v[46:47], v[66:67], v[202:203], v[46:47] op_sel_hi:[0,1,1]
	ds_read_b128 v[244:247], v9
	v_pk_add_f32 v[14:15], v[14:15], v[46:47]
	s_waitcnt lgkmcnt(5)
	v_mov_b32_e32 v46, v213
	s_waitcnt lgkmcnt(4)
	v_mov_b32_e32 v213, v229
	v_mov_b32_e32 v47, v228
	v_pk_mul_f32 v[68:69], v[34:35], v[212:213]
	v_mov_b32_e32 v9, s1
	v_pk_fma_f32 v[46:47], v[34:35], v[46:47], v[68:69] op_sel:[1,0,0] op_sel_hi:[0,1,1]
	v_mov_b32_e32 v68, v214
	v_mov_b32_e32 v69, v230
	v_pk_fma_f32 v[46:47], v[36:37], v[68:69], v[46:47] op_sel_hi:[0,1,1]
	v_mov_b32_e32 v68, v37
	v_mov_b32_e32 v230, v215
	v_pk_fma_f32 v[46:47], v[68:69], v[230:231], v[46:47] op_sel_hi:[0,1,1]
	v_pk_add_f32 v[14:15], v[14:15], v[46:47]
	s_waitcnt lgkmcnt(1)
	v_mov_b32_e32 v46, v241
	s_waitcnt lgkmcnt(0)
	v_mov_b32_e32 v241, v245
	v_mov_b32_e32 v47, v244
	v_pk_mul_f32 v[70:71], v[0:1], v[240:241]
	ds_read_b128 v[178:181], v9
	v_pk_fma_f32 v[46:47], v[0:1], v[46:47], v[70:71] op_sel:[1,0,0] op_sel_hi:[0,1,1]
	v_mov_b32_e32 v70, v242
	v_mov_b32_e32 v71, v246
	v_pk_fma_f32 v[46:47], v[2:3], v[70:71], v[46:47] op_sel_hi:[0,1,1]
	v_mov_b32_e32 v70, v3
	v_mov_b32_e32 v246, v243
	v_pk_fma_f32 v[46:47], v[70:71], v[246:247], v[46:47] op_sel_hi:[0,1,1]
	v_pk_add_f32 v[14:15], v[14:15], v[46:47]
	v_mov_b32_e32 v46, v55
	v_mov_b32_e32 v47, v58
	v_pk_fma_f32 v[30:31], v[30:31], v[46:47], v[248:249] op_sel:[1,0,0] op_sel_hi:[0,1,1]
	v_mov_b32_e32 v46, v56
	v_mov_b32_e32 v47, v60
	v_pk_fma_f32 v[30:31], v[32:33], v[46:47], v[30:31] op_sel_hi:[0,1,1]
	v_mov_b32_e32 v60, v57
	v_pk_fma_f32 v[30:31], v[48:49], v[60:61], v[30:31] op_sel_hi:[0,1,1]
	v_pk_add_f32 v[12:13], v[12:13], v[30:31]
	v_mov_b32_e32 v30, v75
	v_mov_b32_e32 v75, v79
	v_mov_b32_e32 v31, v78
	v_pk_mul_f32 v[32:33], v[26:27], v[74:75]
	v_mov_b32_e32 v9, s0
	v_pk_fma_f32 v[26:27], v[26:27], v[30:31], v[32:33] op_sel:[1,0,0] op_sel_hi:[0,1,1]
	v_mov_b32_e32 v30, v76
	v_mov_b32_e32 v31, v80
	v_pk_fma_f32 v[26:27], v[28:29], v[30:31], v[26:27] op_sel_hi:[0,1,1]
	v_mov_b32_e32 v80, v77
	v_pk_fma_f32 v[26:27], v[50:51], v[80:81], v[26:27] op_sel_hi:[0,1,1]
	v_pk_add_f32 v[12:13], v[12:13], v[26:27]
	v_mov_b32_e32 v26, v143
	v_mov_b32_e32 v143, v147
	v_mov_b32_e32 v27, v146
	v_pk_mul_f32 v[28:29], v[22:23], v[142:143]
	ds_read_b128 v[188:191], v9
	v_pk_fma_f32 v[22:23], v[22:23], v[26:27], v[28:29] op_sel:[1,0,0] op_sel_hi:[0,1,1]
	v_mov_b32_e32 v26, v144
	v_mov_b32_e32 v27, v148
	v_pk_fma_f32 v[22:23], v[24:25], v[26:27], v[22:23] op_sel_hi:[0,1,1]
	v_mov_b32_e32 v148, v145
	v_pk_fma_f32 v[22:23], v[52:53], v[148:149], v[22:23] op_sel_hi:[0,1,1]
	v_pk_add_f32 v[12:13], v[12:13], v[22:23]
	v_mov_b32_e32 v22, v159
	v_mov_b32_e32 v159, v163
	v_mov_b32_e32 v23, v162
	v_pk_mul_f32 v[24:25], v[18:19], v[158:159]
	s_mov_b64 s[0:1], 0
	v_pk_fma_f32 v[18:19], v[18:19], v[22:23], v[24:25] op_sel:[1,0,0] op_sel_hi:[0,1,1]
	v_mov_b32_e32 v22, v160
	v_mov_b32_e32 v23, v164
	v_pk_fma_f32 v[18:19], v[20:21], v[22:23], v[18:19] op_sel_hi:[0,1,1]
	v_mov_b32_e32 v164, v161
	v_pk_fma_f32 v[18:19], v[54:55], v[164:165], v[18:19] op_sel_hi:[0,1,1]
	v_pk_add_f32 v[12:13], v[12:13], v[18:19]
	v_mov_b32_e32 v18, v175
	v_mov_b32_e32 v175, v193
	v_mov_b32_e32 v19, v192
	v_pk_mul_f32 v[20:21], v[42:43], v[174:175]
	s_nop 0
	v_pk_fma_f32 v[18:19], v[42:43], v[18:19], v[20:21] op_sel:[1,0,0] op_sel_hi:[0,1,1]
	v_mov_b32_e32 v20, v176
	v_mov_b32_e32 v21, v194
	v_pk_fma_f32 v[18:19], v[44:45], v[20:21], v[18:19] op_sel_hi:[0,1,1]
	v_mov_b32_e32 v194, v177
	v_pk_fma_f32 v[18:19], v[62:63], v[194:195], v[18:19] op_sel_hi:[0,1,1]
	v_pk_add_f32 v[12:13], v[12:13], v[18:19]
	v_mov_b32_e32 v18, v205
	v_mov_b32_e32 v205, v209
	v_mov_b32_e32 v19, v208
	v_pk_mul_f32 v[20:21], v[38:39], v[204:205]
	s_nop 0
	v_pk_fma_f32 v[18:19], v[38:39], v[18:19], v[20:21] op_sel:[1,0,0] op_sel_hi:[0,1,1]
	v_mov_b32_e32 v20, v206
	v_mov_b32_e32 v21, v210
	v_pk_fma_f32 v[18:19], v[40:41], v[20:21], v[18:19] op_sel_hi:[0,1,1]
	v_mov_b32_e32 v210, v207
	v_pk_fma_f32 v[18:19], v[66:67], v[210:211], v[18:19] op_sel_hi:[0,1,1]
	v_pk_add_f32 v[12:13], v[12:13], v[18:19]
	v_mov_b32_e32 v18, v233
	v_mov_b32_e32 v233, v237
	v_mov_b32_e32 v19, v236
	v_pk_mul_f32 v[20:21], v[34:35], v[232:233]
	s_nop 0
	v_pk_fma_f32 v[18:19], v[34:35], v[18:19], v[20:21] op_sel:[1,0,0] op_sel_hi:[0,1,1]
	v_mov_b32_e32 v20, v234
	v_mov_b32_e32 v21, v238
	v_pk_fma_f32 v[18:19], v[36:37], v[20:21], v[18:19] op_sel_hi:[0,1,1]
	v_mov_b32_e32 v238, v235
	v_pk_fma_f32 v[18:19], v[68:69], v[238:239], v[18:19] op_sel_hi:[0,1,1]
	v_pk_add_f32 v[12:13], v[12:13], v[18:19]
	s_waitcnt lgkmcnt(1)
	v_mov_b32_e32 v18, v179
	s_waitcnt lgkmcnt(0)
	v_mov_b32_e32 v179, v189
	v_mov_b32_e32 v19, v188
	v_pk_mul_f32 v[20:21], v[0:1], v[178:179]
	s_nop 0
	v_pk_fma_f32 v[0:1], v[0:1], v[18:19], v[20:21] op_sel:[1,0,0] op_sel_hi:[0,1,1]
	v_mov_b32_e32 v18, v180
	v_mov_b32_e32 v19, v190
	v_pk_fma_f32 v[0:1], v[2:3], v[18:19], v[0:1] op_sel_hi:[0,1,1]
	v_mov_b32_e32 v190, v181
	v_pk_fma_f32 v[0:1], v[70:71], v[190:191], v[0:1] op_sel_hi:[0,1,1]
	v_pk_add_f32 v[12:13], v[12:13], v[0:1]
	s_cbranch_vccz .LBB0_613
	v_cvt_f32_i32_e32 v0, v8
	s_add_i32 s7, s7, 1
	s_cmp_eq_u32 s7, 8
	v_rcp_f32_e32 v1, s22
	s_nop 0
	v_mul_f32_e32 v0, v0, v1
	v_mul_f32_e32 v0, v16, v0
	v_mul_f32_e32 v0, 0x3fb8aa3b, v0
	v_exp_f32_e32 v0, v0
	v_lshl_add_u32 v1, v8, 2, 0
	v_add_u32_e32 v8, 0x11000, v1
	v_pk_mul_f32 v[2:3], v[0:1], v[14:15] op_sel_hi:[0,1]
	v_pk_mul_f32 v[0:1], v[0:1], v[12:13] op_sel_hi:[0,1]
	v_pk_fma_f32 v[6:7], v[2:3], v[2:3], v[6:7]
	v_pk_fma_f32 v[4:5], v[0:1], v[0:1], v[4:5]
	ds_write2st64_b32 v8, v2, v3 offset1:64
	ds_write2st64_b32 v8, v0, v1 offset0:128 offset1:192
	s_cbranch_scc0 .LBB0_612
	ds_bpermute_b32 v0, v64, v6
	s_waitcnt lgkmcnt(0)
	v_add_f32_e32 v0, v6, v0
	ds_bpermute_b32 v1, v130, v0
	s_waitcnt lgkmcnt(0)
	v_add_f32_e32 v0, v0, v1
	ds_bpermute_b32 v1, v131, v0
	s_waitcnt lgkmcnt(0)
	v_add_f32_e32 v0, v0, v1
	ds_bpermute_b32 v1, v132, v0
	s_waitcnt lgkmcnt(0)
	v_add_f32_e32 v0, v0, v1
	ds_bpermute_b32 v1, v133, v0
	s_waitcnt lgkmcnt(0)
	v_add_f32_e32 v0, v0, v1
	ds_bpermute_b32 v1, v134, v0
	s_and_saveexec_b64 s[0:1], s[46:47]
	s_cbranch_execz .LBB0_617
	s_add_i32 s7, s12, 0
	s_add_i32 s7, s7, 0x25080
	s_waitcnt lgkmcnt(0)
	v_add_f32_e32 v0, v0, v1
	v_mov_b32_e32 v1, s7
	ds_write_b32 v1, v0

; __device__ __forceinline__ float hgrn_lb(const Ctx& C, int l, int ch) {
;     if (l == 0) return 0.f;
;     const float a0 = C.P->in[3][ch], a1 = C.P->in[3][256 + ch];
;     return 1.0f / (1.0f + __expf(a0 - a1));
; }
.LBB0_641:
	s_bfe_u32 s1, s48, 0x20005
	v_readlane_b32 s4, v255, 1
	s_lshl_b32 s0, s1, 6
	v_readlane_b32 s5, v255, 2
	v_or_b32_e32 v192, s0, v118
	s_andn2_b64 vcc, exec, s[4:5]
	v_mov_b32_e32 v193, 0
	s_cbranch_vccnz .LBB0_643
	v_readlane_b32 s4, v251, 4
	v_lshlrev_b32_e32 v0, 2, v192
	v_readlane_b32 s10, v251, 10
	v_readlane_b32 s11, v251, 11
	s_nop 4
	global_load_dword v1, v0, s[10:11]
	s_nop 0
	global_load_dword v0, v0, s[10:11] offset:1024
	v_readlane_b32 s5, v251, 5
	v_readlane_b32 s6, v251, 6
	v_readlane_b32 s7, v251, 7
	v_readlane_b32 s8, v251, 8
	v_readlane_b32 s9, v251, 9
	v_readlane_b32 s12, v251, 12
	v_readlane_b32 s13, v251, 13
	v_readlane_b32 s14, v251, 14
	v_readlane_b32 s15, v251, 15
	v_readlane_b32 s16, v251, 16
	v_readlane_b32 s17, v251, 17
	v_readlane_b32 s18, v251, 18
	v_readlane_b32 s19, v251, 19
	s_waitcnt vmcnt(0)
	v_sub_f32_e32 v0, v1, v0
	v_mul_f32_e32 v0, 0x3fb8aa3b, v0
	v_exp_f32_e32 v0, v0
	s_nop 0
	v_add_f32_e32 v0, 1.0, v0
	v_rcp_f32_e32 v193, v0
	s_nop 0

; __device__ __forceinline__ bf16_t f2bf(float f) { return (bf16_t)(cvt_pk_bf16(f, 0.f) & 0xffffu); }
; __device__ __forceinline__ float bf2f(bf16_t b) { return __uint_as_float(((unsigned)b) << 16); }
; __device__ __forceinline__ float sigmoidf_(float x) { return 1.0f / (1.0f + __expf(-x)); }
; template <int MODE>
; __device__ __forceinline__ void hgrn_mfma(const Ctx& C, int l, int z, int b, int hd, int c, f32x4 (&Sacc)[4][4], float& dectot, unsigned char* wl, float lb) {
;     ...
;             for (int t = 0; t < 16; ++t) { const bf16_t* row = row0 + rstep * t; fv[t] = row[fcol]; vv[t] = row[vcol]; if (MODE != 0) qv[t] = row[qcol]; }
; #pragma unroll
;             for (int t = 0; t < 16; ++t) {
;                 const float fl = bf2f(fv[t]);
;                 const float sg = sigmoidf_(fl);
;                 const float f = lb + (1.0f - lb) * sg, kk = (1.0f - lb) * (1.0f - sg);
;                 bacc += __logf(fmaxf(f, 1e-30f));
;                 Kb[(g8 * 16 + t) * HPT + lane] = f2bf(kk * __expf(fminf(-bacc, 80.f)));
;                 if (MODE != 0) Qt[(g8 * 16 + t) * HPT + lane] = f2bf(bf2f(qv[t]) * __expf(fmaxf(bacc, -80.f)));
.LBB0_645:
	s_lshl_b32 s0, s67, 4
	v_cndmask_b32_e64 v60, 0, 1, s[46:47]
	s_mul_i32 s1, s67, 0x480
	s_sub_i32 s0, s74, s0
	v_cmp_ne_u32_e64 s[4:5], 1, v60
	v_or_b32_e32 v60, s1, v118
	s_mul_hi_i32 s1, s0, 0xa00
	s_mulk_i32 s0, 0xa00
	s_add_u32 s0, s69, s0
	v_lshlrev_b32_e32 v64, 1, v192
	s_addc_u32 s1, s70, s1
	global_load_ushort v70, v64, s[0:1] offset:1536
	global_load_ushort v71, v64, s[0:1] offset:1024
	global_load_ushort v72, v64, s[0:1]
	global_load_ushort v73, v64, s[0:1] offset:-1024
	global_load_ushort v74, v64, s[0:1] offset:-1536
	global_load_ushort v75, v64, s[0:1] offset:-2560
	global_load_ushort v76, v64, s[0:1] offset:-3584
	global_load_ushort v77, v64, s[0:1] offset:-4096
	s_add_u32 s6, s0, 0xffffe200
	s_addc_u32 s7, s1, -1
	global_load_ushort v78, v203, s[6:7]
	global_load_ushort v82, v64, s[6:7]
	global_load_ushort v83, v204, s[6:7]
	s_add_u32 s6, s0, 0xffffd800
	s_addc_u32 s7, s1, -1
	global_load_ushort v84, v203, s[6:7]
	global_load_ushort v85, v64, s[6:7]
	global_load_ushort v86, v204, s[6:7]
	s_add_u32 s6, s0, 0xffffce00
	v_lshl_add_u64 v[62:63], s[0:1], 0, v[64:65]
	s_movk_i32 s8, 0xf000
	s_addc_u32 s7, s1, -1
	v_add_co_u32_e32 v62, vcc, s8, v62
	s_add_u32 s8, s0, 0xffffc400
	global_load_ushort v89, v203, s[6:7]
	global_load_ushort v90, v64, s[6:7]
	global_load_ushort v91, v204, s[6:7]
	s_addc_u32 s9, s1, -1
	s_add_u32 s6, s0, 0xffffba00
	global_load_ushort v92, v204, s[8:9]
	global_load_ushort v93, v203, s[8:9]
	global_load_ushort v94, v64, s[8:9]
	s_addc_u32 s7, s1, -1
	s_add_u32 s8, s0, 0xffffb000
	global_load_ushort v95, v204, s[6:7]
	global_load_ushort v96, v203, s[6:7]
	global_load_ushort v97, v64, s[6:7]
	s_addc_u32 s9, s1, -1
	s_add_u32 s6, s0, 0xffffa600
	global_load_ushort v98, v204, s[8:9]
	global_load_ushort v99, v203, s[8:9]
	global_load_ushort v100, v64, s[8:9]
	s_addc_u32 s7, s1, -1
	s_add_u32 s8, s0, 0xffff9c00
	global_load_ushort v101, v204, s[6:7]
	global_load_ushort v102, v203, s[6:7]
	global_load_ushort v103, v64, s[6:7]
	s_addc_u32 s9, s1, -1
	global_load_ushort v104, v204, s[8:9]
	global_load_ushort v105, v203, s[8:9]
	global_load_ushort v106, v64, s[8:9]
	s_add_u32 s6, s0, 0xffff9200
	s_addc_u32 s7, s1, -1
	s_add_u32 s8, s0, 0xffff8800
	global_load_ushort v108, v204, s[6:7]
	global_load_ushort v109, v203, s[6:7]
	global_load_ushort v110, v64, s[6:7]
	s_addc_u32 s9, s1, -1
	s_add_u32 s6, s0, 0xffff7e00
	global_load_ushort v111, v204, s[8:9]
	global_load_ushort v178, v203, s[8:9]
	global_load_ushort v179, v64, s[8:9]
	s_addc_u32 s7, s1, -1
	s_add_u32 s8, s0, 0xffff7400
	global_load_ushort v180, v204, s[6:7]
	global_load_ushort v181, v203, s[6:7]
	global_load_ushort v188, v64, s[6:7]
	s_addc_u32 s9, s1, -1
	global_load_ushort v189, v204, s[8:9]
	global_load_ushort v190, v203, s[8:9]
	global_load_ushort v191, v64, s[8:9]
	s_add_u32 s0, s0, 0xffff6a00
	s_addc_u32 s1, s1, -1
	v_addc_co_u32_e32 v63, vcc, -1, v63, vcc
	global_load_ushort v87, v204, s[0:1]
	global_load_ushort v208, v[62:63], off offset:-1024
	global_load_ushort v79, v203, s[0:1]
	global_load_ushort v88, v64, s[0:1]
	v_lshl_add_u32 v60, v60, 1, s49
	s_mov_b64 s[46:47], 0
	s_mov_b32 s67, 1
	s_waitcnt vmcnt(47)
	ds_write_b16 v60, v70 offset:9216
	s_waitcnt vmcnt(46)
	v_lshlrev_b32_e32 v62, 16, v71
	v_mul_f32_e32 v62, 0xbfb8aa3b, v62
	v_exp_f32_e32 v62, v62
	s_waitcnt vmcnt(43)
	v_lshlrev_b32_e32 v63, 16, v74
	v_mul_f32_e32 v63, 0xbfb8aa3b, v63
	v_exp_f32_e32 v63, v63
	s_waitcnt vmcnt(40)
	v_lshlrev_b32_e32 v64, 16, v77
	v_mul_f32_e32 v64, 0xbfb8aa3b, v64
	v_exp_f32_e32 v64, v64
	s_waitcnt vmcnt(39)
	v_lshlrev_b32_e32 v70, 16, v78
	v_mul_f32_e32 v70, 0xbfb8aa3b, v70
	v_exp_f32_e32 v70, v70
	s_waitcnt vmcnt(36)
	v_lshlrev_b32_e32 v71, 16, v84
	v_lshlrev_b32_e32 v78, 16, v82
	v_mul_f32_e32 v71, 0xbfb8aa3b, v71
	v_add_f32_e32 v82, 1.0, v62
	v_add_f32_e32 v63, 1.0, v63
	v_add_f32_e32 v64, 1.0, v64
	ds_write_b16 v60, v83 offset:9648
	s_waitcnt vmcnt(35)
	v_lshlrev_b32_e32 v77, 16, v85
	v_exp_f32_e32 v62, v71
	s_waitcnt vmcnt(33)
	v_lshlrev_b32_e32 v71, 16, v89
	s_waitcnt vmcnt(31)
	ds_write_b16 v60, v91 offset:9936
	v_mul_f32_e32 v71, 0xbfb8aa3b, v71
	v_lshlrev_b32_e32 v81, 16, v72
	v_add_f32_e32 v70, 1.0, v70
	v_exp_f32_e32 v71, v71
	s_waitcnt vmcnt(29)
	v_lshlrev_b32_e32 v72, 16, v93
	v_mul_f32_e32 v72, 0xbfb8aa3b, v72
	v_add_f32_e32 v211, 1.0, v62
	v_exp_f32_e32 v62, v72
	s_waitcnt vmcnt(26)
	v_lshlrev_b32_e32 v72, 16, v96
	ds_write_b16 v60, v92 offset:10080
	ds_write_b16 v60, v95 offset:10224
	v_mul_f32_e32 v72, 0xbfb8aa3b, v72
	ds_write_b16 v60, v76 offset:9504
	ds_write_b16 v60, v86 offset:9792
	v_lshlrev_b32_e32 v76, 16, v90
	v_add_f32_e32 v213, 1.0, v71
	v_exp_f32_e32 v71, v72
	s_waitcnt vmcnt(23)
	v_lshlrev_b32_e32 v72, 16, v99
	ds_write_b16 v60, v98 offset:10368
	v_mul_f32_e32 v72, 0xbfb8aa3b, v72
	s_waitcnt vmcnt(20)
	v_lshlrev_b32_e32 v99, 16, v102
	v_add_f32_e32 v107, 1.0, v62
	v_exp_f32_e32 v62, v72
	s_waitcnt vmcnt(19)
	v_lshlrev_b32_e32 v72, 16, v103
	ds_write_b16 v60, v101 offset:10512
	v_mul_f32_e32 v99, 0xbfb8aa3b, v99
	v_lshlrev_b32_e32 v80, 16, v75
	v_lshlrev_b32_e32 v75, 16, v94
	v_exp_f32_e32 v229, v99
	s_waitcnt vmcnt(17)
	v_lshlrev_b32_e32 v99, 16, v105
	v_mul_f32_e32 v89, 0xbfb8aa3b, v99
	v_lshlrev_b32_e32 v74, 16, v97
	v_add_f32_e32 v103, 1.0, v71
	v_exp_f32_e32 v89, v89
	s_waitcnt vmcnt(14)
	v_lshlrev_b32_e32 v91, 16, v109
	v_rcp_f32_e32 v82, v82
	ds_write_b16 v60, v73 offset:9360
	v_lshlrev_b32_e32 v73, 16, v100
	v_add_f32_e32 v99, 1.0, v62
	v_mul_f32_e32 v86, 0xbfb8aa3b, v91
	v_fma_f32 v91, v194, v82, v193
	v_sub_f32_e32 v82, 1.0, v82
	v_rcp_f32_e32 v83, v63
	v_add_f32_e32 v96, 1.0, v229
	ds_write_b16 v60, v104 offset:10656
	v_exp_f32_e32 v104, v86
	s_waitcnt vmcnt(11)
; __device__ __forceinline__ bf16_t f2bf(float f) { return (bf16_t)(cvt_pk_bf16(f, 0.f) & 0xffffu); }
; __device__ __forceinline__ float bf2f(bf16_t b) { return __uint_as_float(((unsigned)b) << 16); }
; __device__ __forceinline__ float sigmoidf_(float x) { return 1.0f / (1.0f + __expf(-x)); }
; template <int MODE>
; __device__ __forceinline__ void hgrn_mfma(const Ctx& C, int l, int z, int b, int hd, int c, f32x4 (&Sacc)[4][4], float& dectot, unsigned char* wl, float lb) {
;     ...
;             for (int t = 0; t < 16; ++t) {
;                 const float fl = bf2f(fv[t]);
;                 const float sg = sigmoidf_(fl);
;                 const float f = lb + (1.0f - lb) * sg, kk = (1.0f - lb) * (1.0f - sg);
;                 bacc += __logf(fmaxf(f, 1e-30f));
;                 Kb[(g8 * 16 + t) * HPT + lane] = f2bf(kk * __expf(fminf(-bacc, 80.f)));
;                 if (MODE != 0) Qt[(g8 * 16 + t) * HPT + lane] = f2bf(bf2f(qv[t]) * __expf(fmaxf(bacc, -80.f)));
;                 Vv[(g8 * 16 + t) * HPT + lane] = vv[t];
	v_lshlrev_b32_e32 v102, 16, v178
	v_mul_f32_e32 v86, v194, v82
	v_max_f32_e32 v82, 0xda24260, v91
	v_fma_f32 v91, v194, v83, v193
	v_sub_f32_e32 v83, 1.0, v83
	v_rcp_f32_e32 v64, v64
	v_lshlrev_b32_e32 v71, 16, v106
	ds_write_b16 v60, v108 offset:10800
	v_mul_f32_e32 v101, 0xbfb8aa3b, v102
	v_cmp_gt_f32_e64 s[0:1], s54, v82
	v_mul_f32_e32 v84, v194, v83
	v_max_f32_e32 v83, 0xda24260, v91
	v_fma_f32 v106, v194, v64, v193
	v_rcp_f32_e32 v70, v70
	v_add_f32_e32 v93, 1.0, v89
	s_waitcnt vmcnt(10)
	v_lshlrev_b32_e32 v63, 16, v179
	v_cndmask_b32_e64 v102, 0, 32, s[0:1]
	v_exp_f32_e32 v179, v101
	s_waitcnt vmcnt(9)
	ds_write_b16 v60, v180 offset:11088
	v_cndmask_b32_e64 v105, 0, v225, s[0:1]
	v_cmp_gt_f32_e32 vcc, s54, v83
	v_max_f32_e32 v180, 0xda24260, v106
	v_fma_f32 v106, v194, v70, v193
	v_lshlrev_b32_e32 v62, 16, v110
	v_sub_f32_e32 v110, 1.0, v64
	s_waitcnt vmcnt(8)
	v_lshlrev_b32_e32 v89, 16, v181
	s_waitcnt vmcnt(7)
	v_lshlrev_b32_e32 v64, 16, v188
	v_cndmask_b32_e64 v97, 0, 32, vcc
	v_rcp_f32_e32 v90, v211
	v_cndmask_b32_e32 v100, 0, v225, vcc
	v_cmp_gt_f32_e64 s[0:1], s54, v180
	v_max_f32_e32 v188, 0xda24260, v106
	v_ldexp_f32 v82, v82, v102
	v_sub_f32_e32 v70, 1.0, v70
	v_mul_f32_e32 v95, 0xbfb8aa3b, v89
	v_ldexp_f32 v83, v83, v97
	v_cndmask_b32_e64 v97, 0, 32, s[0:1]
	v_fma_f32 v209, v194, v90, v193
	v_add_f32_e32 v89, 1.0, v104
	v_cmp_gt_f32_e32 vcc, s54, v188
	v_mul_f32_e32 v85, v194, v110
	v_log_f32_e32 v110, v82
	v_mul_f32_e32 v82, v194, v70
	v_exp_f32_e32 v211, v95
	s_waitcnt vmcnt(5)
	v_lshlrev_b32_e32 v104, 16, v190
	s_waitcnt vmcnt(4)
	v_lshlrev_b32_e32 v70, 16, v191
	ds_write_b16 v60, v189 offset:11232
	v_ldexp_f32 v180, v180, v97
	v_cndmask_b32_e64 v97, 0, v225, s[0:1]
	v_cndmask_b32_e64 v189, 0, 32, vcc
	v_max_f32_e32 v190, 0xda24260, v209
	v_rcp_f32_e32 v191, v213
	v_sub_f32_e32 v90, 1.0, v90
	v_log_f32_e32 v106, v83
	v_mul_f32_e32 v210, 0xbfb8aa3b, v104
	v_log_f32_e32 v104, v180
	v_ldexp_f32 v180, v188, v189
	v_cndmask_b32_e32 v188, 0, v225, vcc
	v_cmp_gt_f32_e64 s[0:1], s54, v190
	v_mul_f32_e32 v83, v194, v90
	s_waitcnt vmcnt(2)
	v_lshlrev_b32_e32 v90, 16, v208
	v_cndmask_b32_e64 v189, 0, 32, s[0:1]
	v_fma_f32 v213, v194, v191, v193
	v_sub_f32_e32 v191, 1.0, v191
	v_add_f32_e32 v208, 1.0, v179
	v_exp_f32_e32 v179, v210
	s_waitcnt vmcnt(1)
	v_lshlrev_b32_e32 v210, 16, v79
	s_waitcnt vmcnt(0)
	v_lshlrev_b32_e32 v79, 16, v88
	ds_write_b16 v60, v87 offset:11376
	v_ldexp_f32 v87, v190, v189
	v_cndmask_b32_e64 v189, 0, v225, s[0:1]
	v_mul_f32_e32 v92, v194, v191
	v_max_f32_e32 v88, 0xda24260, v213
	v_rcp_f32_e32 v107, v107
	ds_write_b16 v60, v111 offset:10944
	v_log_f32_e32 v180, v180
	v_mul_f32_e32 v207, 0xbfb8aa3b, v210
	v_mul_f32_e32 v210, 0x3f317217, v110
	v_cmp_gt_f32_e64 s[0:1], s54, v88
	v_fma_f32 v213, v194, v107, v193
	v_sub_f32_e32 v215, 1.0, v107
	v_add_f32_e32 v107, 1.0, v211
	v_log_f32_e32 v212, v87
	v_cndmask_b32_e64 v87, 0, 32, s[0:1]
	v_exp_f32_e32 v207, v207
	v_fma_f32 v210, v110, s56, -v210
	v_mul_f32_e32 v211, 0x3f317217, v106
	v_cndmask_b32_e64 v223, 0, v225, s[0:1]
	v_max_f32_e32 v213, 0xda24260, v213
	v_rcp_f32_e32 v103, v103
	v_ldexp_f32 v87, v88, v87
	v_fmac_f32_e32 v210, 0x3377d1cf, v110
	v_fma_f32 v211, v106, s56, -v211
	v_cmp_gt_f32_e64 s[0:1], s54, v213
	v_fma_f32 v229, v194, v103, v193
	v_sub_f32_e32 v230, 1.0, v103
	v_add_f32_e32 v103, 1.0, v179
	v_mul_f32_e32 v88, v194, v215
	v_mul_f32_e32 v215, 0x3f317217, v104
	v_log_f32_e32 v228, v87
	v_cndmask_b32_e64 v87, 0, 32, s[0:1]
	v_fmac_f32_e32 v210, 0x3f317217, v110
	v_fmac_f32_e32 v211, 0x3377d1cf, v106
	v_cndmask_b32_e64 v231, 0, v225, s[0:1]
	v_max_f32_e32 v229, 0xda24260, v229
	v_rcp_f32_e32 v99, v99
	v_cmp_lt_f32_e64 vcc, |v110|, s57
	v_fma_f32 v179, v104, s56, -v215
	v_mul_f32_e32 v215, 0x3f317217, v180
	v_ldexp_f32 v213, v213, v87
	v_cndmask_b32_e32 v110, v110, v210, vcc
	v_fmac_f32_e32 v211, 0x3f317217, v106
	v_cmp_lt_f32_e64 s[0:1], |v106|, s57
	v_cmp_gt_f32_e64 s[18:19], s54, v229
	v_fma_f32 v232, v194, v99, v193
	v_mul_f32_e32 v87, v194, v230
	v_fmac_f32_e32 v179, 0x3377d1cf, v104
	v_fma_f32 v113, v180, s56, -v215
	v_mul_f32_e32 v210, 0x3f317217, v212
	v_log_f32_e32 v213, v213
	v_cndmask_b32_e64 v215, 0, 32, s[18:19]
	v_sub_f32_e32 v233, 1.0, v99
	v_add_f32_e32 v99, 1.0, v207
	v_cndmask_b32_e64 v106, v106, v211, s[0:1]
	v_max_f32_e32 v211, 0xda24260, v232
	v_sub_f32_e32 v105, v110, v105
	v_fmac_f32_e32 v179, 0x3f317217, v104
	v_cmp_lt_f32_e64 vcc, |v104|, s57
	v_fmac_f32_e32 v113, 0x3377d1cf, v180
	v_fma_f32 v110, v212, s56, -v210
	v_ldexp_f32 v207, v229, v215
	v_cndmask_b32_e64 v210, 0, v225, s[18:19]
	v_rcp_f32_e32 v111, v96
	v_cmp_gt_f32_e64 s[18:19], s54, v211
	v_add_f32_e32 v61, v61, v105
	v_sub_f32_e32 v100, v106, v100
	v_cndmask_b32_e32 v104, v104, v179, vcc
	v_fmac_f32_e32 v113, 0x3f317217, v180
	v_cmp_lt_f32_e64 s[0:1], |v180|, s57
	v_fmac_f32_e32 v110, 0x3377d1cf, v212
	v_mul_f32_e32 v105, 0x3f317217, v228
	v_log_f32_e32 v106, v207
	v_cndmask_b32_e64 v179, 0, 32, s[18:19]
	v_fma_f32 v207, v194, v111, v193
	v_sub_f32_e32 v111, 1.0, v111
	v_min_f32_e64 v229, -v61, s60
	v_max_f32_e32 v230, 0xc2a00000, v61
	v_add_f32_e32 v100, v61, v100
	v_sub_f32_e32 v97, v104, v97
	v_cndmask_b32_e64 v104, v180, v113, s[0:1]
	v_fmac_f32_e32 v110, 0x3f317217, v212
	v_cmp_lt_f32_e64 vcc, |v212|, s57
	v_fma_f32 v105, v228, s56, -v105
	v_ldexp_f32 v113, v211, v179
	v_mul_f32_e32 v61, v194, v111
	v_max_f32_e32 v111, 0xda24260, v207
	v_rcp_f32_e32 v93, v93
	v_min_f32_e64 v180, -v100, s60
	v_max_f32_e32 v207, 0xc2a00000, v100
	v_add_f32_e32 v97, v100, v97
	v_sub_f32_e32 v100, v104, v188
	v_cndmask_b32_e32 v104, v212, v110, vcc
	v_fmac_f32_e32 v105, 0x3377d1cf, v228
; __device__ __forceinline__ bf16_t f2bf(float f) { return (bf16_t)(cvt_pk_bf16(f, 0.f) & 0xffffu); }
; __device__ __forceinline__ float bf2f(bf16_t b) { return __uint_as_float(((unsigned)b) << 16); }
; __device__ __forceinline__ float sigmoidf_(float x) { return 1.0f / (1.0f + __expf(-x)); }
; template <int MODE>
; __device__ __forceinline__ void hgrn_mfma(const Ctx& C, int l, int z, int b, int hd, int c, f32x4 (&Sacc)[4][4], float& dectot, unsigned char* wl, float lb) {
;     ...
;             for (int t = 0; t < 16; ++t) {
;                 const float fl = bf2f(fv[t]);
;                 const float sg = sigmoidf_(fl);
;                 const float f = lb + (1.0f - lb) * sg, kk = (1.0f - lb) * (1.0f - sg);
;                 bacc += __logf(fmaxf(f, 1e-30f));
;                 Kb[(g8 * 16 + t) * HPT + lane] = f2bf(kk * __expf(fminf(-bacc, 80.f)));
;                 if (MODE != 0) Qt[(g8 * 16 + t) * HPT + lane] = f2bf(bf2f(qv[t]) * __expf(fmaxf(bacc, -80.f)));
;                 Vv[(g8 * 16 + t) * HPT + lane] = vv[t];
	v_mul_f32_e32 v110, 0x3f317217, v213
	v_log_f32_e32 v113, v113
	v_cmp_gt_f32_e64 s[0:1], s54, v111
	v_mul_f32_e32 v98, 0x3fb8aa3b, v229
	v_mul_f32_e32 v112, 0x3fb8aa3b, v230
	v_cndmask_b32_e64 v188, 0, 32, s[0:1]
	v_fma_f32 v211, v194, v93, v193
	v_mul_f32_e32 v207, 0x3fb8aa3b, v207
	v_min_f32_e64 v212, -v97, s60
	v_max_f32_e32 v214, 0xc2a00000, v97
	v_add_f32_e32 v97, v97, v100
	v_sub_f32_e32 v100, v104, v189
	v_fmac_f32_e32 v105, 0x3f317217, v228
	v_cmp_lt_f32_e64 vcc, |v228|, s57
	v_fma_f32 v104, v213, s56, -v110
	v_exp_f32_e32 v98, v98
	v_exp_f32_e32 v112, v112
	v_mul_f32_e32 v180, 0x3fb8aa3b, v180
	v_ldexp_f32 v110, v111, v188
	v_max_f32_e32 v188, 0xda24260, v211
	v_rcp_f32_e32 v89, v89
	v_exp_f32_e32 v181, v207
	v_min_f32_e64 v207, -v97, s60
	v_max_f32_e32 v211, 0xc2a00000, v97
	v_add_f32_e32 v97, v97, v100
	v_cndmask_b32_e32 v100, v228, v105, vcc
	v_fmac_f32_e32 v104, 0x3377d1cf, v213
	v_mul_f32_e32 v105, 0x3f317217, v106
	v_cndmask_b32_e64 v111, 0, v225, s[0:1]
	v_exp_f32_e32 v180, v180
	v_mul_f32_e32 v191, 0x3fb8aa3b, v212
	v_mul_f32_e32 v206, 0x3fb8aa3b, v214
	v_cmp_gt_f32_e64 s[0:1], s54, v188
	v_fma_f32 v214, v194, v89, v193
	v_sub_f32_e32 v100, v100, v223
	v_fmac_f32_e32 v104, 0x3f317217, v213
	v_cmp_lt_f32_e64 vcc, |v213|, s57
	v_fma_f32 v105, v106, s56, -v105
	v_log_f32_e32 v110, v110
	v_cndmask_b32_e64 v212, 0, 32, s[0:1]
	v_exp_f32_e32 v191, v191
	v_exp_f32_e32 v205, v206
	v_mul_f32_e32 v206, 0x3fb8aa3b, v207
	v_mul_f32_e32 v207, 0x3fb8aa3b, v211
	v_min_f32_e64 v211, -v97, s60
	v_max_f32_e32 v228, 0xc2a00000, v97
	v_max_f32_e32 v214, 0xda24260, v214
	v_rcp_f32_e32 v94, v208
	v_add_f32_e32 v97, v97, v100
	v_cndmask_b32_e32 v100, v213, v104, vcc
	v_fmac_f32_e32 v105, 0x3377d1cf, v106
	v_mul_f32_e32 v104, 0x3f317217, v113
	v_ldexp_f32 v188, v188, v212
	v_cndmask_b32_e64 v212, 0, v225, s[0:1]
	v_exp_f32_e32 v189, v206
	v_exp_f32_e32 v206, v207
	v_mul_f32_e32 v207, 0x3fb8aa3b, v211
	v_mul_f32_e32 v208, 0x3fb8aa3b, v228
	v_cmp_gt_f32_e64 s[0:1], s54, v214
	v_fma_f32 v213, v194, v94, v193
	v_sub_f32_e32 v94, 1.0, v94
	v_sub_f32_e32 v100, v100, v231
	v_fmac_f32_e32 v105, 0x3f317217, v106
	v_cmp_lt_f32_e64 vcc, |v106|, s57
	v_fma_f32 v104, v113, s56, -v104
	v_log_f32_e32 v188, v188
	v_cndmask_b32_e64 v211, 0, 32, s[0:1]
	v_mul_f32_e32 v86, v86, v98
	v_mul_f32_e32 v98, v112, v81
	v_exp_f32_e32 v112, v207
	v_exp_f32_e32 v190, v208
	v_min_f32_e64 v207, -v97, s60
	v_max_f32_e32 v208, 0xc2a00000, v97
	v_mul_f32_e32 v81, v194, v94
	v_max_f32_e32 v94, 0xda24260, v213
	v_rcp_f32_e32 v95, v107
	v_add_f32_e32 v97, v97, v100
	v_cndmask_b32_e32 v100, v106, v105, vcc
	v_fmac_f32_e32 v104, 0x3377d1cf, v113
	v_ldexp_f32 v209, v214, v211
	v_cndmask_b32_e64 v211, 0, v225, s[0:1]
	v_cvt_pk_bf16_f32 v86, v86, s0
	v_cvt_pk_bf16_f32 v98, v98, s0
	v_mul_f32_e32 v84, v84, v180
	v_mul_f32_e32 v80, v181, v80
	v_mul_f32_e32 v109, 0x3fb8aa3b, v207
	v_mul_f32_e32 v180, 0x3fb8aa3b, v208
	v_cmp_gt_f32_e64 s[0:1], s54, v94
	v_fma_f32 v207, v194, v95, v193
	v_sub_f32_e32 v95, 1.0, v95
	v_sub_f32_e32 v100, v100, v210
	v_fmac_f32_e32 v104, 0x3f317217, v113
	v_cmp_lt_f32_e64 vcc, |v113|, s57
	v_mul_f32_e32 v105, 0x3f317217, v110
	v_log_f32_e32 v106, v209
	v_cndmask_b32_e64 v181, 0, 32, s[0:1]
	ds_write_b16 v60, v86 offset:4608
	ds_write_b16 v60, v98
	v_cvt_pk_bf16_f32 v84, v84, s0
	v_cvt_pk_bf16_f32 v86, v80, s0
	v_mul_f32_e32 v85, v85, v191
	v_mul_f32_e32 v90, v205, v90
	v_exp_f32_e32 v98, v109
	v_exp_f32_e32 v107, v180
	v_min_f32_e64 v108, -v97, s60
	v_max_f32_e32 v109, 0xc2a00000, v97
	v_mul_f32_e32 v80, v194, v95
	v_max_f32_e32 v95, 0xda24260, v207
	v_rcp_f32_e32 v102, v103
	v_add_f32_e32 v97, v97, v100
	v_cndmask_b32_e32 v100, v113, v104, vcc
	v_cndmask_b32_e64 v179, 0, v225, s[18:19]
	v_fma_f32 v105, v110, s56, -v105
	v_ldexp_f32 v94, v94, v181
	v_cndmask_b32_e64 v180, 0, v225, s[0:1]
	ds_write_b16 v60, v84 offset:4752
	ds_write_b16 v60, v86 offset:144
	v_cvt_pk_bf16_f32 v84, v85, s0
	v_cvt_pk_bf16_f32 v85, v90, s0
	v_mul_f32_e32 v82, v82, v189
	v_mul_f32_e32 v78, v206, v78
	v_mul_f32_e32 v86, 0x3fb8aa3b, v108
	v_cmp_gt_f32_e64 s[0:1], s54, v95
	v_fma_f32 v104, v194, v102, v193
	v_mul_f32_e32 v90, 0x3fb8aa3b, v109
	v_fmac_f32_e32 v105, 0x3377d1cf, v110
	v_mul_f32_e32 v101, 0x3f317217, v188
	v_log_f32_e32 v94, v94
	v_cndmask_b32_e64 v103, 0, 32, s[0:1]
	ds_write_b16 v60, v84 offset:4896
	ds_write_b16 v60, v85 offset:288
	v_cvt_pk_bf16_f32 v82, v82, s0
	v_cvt_pk_bf16_f32 v78, v78, s0
	v_mul_f32_e32 v83, v83, v112
	v_mul_f32_e32 v77, v190, v77
	v_exp_f32_e32 v84, v86
	v_min_f32_e64 v86, -v97, s60
	v_sub_f32_e32 v100, v100, v179
	v_max_f32_e32 v104, 0xda24260, v104
	v_rcp_f32_e32 v96, v99
	s_and_b64 vcc, exec, s[4:5]
	v_exp_f32_e32 v85, v90
	v_max_f32_e32 v90, 0xc2a00000, v97
	v_fmac_f32_e32 v105, 0x3f317217, v110
	v_cmp_lt_f32_e64 s[4:5], |v110|, s57
	v_fma_f32 v101, v188, s56, -v101
	v_ldexp_f32 v95, v95, v103
	v_cndmask_b32_e64 v103, 0, v225, s[0:1]
	ds_write_b16 v60, v82 offset:5040
	ds_write_b16 v60, v78 offset:432
	v_cvt_pk_bf16_f32 v78, v83, s0
	v_cvt_pk_bf16_f32 v77, v77, s0
	v_mul_f32_e32 v82, 0x3fb8aa3b, v86
	v_add_f32_e32 v86, v97, v100
	v_cmp_gt_f32_e64 s[0:1], s54, v104
	v_fma_f32 v100, v194, v96, v193
	v_mul_f32_e32 v83, 0x3fb8aa3b, v90
	v_cndmask_b32_e64 v90, v110, v105, s[4:5]
	v_fmac_f32_e32 v101, 0x3377d1cf, v188
	v_mul_f32_e32 v97, 0x3f317217, v106
	v_log_f32_e32 v95, v95
	v_cndmask_b32_e64 v99, 0, 32, s[0:1]
	ds_write_b16 v60, v78 offset:5184
	ds_write_b16 v60, v77 offset:576
	v_mul_f32_e32 v77, v92, v98
	v_mul_f32_e32 v76, v107, v76
	v_max_f32_e32 v100, 0xda24260, v100
	v_exp_f32_e32 v78, v82
	v_exp_f32_e32 v82, v83
	v_min_f32_e64 v83, -v86, s60
; __device__ __forceinline__ bf16_t f2bf(float f) { return (bf16_t)(cvt_pk_bf16(f, 0.f) & 0xffffu); }
; __device__ __forceinline__ float bf2f(bf16_t b) { return __uint_as_float(((unsigned)b) << 16); }
; __device__ __forceinline__ float sigmoidf_(float x) { return 1.0f / (1.0f + __expf(-x)); }
; template <int MODE>
; __device__ __forceinline__ void hgrn_mfma(const Ctx& C, int l, int z, int b, int hd, int c, f32x4 (&Sacc)[4][4], float& dectot, unsigned char* wl, float lb) {
;     ...
;             for (int t = 0; t < 16; ++t) {
;                 const float fl = bf2f(fv[t]);
;                 const float sg = sigmoidf_(fl);
;                 const float f = lb + (1.0f - lb) * sg, kk = (1.0f - lb) * (1.0f - sg);
;                 bacc += __logf(fmaxf(f, 1e-30f));
;                 Kb[(g8 * 16 + t) * HPT + lane] = f2bf(kk * __expf(fminf(-bacc, 80.f)));
;                 if (MODE != 0) Qt[(g8 * 16 + t) * HPT + lane] = f2bf(bf2f(qv[t]) * __expf(fmaxf(bacc, -80.f)));
;                 Vv[(g8 * 16 + t) * HPT + lane] = vv[t];
	v_max_f32_e32 v92, 0xc2a00000, v86
	v_sub_f32_e32 v90, v90, v111
	v_fmac_f32_e32 v101, 0x3f317217, v188
	v_cmp_lt_f32_e64 s[4:5], |v188|, s57
	v_fma_f32 v97, v106, s56, -v97
	v_ldexp_f32 v98, v104, v99
	v_cndmask_b32_e64 v99, 0, v225, s[0:1]
	v_cvt_pk_bf16_f32 v77, v77, s0
	v_cvt_pk_bf16_f32 v76, v76, s0
	v_cmp_gt_f32_e64 s[0:1], s54, v100
	v_mul_f32_e32 v83, 0x3fb8aa3b, v83
	v_mul_f32_e32 v92, 0x3fb8aa3b, v92
	v_add_f32_e32 v86, v86, v90
	v_cndmask_b32_e64 v90, v188, v101, s[4:5]
	v_fmac_f32_e32 v97, 0x3377d1cf, v106
	v_mul_f32_e32 v101, 0x3f317217, v94
	v_log_f32_e32 v98, v98
	v_cndmask_b32_e64 v104, 0, 32, s[0:1]
	ds_write_b16 v60, v77 offset:5328
	ds_write_b16 v60, v76 offset:720
	v_mul_f32_e32 v76, v88, v84
	v_mul_f32_e32 v75, v85, v75
	v_exp_f32_e32 v77, v83
	v_exp_f32_e32 v83, v92
	v_min_f32_e64 v84, -v86, s60
	v_max_f32_e32 v85, 0xc2a00000, v86
	v_sub_f32_e32 v88, v90, v212
	v_fmac_f32_e32 v97, 0x3f317217, v106
	v_cmp_lt_f32_e64 s[4:5], |v106|, s57
	v_fma_f32 v90, v94, s56, -v101
	v_ldexp_f32 v92, v100, v104
	v_cvt_pk_bf16_f32 v76, v76, s0
	v_cvt_pk_bf16_f32 v75, v75, s0
	v_mul_f32_e32 v84, 0x3fb8aa3b, v84
	v_mul_f32_e32 v85, 0x3fb8aa3b, v85
	v_add_f32_e32 v86, v86, v88
	v_cndmask_b32_e64 v88, v106, v97, s[4:5]
	v_fmac_f32_e32 v90, 0x3377d1cf, v94
	v_mul_f32_e32 v97, 0x3f317217, v95
	v_log_f32_e32 v92, v92
	v_cndmask_b32_e64 v100, 0, v225, s[0:1]
	ds_write_b16 v60, v76 offset:5472
	ds_write_b16 v60, v75 offset:864
	v_mul_f32_e32 v75, v87, v78
	v_mul_f32_e32 v74, v82, v74
	v_exp_f32_e32 v76, v84
	v_exp_f32_e32 v78, v85
	v_min_f32_e64 v82, -v86, s60
	v_max_f32_e32 v84, 0xc2a00000, v86
	v_sub_f32_e32 v85, v88, v211
	v_fmac_f32_e32 v90, 0x3f317217, v94
	v_cmp_lt_f32_e64 s[0:1], |v94|, s57
	v_fma_f32 v87, v95, s56, -v97
	v_mul_f32_e32 v91, v194, v233
	v_cvt_pk_bf16_f32 v75, v75, s0
	v_cvt_pk_bf16_f32 v74, v74, s0
	v_mul_f32_e32 v82, 0x3fb8aa3b, v82
	v_mul_f32_e32 v84, 0x3fb8aa3b, v84
	v_add_f32_e32 v85, v86, v85
	v_cndmask_b32_e64 v86, v94, v90, s[0:1]
	v_fmac_f32_e32 v87, 0x3377d1cf, v95
	v_mul_f32_e32 v88, 0x3f317217, v98
	ds_write_b16 v60, v75 offset:5616
	ds_write_b16 v60, v74 offset:1008
	v_mul_f32_e32 v74, v91, v77
	v_mul_f32_e32 v73, v83, v73
	v_exp_f32_e32 v75, v82
	v_exp_f32_e32 v77, v84
	v_min_f32_e64 v82, -v85, s60
	v_max_f32_e32 v83, 0xc2a00000, v85
	v_sub_f32_e32 v84, v86, v180
	v_fmac_f32_e32 v87, 0x3f317217, v95
	v_cmp_lt_f32_e64 s[0:1], |v95|, s57
	v_fma_f32 v86, v98, s56, -v88
	v_mul_f32_e32 v82, 0x3fb8aa3b, v82
	v_cvt_pk_bf16_f32 v74, v74, s0
	v_cvt_pk_bf16_f32 v73, v73, s0
	v_mul_f32_e32 v83, 0x3fb8aa3b, v83
	v_add_f32_e32 v84, v85, v84
	v_cndmask_b32_e64 v85, v95, v87, s[0:1]
	v_fmac_f32_e32 v86, 0x3377d1cf, v98
	v_mul_f32_e32 v87, 0x3f317217, v92
	v_sub_f32_e32 v93, 1.0, v93
	ds_write_b16 v60, v74 offset:5760
	ds_write_b16 v60, v73 offset:1152
	v_mul_f32_e32 v61, v61, v76
	v_mul_f32_e32 v72, v78, v72
	v_exp_f32_e32 v73, v82
	v_exp_f32_e32 v74, v83
	v_min_f32_e64 v76, -v84, s60
	v_max_f32_e32 v78, 0xc2a00000, v84
	v_sub_f32_e32 v82, v85, v103
	v_fmac_f32_e32 v86, 0x3f317217, v98
	v_cmp_lt_f32_e64 s[0:1], |v98|, s57
	v_fma_f32 v83, v92, s56, -v87
	v_mul_f32_e32 v93, v194, v93
	v_cvt_pk_bf16_f32 v61, v61, s0
	v_cvt_pk_bf16_f32 v72, v72, s0
	v_mul_f32_e32 v76, 0x3fb8aa3b, v76
	v_mul_f32_e32 v78, 0x3fb8aa3b, v78
	v_add_f32_e32 v82, v84, v82
	v_cndmask_b32_e64 v84, v98, v86, s[0:1]
	v_fmac_f32_e32 v83, 0x3377d1cf, v92
	v_sub_f32_e32 v89, 1.0, v89
	ds_write_b16 v60, v61 offset:5904
	ds_write_b16 v60, v72 offset:1296
	v_mul_f32_e32 v61, v93, v75
	v_mul_f32_e32 v71, v77, v71
	v_exp_f32_e32 v72, v76
	v_exp_f32_e32 v75, v78
	v_min_f32_e64 v76, -v82, s60
	v_max_f32_e32 v77, 0xc2a00000, v82
	v_sub_f32_e32 v78, v84, v99
	v_fmac_f32_e32 v83, 0x3f317217, v92
	v_cmp_lt_f32_e64 s[0:1], |v92|, s57
	v_mul_f32_e32 v89, v194, v89
	v_mul_f32_e32 v76, 0x3fb8aa3b, v76
	v_cvt_pk_bf16_f32 v61, v61, s0
	v_cvt_pk_bf16_f32 v71, v71, s0
	v_mul_f32_e32 v77, 0x3fb8aa3b, v77
	v_add_f32_e32 v78, v82, v78
	v_cndmask_b32_e64 v82, v92, v83, s[0:1]
	ds_write_b16 v60, v61 offset:6048
	ds_write_b16 v60, v71 offset:1440
	v_mul_f32_e32 v61, v89, v73
	v_mul_f32_e32 v62, v74, v62
	v_exp_f32_e32 v71, v76
	v_exp_f32_e32 v73, v77
	v_min_f32_e64 v74, -v78, s60
	v_sub_f32_e32 v77, v82, v100
	v_max_f32_e32 v76, 0xc2a00000, v78
	v_cvt_pk_bf16_f32 v82, v61, s0
	v_cvt_pk_bf16_f32 v62, v62, s0
	v_mul_f32_e32 v74, 0x3fb8aa3b, v74
	v_add_f32_e32 v61, v78, v77
	v_mul_f32_e32 v76, 0x3fb8aa3b, v76
	ds_write_b16 v60, v82 offset:6192
	ds_write_b16 v60, v62 offset:1584
	v_mul_f32_e32 v62, v81, v72
	v_mul_f32_e32 v63, v75, v63
	v_exp_f32_e32 v72, v74
	v_min_f32_e64 v75, -v61, s60
	v_exp_f32_e32 v74, v76
	v_max_f32_e32 v76, 0xc2a00000, v61
	v_cvt_pk_bf16_f32 v62, v62, s0
	v_cvt_pk_bf16_f32 v63, v63, s0
	v_mul_f32_e32 v75, 0x3fb8aa3b, v75
	v_sub_f32_e32 v102, 1.0, v102
	v_mul_f32_e32 v76, 0x3fb8aa3b, v76
	ds_write_b16 v60, v62 offset:6336
	ds_write_b16 v60, v63 offset:1728
	v_mul_f32_e32 v62, v80, v71
	v_mul_f32_e32 v63, v73, v64
	v_exp_f32_e32 v64, v75
	v_mul_f32_e32 v102, v194, v102
	v_exp_f32_e32 v71, v76
	v_cvt_pk_bf16_f32 v62, v62, s0
	v_sub_f32_e32 v96, 1.0, v96
	v_cvt_pk_bf16_f32 v63, v63, s0
	ds_write_b16 v60, v62 offset:6480
	ds_write_b16 v60, v63 offset:1872
	v_mul_f32_e32 v62, v102, v72
	v_mul_f32_e32 v96, v194, v96
	v_mul_f32_e32 v63, v74, v70
	v_cvt_pk_bf16_f32 v62, v62, s0
	v_cvt_pk_bf16_f32 v63, v63, s0
	ds_write_b16 v60, v62 offset:6624
	ds_write_b16 v60, v63 offset:2016
	v_mul_f32_e32 v62, v96, v64
	v_mul_f32_e32 v63, v71, v79
	v_cvt_pk_bf16_f32 v62, v62, s0
	v_cvt_pk_bf16_f32 v63, v63, s0
	ds_write_b16 v60, v62 offset:6768
	ds_write_b16 v60, v63 offset:2160
	s_cbranch_vccz .LBB0_645
; template <int MODE>
; __device__ __forceinline__ void hgrn_mfma(const Ctx& C, int l, int z, int b, int hd, int c, f32x4 (&Sacc)[4][4], float& dectot, unsigned char* wl, float lb) {
;     ...
;         { const float eb = __expf(bacc); dl[lane] = eb; dectot *= eb; }
;         wave_lds_fence();
;         f32x4 Oacc[2][4];
;         if (MODE != 0) {
;             bf16x8 Sb[2][4];
; #pragma unroll
;             for (int ks = 0; ks < 2; ++ks)
; #pragma unroll
;                 for (int vt = 0; vt < 4; ++vt) { union { bf16x8 v; unsigned u[4]; } t_;
;                     t_.u[0] = cvt_pk_bf16(Sacc[2 * ks][vt][0], Sacc[2 * ks][vt][1]); t_.u[1] = cvt_pk_bf16(Sacc[2 * ks][vt][2], Sacc[2 * ks][vt][3]);
;                     t_.u[2] = cvt_pk_bf16(Sacc[2 * ks + 1][vt][0], Sacc[2 * ks + 1][vt][1]); t_.u[3] = cvt_pk_bf16(Sacc[2 * ks + 1][vt][2], Sacc[2 * ks + 1][vt][3]); Sb[ks][vt] = t_.v; }
;             float zz = 0.f; asm volatile("" : "+v"(zz));
; #pragma unroll
;             for (int tt = 0; tt < 2; ++tt)
; #pragma unroll
;                 for (int vt = 0; vt < 4; ++vt) Oacc[tt][vt] = (f32x4){zz, zz, zz, zz};
; #pragma unroll
;             for (int tt = 0; tt < 2; ++tt)
; #pragma unroll
;                 for (int ks = 0; ks < 2; ++ks) { const bf16_t* qp = Qt + (16 * tt + fr) * HPT + 32 * ks + 4 * quad;
;                     union { bf16x8 v; u32x2 h[2]; } a_; a_.h[0] = *(const u32x2*)qp; a_.h[1] = *(const u32x2*)(qp + 16);
; #pragma unroll
;                     for (int vt = 0; vt < 4; ++vt) Oacc[tt][vt] = __builtin_amdgcn_mfma_f32_16x16x32_bf16(a_.v, Sb[ks][vt], Oacc[tt][vt], 0, 0, 0); }
;             f32x4 P00 = {zz, zz, zz, zz}, P01 = {zz, zz, zz, zz}, P11 = {zz, zz, zz, zz};
; #pragma unroll
;             for (int ks = 0; ks < 2; ++ks) {
;                 const bf16x8 kA0 = *(const bf16x8*)(Kb + fr * HPT + 32 * ks + 8 * quad), kA1 = *(const bf16x8*)(Kb + (16 + fr) * HPT + 32 * ks + 8 * quad);
;                 const bf16x8 qB0 = *(const bf16x8*)(Qt + fr * HPT + 32 * ks + 8 * quad), qB1 = *(const bf16x8*)(Qt + (16 + fr) * HPT + 32 * ks + 8 * quad);
;                 P00 = __builtin_amdgcn_mfma_f32_16x16x32_bf16(kA0, qB0, P00, 0, 0, 0);
;                 P01 = __builtin_amdgcn_mfma_f32_16x16x32_bf16(kA0, qB1, P01, 0, 0, 0);
;                 P11 = __builtin_amdgcn_mfma_f32_16x16x32_bf16(kA1, qB1, P11, 0, 0, 0);
;             }
; #pragma unroll
	v_mul_f32_e32 v60, 0x3fb8aa3b, v61
	v_exp_f32_e32 v60, v60
	v_mov_b32_e32 v98, v65
	v_cvt_pk_bf16_f32 v61, v2, v3
	v_cvt_pk_bf16_f32 v62, v16, v17
	ds_write_b32 v119, v60 offset:13824
	s_waitcnt lgkmcnt(0)
	ds_read2_b64 v[102:105], v126 offset1:4
	ds_read2_b64 v[188:191], v126 offset0:8 offset1:12
	v_cvt_pk_bf16_f32 v60, v0, v1
	v_cvt_pk_bf16_f32 v63, v18, v19
	v_cvt_pk_bf16_f32 v70, v4, v5
	v_cvt_pk_bf16_f32 v71, v6, v7
	v_cvt_pk_bf16_f32 v72, v20, v21
	v_cvt_pk_bf16_f32 v73, v22, v23
	v_cvt_pk_bf16_f32 v78, v8, v9
	v_cvt_pk_bf16_f32 v79, v10, v11
	v_cvt_pk_bf16_f32 v80, v24, v25
	v_cvt_pk_bf16_f32 v81, v26, v27
	v_cvt_pk_bf16_f32 v86, v12, v13
	v_cvt_pk_bf16_f32 v87, v14, v15
	v_cvt_pk_bf16_f32 v88, v28, v29
	v_cvt_pk_bf16_f32 v89, v30, v31
	v_mov_b32_e32 v99, v98
	v_mov_b32_e32 v100, v98
	v_mov_b32_e32 v101, v98
	v_cvt_pk_bf16_f32 v74, v32, v33
	v_cvt_pk_bf16_f32 v75, v34, v35
	s_waitcnt lgkmcnt(1)
	v_mfma_f32_16x16x32_bf16 v[106:109], v[102:105], v[60:63], v[98:101]
	v_cvt_pk_bf16_f32 v76, v48, v49
	v_cvt_pk_bf16_f32 v77, v50, v51
	v_cvt_pk_bf16_f32 v82, v36, v37
	v_mfma_f32_16x16x32_bf16 v[110:113], v[102:105], v[70:73], v[98:101]
	v_cvt_pk_bf16_f32 v83, v38, v39
	v_cvt_pk_bf16_f32 v84, v66, v67
	v_cvt_pk_bf16_f32 v85, v68, v69
	v_mfma_f32_16x16x32_bf16 v[178:181], v[102:105], v[78:81], v[98:101]
	v_cvt_pk_bf16_f32 v90, v40, v41
	v_cvt_pk_bf16_f32 v91, v42, v43
	v_cvt_pk_bf16_f32 v92, v56, v57
	v_mfma_f32_16x16x32_bf16 v[102:105], v[102:105], v[86:89], v[98:101]
	v_cvt_pk_bf16_f32 v93, v58, v59
	v_cvt_pk_bf16_f32 v94, v44, v45
	v_cvt_pk_bf16_f32 v95, v46, v47
	v_cvt_pk_bf16_f32 v96, v52, v53
	v_cvt_pk_bf16_f32 v97, v54, v55
	v_add_u32_e32 v64, 0x800, v126
	s_waitcnt lgkmcnt(0)
	v_mfma_f32_16x16x32_bf16 v[106:109], v[188:191], v[74:77], v[106:109]
	s_add_i32 s72, s72, 1
	s_cmp_eq_u32 s72, 4
	v_mfma_f32_16x16x32_bf16 v[110:113], v[188:191], v[82:85], v[110:113]
	v_mfma_f32_16x16x32_bf16 v[178:181], v[188:191], v[90:93], v[178:181]
	v_mfma_f32_16x16x32_bf16 v[102:105], v[188:191], v[94:97], v[102:105]
	ds_read2_b64 v[188:191], v64 offset0:32 offset1:36
	s_waitcnt lgkmcnt(0)
	v_mfma_f32_16x16x32_bf16 v[60:63], v[188:191], v[60:63], v[98:101]
	v_mfma_f32_16x16x32_bf16 v[70:73], v[188:191], v[70:73], v[98:101]
	v_mfma_f32_16x16x32_bf16 v[78:81], v[188:191], v[78:81], v[98:101]
	v_mfma_f32_16x16x32_bf16 v[86:89], v[188:191], v[86:89], v[98:101]
	ds_read2_b64 v[188:191], v64 offset0:40 offset1:44
	s_waitcnt lgkmcnt(0)
	v_mfma_f32_16x16x32_bf16 v[74:77], v[188:191], v[74:77], v[60:63]
	v_mfma_f32_16x16x32_bf16 v[206:209], v[188:191], v[82:85], v[70:73]
	v_mfma_f32_16x16x32_bf16 v[78:81], v[188:191], v[90:93], v[78:81]
	v_mfma_f32_16x16x32_bf16 v[188:191], v[188:191], v[94:97], v[86:89]
	ds_read_b128 v[60:63], v123 offset:4608
	ds_read_b128 v[70:73], v123 offset:6912
	ds_read_b128 v[82:85], v123
	ds_read_b128 v[86:89], v123 offset:2304
	ds_read_b128 v[90:93], v123 offset:4672
	ds_read_b128 v[94:97], v123 offset:6976
	ds_read_b128 v[210:213], v123 offset:64
	ds_read_b128 v[228:231], v123 offset:2368
	s_waitcnt lgkmcnt(5)
	v_mfma_f32_16x16x32_bf16 v[82:85], v[60:63], v[82:85], v[98:101]
	s_waitcnt lgkmcnt(4)
	v_mfma_f32_16x16x32_bf16 v[70:73], v[70:73], v[86:89], v[98:101]
	s_waitcnt lgkmcnt(1)
	v_mfma_f32_16x16x32_bf16 v[82:85], v[90:93], v[210:213], v[82:85]
	s_waitcnt lgkmcnt(0)
	v_mfma_f32_16x16x32_bf16 v[70:73], v[94:97], v[228:231], v[70:73]
	v_mfma_f32_16x16x32_bf16 v[60:63], v[60:63], v[86:89], v[98:101]
	s_nop 4
	v_cndmask_b32_e64 v64, v85, 0, s[42:43]
	s_nop 0
	v_cndmask_b32_e64 v85, v73, 0, s[42:43]
	v_cndmask_b32_e64 v94, v72, 0, s[20:21]
	v_cndmask_b32_e64 v95, v71, 0, s[38:39]
	v_cndmask_b32_e64 v96, v70, 0, s[44:45]
	v_mfma_f32_16x16x32_bf16 v[70:73], v[90:93], v[228:231], v[60:63]
	v_cndmask_b32_e64 v84, v84, 0, s[20:21]
	v_cndmask_b32_e64 v83, v83, 0, s[38:39]
	v_cndmask_b32_e64 v82, v82, 0, s[44:45]
	v_cvt_pk_bf16_f32 v62, v82, v83
	v_cvt_pk_bf16_f32 v63, v84, v64
	v_mov_b32_e32 v64, v65
	s_nop 1
	v_cvt_pk_bf16_f32 v98, v70, v71
	v_cvt_pk_bf16_f32 v99, v72, v73
	ds_read_b64_tr_b16 v[72:73], v124 offset:11520
	ds_read_b64_tr_b16 v[70:71], v124 offset:9216
	ds_read_b64_tr_b16 v[90:91], v124 offset:9248
	v_cvt_pk_bf16_f32 v100, v96, v95
	v_cvt_pk_bf16_f32 v101, v94, v85
	s_waitcnt lgkmcnt(1)
	v_mfma_f32_16x16x32_bf16 v[82:85], v[62:65], v[70:73], v[106:109]
	ds_read_b64_tr_b16 v[92:93], v124 offset:11552
	ds_read_b64_tr_b16 v[94:95], v124 offset:9280
	ds_read_b64_tr_b16 v[96:97], v124 offset:11584
	ds_read_b64_tr_b16 v[106:107], v124 offset:9312
	ds_read_b64_tr_b16 v[108:109], v124 offset:11616
	v_mfma_f32_16x16x32_bf16 v[70:73], v[98:101], v[70:73], v[74:77]
	s_waitcnt lgkmcnt(4)
	v_mfma_f32_16x16x32_bf16 v[86:89], v[62:65], v[90:93], v[110:113]
	v_mfma_f32_16x16x32_bf16 v[74:77], v[98:101], v[90:93], v[206:209]
	s_waitcnt lgkmcnt(2)
	v_mfma_f32_16x16x32_bf16 v[90:93], v[62:65], v[94:97], v[178:181]
	v_mfma_f32_16x16x32_bf16 v[78:81], v[98:101], v[94:97], v[78:81]
	s_waitcnt lgkmcnt(0)
	v_mfma_f32_16x16x32_bf16 v[94:97], v[62:65], v[106:109], v[102:105]
	v_add_u32_e32 v64, v122, v121
	v_mfma_f32_16x16x32_bf16 v[60:63], v[98:101], v[106:109], v[188:191]
	ds_read_b64_tr_b16 v[110:111], v125 offset:9216
	ds_read_b64_tr_b16 v[112:113], v125 offset:9792
	ds_read_b64_tr_b16 v[106:107], v125 offset:9248
	ds_read_b64_tr_b16 v[108:109], v125 offset:9824
	ds_read_b64_tr_b16 v[102:103], v125 offset:9280
	ds_read_b64_tr_b16 v[104:105], v125 offset:9856
	ds_read_b64_tr_b16 v[98:99], v125 offset:9312
	ds_read_b64_tr_b16 v[100:101], v125 offset:9888
	ds_read_b64_tr_b16 v[180:181], v125 offset:5184
	ds_read_b64_tr_b16 v[178:179], v125 offset:4608
	ds_read_b64_tr_b16 v[188:189], v125 offset:4640
	ds_read_b128 v[206:209], v64 offset:13824
	v_cvt_pk_bf16_f32 v60, v60, s0
	s_waitcnt lgkmcnt(2)
; __device__ __forceinline__ bf16_t f2bf(float f) { return (bf16_t)(cvt_pk_bf16(f, 0.f) & 0xffffu); }
; template <int MODE>
; __device__ __forceinline__ void hgrn_mfma(const Ctx& C, int l, int z, int b, int hd, int c, f32x4 (&Sacc)[4][4], float& dectot, unsigned char* wl, float lb) {
;     ...
;         {
;             bf16x8 vB[4];
; #pragma unroll
;             for (int vt = 0; vt < 4; ++vt) { const bf16_t* vp = Vv + (8 * quad + (fr >> 2)) * HPT + 16 * vt + 4 * (fr & 3);
;                 union { bf16x8 v; s16x4 h[2]; } vb; vb.h[0] = lds_tr(vp); vb.h[1] = lds_tr(vp + 4 * HPT); vB[vt] = vb.v; }
; #pragma unroll
;             for (int kt = 0; kt < 4; ++kt) { const bf16_t* kp = Kb + (8 * quad + (fr >> 2)) * HPT + 16 * kt + 4 * (fr & 3);
;                 union { bf16x8 v; s16x4 h[2]; } ka; ka.h[0] = lds_tr(kp); ka.h[1] = lds_tr(kp + 4 * HPT);
;                 const f32x4 d4 = *(const f32x4*)(dl + 16 * kt + 4 * quad);
; #pragma unroll
;                 for (int vt = 0; vt < 4; ++vt) { Sacc[kt][vt] = __builtin_amdgcn_mfma_f32_16x16x32_bf16(ka.v, vB[vt], Sacc[kt][vt], 0, 0, 0); Sacc[kt][vt] *= d4; } }
;         }
;         if (MODE == 1) {
; #pragma unroll
;             for (int tt = 0; tt < 2; ++tt)
; #pragma unroll
;                 for (int r = 0; r < 4; ++r) { const int st = c * 128 + sc * 32 + 16 * tt + 4 * quad + r; const int tq = z ? 4095 - st : st;
;                     bf16_t* yp = ya + (size_t)(b * SEQ + tq) * 256 + hd * 64 + fr;
; #pragma unroll
;                     for (int vt = 0; vt < 4; ++vt) yp[16 * vt] = f2bf(Oacc[tt][vt][r]); }
	v_mfma_f32_16x16x32_bf16 v[0:3], v[178:181], v[110:113], v[0:3]
	v_cvt_pk_bf16_f32 v62, v62, s0
	v_mfma_f32_16x16x32_bf16 v[4:7], v[178:181], v[106:109], v[4:7]
	v_mfma_f32_16x16x32_bf16 v[8:11], v[178:181], v[102:105], v[8:11]
	s_waitcnt lgkmcnt(0)
	s_nop 3
	v_pk_mul_f32 v[2:3], v[208:209], v[2:3]
	v_pk_mul_f32 v[0:1], v[206:207], v[0:1]
	v_pk_mul_f32 v[6:7], v[208:209], v[6:7]
	v_mfma_f32_16x16x32_bf16 v[12:15], v[178:181], v[98:101], v[12:15]
	ds_read_b64_tr_b16 v[190:191], v125 offset:5216
	ds_read_b128 v[178:181], v64 offset:13888
	v_pk_mul_f32 v[4:5], v[206:207], v[4:5]
	v_pk_mul_f32 v[10:11], v[208:209], v[10:11]
	s_waitcnt lgkmcnt(1)
	v_mfma_f32_16x16x32_bf16 v[16:19], v[188:191], v[110:113], v[16:19]
	v_mul_f32_e64 v8, v206, v8
	v_mul_f32_e64 v9, v207, v9
	v_pk_mul_f32 v[14:15], v[208:209], v[14:15]
	v_pk_mul_f32 v[12:13], v[206:207], v[12:13]
	v_mfma_f32_16x16x32_bf16 v[20:23], v[188:191], v[106:109], v[20:23]
	s_waitcnt lgkmcnt(0)
	s_nop 1
	v_pk_mul_f32 v[18:19], v[180:181], v[18:19]
	v_pk_mul_f32 v[16:17], v[178:179], v[16:17]
	v_mfma_f32_16x16x32_bf16 v[24:27], v[188:191], v[102:105], v[24:27]
	v_mfma_f32_16x16x32_bf16 v[28:31], v[188:191], v[98:101], v[28:31]
	s_nop 0
	v_mul_f32_e64 v22, v180, v22
	v_mul_f32_e64 v23, v181, v23
	v_pk_mul_f32 v[20:21], v[178:179], v[20:21]
	s_nop 2
	v_pk_mul_f32 v[26:27], v[180:181], v[26:27]
	v_pk_mul_f32 v[24:25], v[178:179], v[24:25]
	v_pk_mul_f32 v[30:31], v[180:181], v[30:31]
	v_pk_mul_f32 v[28:29], v[178:179], v[28:29]
	ds_read_b64_tr_b16 v[178:179], v125 offset:4672
	ds_read_b64_tr_b16 v[180:181], v125 offset:5248
	ds_read_b128 v[188:191], v64 offset:13952
	s_waitcnt lgkmcnt(1)
	v_mfma_f32_16x16x32_bf16 v[32:35], v[178:181], v[110:113], v[32:35]
	v_mfma_f32_16x16x32_bf16 v[36:39], v[178:181], v[106:109], v[36:39]
	s_waitcnt lgkmcnt(0)
	s_nop 5
	v_pk_mul_f32 v[34:35], v[190:191], v[34:35]
	v_pk_mul_f32 v[32:33], v[188:189], v[32:33]
	v_mfma_f32_16x16x32_bf16 v[40:43], v[178:181], v[102:105], v[40:43]
	v_mfma_f32_16x16x32_bf16 v[44:47], v[178:181], v[98:101], v[44:47]
	v_mul_f32_e64 v38, v190, v38
	v_mul_f32_e64 v39, v191, v39
	v_pk_mul_f32 v[36:37], v[188:189], v[36:37]
	s_nop 3
	v_pk_mul_f32 v[42:43], v[190:191], v[42:43]
	v_pk_mul_f32 v[40:41], v[188:189], v[40:41]
	v_pk_mul_f32 v[46:47], v[190:191], v[46:47]
	v_pk_mul_f32 v[44:45], v[188:189], v[44:45]
	ds_read_b64_tr_b16 v[178:179], v125 offset:4704
	ds_read_b64_tr_b16 v[180:181], v125 offset:5280
	ds_read_b128 v[188:191], v64 offset:14016
	s_waitcnt lgkmcnt(1)
	v_mfma_f32_16x16x32_bf16 v[52:55], v[178:181], v[98:101], v[52:55]
	v_add_u32_e32 v98, s36, v195
	v_ashrrev_i32_e32 v99, 31, v98
	v_lshlrev_b64 v[98:99], 9, v[98:99]
	v_lshl_add_u64 v[98:99], v[116:117], 0, v[98:99]
	v_cvt_pk_bf16_f32 v64, v82, s0
	global_store_short v[98:99], v64, off
	v_cvt_pk_bf16_f32 v64, v86, s0
	global_store_short v[98:99], v64, off offset:32
	v_cvt_pk_bf16_f32 v64, v90, s0
	global_store_short v[98:99], v64, off offset:64
	v_cvt_pk_bf16_f32 v64, v94, s0
	global_store_short v[98:99], v64, off offset:96
	v_add_u32_e32 v98, s36, v196
	v_ashrrev_i32_e32 v99, 31, v98
	v_lshlrev_b64 v[98:99], 9, v[98:99]
	v_lshl_add_u64 v[98:99], v[116:117], 0, v[98:99]
	v_cvt_pk_bf16_f32 v64, v83, s0
	global_store_short v[98:99], v64, off
	v_cvt_pk_bf16_f32 v64, v87, s0
	v_add_u32_e32 v82, s36, v197
	global_store_short v[98:99], v64, off offset:32
	v_cvt_pk_bf16_f32 v64, v91, s0
	v_ashrrev_i32_e32 v83, 31, v82
	global_store_short v[98:99], v64, off offset:64
	v_cvt_pk_bf16_f32 v64, v95, s0
	v_lshlrev_b64 v[82:83], 9, v[82:83]
	global_store_short v[98:99], v64, off offset:96
	v_lshl_add_u64 v[82:83], v[116:117], 0, v[82:83]
	v_cvt_pk_bf16_f32 v64, v84, s0
	global_store_short v[82:83], v64, off
	v_cvt_pk_bf16_f32 v64, v88, s0
	global_store_short v[82:83], v64, off offset:32
	v_cvt_pk_bf16_f32 v64, v92, s0
	global_store_short v[82:83], v64, off offset:64
	v_cvt_pk_bf16_f32 v64, v96, s0
	global_store_short v[82:83], v64, off offset:96
	v_add_u32_e32 v82, s36, v198
	v_ashrrev_i32_e32 v83, 31, v82
	v_lshlrev_b64 v[82:83], 9, v[82:83]
	v_lshl_add_u64 v[82:83], v[116:117], 0, v[82:83]
	v_cvt_pk_bf16_f32 v64, v85, s0
	global_store_short v[82:83], v64, off
	v_cvt_pk_bf16_f32 v64, v89, s0
	global_store_short v[82:83], v64, off offset:32
	v_cvt_pk_bf16_f32 v64, v93, s0
	global_store_short v[82:83], v64, off offset:64
	v_cvt_pk_bf16_f32 v64, v97, s0
	global_store_short v[82:83], v64, off offset:96
	v_add_u32_e32 v82, s36, v199
	v_ashrrev_i32_e32 v83, 31, v82
	v_lshlrev_b64 v[82:83], 9, v[82:83]
	v_lshl_add_u64 v[82:83], v[116:117], 0, v[82:83]
	v_cvt_pk_bf16_f32 v64, v70, s0
	global_store_short v[82:83], v64, off
	v_cvt_pk_bf16_f32 v64, v74, s0
	global_store_short v[82:83], v64, off offset:32
	v_cvt_pk_bf16_f32 v64, v78, s0
	global_store_short v[82:83], v64, off offset:64
	global_store_short v[82:83], v60, off offset:96
	v_add_u32_e32 v82, s36, v200
	v_ashrrev_i32_e32 v83, 31, v82
	v_lshlrev_b64 v[82:83], 9, v[82:83]
	v_lshl_add_u64 v[82:83], v[116:117], 0, v[82:83]
	v_cvt_pk_bf16_f32 v60, v71, s0
	global_store_short v[82:83], v60, off
	v_cvt_pk_bf16_f32 v60, v75, s0
	global_store_short v[82:83], v60, off offset:32
	v_cvt_pk_bf16_f32 v60, v79, s0
	global_store_short v[82:83], v60, off offset:64
	v_cvt_pk_bf16_f32 v60, v61, s0
	global_store_short v[82:83], v60, off offset:96
	v_add_u32_e32 v60, s36, v201
	v_ashrrev_i32_e32 v61, 31, v60
	v_lshlrev_b64 v[60:61], 9, v[60:61]
	v_lshl_add_u64 v[60:61], v[116:117], 0, v[60:61]
	v_cvt_pk_bf16_f32 v64, v72, s0
	global_store_short v[60:61], v64, off
	v_cvt_pk_bf16_f32 v64, v76, s0
	global_store_short v[60:61], v64, off offset:32
	v_cvt_pk_bf16_f32 v64, v80, s0
	global_store_short v[60:61], v64, off offset:64
	global_store_short v[60:61], v62, off offset:96
	v_add_u32_e32 v60, s36, v202
	v_ashrrev_i32_e32 v61, 31, v60
	v_lshlrev_b64 v[60:61], 9, v[60:61]
	v_lshl_add_u64 v[60:61], v[116:117], 0, v[60:61]
	v_cvt_pk_bf16_f32 v62, v73, s0
	global_store_short v[60:61], v62, off
	v_cvt_pk_bf16_f32 v62, v77, s0
	global_store_short v[60:61], v62, off offset:32
	v_cvt_pk_bf16_f32 v62, v81, s0
	v_mfma_f32_16x16x32_bf16 v[48:51], v[178:181], v[110:113], v[48:51]
	global_store_short v[60:61], v62, off offset:64
	v_cvt_pk_bf16_f32 v62, v63, s0
	global_store_short v[60:61], v62, off offset:96
	v_mfma_f32_16x16x32_bf16 v[66:69], v[178:181], v[106:109], v[66:69]
	s_waitcnt lgkmcnt(0)
	s_waitcnt lgkmcnt(0)
	s_nop 2
	v_pk_mul_f32 v[50:51], v[190:191], v[50:51]
	v_pk_mul_f32 v[48:49], v[188:189], v[48:49]
	v_mfma_f32_16x16x32_bf16 v[56:59], v[178:181], v[102:105], v[56:59]
	v_mul_f32_e64 v54, v190, v54
	v_mul_f32_e64 v55, v191, v55
	v_pk_mul_f32 v[68:69], v[190:191], v[68:69]
	v_pk_mul_f32 v[66:67], v[188:189], v[66:67]
	v_pk_mul_f32 v[52:53], v[188:189], v[52:53]
	s_nop 2
	v_pk_mul_f32 v[58:59], v[190:191], v[58:59]
	v_pk_mul_f32 v[56:57], v[188:189], v[56:57]
	s_cbranch_scc0 .LBB0_644
	v_readlane_b32 s0, v254, 20
	s_add_i32 s48, s48, s0
	s_cmpk_gt_i32 s48, 0x3ff
	v_readlane_b32 s1, v254, 21
	s_cbranch_scc0 .LBB0_641

; __device__ __forceinline__ bf16_t f2bf(float f) { return (bf16_t)(cvt_pk_bf16(f, 0.f) & 0xffffu); }
; __device__ __forceinline__ float bf2f(bf16_t b) { return __uint_as_float(((unsigned)b) << 16); }
; __device__ __forceinline__ float sigmoidf_(float x) { return 1.0f / (1.0f + __expf(-x)); }
; template <bool FINAL>
; __device__ __forceinline__ void lru_item(const Ctx& C, int l, int item) {
;     ...
;         for (int s4 = 0; s4 < 4; ++s4) { const int tt = z ? 3 - s4 : s4;
;             const bf16_t* xrow = xc + (16 * tt + fr) * XCP + n * 64 + 8 * quad;
;             const bf16x8 xa0 = *(const bf16x8*)xrow, xa1 = *(const bf16x8*)(xrow + 32);
; #pragma unroll
;             for (int dt = 0; dt < 4; ++dt) {
;                 f32x4 Da = {0.f, 0.f, 0.f, 0.f}, Dx = {0.f, 0.f, 0.f, 0.f};
;                 Da = __builtin_amdgcn_mfma_f32_16x16x32_bf16(xa0, Bw[0][dt][0], Da, 0, 0, 0); Da = __builtin_amdgcn_mfma_f32_16x16x32_bf16(xa1, Bw[0][dt][1], Da, 0, 0, 0);
;                 Dx = __builtin_amdgcn_mfma_f32_16x16x32_bf16(xa0, Bw[1][dt][0], Dx, 0, 0, 0); Dx = __builtin_amdgcn_mfma_f32_16x16x32_bf16(xa1, Bw[1][dt][1], Dx, 0, 0, 0);
; #pragma unroll
;                 for (int r = 0; r < 4; ++r) { const int tloc = 4 * quad + r, d = 16 * dt + fr;
;                     const float rg = sigmoidf_(Da[r] + bav[dt]), ig = sigmoidf_(Dx[r] + bxv[dt]), la = -8.0f * rg * spv[dt], a = __expf(la);
;                     const float x = bf2f(xc[(16 * tt + tloc) * XCP + n * 64 + d]);
;                     Al[tloc * 68 + d] = a; Ul[tloc * 68 + d] = f2bf(sqrtf(fmaxf(1.0f - a * a, 0.f)) * ig * x); }
.LBB0_681:
	s_and_b64 s[0:1], s[4:5], exec
	s_cselect_b32 s0, s9, s51
	s_lshl_b32 s52, s0, 4
	v_or_b32_e32 v66, s52, v97
	v_mad_u64_u32 v[66:67], s[0:1], v66, s58, v[96:97]
	ds_read_b128 v[70:73], v66
	ds_read_b128 v[66:69], v66 offset:64
	s_add_i32 s9, s9, 1
	s_add_i32 s51, s51, -1
	s_waitcnt lgkmcnt(1)
	v_mfma_f32_16x16x32_bf16 v[74:77], v[70:73], v[0:3], 0
	s_waitcnt lgkmcnt(0)
	v_mfma_f32_16x16x32_bf16 v[74:77], v[66:69], v[16:19], v[74:77]
	v_mfma_f32_16x16x32_bf16 v[104:107], v[70:73], v[32:35], 0
	v_mfma_f32_16x16x32_bf16 v[174:177], v[66:69], v[48:51], v[104:107]
	s_nop 5
	v_add_f32_e32 v74, v64, v74
	v_mul_f32_e32 v74, 0xbfb8aa3b, v74
	v_exp_f32_e32 v74, v74
	s_nop 0
	v_add_f32_e32 v74, 1.0, v74
	s_nop 0
	v_rcp_f32_e32 v74, v74
	v_add_f32_e32 v104, v162, v174
	v_mul_f32_e32 v104, 0xbfb8aa3b, v104
	v_exp_f32_e32 v104, v104
	v_mul_f32_e32 v74, 0xc1000000, v74
	v_mul_f32_e32 v74, v163, v74
	v_mul_f32_e32 v74, 0x3fb8aa3b, v74
	v_add_f32_e32 v104, 1.0, v104
	v_exp_f32_e32 v74, v74
	ds_write_b32 v114, v74 offset:33792
	v_fma_f32 v74, -v74, v74, 1.0
	v_max_f32_e32 v74, 0, v74
	v_cmp_gt_f32_e32 vcc, s59, v74
	v_mul_f32_e32 v106, 0x4f800000, v74
	v_rcp_f32_e32 v104, v104
	v_cndmask_b32_e32 v74, v74, v106, vcc
	v_sqrt_f32_e32 v106, v74
	v_or_b32_e32 v105, s52, v112
	v_mad_u64_u32 v[110:111], s[0:1], v105, s58, v[98:99]
	v_add_u32_e32 v107, -1, v106
	v_fma_f32 v108, -v107, v106, v74
	v_cmp_ge_f32_e64 s[0:1], 0, v108
	v_add_u32_e32 v108, 1, v106
	ds_read_u16 v105, v110
	v_cndmask_b32_e64 v107, v106, v107, s[0:1]
	v_fma_f32 v106, -v108, v106, v74
	v_cmp_lt_f32_e64 s[0:1], 0, v106
	s_waitcnt lgkmcnt(0)
	v_lshlrev_b32_e32 v105, 16, v105
	v_cndmask_b32_e64 v106, v107, v108, s[0:1]
	v_mul_f32_e32 v107, 0x37800000, v106
	v_cndmask_b32_e32 v106, v106, v107, vcc
	v_cmp_class_f32_e32 vcc, v74, v220
	s_nop 1
	v_cndmask_b32_e32 v74, v106, v74, vcc
	v_mul_f32_e32 v74, v104, v74
	v_mul_f32_e32 v74, v74, v105
	v_cvt_pk_bf16_f32 v74, v74, s0
	ds_write_b16 v87, v74 offset:38144
	v_add_f32_e32 v74, v64, v75
	v_mul_f32_e32 v74, 0xbfb8aa3b, v74
	v_exp_f32_e32 v74, v74
	s_nop 0
	v_add_f32_e32 v74, 1.0, v74
	s_nop 0
	v_rcp_f32_e32 v74, v74
	v_add_f32_e32 v75, v162, v175
	v_mul_f32_e32 v75, 0xbfb8aa3b, v75
	v_exp_f32_e32 v75, v75
	v_mul_f32_e32 v74, 0xc1000000, v74
	v_mul_f32_e32 v74, v163, v74
	v_mul_f32_e32 v74, 0x3fb8aa3b, v74
	v_add_f32_e32 v75, 1.0, v75
	v_exp_f32_e32 v74, v74
	ds_write_b32 v116, v74 offset:33792
	v_fma_f32 v74, -v74, v74, 1.0
	v_max_f32_e32 v74, 0, v74
	v_cmp_gt_f32_e32 vcc, s59, v74
	v_mul_f32_e32 v105, 0x4f800000, v74
	v_rcp_f32_e32 v75, v75
	v_cndmask_b32_e32 v74, v74, v105, vcc
	v_sqrt_f32_e32 v105, v74
	v_or_b32_e32 v104, s52, v115
	v_mad_u64_u32 v[108:109], s[0:1], v104, s58, v[98:99]
	v_add_u32_e32 v106, -1, v105
	v_fma_f32 v107, -v106, v105, v74
	v_cmp_ge_f32_e64 s[0:1], 0, v107
	v_add_u32_e32 v107, 1, v105
	ds_read_u16 v104, v108
	v_cndmask_b32_e64 v106, v105, v106, s[0:1]
	v_fma_f32 v105, -v107, v105, v74
	v_cmp_lt_f32_e64 s[0:1], 0, v105
	s_waitcnt lgkmcnt(0)
	v_lshlrev_b32_e32 v104, 16, v104
	v_cndmask_b32_e64 v105, v106, v107, s[0:1]
	v_mul_f32_e32 v106, 0x37800000, v105
	v_cndmask_b32_e32 v105, v105, v106, vcc
	v_cmp_class_f32_e32 vcc, v74, v220
	s_nop 1
	v_cndmask_b32_e32 v74, v105, v74, vcc
	v_mul_f32_e32 v74, v75, v74
	v_mul_f32_e32 v74, v74, v104
	v_cvt_pk_bf16_f32 v74, v74, s0
	ds_write_b16 v144, v74 offset:38144
	v_add_f32_e32 v74, v64, v76
	v_mul_f32_e32 v74, 0xbfb8aa3b, v74
	v_exp_f32_e32 v74, v74
	s_nop 0
	v_add_f32_e32 v74, 1.0, v74
	s_nop 0
	v_rcp_f32_e32 v74, v74
	v_add_f32_e32 v75, v162, v176
	v_mul_f32_e32 v75, 0xbfb8aa3b, v75
	v_exp_f32_e32 v75, v75
	v_mul_f32_e32 v74, 0xc1000000, v74
	v_mul_f32_e32 v74, v163, v74
	v_mul_f32_e32 v74, 0x3fb8aa3b, v74
	v_add_f32_e32 v75, 1.0, v75
	v_exp_f32_e32 v74, v74
	ds_write_b32 v118, v74 offset:33792
	v_fma_f32 v74, -v74, v74, 1.0
	v_max_f32_e32 v74, 0, v74
	v_cmp_gt_f32_e32 vcc, s59, v74
	v_mul_f32_e32 v104, 0x4f800000, v74
	v_rcp_f32_e32 v75, v75
	v_cndmask_b32_e32 v74, v74, v104, vcc
	v_sqrt_f32_e32 v104, v74
	v_or_b32_e32 v76, s52, v117
	v_mad_u64_u32 v[106:107], s[0:1], v76, s58, v[98:99]
	v_add_u32_e32 v105, -1, v104
	v_fma_f32 v107, -v105, v104, v74
	v_cmp_ge_f32_e64 s[0:1], 0, v107
	v_add_u32_e32 v107, 1, v104
	ds_read_u16 v76, v106
	v_cndmask_b32_e64 v105, v104, v105, s[0:1]
	v_fma_f32 v104, -v107, v104, v74
	v_cmp_lt_f32_e64 s[0:1], 0, v104
	s_waitcnt lgkmcnt(0)
	v_lshlrev_b32_e32 v76, 16, v76
	v_cndmask_b32_e64 v104, v105, v107, s[0:1]
	v_mul_f32_e32 v105, 0x37800000, v104
	v_cndmask_b32_e32 v104, v104, v105, vcc
	v_cmp_class_f32_e32 vcc, v74, v220
	s_nop 1
	v_cndmask_b32_e32 v74, v104, v74, vcc
	v_mul_f32_e32 v74, v75, v74
	v_mul_f32_e32 v74, v74, v76
	v_cvt_pk_bf16_f32 v74, v74, s0
	ds_write_b16 v145, v74 offset:38144
	v_add_f32_e32 v74, v64, v77
	v_mul_f32_e32 v74, 0xbfb8aa3b, v74
	v_exp_f32_e32 v74, v74
	s_nop 0
	v_add_f32_e32 v74, 1.0, v74
	s_nop 0
	v_rcp_f32_e32 v74, v74
	v_add_f32_e32 v75, v162, v177
	v_mul_f32_e32 v75, 0xbfb8aa3b, v75
	v_exp_f32_e32 v75, v75
	v_mul_f32_e32 v74, 0xc1000000, v74
	v_mul_f32_e32 v74, v163, v74
	v_mul_f32_e32 v74, 0x3fb8aa3b, v74
	v_add_f32_e32 v75, 1.0, v75
	v_exp_f32_e32 v74, v74
	v_mfma_f32_16x16x32_bf16 v[174:177], v[70:73], v[36:39], 0
	ds_write_b32 v120, v74 offset:33792
	v_fma_f32 v74, -v74, v74, 1.0
	v_max_f32_e32 v74, 0, v74
	v_cmp_gt_f32_e32 vcc, s59, v74
	v_mul_f32_e32 v77, 0x4f800000, v74
	v_rcp_f32_e32 v75, v75
	v_cndmask_b32_e32 v74, v74, v77, vcc
	v_sqrt_f32_e32 v77, v74
	v_or_b32_e32 v76, s52, v119
	v_mad_u64_u32 v[104:105], s[0:1], v76, s58, v[98:99]
	v_add_u32_e32 v105, -1, v77
	v_fma_f32 v107, -v105, v77, v74
	v_cmp_ge_f32_e64 s[0:1], 0, v107
	v_add_u32_e32 v107, 1, v77
	ds_read_u16 v76, v104
	v_cndmask_b32_e64 v105, v77, v105, s[0:1]
	v_fma_f32 v77, -v107, v77, v74
	v_cmp_lt_f32_e64 s[0:1], 0, v77
	v_mfma_f32_16x16x32_bf16 v[174:177], v[66:69], v[52:55], v[174:177]
	s_waitcnt lgkmcnt(0)
; __device__ __forceinline__ bf16_t f2bf(float f) { return (bf16_t)(cvt_pk_bf16(f, 0.f) & 0xffffu); }
; __device__ __forceinline__ float bf2f(bf16_t b) { return __uint_as_float(((unsigned)b) << 16); }
; __device__ __forceinline__ float sigmoidf_(float x) { return 1.0f / (1.0f + __expf(-x)); }
; template <bool FINAL>
; __device__ __forceinline__ void lru_item(const Ctx& C, int l, int item) {
;     ...
;             for (int dt = 0; dt < 4; ++dt) {
;                 f32x4 Da = {0.f, 0.f, 0.f, 0.f}, Dx = {0.f, 0.f, 0.f, 0.f};
;                 Da = __builtin_amdgcn_mfma_f32_16x16x32_bf16(xa0, Bw[0][dt][0], Da, 0, 0, 0); Da = __builtin_amdgcn_mfma_f32_16x16x32_bf16(xa1, Bw[0][dt][1], Da, 0, 0, 0);
;                 Dx = __builtin_amdgcn_mfma_f32_16x16x32_bf16(xa0, Bw[1][dt][0], Dx, 0, 0, 0); Dx = __builtin_amdgcn_mfma_f32_16x16x32_bf16(xa1, Bw[1][dt][1], Dx, 0, 0, 0);
; #pragma unroll
;                 for (int r = 0; r < 4; ++r) { const int tloc = 4 * quad + r, d = 16 * dt + fr;
;                     const float rg = sigmoidf_(Da[r] + bav[dt]), ig = sigmoidf_(Dx[r] + bxv[dt]), la = -8.0f * rg * spv[dt], a = __expf(la);
;                     const float x = bf2f(xc[(16 * tt + tloc) * XCP + n * 64 + d]);
;                     Al[tloc * 68 + d] = a; Ul[tloc * 68 + d] = f2bf(sqrtf(fmaxf(1.0f - a * a, 0.f)) * ig * x); }
	v_lshlrev_b32_e32 v76, 16, v76
	v_cndmask_b32_e64 v77, v105, v107, s[0:1]
	v_mul_f32_e32 v105, 0x37800000, v77
	v_cndmask_b32_e32 v77, v77, v105, vcc
	v_cmp_class_f32_e32 vcc, v74, v220
	s_nop 1
	v_cndmask_b32_e32 v74, v77, v74, vcc
	v_mul_f32_e32 v74, v75, v74
	v_mul_f32_e32 v74, v74, v76
	v_cvt_pk_bf16_f32 v74, v74, s0
	ds_write_b16 v146, v74 offset:38144
	v_mfma_f32_16x16x32_bf16 v[74:77], v[70:73], v[4:7], 0
	v_mfma_f32_16x16x32_bf16 v[74:77], v[66:69], v[20:23], v[74:77]
	s_nop 7
	v_add_f32_e32 v74, v164, v74
	v_mul_f32_e32 v74, 0xbfb8aa3b, v74
	v_exp_f32_e32 v74, v74
	s_nop 0
	v_add_f32_e32 v74, 1.0, v74
	s_nop 0
	v_rcp_f32_e32 v74, v74
	v_add_f32_e32 v105, v165, v174
	v_mul_f32_e32 v105, 0xbfb8aa3b, v105
	v_exp_f32_e32 v105, v105
	v_mul_f32_e32 v74, 0xc1000000, v74
	v_mul_f32_e32 v74, v166, v74
	v_mul_f32_e32 v74, 0x3fb8aa3b, v74
	v_add_f32_e32 v105, 1.0, v105
	v_exp_f32_e32 v74, v74
	ds_write_b32 v114, v74 offset:33856
	v_fma_f32 v74, -v74, v74, 1.0
	v_max_f32_e32 v74, 0, v74
	v_cmp_gt_f32_e32 vcc, s59, v74
	v_mul_f32_e32 v109, 0x4f800000, v74
	v_rcp_f32_e32 v105, v105
	v_cndmask_b32_e32 v74, v74, v109, vcc
	v_sqrt_f32_e32 v109, v74
	ds_read_u16 v107, v110 offset:32
	v_add_u32_e32 v111, -1, v109
	v_fma_f32 v174, -v111, v109, v74
	v_cmp_ge_f32_e64 s[0:1], 0, v174
	v_add_u32_e32 v174, 1, v109
	s_waitcnt lgkmcnt(0)
	v_lshlrev_b32_e32 v107, 16, v107
	v_cndmask_b32_e64 v111, v109, v111, s[0:1]
	v_fma_f32 v109, -v174, v109, v74
	v_cmp_lt_f32_e64 s[0:1], 0, v109
	s_nop 1
	v_cndmask_b32_e64 v109, v111, v174, s[0:1]
	v_mul_f32_e32 v111, 0x37800000, v109
	v_cndmask_b32_e32 v109, v109, v111, vcc
	v_cmp_class_f32_e32 vcc, v74, v220
	s_nop 1
	v_cndmask_b32_e32 v74, v109, v74, vcc
	v_mul_f32_e32 v74, v105, v74
	v_mul_f32_e32 v74, v74, v107
	v_cvt_pk_bf16_f32 v74, v74, s0
	ds_write_b16 v121, v74 offset:38176
	v_add_f32_e32 v74, v164, v75
	v_mul_f32_e32 v74, 0xbfb8aa3b, v74
	v_exp_f32_e32 v74, v74
	s_nop 0
	v_add_f32_e32 v74, 1.0, v74
	s_nop 0
	v_rcp_f32_e32 v74, v74
	v_add_f32_e32 v75, v165, v175
	v_mul_f32_e32 v75, 0xbfb8aa3b, v75
	v_exp_f32_e32 v75, v75
	v_mul_f32_e32 v74, 0xc1000000, v74
	v_mul_f32_e32 v74, v166, v74
	v_mul_f32_e32 v74, 0x3fb8aa3b, v74
	v_add_f32_e32 v75, 1.0, v75
	v_exp_f32_e32 v74, v74
	ds_write_b32 v116, v74 offset:33856
	v_fma_f32 v74, -v74, v74, 1.0
	v_max_f32_e32 v74, 0, v74
	v_cmp_gt_f32_e32 vcc, s59, v74
	v_mul_f32_e32 v107, 0x4f800000, v74
	v_rcp_f32_e32 v75, v75
	v_cndmask_b32_e32 v74, v74, v107, vcc
	v_sqrt_f32_e32 v107, v74
	ds_read_u16 v105, v108 offset:32
	v_add_u32_e32 v109, -1, v107
	v_fma_f32 v111, -v109, v107, v74
	v_cmp_ge_f32_e64 s[0:1], 0, v111
	v_add_u32_e32 v111, 1, v107
	s_waitcnt lgkmcnt(0)
	v_lshlrev_b32_e32 v105, 16, v105
	v_cndmask_b32_e64 v109, v107, v109, s[0:1]
	v_fma_f32 v107, -v111, v107, v74
	v_cmp_lt_f32_e64 s[0:1], 0, v107
	s_nop 1
	v_cndmask_b32_e64 v107, v109, v111, s[0:1]
	v_mul_f32_e32 v109, 0x37800000, v107
	v_cndmask_b32_e32 v107, v107, v109, vcc
	v_cmp_class_f32_e32 vcc, v74, v220
	s_nop 1
	v_cndmask_b32_e32 v74, v107, v74, vcc
	v_mul_f32_e32 v74, v75, v74
	v_mul_f32_e32 v74, v74, v105
	v_cvt_pk_bf16_f32 v74, v74, s0
	ds_write_b16 v122, v74 offset:38176
	v_add_f32_e32 v74, v164, v76
	v_mul_f32_e32 v74, 0xbfb8aa3b, v74
	v_exp_f32_e32 v74, v74
	s_nop 0
	v_add_f32_e32 v74, 1.0, v74
	s_nop 0
	v_rcp_f32_e32 v74, v74
	v_add_f32_e32 v75, v165, v176
	v_mul_f32_e32 v75, 0xbfb8aa3b, v75
	v_exp_f32_e32 v75, v75
	v_mul_f32_e32 v74, 0xc1000000, v74
	v_mul_f32_e32 v74, v166, v74
	v_mul_f32_e32 v74, 0x3fb8aa3b, v74
	v_add_f32_e32 v75, 1.0, v75
	v_exp_f32_e32 v74, v74
	ds_write_b32 v118, v74 offset:33856
	v_fma_f32 v74, -v74, v74, 1.0
	v_max_f32_e32 v74, 0, v74
	v_cmp_gt_f32_e32 vcc, s59, v74
	v_mul_f32_e32 v105, 0x4f800000, v74
	v_rcp_f32_e32 v75, v75
	v_cndmask_b32_e32 v74, v74, v105, vcc
	v_sqrt_f32_e32 v105, v74
	ds_read_u16 v76, v106 offset:32
	v_add_u32_e32 v107, -1, v105
	v_fma_f32 v109, -v107, v105, v74
	v_cmp_ge_f32_e64 s[0:1], 0, v109
	v_add_u32_e32 v109, 1, v105
	s_waitcnt lgkmcnt(0)
	v_lshlrev_b32_e32 v76, 16, v76
	v_cndmask_b32_e64 v107, v105, v107, s[0:1]
	v_fma_f32 v105, -v109, v105, v74
	v_cmp_lt_f32_e64 s[0:1], 0, v105
	s_nop 1
	v_cndmask_b32_e64 v105, v107, v109, s[0:1]
	v_mul_f32_e32 v107, 0x37800000, v105
	v_cndmask_b32_e32 v105, v105, v107, vcc
	v_cmp_class_f32_e32 vcc, v74, v220
	s_nop 1
	v_cndmask_b32_e32 v74, v105, v74, vcc
	v_mul_f32_e32 v74, v75, v74
	v_mul_f32_e32 v74, v74, v76
	v_cvt_pk_bf16_f32 v74, v74, s0
	ds_write_b16 v123, v74 offset:38176
	v_add_f32_e32 v74, v164, v77
	v_mul_f32_e32 v74, 0xbfb8aa3b, v74
	v_exp_f32_e32 v74, v74
	s_nop 0
	v_add_f32_e32 v74, 1.0, v74
	s_nop 0
	v_rcp_f32_e32 v74, v74
	v_add_f32_e32 v75, v165, v177
	v_mul_f32_e32 v75, 0xbfb8aa3b, v75
	v_exp_f32_e32 v75, v75
	v_mul_f32_e32 v74, 0xc1000000, v74
	v_mul_f32_e32 v74, v166, v74
	v_mul_f32_e32 v74, 0x3fb8aa3b, v74
	v_add_f32_e32 v75, 1.0, v75
	v_exp_f32_e32 v74, v74
	v_mfma_f32_16x16x32_bf16 v[174:177], v[70:73], v[40:43], 0
	ds_write_b32 v120, v74 offset:33856
	v_fma_f32 v74, -v74, v74, 1.0
	v_max_f32_e32 v74, 0, v74
	v_cmp_gt_f32_e32 vcc, s59, v74
	v_mul_f32_e32 v77, 0x4f800000, v74
	v_rcp_f32_e32 v75, v75
	v_cndmask_b32_e32 v74, v74, v77, vcc
	v_sqrt_f32_e32 v77, v74
	ds_read_u16 v76, v104 offset:32
	v_mfma_f32_16x16x32_bf16 v[174:177], v[66:69], v[56:59], v[174:177]
	v_add_u32_e32 v105, -1, v77
	v_fma_f32 v107, -v105, v77, v74
	v_cmp_ge_f32_e64 s[0:1], 0, v107
	v_add_u32_e32 v107, 1, v77
	s_waitcnt lgkmcnt(0)
; __device__ __forceinline__ bf16_t f2bf(float f) { return (bf16_t)(cvt_pk_bf16(f, 0.f) & 0xffffu); }
; __device__ __forceinline__ float bf2f(bf16_t b) { return __uint_as_float(((unsigned)b) << 16); }
; __device__ __forceinline__ float sigmoidf_(float x) { return 1.0f / (1.0f + __expf(-x)); }
; template <bool FINAL>
; __device__ __forceinline__ void lru_item(const Ctx& C, int l, int item) {
;     ...
;             for (int dt = 0; dt < 4; ++dt) {
;                 f32x4 Da = {0.f, 0.f, 0.f, 0.f}, Dx = {0.f, 0.f, 0.f, 0.f};
;                 Da = __builtin_amdgcn_mfma_f32_16x16x32_bf16(xa0, Bw[0][dt][0], Da, 0, 0, 0); Da = __builtin_amdgcn_mfma_f32_16x16x32_bf16(xa1, Bw[0][dt][1], Da, 0, 0, 0);
;                 Dx = __builtin_amdgcn_mfma_f32_16x16x32_bf16(xa0, Bw[1][dt][0], Dx, 0, 0, 0); Dx = __builtin_amdgcn_mfma_f32_16x16x32_bf16(xa1, Bw[1][dt][1], Dx, 0, 0, 0);
; #pragma unroll
;                 for (int r = 0; r < 4; ++r) { const int tloc = 4 * quad + r, d = 16 * dt + fr;
;                     const float rg = sigmoidf_(Da[r] + bav[dt]), ig = sigmoidf_(Dx[r] + bxv[dt]), la = -8.0f * rg * spv[dt], a = __expf(la);
;                     const float x = bf2f(xc[(16 * tt + tloc) * XCP + n * 64 + d]);
;                     Al[tloc * 68 + d] = a; Ul[tloc * 68 + d] = f2bf(sqrtf(fmaxf(1.0f - a * a, 0.f)) * ig * x); }
	v_lshlrev_b32_e32 v76, 16, v76
	v_cndmask_b32_e64 v105, v77, v105, s[0:1]
	v_fma_f32 v77, -v107, v77, v74
	v_cmp_lt_f32_e64 s[0:1], 0, v77
	s_nop 1
	v_cndmask_b32_e64 v77, v105, v107, s[0:1]
	v_mul_f32_e32 v105, 0x37800000, v77
	v_cndmask_b32_e32 v77, v77, v105, vcc
	v_cmp_class_f32_e32 vcc, v74, v220
	s_nop 1
	v_cndmask_b32_e32 v74, v77, v74, vcc
	v_mul_f32_e32 v74, v75, v74
	v_mul_f32_e32 v74, v74, v76
	v_cvt_pk_bf16_f32 v74, v74, s0
	ds_write_b16 v124, v74 offset:38176
	v_mfma_f32_16x16x32_bf16 v[74:77], v[70:73], v[8:11], 0
	v_mfma_f32_16x16x32_bf16 v[74:77], v[66:69], v[24:27], v[74:77]
	s_nop 7
	v_add_f32_e32 v74, v167, v74
	v_mul_f32_e32 v74, 0xbfb8aa3b, v74
	v_exp_f32_e32 v74, v74
	s_nop 0
	v_add_f32_e32 v74, 1.0, v74
	s_nop 0
	v_rcp_f32_e32 v74, v74
	v_add_f32_e32 v105, v168, v174
	v_mul_f32_e32 v105, 0xbfb8aa3b, v105
	v_exp_f32_e32 v105, v105
	v_mul_f32_e32 v74, 0xc1000000, v74
	v_mul_f32_e32 v74, v169, v74
	v_mul_f32_e32 v74, 0x3fb8aa3b, v74
	v_add_f32_e32 v105, 1.0, v105
	v_exp_f32_e32 v74, v74
	ds_write_b32 v114, v74 offset:33920
	v_fma_f32 v74, -v74, v74, 1.0
	v_max_f32_e32 v74, 0, v74
	v_cmp_gt_f32_e32 vcc, s59, v74
	v_mul_f32_e32 v109, 0x4f800000, v74
	v_rcp_f32_e32 v105, v105
	v_cndmask_b32_e32 v74, v74, v109, vcc
	v_sqrt_f32_e32 v109, v74
	ds_read_u16 v107, v110 offset:64
	v_add_u32_e32 v111, -1, v109
	v_fma_f32 v174, -v111, v109, v74
	v_cmp_ge_f32_e64 s[0:1], 0, v174
	v_add_u32_e32 v174, 1, v109
	s_waitcnt lgkmcnt(0)
	v_lshlrev_b32_e32 v107, 16, v107
	v_cndmask_b32_e64 v111, v109, v111, s[0:1]
	v_fma_f32 v109, -v174, v109, v74
	v_cmp_lt_f32_e64 s[0:1], 0, v109
	s_nop 1
	v_cndmask_b32_e64 v109, v111, v174, s[0:1]
	v_mul_f32_e32 v111, 0x37800000, v109
	v_cndmask_b32_e32 v109, v109, v111, vcc
	v_cmp_class_f32_e32 vcc, v74, v220
	s_nop 1
	v_cndmask_b32_e32 v74, v109, v74, vcc
	v_mul_f32_e32 v74, v105, v74
	v_mul_f32_e32 v74, v74, v107
	v_cvt_pk_bf16_f32 v74, v74, s0
	ds_write_b16 v121, v74 offset:38208
	v_add_f32_e32 v74, v167, v75
	v_mul_f32_e32 v74, 0xbfb8aa3b, v74
	v_exp_f32_e32 v74, v74
	s_nop 0
	v_add_f32_e32 v74, 1.0, v74
	s_nop 0
	v_rcp_f32_e32 v74, v74
	v_add_f32_e32 v75, v168, v175
	v_mul_f32_e32 v75, 0xbfb8aa3b, v75
	v_exp_f32_e32 v75, v75
	v_mul_f32_e32 v74, 0xc1000000, v74
	v_mul_f32_e32 v74, v169, v74
	v_mul_f32_e32 v74, 0x3fb8aa3b, v74
	v_add_f32_e32 v75, 1.0, v75
	v_exp_f32_e32 v74, v74
	ds_write_b32 v116, v74 offset:33920
	v_fma_f32 v74, -v74, v74, 1.0
	v_max_f32_e32 v74, 0, v74
	v_cmp_gt_f32_e32 vcc, s59, v74
	v_mul_f32_e32 v107, 0x4f800000, v74
	v_rcp_f32_e32 v75, v75
	v_cndmask_b32_e32 v74, v74, v107, vcc
	v_sqrt_f32_e32 v107, v74
	ds_read_u16 v105, v108 offset:64
	v_add_u32_e32 v109, -1, v107
	v_fma_f32 v111, -v109, v107, v74
	v_cmp_ge_f32_e64 s[0:1], 0, v111
	v_add_u32_e32 v111, 1, v107
	s_waitcnt lgkmcnt(0)
	v_lshlrev_b32_e32 v105, 16, v105
	v_cndmask_b32_e64 v109, v107, v109, s[0:1]
	v_fma_f32 v107, -v111, v107, v74
	v_cmp_lt_f32_e64 s[0:1], 0, v107
	s_nop 1
	v_cndmask_b32_e64 v107, v109, v111, s[0:1]
	v_mul_f32_e32 v109, 0x37800000, v107
	v_cndmask_b32_e32 v107, v107, v109, vcc
	v_cmp_class_f32_e32 vcc, v74, v220
	s_nop 1
	v_cndmask_b32_e32 v74, v107, v74, vcc
	v_mul_f32_e32 v74, v75, v74
	v_mul_f32_e32 v74, v74, v105
	v_cvt_pk_bf16_f32 v74, v74, s0
	ds_write_b16 v122, v74 offset:38208
	v_add_f32_e32 v74, v167, v76
	v_mul_f32_e32 v74, 0xbfb8aa3b, v74
	v_exp_f32_e32 v74, v74
	s_nop 0
	v_add_f32_e32 v74, 1.0, v74
	s_nop 0
	v_rcp_f32_e32 v74, v74
	v_add_f32_e32 v75, v168, v176
	v_mul_f32_e32 v75, 0xbfb8aa3b, v75
	v_exp_f32_e32 v75, v75
	v_mul_f32_e32 v74, 0xc1000000, v74
	v_mul_f32_e32 v74, v169, v74
	v_mul_f32_e32 v74, 0x3fb8aa3b, v74
	v_add_f32_e32 v75, 1.0, v75
	v_exp_f32_e32 v74, v74
	ds_write_b32 v118, v74 offset:33920
	v_fma_f32 v74, -v74, v74, 1.0
	v_max_f32_e32 v74, 0, v74
	v_cmp_gt_f32_e32 vcc, s59, v74
	v_mul_f32_e32 v105, 0x4f800000, v74
	v_rcp_f32_e32 v75, v75
	v_cndmask_b32_e32 v74, v74, v105, vcc
	v_sqrt_f32_e32 v105, v74
	ds_read_u16 v76, v106 offset:64
	v_add_u32_e32 v107, -1, v105
	v_fma_f32 v109, -v107, v105, v74
	v_cmp_ge_f32_e64 s[0:1], 0, v109
	v_add_u32_e32 v109, 1, v105
	s_waitcnt lgkmcnt(0)
	v_lshlrev_b32_e32 v76, 16, v76
	v_cndmask_b32_e64 v107, v105, v107, s[0:1]
	v_fma_f32 v105, -v109, v105, v74
	v_cmp_lt_f32_e64 s[0:1], 0, v105
	s_nop 1
	v_cndmask_b32_e64 v105, v107, v109, s[0:1]
	v_mul_f32_e32 v107, 0x37800000, v105
	v_cndmask_b32_e32 v105, v105, v107, vcc
	v_cmp_class_f32_e32 vcc, v74, v220
	s_nop 1
	v_cndmask_b32_e32 v74, v105, v74, vcc
	v_mul_f32_e32 v74, v75, v74
	v_mul_f32_e32 v74, v74, v76
	v_cvt_pk_bf16_f32 v74, v74, s0
	ds_write_b16 v123, v74 offset:38208
	v_add_f32_e32 v74, v167, v77
	v_mul_f32_e32 v74, 0xbfb8aa3b, v74
	v_exp_f32_e32 v74, v74
	s_nop 0
	v_add_f32_e32 v74, 1.0, v74
	s_nop 0
	v_rcp_f32_e32 v74, v74
	v_add_f32_e32 v75, v168, v177
	v_mul_f32_e32 v75, 0xbfb8aa3b, v75
	v_exp_f32_e32 v75, v75
	v_mul_f32_e32 v74, 0xc1000000, v74
	v_mul_f32_e32 v74, v169, v74
	v_mul_f32_e32 v74, 0x3fb8aa3b, v74
	v_add_f32_e32 v75, 1.0, v75
	v_exp_f32_e32 v74, v74
	ds_write_b32 v120, v74 offset:33920
	v_fma_f32 v74, -v74, v74, 1.0
	v_max_f32_e32 v74, 0, v74
	v_cmp_gt_f32_e32 vcc, s59, v74
	v_mul_f32_e32 v77, 0x4f800000, v74
	v_rcp_f32_e32 v75, v75
	v_cndmask_b32_e32 v74, v74, v77, vcc
	v_sqrt_f32_e32 v77, v74
	ds_read_u16 v76, v104 offset:64
	v_add_u32_e32 v105, -1, v77
	v_fma_f32 v107, -v105, v77, v74
	v_cmp_ge_f32_e64 s[0:1], 0, v107
	v_add_u32_e32 v107, 1, v77
	s_waitcnt lgkmcnt(0)
; __device__ __forceinline__ bf16_t f2bf(float f) { return (bf16_t)(cvt_pk_bf16(f, 0.f) & 0xffffu); }
; __device__ __forceinline__ float bf2f(bf16_t b) { return __uint_as_float(((unsigned)b) << 16); }
; __device__ __forceinline__ float sigmoidf_(float x) { return 1.0f / (1.0f + __expf(-x)); }
; template <bool FINAL>
; __device__ __forceinline__ void lru_item(const Ctx& C, int l, int item) {
;     ...
;             for (int dt = 0; dt < 4; ++dt) {
;                 f32x4 Da = {0.f, 0.f, 0.f, 0.f}, Dx = {0.f, 0.f, 0.f, 0.f};
;                 Da = __builtin_amdgcn_mfma_f32_16x16x32_bf16(xa0, Bw[0][dt][0], Da, 0, 0, 0); Da = __builtin_amdgcn_mfma_f32_16x16x32_bf16(xa1, Bw[0][dt][1], Da, 0, 0, 0);
;                 Dx = __builtin_amdgcn_mfma_f32_16x16x32_bf16(xa0, Bw[1][dt][0], Dx, 0, 0, 0); Dx = __builtin_amdgcn_mfma_f32_16x16x32_bf16(xa1, Bw[1][dt][1], Dx, 0, 0, 0);
; #pragma unroll
;                 for (int r = 0; r < 4; ++r) { const int tloc = 4 * quad + r, d = 16 * dt + fr;
;                     const float rg = sigmoidf_(Da[r] + bav[dt]), ig = sigmoidf_(Dx[r] + bxv[dt]), la = -8.0f * rg * spv[dt], a = __expf(la);
;                     const float x = bf2f(xc[(16 * tt + tloc) * XCP + n * 64 + d]);
;                     Al[tloc * 68 + d] = a; Ul[tloc * 68 + d] = f2bf(sqrtf(fmaxf(1.0f - a * a, 0.f)) * ig * x); }
	v_lshlrev_b32_e32 v76, 16, v76
	v_cndmask_b32_e64 v105, v77, v105, s[0:1]
	v_fma_f32 v77, -v107, v77, v74
	v_cmp_lt_f32_e64 s[0:1], 0, v77
	s_nop 1
	v_cndmask_b32_e64 v77, v105, v107, s[0:1]
	v_mul_f32_e32 v105, 0x37800000, v77
	v_cndmask_b32_e32 v77, v77, v105, vcc
	v_cmp_class_f32_e32 vcc, v74, v220
	s_nop 1
	v_cndmask_b32_e32 v74, v77, v74, vcc
	v_mul_f32_e32 v74, v75, v74
	v_mul_f32_e32 v74, v74, v76
	v_cvt_pk_bf16_f32 v74, v74, s0
	ds_write_b16 v124, v74 offset:38208
	v_mfma_f32_16x16x32_bf16 v[74:77], v[70:73], v[12:15], 0
	v_mfma_f32_16x16x32_bf16 v[74:77], v[66:69], v[28:31], v[74:77]
	v_mfma_f32_16x16x32_bf16 v[70:73], v[70:73], v[44:47], 0
	v_mfma_f32_16x16x32_bf16 v[66:69], v[66:69], v[60:63], v[70:73]
	s_waitcnt vmcnt(2)
	s_nop 5
	v_add_f32_e32 v70, v170, v74
	v_mul_f32_e32 v70, 0xbfb8aa3b, v70
	v_exp_f32_e32 v70, v70
	s_waitcnt vmcnt(1)
	v_add_f32_e32 v66, v171, v66
	v_mul_f32_e32 v66, 0xbfb8aa3b, v66
	v_exp_f32_e32 v66, v66
	v_add_f32_e32 v70, 1.0, v70
	v_add_f32_e32 v66, 1.0, v66
	v_add_f32_e32 v67, v171, v67
	v_mul_f32_e32 v67, 0xbfb8aa3b, v67
	v_rcp_f32_e32 v70, v70
	s_nop 0
	v_mul_f32_e32 v70, 0xc1000000, v70
	v_mul_f32_e32 v70, v172, v70
	v_mul_f32_e32 v70, 0x3fb8aa3b, v70
	v_exp_f32_e32 v70, v70
	ds_write_b32 v114, v70 offset:33984
	v_fma_f32 v70, -v70, v70, 1.0
	v_max_f32_e32 v70, 0, v70
	v_cmp_gt_f32_e32 vcc, s59, v70
	v_mul_f32_e32 v72, 0x4f800000, v70
	v_rcp_f32_e32 v66, v66
	v_cndmask_b32_e32 v70, v70, v72, vcc
	v_sqrt_f32_e32 v72, v70
	ds_read_u16 v71, v110 offset:96
	v_exp_f32_e32 v67, v67
	v_add_u32_e32 v73, -1, v72
	v_fma_f32 v74, -v73, v72, v70
	v_cmp_ge_f32_e64 s[0:1], 0, v74
	v_add_u32_e32 v74, 1, v72
	s_waitcnt lgkmcnt(0)
	v_lshlrev_b32_e32 v71, 16, v71
	v_cndmask_b32_e64 v73, v72, v73, s[0:1]
	v_fma_f32 v72, -v74, v72, v70
	v_cmp_lt_f32_e64 s[0:1], 0, v72
	v_add_f32_e32 v67, 1.0, v67
	s_nop 0
	v_cndmask_b32_e64 v72, v73, v74, s[0:1]
	v_mul_f32_e32 v73, 0x37800000, v72
	v_cndmask_b32_e32 v72, v72, v73, vcc
	v_cmp_class_f32_e32 vcc, v70, v220
	s_nop 1
	v_cndmask_b32_e32 v70, v72, v70, vcc
	v_mul_f32_e32 v66, v66, v70
	v_mul_f32_e32 v66, v66, v71
	v_cvt_pk_bf16_f32 v66, v66, s0
	ds_write_b16 v121, v66 offset:38240
	v_add_f32_e32 v66, v170, v75
	v_mul_f32_e32 v66, 0xbfb8aa3b, v66
	v_exp_f32_e32 v66, v66
	s_nop 0
	v_add_f32_e32 v66, 1.0, v66
	s_nop 0
	v_rcp_f32_e32 v66, v66
	s_nop 0
	v_mul_f32_e32 v66, 0xc1000000, v66
	v_mul_f32_e32 v66, v172, v66
	v_mul_f32_e32 v66, 0x3fb8aa3b, v66
	v_exp_f32_e32 v66, v66
	ds_write_b32 v116, v66 offset:33984
	v_fma_f32 v66, -v66, v66, 1.0
	v_max_f32_e32 v66, 0, v66
	v_cmp_gt_f32_e32 vcc, s59, v66
	v_mul_f32_e32 v71, 0x4f800000, v66
	v_rcp_f32_e32 v67, v67
	v_cndmask_b32_e32 v66, v66, v71, vcc
	v_sqrt_f32_e32 v71, v66
	ds_read_u16 v70, v108 offset:96
	v_add_u32_e32 v72, -1, v71
	v_fma_f32 v73, -v72, v71, v66
	v_cmp_ge_f32_e64 s[0:1], 0, v73
	v_add_u32_e32 v73, 1, v71
	s_waitcnt lgkmcnt(0)
	v_lshlrev_b32_e32 v70, 16, v70
	v_cndmask_b32_e64 v72, v71, v72, s[0:1]
	v_fma_f32 v71, -v73, v71, v66
	v_cmp_lt_f32_e64 s[0:1], 0, v71
	s_nop 1
	v_cndmask_b32_e64 v71, v72, v73, s[0:1]
	v_mul_f32_e32 v72, 0x37800000, v71
	v_cndmask_b32_e32 v71, v71, v72, vcc
	v_cmp_class_f32_e32 vcc, v66, v220
	s_nop 1
	v_cndmask_b32_e32 v66, v71, v66, vcc
	v_mul_f32_e32 v66, v67, v66
	v_mul_f32_e32 v66, v66, v70
	v_cvt_pk_bf16_f32 v66, v66, s0
	ds_write_b16 v122, v66 offset:38240
	v_add_f32_e32 v66, v170, v76
	v_mul_f32_e32 v66, 0xbfb8aa3b, v66
	v_exp_f32_e32 v66, v66
	s_nop 0
	v_add_f32_e32 v66, 1.0, v66
	s_nop 0
	v_rcp_f32_e32 v66, v66
	v_add_f32_e32 v67, v171, v68
	v_mul_f32_e32 v67, 0xbfb8aa3b, v67
	v_exp_f32_e32 v67, v67
	v_mul_f32_e32 v66, 0xc1000000, v66
	v_mul_f32_e32 v66, v172, v66
	v_mul_f32_e32 v66, 0x3fb8aa3b, v66
	v_add_f32_e32 v67, 1.0, v67
	v_exp_f32_e32 v66, v66
	ds_write_b32 v118, v66 offset:33984
	v_fma_f32 v66, -v66, v66, 1.0
	v_max_f32_e32 v66, 0, v66
	v_cmp_gt_f32_e32 vcc, s59, v66
	v_mul_f32_e32 v70, 0x4f800000, v66
	v_rcp_f32_e32 v67, v67
	v_cndmask_b32_e32 v66, v66, v70, vcc
	v_sqrt_f32_e32 v70, v66
	ds_read_u16 v68, v106 offset:96
	v_add_u32_e32 v71, -1, v70
	v_fma_f32 v72, -v71, v70, v66
	v_cmp_ge_f32_e64 s[0:1], 0, v72
	v_add_u32_e32 v72, 1, v70
	s_waitcnt lgkmcnt(0)
	v_lshlrev_b32_e32 v68, 16, v68
	v_cndmask_b32_e64 v71, v70, v71, s[0:1]
	v_fma_f32 v70, -v72, v70, v66
	v_cmp_lt_f32_e64 s[0:1], 0, v70
	s_nop 1
	v_cndmask_b32_e64 v70, v71, v72, s[0:1]
	v_mul_f32_e32 v71, 0x37800000, v70
	v_cndmask_b32_e32 v70, v70, v71, vcc
	v_cmp_class_f32_e32 vcc, v66, v220
	s_nop 1
	v_cndmask_b32_e32 v66, v70, v66, vcc
	v_mul_f32_e32 v66, v67, v66
	v_mul_f32_e32 v66, v66, v68
	v_cvt_pk_bf16_f32 v66, v66, s0
	ds_write_b16 v123, v66 offset:38240
	v_add_f32_e32 v66, v170, v77
	v_mul_f32_e32 v66, 0xbfb8aa3b, v66
	v_exp_f32_e32 v66, v66
	s_nop 0
	v_add_f32_e32 v66, 1.0, v66
	s_nop 0
	v_rcp_f32_e32 v66, v66
	v_add_f32_e32 v67, v171, v69
	v_mul_f32_e32 v67, 0xbfb8aa3b, v67
	v_exp_f32_e32 v67, v67
	v_mul_f32_e32 v66, 0xc1000000, v66
	v_mul_f32_e32 v66, v172, v66
	v_mul_f32_e32 v66, 0x3fb8aa3b, v66
	v_add_f32_e32 v67, 1.0, v67
	v_exp_f32_e32 v66, v66
	ds_write_b32 v120, v66 offset:33984
	v_fma_f32 v66, -v66, v66, 1.0
	v_max_f32_e32 v66, 0, v66
	v_cmp_gt_f32_e32 vcc, s59, v66
	v_mul_f32_e32 v69, 0x4f800000, v66
	v_rcp_f32_e32 v67, v67
	v_cndmask_b32_e32 v66, v66, v69, vcc
	v_sqrt_f32_e32 v69, v66
	ds_read_u16 v68, v104 offset:96
	v_add_u32_e32 v70, -1, v69
	v_fma_f32 v71, -v70, v69, v66
	v_cmp_ge_f32_e64 s[0:1], 0, v71
	v_add_u32_e32 v71, 1, v69
	s_waitcnt lgkmcnt(0)
; __device__ __forceinline__ bf16_t f2bf(float f) { return (bf16_t)(cvt_pk_bf16(f, 0.f) & 0xffffu); }
; __device__ __forceinline__ float bf2f(bf16_t b) { return __uint_as_float(((unsigned)b) << 16); }
; __device__ __forceinline__ void wave_lds_fence() { asm volatile("s_waitcnt lgkmcnt(0)" ::: "memory"); __builtin_amdgcn_wave_barrier(); }
;     __device__ __forceinline__ bf16_t* bfp(size_t off) const { return (bf16_t*)(ws + off); }
;     __device__ __forceinline__ float* fp(size_t off) const { return (float*)(ws + off); }
; template <bool FINAL>
; __device__ __forceinline__ void lru_item(const Ctx& C, int l, int item) {
;     ...
;             wave_lds_fence();
; #pragma unroll
;             for (int j = 0; j < 16; ++j) { const int tloc = z ? 15 - j : j;
;                 const float a = Al[tloc * 68 + lane], u = bf2f(Ul[tloc * 68 + lane]);
;                 h = fmaf(a, h, u); Ap *= a;
;                 if (FINAL) Hz[(16 * tt + tloc) * 256 + n * 64 + lane] = f2bf(h); }
;             wave_lds_fence();
;         }
;         if (!FINAL) { C.fp(OFF_CARA)[cidx] = Ap; C.fp(OFF_CARH)[cidx] = h; }
;     }
;     if (FINAL) {
;         __syncthreads();
;         int ch = tid & 255; asm volatile("" : "+v"(ch)); const int zz = tid >> 8;
;         const bf16_t* gp = pb + (size_t)(b * SEQ + c * 64) * 512 + 256 + ch; bf16_t* yb = C.bfp(OFF_YB) + (size_t)(b * SEQ + c * 64) * 256 + ch;
	v_lshlrev_b32_e32 v68, 16, v68
	v_cndmask_b32_e64 v70, v69, v70, s[0:1]
	v_fma_f32 v69, -v71, v69, v66
	v_cmp_lt_f32_e64 s[0:1], 0, v69
	s_nop 1
	v_cndmask_b32_e64 v69, v70, v71, s[0:1]
	v_mul_f32_e32 v70, 0x37800000, v69
	v_cndmask_b32_e32 v69, v69, v70, vcc
	v_cmp_class_f32_e32 vcc, v66, v220
	s_nop 1
	v_cndmask_b32_e32 v66, v69, v66, vcc
	v_mul_f32_e32 v66, v67, v66
	v_mul_f32_e32 v66, v66, v68
	v_cvt_pk_bf16_f32 v66, v66, s0
	ds_write_b16 v124, v66 offset:38240
	s_waitcnt lgkmcnt(0)
	ds_read_b32 v67, v113 offset:33792
	ds_read_u16 v66, v125 offset:38144
	s_waitcnt lgkmcnt(0)
	v_lshlrev_b32_e32 v66, 16, v66
	s_waitcnt vmcnt(0)
	v_fmac_f32_e32 v66, v67, v173
	v_cvt_pk_bf16_f32 v67, v66, s0
	s_or_b32 s0, s52, s13
	v_lshl_add_u32 v68, s0, 9, v141
	ds_write_b16 v68, v67
	ds_read_b32 v68, v126 offset:33792
	ds_read_u16 v67, v147 offset:38144
	s_waitcnt lgkmcnt(0)
	v_lshlrev_b32_e32 v67, 16, v67
	v_fmac_f32_e32 v67, v68, v66
	v_cvt_pk_bf16_f32 v66, v67, s0
	s_or_b32 s0, s52, s14
	v_lshl_add_u32 v68, s0, 9, v141
	ds_write_b16 v68, v66
	ds_read_b32 v66, v127 offset:33792
	ds_read_u16 v68, v148 offset:38144
	s_waitcnt lgkmcnt(0)
	v_lshlrev_b32_e32 v68, 16, v68
	v_fmac_f32_e32 v68, v66, v67
	v_cvt_pk_bf16_f32 v66, v68, s0
	s_or_b32 s0, s52, s15
	v_lshl_add_u32 v67, s0, 9, v141
	ds_write_b16 v67, v66
	ds_read_b32 v66, v128 offset:33792
	ds_read_u16 v67, v149 offset:38144
	s_waitcnt lgkmcnt(0)
	v_lshlrev_b32_e32 v67, 16, v67
	v_fmac_f32_e32 v67, v66, v68
	v_cvt_pk_bf16_f32 v66, v67, s0
	s_or_b32 s0, s52, s16
	v_lshl_add_u32 v68, s0, 9, v141
	ds_write_b16 v68, v66
	ds_read_b32 v66, v129 offset:33792
	ds_read_u16 v68, v150 offset:38144
	s_waitcnt lgkmcnt(0)
	v_lshlrev_b32_e32 v68, 16, v68
	v_fmac_f32_e32 v68, v66, v67
	v_cvt_pk_bf16_f32 v66, v68, s0
	s_or_b32 s0, s52, s17
	v_lshl_add_u32 v67, s0, 9, v141
	ds_write_b16 v67, v66
	ds_read_b32 v66, v130 offset:33792
	ds_read_u16 v67, v151 offset:38144
	s_waitcnt lgkmcnt(0)
	v_lshlrev_b32_e32 v67, 16, v67
	v_fmac_f32_e32 v67, v66, v68
	v_cvt_pk_bf16_f32 v66, v67, s0
	s_or_b32 s0, s52, s18
	v_lshl_add_u32 v68, s0, 9, v141
	ds_write_b16 v68, v66
	ds_read_b32 v66, v131 offset:33792
	ds_read_u16 v68, v152 offset:38144
	s_waitcnt lgkmcnt(0)
	v_lshlrev_b32_e32 v68, 16, v68
	v_fmac_f32_e32 v68, v66, v67
	v_cvt_pk_bf16_f32 v66, v68, s0
	s_or_b32 s0, s52, s19
	v_lshl_add_u32 v67, s0, 9, v141
	ds_write_b16 v67, v66
	ds_read_b32 v66, v132 offset:33792
	ds_read_u16 v67, v153 offset:38144
	s_waitcnt lgkmcnt(0)
	v_lshlrev_b32_e32 v67, 16, v67
	v_fmac_f32_e32 v67, v66, v68
	v_cvt_pk_bf16_f32 v66, v67, s0
	s_or_b32 s0, s52, s20
	v_lshl_add_u32 v68, s0, 9, v141
	ds_write_b16 v68, v66
	ds_read_b32 v66, v133 offset:33792
	ds_read_u16 v68, v154 offset:38144
	s_waitcnt lgkmcnt(0)
	v_lshlrev_b32_e32 v68, 16, v68
	v_fmac_f32_e32 v68, v66, v67
	v_cvt_pk_bf16_f32 v66, v68, s0
	s_or_b32 s0, s52, s21
	v_lshl_add_u32 v67, s0, 9, v141
	ds_write_b16 v67, v66
	ds_read_b32 v66, v134 offset:33792
	ds_read_u16 v67, v155 offset:38144
	s_waitcnt lgkmcnt(0)
	v_lshlrev_b32_e32 v67, 16, v67
	v_fmac_f32_e32 v67, v66, v68
	v_cvt_pk_bf16_f32 v66, v67, s0
	s_or_b32 s0, s52, s36
	v_lshl_add_u32 v68, s0, 9, v141
	ds_write_b16 v68, v66
	ds_read_b32 v66, v135 offset:33792
	ds_read_u16 v68, v156 offset:38144
	s_waitcnt lgkmcnt(0)
	v_lshlrev_b32_e32 v68, 16, v68
	v_fmac_f32_e32 v68, v66, v67
	v_cvt_pk_bf16_f32 v66, v68, s0
	s_or_b32 s0, s52, s38
	v_lshl_add_u32 v67, s0, 9, v141
	ds_write_b16 v67, v66
	ds_read_b32 v66, v136 offset:33792
	ds_read_u16 v67, v157 offset:38144
	s_waitcnt lgkmcnt(0)
	v_lshlrev_b32_e32 v67, 16, v67
	v_fmac_f32_e32 v67, v66, v68
	v_cvt_pk_bf16_f32 v66, v67, s0
	s_or_b32 s0, s52, s39
	v_lshl_add_u32 v68, s0, 9, v141
	ds_write_b16 v68, v66
	ds_read_b32 v66, v137 offset:33792
	ds_read_u16 v68, v158 offset:38144
	s_waitcnt lgkmcnt(0)
	v_lshlrev_b32_e32 v68, 16, v68
	v_fmac_f32_e32 v68, v66, v67
	v_cvt_pk_bf16_f32 v66, v68, s0
	s_or_b32 s0, s52, s42
	v_lshl_add_u32 v67, s0, 9, v141
	ds_write_b16 v67, v66
	ds_read_b32 v66, v138 offset:33792
	ds_read_u16 v67, v159 offset:38144
	s_waitcnt lgkmcnt(0)
	v_lshlrev_b32_e32 v67, 16, v67
	v_fmac_f32_e32 v67, v66, v68
	v_cvt_pk_bf16_f32 v66, v67, s0
	s_or_b32 s0, s52, s43
	v_lshl_add_u32 v68, s0, 9, v141
	ds_write_b16 v68, v66
	ds_read_b32 v68, v139 offset:33792
	ds_read_u16 v66, v160 offset:38144
	s_waitcnt lgkmcnt(0)
	v_lshlrev_b32_e32 v66, 16, v66
	v_fmac_f32_e32 v66, v68, v67
	v_cvt_pk_bf16_f32 v67, v66, s0
	s_or_b32 s0, s52, s44
	v_lshl_add_u32 v68, s0, 9, v141
	ds_write_b16 v68, v67
	ds_read_b32 v67, v140 offset:33792
	ds_read_u16 v68, v161 offset:38144
	s_waitcnt lgkmcnt(0)
	v_lshlrev_b32_e32 v173, 16, v68
	v_fmac_f32_e32 v173, v67, v66
	v_cvt_pk_bf16_f32 v66, v173, s0
	s_or_b32 s0, s52, s45
	v_lshl_add_u32 v67, s0, 9, v141
	ds_write_b16 v67, v66
	s_waitcnt lgkmcnt(0)
	s_cmp_eq_u32 s9, 4
	s_cbranch_scc0 .LBB0_681
	s_add_i32 s0, s8, s49
	s_ashr_i32 s1, s0, 31
	v_mov_b32_e32 v4, v99
	s_lshl_b64 s[8:9], s[0:1], 10
	s_lshl_b64 s[0:1], s[0:1], 9
	s_waitcnt lgkmcnt(0)
	s_barrier
	v_lshl_add_u64 v[0:1], v[100:101], 0, s[8:9]
	v_ashrrev_i32_e32 v5, 31, v4
	v_lshl_add_u64 v[2:3], v[102:103], 0, s[0:1]
	v_lshl_add_u32 v8, v4, 1, v143
	v_lshlrev_b64 v[4:5], 1, v[4:5]
	s_mov_b32 s0, 0
; __device__ __forceinline__ bf16_t f2bf(float f) { return (bf16_t)(cvt_pk_bf16(f, 0.f) & 0xffffu); }
; __device__ __forceinline__ float bf2f(bf16_t b) { return __uint_as_float(((unsigned)b) << 16); }
; __device__ __forceinline__ float geluf_(float x) { const float y = 0.7978845608028654f * (x + 0.044715f * x * x * x); const float t = 1.0f - 2.0f / (1.0f + __expf(2.0f * y)); return 0.5f * x * (1.0f + t); }
; template <bool FINAL>
; __device__ __forceinline__ void lru_item(const Ctx& C, int l, int item) {
;     ...
;         for (int k8 = 0; k8 < 4; ++k8) { bf16_t gv_[8];
; #pragma unroll
;             for (int k = 0; k < 8; ++k) gv_[k] = gp[(size_t)(zz * 32 + k8 * 8 + k) * 512];
; #pragma unroll
;             for (int k = 0; k < 8; ++k) { const int tl = zz * 32 + k8 * 8 + k; const float hs = bf2f(H0[tl * 256 + ch]) + bf2f(H1[tl * 256 + ch]);
;                 yb[(size_t)tl * 256] = f2bf(hs * geluf_(bf2f(gv_[k]))); } }
.LBB0_683:
	v_add_u32_e32 v9, s0, v8
	v_add_u32_e32 v6, 0x15000, v9
	v_add_u32_e32 v7, 0x1d000, v9
	ds_read_u16 v6, v6
	ds_read_u16 v7, v7
	v_lshl_add_u64 v[10:11], v[0:1], 0, v[4:5]
	v_add_co_u32_e32 v12, vcc, 0xc000000, v10
	s_waitcnt lgkmcnt(1)
	v_lshlrev_b32_e32 v6, 16, v6
	s_waitcnt lgkmcnt(0)
	v_lshlrev_b32_e32 v7, 16, v7
	v_addc_co_u32_e32 v13, vcc, 0, v11, vcc
	v_add_f32_e32 v6, v6, v7
	global_load_ushort v7, v[12:13], off offset:512
	s_mov_b32 s1, 0xc001000
	v_lshl_add_u64 v[0:1], v[0:1], 0, s[30:31]
	s_waitcnt vmcnt(0)
	v_lshlrev_b32_e32 v7, 16, v7
	v_mul_f32_e32 v14, 0x3d372713, v7
	v_mul_f32_e32 v14, v14, v7
	v_fma_f32 v14, v14, v7, v7
	v_mul_f32_e32 v14, 0x3f4c422a, v14
	v_add_f32_e32 v14, v14, v14
	v_mul_f32_e32 v14, 0x3fb8aa3b, v14
	v_exp_f32_e32 v14, v14
	v_mul_f32_e32 v7, 0.5, v7
	v_add_f32_e32 v14, 1.0, v14
	s_nop 0
	v_rcp_f32_e32 v15, v14
	s_nop 0
	v_mul_f32_e32 v14, 2.0, v15
	global_load_ushort v15, v[12:13], off offset:1536
	global_load_ushort v16, v[12:13], off offset:2560
	s_nop 0
	global_load_ushort v12, v[12:13], off offset:3584
	v_sub_f32_e32 v14, 1.0, v14
	v_add_f32_e32 v14, 1.0, v14
	v_mul_f32_e32 v7, v7, v14
	v_mul_f32_e32 v6, v6, v7
	v_add_co_u32_e32 v10, vcc, s1, v10
	v_cvt_pk_bf16_f32 v14, v6, s0
	v_lshl_add_u64 v[6:7], v[2:3], 0, v[4:5]
	v_addc_co_u32_e32 v11, vcc, 0, v11, vcc
	global_load_ushort v13, v[10:11], off offset:512
	global_load_ushort v17, v[10:11], off offset:1536
	global_load_ushort v18, v[10:11], off offset:2560
	s_nop 0
	global_load_ushort v10, v[10:11], off offset:3584
	v_add_u32_e32 v11, 0x15200, v9
	global_store_short v[6:7], v14, off offset:-2048
	v_add_u32_e32 v14, 0x1d200, v9
	ds_read_u16 v11, v11
	ds_read_u16 v14, v14
	v_lshl_add_u64 v[2:3], v[2:3], 0, s[22:23]
	s_waitcnt lgkmcnt(1)
	v_lshlrev_b32_e32 v11, 16, v11
	s_waitcnt lgkmcnt(0)
	v_lshlrev_b32_e32 v14, 16, v14
	v_add_f32_e32 v11, v11, v14
	s_waitcnt vmcnt(7)
	v_lshlrev_b32_e32 v14, 16, v15
	v_mul_f32_e32 v15, 0x3d372713, v14
	v_mul_f32_e32 v15, v15, v14
	v_fma_f32 v15, v15, v14, v14
	v_mul_f32_e32 v15, 0x3f4c422a, v15
	v_add_f32_e32 v15, v15, v15
	v_mul_f32_e32 v15, 0x3fb8aa3b, v15
	v_exp_f32_e32 v15, v15
	v_mul_f32_e32 v14, 0.5, v14
	s_waitcnt vmcnt(5)
	v_lshlrev_b32_e32 v12, 16, v12
	v_add_f32_e32 v15, 1.0, v15
	s_waitcnt vmcnt(1)
	v_lshlrev_b32_e32 v10, 16, v10
	v_rcp_f32_e32 v19, v15
	s_nop 0
	v_mul_f32_e32 v15, 2.0, v19
	v_sub_f32_e32 v15, 1.0, v15
	v_add_f32_e32 v15, 1.0, v15
	v_mul_f32_e32 v14, v14, v15
	v_mul_f32_e32 v11, v11, v14
	v_cvt_pk_bf16_f32 v11, v11, s0
	global_store_short v[6:7], v11, off offset:-1536
	v_add_u32_e32 v11, 0x15400, v9
	v_add_u32_e32 v14, 0x1d400, v9
	ds_read_u16 v11, v11
	ds_read_u16 v14, v14
	s_waitcnt lgkmcnt(1)
	v_lshlrev_b32_e32 v11, 16, v11
	s_waitcnt lgkmcnt(0)
	v_lshlrev_b32_e32 v14, 16, v14
	v_add_f32_e32 v11, v11, v14
	v_lshlrev_b32_e32 v14, 16, v16
	v_mul_f32_e32 v15, 0x3d372713, v14
	v_mul_f32_e32 v15, v15, v14
	v_fma_f32 v15, v15, v14, v14
	v_mul_f32_e32 v15, 0x3f4c422a, v15
	v_add_f32_e32 v15, v15, v15
	v_mul_f32_e32 v15, 0x3fb8aa3b, v15
	v_exp_f32_e32 v15, v15
	v_mul_f32_e32 v14, 0.5, v14
	v_add_f32_e32 v15, 1.0, v15
	s_nop 0
	v_rcp_f32_e32 v16, v15
	s_nop 0
	v_mul_f32_e32 v15, 2.0, v16
	v_sub_f32_e32 v15, 1.0, v15
	v_add_f32_e32 v15, 1.0, v15
	v_mul_f32_e32 v14, v14, v15
	v_mul_f32_e32 v11, v14, v11
	v_cvt_pk_bf16_f32 v11, v11, s0
	global_store_short v[6:7], v11, off offset:-1024
	v_add_u32_e32 v11, 0x15600, v9
	v_add_u32_e32 v14, 0x1d600, v9
	ds_read_u16 v11, v11
	ds_read_u16 v14, v14
	s_waitcnt lgkmcnt(1)
	v_lshlrev_b32_e32 v11, 16, v11
	s_waitcnt lgkmcnt(0)
; __device__ __forceinline__ bf16_t f2bf(float f) { return (bf16_t)(cvt_pk_bf16(f, 0.f) & 0xffffu); }
; __device__ __forceinline__ float bf2f(bf16_t b) { return __uint_as_float(((unsigned)b) << 16); }
; __device__ __forceinline__ float geluf_(float x) { const float y = 0.7978845608028654f * (x + 0.044715f * x * x * x); const float t = 1.0f - 2.0f / (1.0f + __expf(2.0f * y)); return 0.5f * x * (1.0f + t); }
; template <bool FINAL>
; __device__ __forceinline__ void lru_item(const Ctx& C, int l, int item) {
;     ...
;         for (int k8 = 0; k8 < 4; ++k8) { bf16_t gv_[8];
; #pragma unroll
;             for (int k = 0; k < 8; ++k) gv_[k] = gp[(size_t)(zz * 32 + k8 * 8 + k) * 512];
; #pragma unroll
;             for (int k = 0; k < 8; ++k) { const int tl = zz * 32 + k8 * 8 + k; const float hs = bf2f(H0[tl * 256 + ch]) + bf2f(H1[tl * 256 + ch]);
;                 yb[(size_t)tl * 256] = f2bf(hs * geluf_(bf2f(gv_[k]))); } }
	v_lshlrev_b32_e32 v14, 16, v14
	v_add_f32_e32 v11, v11, v14
	v_mul_f32_e32 v14, 0x3d372713, v12
	v_mul_f32_e32 v14, v14, v12
	v_fma_f32 v14, v14, v12, v12
	v_mul_f32_e32 v14, 0x3f4c422a, v14
	v_add_f32_e32 v14, v14, v14
	v_mul_f32_e32 v14, 0x3fb8aa3b, v14
	v_exp_f32_e32 v14, v14
	v_mul_f32_e32 v12, 0.5, v12
	v_add_f32_e32 v14, 1.0, v14
	s_nop 0
	v_rcp_f32_e32 v15, v14
	s_nop 0
	v_mul_f32_e32 v14, 2.0, v15
	v_sub_f32_e32 v14, 1.0, v14
	v_add_f32_e32 v14, 1.0, v14
	v_mul_f32_e32 v12, v12, v14
	v_mul_f32_e32 v11, v12, v11
	v_cvt_pk_bf16_f32 v11, v11, s0
	global_store_short v[6:7], v11, off offset:-512
	v_add_u32_e32 v11, 0x15800, v9
	v_add_u32_e32 v12, 0x1d800, v9
	ds_read_u16 v11, v11
	ds_read_u16 v12, v12
	s_waitcnt lgkmcnt(1)
	v_lshlrev_b32_e32 v11, 16, v11
	s_waitcnt lgkmcnt(0)
	v_lshlrev_b32_e32 v12, 16, v12
	v_add_f32_e32 v11, v11, v12
	v_lshlrev_b32_e32 v12, 16, v13
	v_mul_f32_e32 v13, 0x3d372713, v12
	v_mul_f32_e32 v13, v13, v12
	v_fma_f32 v13, v13, v12, v12
	v_mul_f32_e32 v13, 0x3f4c422a, v13
	v_add_f32_e32 v13, v13, v13
	v_mul_f32_e32 v13, 0x3fb8aa3b, v13
	v_exp_f32_e32 v13, v13
	v_mul_f32_e32 v12, 0.5, v12
	v_add_f32_e32 v13, 1.0, v13
	s_nop 0
	v_rcp_f32_e32 v14, v13
	s_nop 0
	v_mul_f32_e32 v13, 2.0, v14
	v_sub_f32_e32 v13, 1.0, v13
	v_add_f32_e32 v13, 1.0, v13
	v_mul_f32_e32 v12, v12, v13
	v_mul_f32_e32 v11, v12, v11
	v_cvt_pk_bf16_f32 v11, v11, s0
	global_store_short v[6:7], v11, off
	v_add_u32_e32 v11, 0x15a00, v9
	v_add_u32_e32 v12, 0x1da00, v9
	ds_read_u16 v11, v11
	ds_read_u16 v12, v12
	s_waitcnt lgkmcnt(1)
	v_lshlrev_b32_e32 v11, 16, v11
	s_waitcnt lgkmcnt(0)
	v_lshlrev_b32_e32 v12, 16, v12
	v_add_f32_e32 v11, v11, v12
	v_lshlrev_b32_e32 v12, 16, v17
	v_mul_f32_e32 v13, 0x3d372713, v12
	v_mul_f32_e32 v13, v13, v12
	v_fma_f32 v13, v13, v12, v12
	v_mul_f32_e32 v13, 0x3f4c422a, v13
	v_add_f32_e32 v13, v13, v13
	v_mul_f32_e32 v13, 0x3fb8aa3b, v13
	v_exp_f32_e32 v13, v13
	v_mul_f32_e32 v12, 0.5, v12
	v_add_f32_e32 v13, 1.0, v13
	s_nop 0
	v_rcp_f32_e32 v14, v13
	s_nop 0
	v_mul_f32_e32 v13, 2.0, v14
	v_sub_f32_e32 v13, 1.0, v13
	v_add_f32_e32 v13, 1.0, v13
	v_mul_f32_e32 v12, v12, v13
	v_mul_f32_e32 v11, v12, v11
	v_cvt_pk_bf16_f32 v11, v11, s0
	global_store_short v[6:7], v11, off offset:512
	v_add_u32_e32 v11, 0x15c00, v9
	v_add_u32_e32 v12, 0x1dc00, v9
	ds_read_u16 v11, v11
	ds_read_u16 v12, v12
	s_waitcnt lgkmcnt(1)
	v_lshlrev_b32_e32 v11, 16, v11
	s_waitcnt lgkmcnt(0)
	v_lshlrev_b32_e32 v12, 16, v12
	v_add_f32_e32 v11, v11, v12
	v_lshlrev_b32_e32 v12, 16, v18
	v_mul_f32_e32 v13, 0x3d372713, v12
	v_mul_f32_e32 v13, v13, v12
	v_fma_f32 v13, v13, v12, v12
	v_mul_f32_e32 v13, 0x3f4c422a, v13
	v_add_f32_e32 v13, v13, v13
	v_mul_f32_e32 v13, 0x3fb8aa3b, v13
	v_exp_f32_e32 v13, v13
	v_mul_f32_e32 v12, 0.5, v12
	v_add_f32_e32 v13, 1.0, v13
	s_nop 0
	v_rcp_f32_e32 v14, v13
	s_nop 0
	v_mul_f32_e32 v13, 2.0, v14
	v_sub_f32_e32 v13, 1.0, v13
	v_add_f32_e32 v13, 1.0, v13
	v_mul_f32_e32 v12, v12, v13
	v_mul_f32_e32 v11, v12, v11
	v_cvt_pk_bf16_f32 v11, v11, s0
	global_store_short v[6:7], v11, off offset:1024
	v_add_u32_e32 v11, 0x15e00, v9
	v_add_u32_e32 v9, 0x1de00, v9
	ds_read_u16 v11, v11
	ds_read_u16 v9, v9
	s_waitcnt lgkmcnt(1)
	v_lshlrev_b32_e32 v11, 16, v11
	s_waitcnt lgkmcnt(0)
	v_lshlrev_b32_e32 v9, 16, v9
	v_add_f32_e32 v9, v11, v9
	v_mul_f32_e32 v11, 0x3d372713, v10
	v_mul_f32_e32 v11, v11, v10
	v_fma_f32 v11, v11, v10, v10
	v_mul_f32_e32 v11, 0x3f4c422a, v11
	v_add_f32_e32 v11, v11, v11
	v_mul_f32_e32 v11, 0x3fb8aa3b, v11
	v_exp_f32_e32 v11, v11
	v_mul_f32_e32 v10, 0.5, v10
	v_add_f32_e32 v11, 1.0, v11
	s_nop 0
	v_rcp_f32_e32 v12, v11
	s_nop 0
	v_mul_f32_e32 v11, 2.0, v12
	v_sub_f32_e32 v11, 1.0, v11
	v_add_f32_e32 v11, 1.0, v11
	v_mul_f32_e32 v10, v10, v11
	v_mul_f32_e32 v9, v10, v9
	v_cvt_pk_bf16_f32 v9, v9, s0
	s_addk_i32 s0, 0x1000
	s_cmpk_lg_i32 s0, 0x4000
	global_store_short v[6:7], v9, off offset:1536
	s_cbranch_scc1 .LBB0_683
	v_readlane_b32 s0, v254, 27
	s_add_i32 s48, s48, s26
	s_add_i32 s47, s47, s26
	s_add_i32 s46, s46, s0
	s_cmpk_gt_i32 s48, 0x1ff
	s_barrier
	s_cbranch_scc0 .LBB0_650

; __device__ __forceinline__ float hgrn_lb(const Ctx& C, int l, int ch) {
;     if (l == 0) return 0.f;
;     const float a0 = C.P->in[3][ch], a1 = C.P->in[3][256 + ch];
;     return 1.0f / (1.0f + __expf(a0 - a1));
; }
; template <int DIR>
; __device__ __forceinline__ void hgrn_pass3_item(const Ctx& C, int l, int item) {
;     const int c = item & 31, hd = (item >> 5) & 3, b = item >> 7;
;     unsigned char* wl = C.lds + C.wave * 14336;
;     const float lb = hgrn_lb(C, l, hd * 64 + C.lane);
;     const int fr = C.lane & 15, quad = C.lane >> 4;
.LBB0_739:
	s_bfe_u32 s1, s73, 0x20005
	v_readlane_b32 s4, v255, 1
	s_lshl_b32 s0, s1, 6
	v_readlane_b32 s5, v255, 2
	v_or_b32_e32 v207, s0, v132
	s_andn2_b64 vcc, exec, s[4:5]
	v_mov_b32_e32 v208, 0
	s_cbranch_vccnz .LBB0_741
	v_readlane_b32 s4, v251, 4
	v_lshlrev_b32_e32 v0, 2, v207
	v_readlane_b32 s10, v251, 10
	v_readlane_b32 s11, v251, 11
	s_nop 4
	global_load_dword v1, v0, s[10:11]
	s_nop 0
	global_load_dword v0, v0, s[10:11] offset:1024
	v_readlane_b32 s5, v251, 5
	v_readlane_b32 s6, v251, 6
	v_readlane_b32 s7, v251, 7
	v_readlane_b32 s8, v251, 8
	v_readlane_b32 s9, v251, 9
	v_readlane_b32 s12, v251, 12
	v_readlane_b32 s13, v251, 13
	v_readlane_b32 s14, v251, 14
	v_readlane_b32 s15, v251, 15
	v_readlane_b32 s16, v251, 16
	v_readlane_b32 s17, v251, 17
	v_readlane_b32 s18, v251, 18
	v_readlane_b32 s19, v251, 19
	s_waitcnt vmcnt(0)
	v_sub_f32_e32 v0, v1, v0
	v_mul_f32_e32 v0, 0x3fb8aa3b, v0
	v_exp_f32_e32 v0, v0
	s_nop 0
	v_add_f32_e32 v0, 1.0, v0
	v_rcp_f32_e32 v208, v0
	s_nop 0

; __device__ __forceinline__ bf16_t f2bf(float f) { return (bf16_t)(cvt_pk_bf16(f, 0.f) & 0xffffu); }
; __device__ __forceinline__ float bf2f(bf16_t b) { return __uint_as_float(((unsigned)b) << 16); }
; __device__ __forceinline__ float sigmoidf_(float x) { return 1.0f / (1.0f + __expf(-x)); }
; template <int MODE>
; __device__ __forceinline__ void hgrn_mfma(const Ctx& C, int l, int z, int b, int hd, int c, f32x4 (&Sacc)[4][4], float& dectot, unsigned char* wl, float lb) {
;     ...
;             const int st0 = c * 128 + sc * 32 + g8 * 16; const int tq0 = z ? 4095 - st0 : st0;
;             const bf16_t* row0 = pa + (size_t)(b * SEQ + tq0) * 1280; const ptrdiff_t rstep = z ? -1280 : 1280;
; #pragma unroll
;             for (int t = 0; t < 16; ++t) { const bf16_t* row = row0 + rstep * t; fv[t] = row[fcol]; vv[t] = row[vcol]; if (MODE != 0) qv[t] = row[qcol]; }
; #pragma unroll
;             for (int t = 0; t < 16; ++t) {
;                 const float fl = bf2f(fv[t]);
;                 const float sg = sigmoidf_(fl);
;                 const float f = lb + (1.0f - lb) * sg, kk = (1.0f - lb) * (1.0f - sg);
;                 bacc += __logf(fmaxf(f, 1e-30f));
;                 Kb[(g8 * 16 + t) * HPT + lane] = f2bf(kk * __expf(fminf(-bacc, 80.f)));
;                 if (MODE != 0) Qt[(g8 * 16 + t) * HPT + lane] = f2bf(bf2f(qv[t]) * __expf(fmaxf(bacc, -80.f)));
;                 Vv[(g8 * 16 + t) * HPT + lane] = vv[t];
.LBB0_743:
	s_lshl_b32 s0, s67, 4
	v_cndmask_b32_e64 v61, 0, 1, s[52:53]
	s_mul_i32 s1, s67, 0x480
	s_or_b32 s0, s0, s76
	v_cmp_ne_u32_e64 s[4:5], 1, v61
	v_or_b32_e32 v61, s1, v132
	s_mul_hi_i32 s1, s0, 0xa00
	s_mulk_i32 s0, 0xa00
	s_add_u32 s0, s44, s0
	v_lshlrev_b32_e32 v62, 1, v207
	s_addc_u32 s1, s45, s1
	global_load_ushort v63, v62, s[0:1] offset:512
	global_load_ushort v64, v62, s[0:1] offset:1536
	global_load_ushort v70, v62, s[0:1] offset:3072
	global_load_ushort v71, v215, s[0:1] offset:2560
	s_add_u32 s6, s0, 0x1400
	s_addc_u32 s7, s1, 0
	global_load_ushort v72, v228, s[6:7]
	global_load_ushort v73, v62, s[6:7]
	global_load_ushort v74, v215, s[6:7]
	s_add_u32 s6, s0, 0x1e00
	s_addc_u32 s7, s1, 0
	global_load_ushort v75, v228, s[6:7]
	global_load_ushort v76, v62, s[6:7]
	global_load_ushort v77, v215, s[6:7]
	s_add_u32 s6, s0, 0x2800
	s_addc_u32 s7, s1, 0
	global_load_ushort v78, v62, s[6:7]
	global_load_ushort v81, v62, s[0:1] offset:2560
	global_load_ushort v82, v62, s[0:1]
	global_load_ushort v83, v228, s[6:7]
	global_load_ushort v84, v215, s[6:7]
	s_add_u32 s6, s0, 0x3200
	s_addc_u32 s7, s1, 0
	s_add_u32 s8, s0, 0x3c00
	global_load_ushort v85, v215, s[6:7]
	global_load_ushort v86, v228, s[6:7]
	global_load_ushort v87, v62, s[6:7]
	s_addc_u32 s9, s1, 0
	s_add_u32 s6, s0, 0x4600
	global_load_ushort v88, v215, s[8:9]
	global_load_ushort v89, v228, s[8:9]
	global_load_ushort v90, v62, s[8:9]
	s_addc_u32 s7, s1, 0
	s_add_u32 s8, s0, 0x5000
	global_load_ushort v91, v215, s[6:7]
	global_load_ushort v92, v228, s[6:7]
	global_load_ushort v93, v62, s[6:7]
	s_addc_u32 s9, s1, 0
	s_add_u32 s6, s0, 0x5a00
	global_load_ushort v94, v215, s[8:9]
	global_load_ushort v95, v228, s[8:9]
	global_load_ushort v96, v62, s[8:9]
	s_addc_u32 s7, s1, 0
	s_add_u32 s8, s0, 0x6400
	global_load_ushort v97, v215, s[6:7]
	global_load_ushort v98, v228, s[6:7]
	global_load_ushort v99, v62, s[6:7]
	s_addc_u32 s9, s1, 0
	s_add_u32 s6, s0, 0x6e00
	global_load_ushort v100, v215, s[8:9]
	global_load_ushort v101, v228, s[8:9]
	global_load_ushort v110, v62, s[8:9]
	s_addc_u32 s7, s1, 0
	s_add_u32 s8, s0, 0x7800
	global_load_ushort v111, v215, s[6:7]
	global_load_ushort v112, v228, s[6:7]
	global_load_ushort v113, v62, s[6:7]
	s_addc_u32 s9, s1, 0
	global_load_ushort v114, v215, s[8:9]
	global_load_ushort v115, v228, s[8:9]
	global_load_ushort v116, v62, s[8:9]
	s_add_u32 s6, s0, 0x8200
	s_addc_u32 s7, s1, 0
	s_add_u32 s8, s0, 0x8c00
	global_load_ushort v117, v215, s[6:7]
	global_load_ushort v118, v228, s[6:7]
	global_load_ushort v119, v62, s[6:7]
	s_addc_u32 s9, s1, 0
	s_add_u32 s0, s0, 0x9600
	global_load_ushort v120, v215, s[8:9]
	global_load_ushort v121, v228, s[8:9]
	global_load_ushort v122, v62, s[8:9]
	s_addc_u32 s1, s1, 0
	global_load_ushort v123, v215, s[0:1]
	global_load_ushort v124, v228, s[0:1]
	global_load_ushort v125, v62, s[0:1]
	v_lshl_add_u32 v61, v61, 1, s70
	s_mov_b64 s[52:53], 0
	s_mov_b32 s67, 1
	s_waitcnt vmcnt(47)
	v_lshlrev_b32_e32 v62, 16, v63
	v_mul_f32_e32 v62, 0xbfb8aa3b, v62
	s_waitcnt vmcnt(45)
	v_lshlrev_b32_e32 v63, 16, v70
	v_mul_f32_e32 v63, 0xbfb8aa3b, v63
	ds_write_b16 v61, v64 offset:9216
	v_exp_f32_e32 v62, v62
	v_exp_f32_e32 v63, v63
	s_waitcnt vmcnt(43)
	v_lshlrev_b32_e32 v64, 16, v72
	v_mul_f32_e32 v64, 0xbfb8aa3b, v64
	v_exp_f32_e32 v64, v64
	s_waitcnt vmcnt(40)
	v_lshlrev_b32_e32 v70, 16, v75
	v_mul_f32_e32 v70, 0xbfb8aa3b, v70
	v_lshlrev_b32_e32 v80, 16, v73
	v_add_f32_e32 v73, 1.0, v62
	v_add_f32_e32 v63, 1.0, v63
	v_exp_f32_e32 v62, v70
	s_waitcnt vmcnt(34)
	v_lshlrev_b32_e32 v70, 16, v83
	v_mul_f32_e32 v70, 0xbfb8aa3b, v70
	v_add_f32_e32 v128, 1.0, v64
	v_exp_f32_e32 v64, v70
	s_waitcnt vmcnt(31)
	v_lshlrev_b32_e32 v70, 16, v86
	ds_write_b16 v61, v85 offset:9936
	ds_write_b16 v61, v77 offset:9648
	s_waitcnt vmcnt(30)
	v_lshlrev_b32_e32 v77, 16, v87
	v_mul_f32_e32 v70, 0xbfb8aa3b, v70
	v_add_f32_e32 v129, 1.0, v62
	v_exp_f32_e32 v62, v70
	s_waitcnt vmcnt(28)
	v_lshlrev_b32_e32 v70, 16, v89
	ds_write_b16 v61, v88 offset:10080
	ds_write_b16 v61, v71 offset:9360
	ds_write_b16 v61, v74 offset:9504
	s_waitcnt vmcnt(27)
	v_lshlrev_b32_e32 v74, 16, v90
	v_mul_f32_e32 v70, 0xbfb8aa3b, v70
	v_lshlrev_b32_e32 v79, 16, v76
	ds_write_b16 v61, v84 offset:9792
	v_add_f32_e32 v131, 1.0, v64
	v_exp_f32_e32 v64, v70
	s_waitcnt vmcnt(25)
	v_lshlrev_b32_e32 v70, 16, v92
	s_waitcnt vmcnt(24)
	v_lshlrev_b32_e32 v72, 16, v93
	v_mul_f32_e32 v70, 0xbfb8aa3b, v70
	v_add_f32_e32 v180, 1.0, v62
	v_exp_f32_e32 v62, v70
	s_waitcnt vmcnt(22)
	v_lshlrev_b32_e32 v70, 16, v95
	ds_write_b16 v61, v94 offset:10368
	s_waitcnt vmcnt(21)
	v_lshlrev_b32_e32 v71, 16, v96
	v_mul_f32_e32 v70, 0xbfb8aa3b, v70
	v_add_f32_e32 v188, 1.0, v64
	v_exp_f32_e32 v70, v70
	s_waitcnt vmcnt(19)
	v_lshlrev_b32_e32 v98, 16, v98
	ds_write_b16 v61, v97 offset:10512
	v_mul_f32_e32 v97, 0xbfb8aa3b, v98
	s_waitcnt vmcnt(18)
	v_lshlrev_b32_e32 v64, 16, v99
	v_add_f32_e32 v99, 1.0, v62
	v_exp_f32_e32 v97, v97
	s_waitcnt vmcnt(16)
	v_lshlrev_b32_e32 v101, 16, v101
	v_rcp_f32_e32 v73, v73
	ds_write_b16 v61, v91 offset:10224
	ds_write_b16 v61, v100 offset:10656
	v_mul_f32_e32 v93, 0xbfb8aa3b, v101
	v_fma_f32 v100, v213, v73, v208
	v_sub_f32_e32 v73, 1.0, v73
	v_rcp_f32_e32 v75, v63
	s_waitcnt vmcnt(15)
	v_lshlrev_b32_e32 v62, 16, v110
	v_add_f32_e32 v101, 1.0, v70
	v_exp_f32_e32 v93, v93
	s_waitcnt vmcnt(13)
	v_lshlrev_b32_e32 v70, 16, v112
	v_mul_f32_e32 v110, v213, v73
	v_max_f32_e32 v73, 0xda24260, v100
	v_fma_f32 v100, v213, v75, v208
	v_sub_f32_e32 v75, 1.0, v75
	v_rcp_f32_e32 v76, v128
	v_mul_f32_e32 v70, 0xbfb8aa3b, v70
	v_mul_f32_e32 v112, v213, v75
	v_max_f32_e32 v75, 0xda24260, v100
	v_cmp_gt_f32_e32 vcc, s54, v73
	s_waitcnt vmcnt(12)
; __device__ __forceinline__ bf16_t f2bf(float f) { return (bf16_t)(cvt_pk_bf16(f, 0.f) & 0xffffu); }
; __device__ __forceinline__ float bf2f(bf16_t b) { return __uint_as_float(((unsigned)b) << 16); }
; __device__ __forceinline__ float sigmoidf_(float x) { return 1.0f / (1.0f + __expf(-x)); }
; template <int MODE>
; __device__ __forceinline__ void hgrn_mfma(const Ctx& C, int l, int z, int b, int hd, int c, f32x4 (&Sacc)[4][4], float& dectot, unsigned char* wl, float lb) {
;     ...
;             for (int t = 0; t < 16; ++t) {
;                 const float fl = bf2f(fv[t]);
;                 const float sg = sigmoidf_(fl);
;                 const float f = lb + (1.0f - lb) * sg, kk = (1.0f - lb) * (1.0f - sg);
;                 bacc += __logf(fmaxf(f, 1e-30f));
;                 Kb[(g8 * 16 + t) * HPT + lane] = f2bf(kk * __expf(fminf(-bacc, 80.f)));
;                 if (MODE != 0) Qt[(g8 * 16 + t) * HPT + lane] = f2bf(bf2f(qv[t]) * __expf(fmaxf(bacc, -80.f)));
;                 Vv[(g8 * 16 + t) * HPT + lane] = vv[t];
	v_lshlrev_b32_e32 v63, 16, v113
	v_fma_f32 v100, v213, v76, v208
	v_sub_f32_e32 v76, 1.0, v76
	v_add_f32_e32 v97, 1.0, v97
	v_exp_f32_e32 v126, v70
	s_waitcnt vmcnt(9)
	v_lshlrev_b32_e32 v70, 16, v116
	ds_write_b16 v61, v114 offset:10944
	v_cndmask_b32_e64 v114, 0, 32, vcc
	v_cndmask_b32_e32 v116, 0, v225, vcc
	v_cmp_gt_f32_e32 vcc, s54, v75
	v_lshlrev_b32_e32 v115, 16, v115
	v_mul_f32_e32 v127, v213, v76
	v_max_f32_e32 v76, 0xda24260, v100
	v_rcp_f32_e32 v83, v129
	v_cndmask_b32_e64 v128, 0, 32, vcc
	v_cndmask_b32_e32 v129, 0, v225, vcc
	v_mul_f32_e32 v115, 0xbfb8aa3b, v115
	v_ldexp_f32 v114, v73, v114
	v_fma_f32 v130, v213, v83, v208
	v_add_f32_e32 v93, 1.0, v93
	v_cmp_gt_f32_e32 vcc, s54, v76
	v_exp_f32_e32 v115, v115
	s_waitcnt vmcnt(7)
	v_lshlrev_b32_e32 v118, 16, v118
	s_waitcnt vmcnt(6)
	v_lshlrev_b32_e32 v73, 16, v119
	ds_write_b16 v61, v117 offset:11088
	v_log_f32_e32 v114, v114
	v_ldexp_f32 v75, v75, v128
	v_cndmask_b32_e64 v117, 0, 32, vcc
	v_cndmask_b32_e32 v119, 0, v225, vcc
	v_max_f32_e32 v128, 0xda24260, v130
	v_rcp_f32_e32 v85, v131
	v_mul_f32_e32 v118, 0xbfb8aa3b, v118
	v_log_f32_e32 v178, v75
	v_ldexp_f32 v76, v76, v117
	v_fma_f32 v117, v213, v85, v208
	v_cmp_gt_f32_e32 vcc, s54, v128
	ds_write_b16 v61, v111 offset:10800
	v_add_f32_e32 v126, 1.0, v126
	v_exp_f32_e32 v118, v118
	s_waitcnt vmcnt(4)
	v_lshlrev_b32_e32 v121, 16, v121
	s_waitcnt vmcnt(3)
	v_lshlrev_b32_e32 v75, 16, v122
	ds_write_b16 v61, v120 offset:11232
	v_log_f32_e32 v120, v76
	v_cndmask_b32_e64 v76, 0, 32, vcc
	v_cndmask_b32_e32 v122, 0, v225, vcc
	v_max_f32_e32 v117, 0xda24260, v117
	v_rcp_f32_e32 v88, v180
	v_mul_f32_e32 v121, 0xbfb8aa3b, v121
	v_ldexp_f32 v128, v128, v76
	v_fma_f32 v189, v213, v88, v208
	v_cmp_gt_f32_e32 vcc, s54, v117
	v_add_f32_e32 v115, 1.0, v115
	v_exp_f32_e32 v121, v121
	s_waitcnt vmcnt(1)
	v_lshlrev_b32_e32 v124, 16, v124
	s_waitcnt vmcnt(0)
	v_lshlrev_b32_e32 v76, 16, v125
	ds_write_b16 v61, v123 offset:11376
	v_mul_f32_e32 v123, 0x3f317217, v114
	v_log_f32_e32 v125, v128
	v_cndmask_b32_e64 v128, 0, 32, vcc
	v_cndmask_b32_e32 v190, 0, v225, vcc
	v_max_f32_e32 v189, 0xda24260, v189
	v_rcp_f32_e32 v84, v188
	v_mul_f32_e32 v124, 0xbfb8aa3b, v124
	v_fma_f32 v123, v114, s56, -v123
	v_mul_f32_e32 v191, 0x3f317217, v178
	v_ldexp_f32 v117, v117, v128
	v_fma_f32 v128, v213, v84, v208
	v_cmp_gt_f32_e32 vcc, s54, v189
	v_add_f32_e32 v118, 1.0, v118
	v_exp_f32_e32 v124, v124
	v_fmac_f32_e32 v123, 0x3377d1cf, v114
	v_fma_f32 v191, v178, s56, -v191
	v_mul_f32_e32 v223, 0x3f317217, v120
	v_log_f32_e32 v117, v117
	v_cndmask_b32_e64 v229, 0, 32, vcc
	v_cndmask_b32_e32 v230, 0, v225, vcc
	v_max_f32_e32 v128, 0xda24260, v128
	v_rcp_f32_e32 v86, v99
	v_fmac_f32_e32 v123, 0x3f317217, v114
	v_cmp_lt_f32_e64 s[0:1], |v114|, s57
	v_fmac_f32_e32 v191, 0x3377d1cf, v178
	v_fma_f32 v223, v120, s56, -v223
	v_ldexp_f32 v189, v189, v229
	v_fma_f32 v229, v213, v86, v208
	v_cmp_gt_f32_e32 vcc, s54, v128
	v_fmac_f32_e32 v191, 0x3f317217, v178
	v_cmp_lt_f32_e64 s[18:19], |v178|, s57
	v_add_f32_e32 v121, 1.0, v121
	v_cndmask_b32_e64 v114, v114, v123, s[0:1]
	v_fmac_f32_e32 v223, 0x3377d1cf, v120
	v_mul_f32_e32 v123, 0x3f317217, v125
	v_log_f32_e32 v189, v189
	v_cndmask_b32_e64 v231, 0, 32, vcc
	v_cndmask_b32_e32 v232, 0, v225, vcc
	v_max_f32_e32 v229, 0xda24260, v229
	v_rcp_f32_e32 v87, v101
	v_fmac_f32_e32 v223, 0x3f317217, v120
	v_cmp_lt_f32_e64 s[0:1], |v120|, s57
	v_sub_f32_e32 v114, v114, v116
	v_cndmask_b32_e64 v116, v178, v191, s[18:19]
	v_fma_f32 v123, v125, s56, -v123
	v_ldexp_f32 v128, v128, v231
	v_fma_f32 v178, v213, v87, v208
	v_cmp_gt_f32_e32 vcc, s54, v229
	v_add_f32_e32 v124, 1.0, v124
	v_add_f32_e32 v60, v60, v114
	v_sub_f32_e32 v114, v116, v129
	v_cndmask_b32_e64 v116, v120, v223, s[0:1]
	v_fmac_f32_e32 v123, 0x3377d1cf, v125
	v_mul_f32_e32 v120, 0x3f317217, v117
	v_log_f32_e32 v128, v128
	v_cndmask_b32_e64 v129, 0, 32, vcc
	v_cndmask_b32_e32 v191, 0, v225, vcc
	v_max_f32_e32 v178, 0xda24260, v178
	v_fmac_f32_e32 v123, 0x3f317217, v125
	v_cmp_lt_f32_e64 s[0:1], |v125|, s57
	v_rcp_f32_e32 v89, v97
	v_min_f32_e64 v223, -v60, s60
	v_max_f32_e32 v231, 0xc2a00000, v60
	v_add_f32_e32 v60, v60, v114
	v_sub_f32_e32 v114, v116, v119
	v_fma_f32 v116, v117, s56, -v120
	v_ldexp_f32 v119, v229, v129
	v_cmp_gt_f32_e32 vcc, s54, v178
	v_fma_f32 v120, v213, v89, v208
	v_mul_f32_e32 v181, 0x3fb8aa3b, v223
	v_mul_f32_e32 v223, 0x3fb8aa3b, v231
	v_min_f32_e64 v229, -v60, s60
	v_max_f32_e32 v231, 0xc2a00000, v60
	v_add_f32_e32 v60, v60, v114
	v_cndmask_b32_e64 v114, v125, v123, s[0:1]
	v_fmac_f32_e32 v116, 0x3377d1cf, v117
	v_mul_f32_e32 v123, 0x3f317217, v189
	v_log_f32_e32 v119, v119
	v_cndmask_b32_e64 v125, 0, 32, vcc
	v_fmac_f32_e32 v116, 0x3f317217, v117
	v_cmp_lt_f32_e64 s[0:1], |v117|, s57
	v_cndmask_b32_e32 v233, 0, v225, vcc
	v_max_f32_e32 v120, 0xda24260, v120
	v_rcp_f32_e32 v90, v93
	v_exp_f32_e32 v97, v181
	v_exp_f32_e32 v180, v223
	v_mul_f32_e32 v181, 0x3fb8aa3b, v229
	v_mul_f32_e32 v223, 0x3fb8aa3b, v231
	v_min_f32_e64 v229, -v60, s60
	v_max_f32_e32 v231, 0xc2a00000, v60
	v_sub_f32_e32 v114, v114, v122
	v_fma_f32 v122, v189, s56, -v123
	v_ldexp_f32 v123, v178, v125
	v_fma_f32 v125, v213, v90, v208
	v_exp_f32_e32 v130, v181
	v_exp_f32_e32 v178, v223
	v_mul_f32_e32 v181, 0x3fb8aa3b, v229
	v_mul_f32_e32 v223, 0x3fb8aa3b, v231
	v_add_f32_e32 v60, v60, v114
	v_cndmask_b32_e64 v114, v117, v116, s[0:1]
	v_fmac_f32_e32 v122, 0x3377d1cf, v189
	v_mul_f32_e32 v116, 0x3f317217, v128
	v_log_f32_e32 v117, v123
	v_cmp_gt_f32_e32 vcc, s54, v120
	s_nop 0
	s_nop 0
	v_cndmask_b32_e64 v123, 0, 32, vcc
	v_fmac_f32_e32 v122, 0x3f317217, v189
	v_cmp_lt_f32_e64 s[0:1], |v189|, s57
; __device__ __forceinline__ bf16_t f2bf(float f) { return (bf16_t)(cvt_pk_bf16(f, 0.f) & 0xffffu); }
; __device__ __forceinline__ float bf2f(bf16_t b) { return __uint_as_float(((unsigned)b) << 16); }
; __device__ __forceinline__ float sigmoidf_(float x) { return 1.0f / (1.0f + __expf(-x)); }
; template <int MODE>
; __device__ __forceinline__ void hgrn_mfma(const Ctx& C, int l, int z, int b, int hd, int c, f32x4 (&Sacc)[4][4], float& dectot, unsigned char* wl, float lb) {
;     ...
;             for (int t = 0; t < 16; ++t) {
;                 const float fl = bf2f(fv[t]);
;                 const float sg = sigmoidf_(fl);
;                 const float f = lb + (1.0f - lb) * sg, kk = (1.0f - lb) * (1.0f - sg);
;                 bacc += __logf(fmaxf(f, 1e-30f));
;                 Kb[(g8 * 16 + t) * HPT + lane] = f2bf(kk * __expf(fminf(-bacc, 80.f)));
;                 if (MODE != 0) Qt[(g8 * 16 + t) * HPT + lane] = f2bf(bf2f(qv[t]) * __expf(fmaxf(bacc, -80.f)));
;                 Vv[(g8 * 16 + t) * HPT + lane] = vv[t];
	v_cndmask_b32_e32 v229, 0, v225, vcc
	v_max_f32_e32 v125, 0xda24260, v125
	v_rcp_f32_e32 v92, v126
	v_exp_f32_e32 v98, v181
	v_exp_f32_e32 v181, v223
	v_min_f32_e64 v188, -v60, s60
	v_max_f32_e32 v223, 0xc2a00000, v60
	v_sub_f32_e32 v114, v114, v190
	v_fma_f32 v116, v128, s56, -v116
	v_lshlrev_b32_e32 v82, 16, v82
	v_ldexp_f32 v120, v120, v123
	v_fma_f32 v123, v213, v92, v208
	v_mul_f32_e32 v126, 0x3fb8aa3b, v188
	v_mul_f32_e32 v188, 0x3fb8aa3b, v223
	v_add_f32_e32 v60, v60, v114
	v_cndmask_b32_e64 v114, v189, v122, s[0:1]
	v_fmac_f32_e32 v116, 0x3377d1cf, v128
	v_mul_f32_e32 v122, 0x3f317217, v119
	v_cmp_gt_f32_e32 vcc, s54, v125
	v_lshlrev_b32_e32 v81, 16, v81
	v_log_f32_e32 v120, v120
	v_cndmask_b32_e64 v189, 0, 32, vcc
	v_fmac_f32_e32 v116, 0x3f317217, v128
	v_cmp_lt_f32_e64 s[0:1], |v128|, s57
	v_cndmask_b32_e32 v190, 0, v225, vcc
	v_max_f32_e32 v123, 0xda24260, v123
	v_rcp_f32_e32 v91, v115
	v_mul_f32_e32 v96, v110, v97
	v_mul_f32_e32 v82, v180, v82
	v_exp_f32_e32 v97, v126
	v_exp_f32_e32 v110, v188
	v_min_f32_e64 v115, -v60, s60
	v_max_f32_e32 v126, 0xc2a00000, v60
	v_sub_f32_e32 v114, v114, v230
	v_fma_f32 v122, v119, s56, -v122
	v_ldexp_f32 v125, v125, v189
	v_fma_f32 v180, v213, v91, v208
	v_cvt_pk_bf16_f32 v96, v96, s0
	v_cvt_pk_bf16_f32 v82, v82, s0
	v_mul_f32_e32 v111, v112, v130
	v_mul_f32_e32 v81, v178, v81
	v_mul_f32_e32 v112, 0x3fb8aa3b, v115
	v_mul_f32_e32 v113, 0x3fb8aa3b, v126
	v_add_f32_e32 v60, v60, v114
	v_cndmask_b32_e64 v114, v128, v116, s[0:1]
	v_fmac_f32_e32 v122, 0x3377d1cf, v119
	v_mul_f32_e32 v115, 0x3f317217, v117
	v_cmp_gt_f32_e32 vcc, s54, v123
	v_cmp_lt_f32_e64 s[0:1], |v119|, s57
	v_sub_f32_e32 v83, 1.0, v83
	v_log_f32_e32 v116, v125
	v_cndmask_b32_e64 v125, 0, 32, vcc
	v_fmac_f32_e32 v122, 0x3f317217, v119
	v_cndmask_b32_e32 v126, 0, v225, vcc
	v_max_f32_e32 v128, 0xda24260, v180
	v_rcp_f32_e32 v93, v118
	ds_write_b16 v61, v96 offset:4608
	ds_write_b16 v61, v82
	v_cvt_pk_bf16_f32 v82, v111, s0
	v_cvt_pk_bf16_f32 v81, v81, s0
	v_mul_f32_e32 v96, v127, v98
	v_mul_f32_e32 v80, v181, v80
	v_exp_f32_e32 v98, v112
	v_exp_f32_e32 v111, v113
	v_min_f32_e64 v112, -v60, s60
	v_max_f32_e32 v113, 0xc2a00000, v60
	v_fma_f32 v115, v117, s56, -v115
	v_mul_f32_e32 v83, v213, v83
	v_sub_f32_e32 v114, v114, v232
	v_ldexp_f32 v118, v123, v125
	v_fma_f32 v123, v213, v93, v208
	ds_write_b16 v61, v82 offset:4752
	ds_write_b16 v61, v81 offset:144
	v_cvt_pk_bf16_f32 v81, v96, s0
	v_cvt_pk_bf16_f32 v80, v80, s0
	v_mul_f32_e32 v82, 0x3fb8aa3b, v112
	v_mul_f32_e32 v96, 0x3fb8aa3b, v113
	v_cndmask_b32_e64 v99, v119, v122, s[0:1]
	v_fmac_f32_e32 v115, 0x3377d1cf, v117
	v_cmp_gt_f32_e32 vcc, s54, v128
	v_sub_f32_e32 v85, 1.0, v85
	v_add_f32_e32 v60, v60, v114
	v_mul_f32_e32 v101, 0x3f317217, v120
	v_log_f32_e32 v112, v118
	v_cndmask_b32_e64 v113, 0, 32, vcc
	v_fmac_f32_e32 v115, 0x3f317217, v117
	v_cmp_lt_f32_e64 s[0:1], |v117|, s57
	v_cndmask_b32_e32 v114, 0, v225, vcc
	v_max_f32_e32 v118, 0xda24260, v123
	v_rcp_f32_e32 v95, v121
	ds_write_b16 v61, v81 offset:4896
	ds_write_b16 v61, v80 offset:288
	v_mul_f32_e32 v80, v83, v97
	v_mul_f32_e32 v79, v110, v79
	v_exp_f32_e32 v81, v82
	v_exp_f32_e32 v82, v96
	v_sub_f32_e32 v97, v99, v191
	v_lshlrev_b32_e32 v78, 16, v78
	v_mul_f32_e32 v85, v213, v85
	v_min_f32_e64 v83, -v60, s60
	v_max_f32_e32 v96, 0xc2a00000, v60
	v_fma_f32 v99, v120, s56, -v101
	v_ldexp_f32 v101, v128, v113
	v_fma_f32 v110, v213, v95, v208
	v_cvt_pk_bf16_f32 v80, v80, s0
	v_cvt_pk_bf16_f32 v79, v79, s0
	v_add_f32_e32 v60, v60, v97
	v_cndmask_b32_e64 v97, v117, v115, s[0:1]
	v_cmp_gt_f32_e64 s[0:1], s54, v118
	v_sub_f32_e32 v88, 1.0, v88
	v_mul_f32_e32 v83, 0x3fb8aa3b, v83
	v_mul_f32_e32 v96, 0x3fb8aa3b, v96
	v_fmac_f32_e32 v99, 0x3377d1cf, v120
	v_mul_f32_e32 v100, 0x3f317217, v116
	v_log_f32_e32 v101, v101
	v_cndmask_b32_e64 v113, 0, 32, s[0:1]
	v_max_f32_e32 v110, 0xda24260, v110
	v_rcp_f32_e32 v94, v124
	ds_write_b16 v61, v80 offset:5040
	ds_write_b16 v61, v79 offset:432
	v_mul_f32_e32 v79, v85, v98
	v_mul_f32_e32 v78, v111, v78
	v_mul_f32_e32 v88, v213, v88
	s_and_b64 vcc, exec, s[4:5]
	v_fmac_f32_e32 v99, 0x3f317217, v120
	v_cmp_lt_f32_e64 s[4:5], |v120|, s57
	v_cndmask_b32_e64 v115, 0, v225, s[0:1]
	v_exp_f32_e32 v80, v83
	v_exp_f32_e32 v83, v96
	v_min_f32_e64 v85, -v60, s60
	v_max_f32_e32 v96, 0xc2a00000, v60
	v_sub_f32_e32 v97, v97, v233
	v_fma_f32 v98, v116, s56, -v100
	v_ldexp_f32 v100, v118, v113
	v_fma_f32 v111, v213, v94, v208
	v_cvt_pk_bf16_f32 v79, v79, s0
	v_cvt_pk_bf16_f32 v78, v78, s0
	v_cmp_gt_f32_e64 s[0:1], s54, v110
	v_mul_f32_e32 v85, 0x3fb8aa3b, v85
	v_mul_f32_e32 v96, 0x3fb8aa3b, v96
	v_add_f32_e32 v60, v60, v97
	v_cndmask_b32_e64 v97, v120, v99, s[4:5]
	v_fmac_f32_e32 v98, 0x3377d1cf, v116
	v_mul_f32_e32 v99, 0x3f317217, v112
	v_log_f32_e32 v100, v100
	v_cndmask_b32_e64 v113, 0, 32, s[0:1]
	v_max_f32_e32 v111, 0xda24260, v111
	ds_write_b16 v61, v79 offset:5184
	ds_write_b16 v61, v78 offset:576
	v_mul_f32_e32 v78, v88, v81
	v_mul_f32_e32 v77, v82, v77
	v_sub_f32_e32 v84, 1.0, v84
	v_fmac_f32_e32 v98, 0x3f317217, v116
	v_cmp_lt_f32_e64 s[4:5], |v116|, s57
	v_cndmask_b32_e64 v117, 0, v225, s[0:1]
	v_exp_f32_e32 v79, v85
	v_exp_f32_e32 v81, v96
	v_min_f32_e64 v82, -v60, s60
	v_max_f32_e32 v85, 0xc2a00000, v60
	v_sub_f32_e32 v88, v97, v229
	v_fma_f32 v96, v112, s56, -v99
	v_ldexp_f32 v97, v110, v113
	v_cvt_pk_bf16_f32 v78, v78, s0
	v_cvt_pk_bf16_f32 v77, v77, s0
	v_cmp_gt_f32_e64 s[0:1], s54, v111
	v_mul_f32_e32 v84, v213, v84
	v_mul_f32_e32 v82, 0x3fb8aa3b, v82
	v_mul_f32_e32 v85, 0x3fb8aa3b, v85
	v_add_f32_e32 v60, v60, v88
	v_cndmask_b32_e64 v88, v116, v98, s[4:5]
	v_fmac_f32_e32 v96, 0x3377d1cf, v112
; __device__ __forceinline__ bf16_t f2bf(float f) { return (bf16_t)(cvt_pk_bf16(f, 0.f) & 0xffffu); }
; __device__ __forceinline__ float bf2f(bf16_t b) { return __uint_as_float(((unsigned)b) << 16); }
; __device__ __forceinline__ float sigmoidf_(float x) { return 1.0f / (1.0f + __expf(-x)); }
; template <int MODE>
; __device__ __forceinline__ void hgrn_mfma(const Ctx& C, int l, int z, int b, int hd, int c, f32x4 (&Sacc)[4][4], float& dectot, unsigned char* wl, float lb) {
;     ...
;             for (int t = 0; t < 16; ++t) {
;                 const float fl = bf2f(fv[t]);
;                 const float sg = sigmoidf_(fl);
;                 const float f = lb + (1.0f - lb) * sg, kk = (1.0f - lb) * (1.0f - sg);
;                 bacc += __logf(fmaxf(f, 1e-30f));
;                 Kb[(g8 * 16 + t) * HPT + lane] = f2bf(kk * __expf(fminf(-bacc, 80.f)));
;                 if (MODE != 0) Qt[(g8 * 16 + t) * HPT + lane] = f2bf(bf2f(qv[t]) * __expf(fmaxf(bacc, -80.f)));
;                 Vv[(g8 * 16 + t) * HPT + lane] = vv[t];
	v_mul_f32_e32 v98, 0x3f317217, v101
	v_log_f32_e32 v97, v97
	v_cndmask_b32_e64 v99, 0, 32, s[0:1]
	v_sub_f32_e32 v86, 1.0, v86
	v_fmac_f32_e32 v96, 0x3f317217, v112
	v_cmp_lt_f32_e64 s[4:5], |v112|, s57
	ds_write_b16 v61, v78 offset:5328
	ds_write_b16 v61, v77 offset:720
	v_mul_f32_e32 v77, v84, v80
	v_mul_f32_e32 v74, v83, v74
	v_exp_f32_e32 v78, v82
	v_exp_f32_e32 v80, v85
	v_min_f32_e64 v82, -v60, s60
	v_max_f32_e32 v83, 0xc2a00000, v60
	v_sub_f32_e32 v84, v88, v190
	v_fma_f32 v85, v101, s56, -v98
	v_ldexp_f32 v88, v111, v99
	v_mul_f32_e32 v86, v213, v86
	v_cvt_pk_bf16_f32 v77, v77, s0
	v_cvt_pk_bf16_f32 v74, v74, s0
	v_mul_f32_e32 v82, 0x3fb8aa3b, v82
	v_mul_f32_e32 v83, 0x3fb8aa3b, v83
	v_add_f32_e32 v60, v60, v84
	v_cndmask_b32_e64 v84, v112, v96, s[4:5]
	v_fmac_f32_e32 v85, 0x3377d1cf, v101
	v_mul_f32_e32 v96, 0x3f317217, v100
	v_log_f32_e32 v88, v88
	v_sub_f32_e32 v87, 1.0, v87
	v_cndmask_b32_e64 v110, 0, v225, s[0:1]
	v_fmac_f32_e32 v85, 0x3f317217, v101
	v_cmp_lt_f32_e64 s[0:1], |v101|, s57
	ds_write_b16 v61, v77 offset:5472
	ds_write_b16 v61, v74 offset:864
	v_mul_f32_e32 v74, v86, v79
	v_mul_f32_e32 v72, v81, v72
	v_exp_f32_e32 v77, v82
	v_exp_f32_e32 v79, v83
	v_min_f32_e64 v81, -v60, s60
	v_max_f32_e32 v82, 0xc2a00000, v60
	v_sub_f32_e32 v83, v84, v126
	v_fma_f32 v84, v100, s56, -v96
	v_mul_f32_e32 v87, v213, v87
	v_cvt_pk_bf16_f32 v74, v74, s0
	v_cvt_pk_bf16_f32 v72, v72, s0
	v_mul_f32_e32 v81, 0x3fb8aa3b, v81
	v_mul_f32_e32 v82, 0x3fb8aa3b, v82
	v_add_f32_e32 v60, v60, v83
	v_cndmask_b32_e64 v83, v101, v85, s[0:1]
	v_fmac_f32_e32 v84, 0x3377d1cf, v100
	v_mul_f32_e32 v85, 0x3f317217, v97
	v_sub_f32_e32 v89, 1.0, v89
	v_fmac_f32_e32 v84, 0x3f317217, v100
	v_cmp_lt_f32_e64 s[0:1], |v100|, s57
	ds_write_b16 v61, v74 offset:5616
	ds_write_b16 v61, v72 offset:1008
	v_mul_f32_e32 v72, v87, v78
	v_mul_f32_e32 v71, v80, v71
	v_exp_f32_e32 v74, v81
	v_exp_f32_e32 v78, v82
	v_min_f32_e64 v80, -v60, s60
	v_max_f32_e32 v81, 0xc2a00000, v60
	v_sub_f32_e32 v82, v83, v114
	v_fma_f32 v83, v97, s56, -v85
	v_mul_f32_e32 v89, v213, v89
	v_cvt_pk_bf16_f32 v72, v72, s0
	v_cvt_pk_bf16_f32 v71, v71, s0
	v_mul_f32_e32 v80, 0x3fb8aa3b, v80
	v_mul_f32_e32 v81, 0x3fb8aa3b, v81
	v_add_f32_e32 v60, v60, v82
	v_cndmask_b32_e64 v82, v100, v84, s[0:1]
	v_fmac_f32_e32 v83, 0x3377d1cf, v97
	v_mul_f32_e32 v84, 0x3f317217, v88
	v_sub_f32_e32 v90, 1.0, v90
	v_fmac_f32_e32 v83, 0x3f317217, v97
	v_cmp_lt_f32_e64 s[0:1], |v97|, s57
	ds_write_b16 v61, v72 offset:5760
	ds_write_b16 v61, v71 offset:1152
	v_mul_f32_e32 v71, v89, v77
	v_mul_f32_e32 v64, v79, v64
	v_exp_f32_e32 v72, v80
	v_exp_f32_e32 v77, v81
	v_min_f32_e64 v79, -v60, s60
	v_max_f32_e32 v80, 0xc2a00000, v60
	v_sub_f32_e32 v81, v82, v115
	v_fma_f32 v82, v88, s56, -v84
	v_mul_f32_e32 v90, v213, v90
	v_cvt_pk_bf16_f32 v71, v71, s0
	v_cvt_pk_bf16_f32 v64, v64, s0
	v_mul_f32_e32 v79, 0x3fb8aa3b, v79
	v_mul_f32_e32 v80, 0x3fb8aa3b, v80
	v_add_f32_e32 v60, v60, v81
	v_cndmask_b32_e64 v81, v97, v83, s[0:1]
	v_fmac_f32_e32 v82, 0x3377d1cf, v88
	v_sub_f32_e32 v92, 1.0, v92
	v_fmac_f32_e32 v82, 0x3f317217, v88
	v_cmp_lt_f32_e64 s[0:1], |v88|, s57
	ds_write_b16 v61, v71 offset:5904
	ds_write_b16 v61, v64 offset:1296
	v_mul_f32_e32 v64, v90, v74
	v_mul_f32_e32 v62, v78, v62
	v_exp_f32_e32 v71, v79
	v_exp_f32_e32 v74, v80
	v_min_f32_e64 v78, -v60, s60
	v_max_f32_e32 v79, 0xc2a00000, v60
	v_sub_f32_e32 v80, v81, v117
	v_mul_f32_e32 v92, v213, v92
	v_cvt_pk_bf16_f32 v64, v64, s0
	v_cvt_pk_bf16_f32 v62, v62, s0
	v_mul_f32_e32 v78, 0x3fb8aa3b, v78
	v_mul_f32_e32 v79, 0x3fb8aa3b, v79
	v_add_f32_e32 v60, v60, v80
	v_cndmask_b32_e64 v80, v88, v82, s[0:1]
	v_sub_f32_e32 v91, 1.0, v91
	ds_write_b16 v61, v64 offset:6048
	ds_write_b16 v61, v62 offset:1440
	v_mul_f32_e32 v62, v92, v72
	v_mul_f32_e32 v63, v77, v63
	v_exp_f32_e32 v64, v78
	v_exp_f32_e32 v72, v79
	v_min_f32_e64 v77, -v60, s60
	v_sub_f32_e32 v79, v80, v110
	v_mul_f32_e32 v91, v213, v91
	v_max_f32_e32 v78, 0xc2a00000, v60
	v_cvt_pk_bf16_f32 v62, v62, s0
	v_cvt_pk_bf16_f32 v63, v63, s0
	v_mul_f32_e32 v77, 0x3fb8aa3b, v77
	v_add_f32_e32 v60, v60, v79
	v_sub_f32_e32 v93, 1.0, v93
	v_mul_f32_e32 v78, 0x3fb8aa3b, v78
	ds_write_b16 v61, v62 offset:6192
	ds_write_b16 v61, v63 offset:1584
	v_mul_f32_e32 v62, v91, v71
	v_mul_f32_e32 v63, v74, v70
	v_exp_f32_e32 v70, v77
	v_min_f32_e64 v74, -v60, s60
	v_mul_f32_e32 v93, v213, v93
	v_exp_f32_e32 v71, v78
	v_max_f32_e32 v77, 0xc2a00000, v60
	v_cvt_pk_bf16_f32 v62, v62, s0
	v_mul_f32_e32 v74, 0x3fb8aa3b, v74
	v_sub_f32_e32 v95, 1.0, v95
	v_cvt_pk_bf16_f32 v63, v63, s0
	v_mul_f32_e32 v77, 0x3fb8aa3b, v77
	ds_write_b16 v61, v62 offset:6336
	ds_write_b16 v61, v63 offset:1728
	v_mul_f32_e32 v62, v93, v64
	v_exp_f32_e32 v64, v74
	v_mul_f32_e32 v95, v213, v95
	v_mul_f32_e32 v63, v72, v73
	v_exp_f32_e32 v72, v77
	v_cvt_pk_bf16_f32 v62, v62, s0
	v_sub_f32_e32 v94, 1.0, v94
	v_cvt_pk_bf16_f32 v63, v63, s0
	ds_write_b16 v61, v62 offset:6480
	ds_write_b16 v61, v63 offset:1872
	v_mul_f32_e32 v62, v95, v70
	v_mul_f32_e32 v94, v213, v94
	v_mul_f32_e32 v63, v71, v75
	v_cvt_pk_bf16_f32 v62, v62, s0
	v_cvt_pk_bf16_f32 v63, v63, s0
	ds_write_b16 v61, v62 offset:6624
	ds_write_b16 v61, v63 offset:2016
	v_mul_f32_e32 v62, v94, v64
	v_mul_f32_e32 v63, v72, v76
	v_cvt_pk_bf16_f32 v62, v62, s0
	v_cvt_pk_bf16_f32 v63, v63, s0
	ds_write_b16 v61, v62 offset:6768
	ds_write_b16 v61, v63 offset:2160
	s_cbranch_vccz .LBB0_743
; template <int MODE>
; __device__ __forceinline__ void hgrn_mfma(const Ctx& C, int l, int z, int b, int hd, int c, f32x4 (&Sacc)[4][4], float& dectot, unsigned char* wl, float lb) {
;     ...
;         { const float eb = __expf(bacc); dl[lane] = eb; dectot *= eb; }
;         wave_lds_fence();
;         f32x4 Oacc[2][4];
;         if (MODE != 0) {
;             bf16x8 Sb[2][4];
; #pragma unroll
;             for (int ks = 0; ks < 2; ++ks)
; #pragma unroll
;                 for (int vt = 0; vt < 4; ++vt) { union { bf16x8 v; unsigned u[4]; } t_;
;                     t_.u[0] = cvt_pk_bf16(Sacc[2 * ks][vt][0], Sacc[2 * ks][vt][1]); t_.u[1] = cvt_pk_bf16(Sacc[2 * ks][vt][2], Sacc[2 * ks][vt][3]);
;                     t_.u[2] = cvt_pk_bf16(Sacc[2 * ks + 1][vt][0], Sacc[2 * ks + 1][vt][1]); t_.u[3] = cvt_pk_bf16(Sacc[2 * ks + 1][vt][2], Sacc[2 * ks + 1][vt][3]); Sb[ks][vt] = t_.v; }
;             float zz = 0.f; asm volatile("" : "+v"(zz));
; #pragma unroll
;             for (int tt = 0; tt < 2; ++tt)
; #pragma unroll
;                 for (int vt = 0; vt < 4; ++vt) Oacc[tt][vt] = (f32x4){zz, zz, zz, zz};
; #pragma unroll
;             for (int tt = 0; tt < 2; ++tt)
; #pragma unroll
;                 for (int ks = 0; ks < 2; ++ks) { const bf16_t* qp = Qt + (16 * tt + fr) * HPT + 32 * ks + 4 * quad;
;                     union { bf16x8 v; u32x2 h[2]; } a_; a_.h[0] = *(const u32x2*)qp; a_.h[1] = *(const u32x2*)(qp + 16);
; #pragma unroll
;                     for (int vt = 0; vt < 4; ++vt) Oacc[tt][vt] = __builtin_amdgcn_mfma_f32_16x16x32_bf16(a_.v, Sb[ks][vt], Oacc[tt][vt], 0, 0, 0); }
;             f32x4 P00 = {zz, zz, zz, zz}, P01 = {zz, zz, zz, zz}, P11 = {zz, zz, zz, zz};
; #pragma unroll
;             for (int ks = 0; ks < 2; ++ks) {
;                 const bf16x8 kA0 = *(const bf16x8*)(Kb + fr * HPT + 32 * ks + 8 * quad), kA1 = *(const bf16x8*)(Kb + (16 + fr) * HPT + 32 * ks + 8 * quad);
;                 const bf16x8 qB0 = *(const bf16x8*)(Qt + fr * HPT + 32 * ks + 8 * quad), qB1 = *(const bf16x8*)(Qt + (16 + fr) * HPT + 32 * ks + 8 * quad);
;                 P00 = __builtin_amdgcn_mfma_f32_16x16x32_bf16(kA0, qB0, P00, 0, 0, 0);
;                 P01 = __builtin_amdgcn_mfma_f32_16x16x32_bf16(kA0, qB1, P01, 0, 0, 0);
;                 P11 = __builtin_amdgcn_mfma_f32_16x16x32_bf16(kA1, qB1, P11, 0, 0, 0);
;             }
; #pragma unroll
	v_mul_f32_e32 v60, 0x3fb8aa3b, v60
	v_exp_f32_e32 v60, v60
	v_mov_b32_e32 v98, v65
	v_cvt_pk_bf16_f32 v61, v2, v3
	v_cvt_pk_bf16_f32 v62, v16, v17
	ds_write_b32 v134, v60 offset:13824
	s_waitcnt lgkmcnt(0)
	ds_read2_b64 v[110:113], v141 offset1:4
	ds_read2_b64 v[126:129], v141 offset0:8 offset1:12
	v_cvt_pk_bf16_f32 v60, v0, v1
	v_cvt_pk_bf16_f32 v63, v18, v19
	v_cvt_pk_bf16_f32 v70, v4, v5
	v_cvt_pk_bf16_f32 v71, v6, v7
	v_cvt_pk_bf16_f32 v72, v20, v21
	v_cvt_pk_bf16_f32 v73, v22, v23
	v_cvt_pk_bf16_f32 v78, v8, v9
	v_cvt_pk_bf16_f32 v79, v10, v11
	v_cvt_pk_bf16_f32 v80, v24, v25
	v_cvt_pk_bf16_f32 v81, v26, v27
	v_cvt_pk_bf16_f32 v86, v12, v13
	v_cvt_pk_bf16_f32 v87, v14, v15
	v_cvt_pk_bf16_f32 v88, v28, v29
	v_cvt_pk_bf16_f32 v89, v30, v31
	v_mov_b32_e32 v99, v98
	v_mov_b32_e32 v100, v98
	v_mov_b32_e32 v101, v98
	v_cvt_pk_bf16_f32 v74, v32, v33
	v_cvt_pk_bf16_f32 v75, v34, v35
	s_waitcnt lgkmcnt(1)
	v_mfma_f32_16x16x32_bf16 v[114:117], v[110:113], v[60:63], v[98:101]
	v_cvt_pk_bf16_f32 v76, v48, v49
	v_cvt_pk_bf16_f32 v77, v50, v51
	v_cvt_pk_bf16_f32 v82, v36, v37
	v_mfma_f32_16x16x32_bf16 v[118:121], v[110:113], v[70:73], v[98:101]
	v_cvt_pk_bf16_f32 v83, v38, v39
	v_cvt_pk_bf16_f32 v84, v52, v53
	v_cvt_pk_bf16_f32 v85, v54, v55
	v_mfma_f32_16x16x32_bf16 v[122:125], v[110:113], v[78:81], v[98:101]
	v_cvt_pk_bf16_f32 v90, v40, v41
	v_cvt_pk_bf16_f32 v91, v42, v43
	v_cvt_pk_bf16_f32 v92, v56, v57
	v_mfma_f32_16x16x32_bf16 v[110:113], v[110:113], v[86:89], v[98:101]
	v_cvt_pk_bf16_f32 v93, v58, v59
	v_cvt_pk_bf16_f32 v94, v44, v45
	v_cvt_pk_bf16_f32 v95, v46, v47
	v_cvt_pk_bf16_f32 v96, v66, v67
	v_cvt_pk_bf16_f32 v97, v68, v69
	v_add_u32_e32 v64, 0x800, v141
	s_waitcnt lgkmcnt(0)
	v_mfma_f32_16x16x32_bf16 v[114:117], v[126:129], v[74:77], v[114:117]
	s_add_i32 s36, s36, 1
	s_cmp_eq_u32 s36, 4
	v_mfma_f32_16x16x32_bf16 v[118:121], v[126:129], v[82:85], v[118:121]
	v_mfma_f32_16x16x32_bf16 v[122:125], v[126:129], v[90:93], v[122:125]
	v_mfma_f32_16x16x32_bf16 v[110:113], v[126:129], v[94:97], v[110:113]
	ds_read2_b64 v[126:129], v64 offset0:32 offset1:36
	s_waitcnt lgkmcnt(0)
	v_mfma_f32_16x16x32_bf16 v[60:63], v[126:129], v[60:63], v[98:101]
	v_mfma_f32_16x16x32_bf16 v[70:73], v[126:129], v[70:73], v[98:101]
	v_mfma_f32_16x16x32_bf16 v[78:81], v[126:129], v[78:81], v[98:101]
	v_mfma_f32_16x16x32_bf16 v[86:89], v[126:129], v[86:89], v[98:101]
	ds_read2_b64 v[126:129], v64 offset0:40 offset1:44
	s_waitcnt lgkmcnt(0)
	v_mfma_f32_16x16x32_bf16 v[74:77], v[126:129], v[74:77], v[60:63]
	v_mfma_f32_16x16x32_bf16 v[178:181], v[126:129], v[82:85], v[70:73]
	v_mfma_f32_16x16x32_bf16 v[78:81], v[126:129], v[90:93], v[78:81]
	v_mfma_f32_16x16x32_bf16 v[126:129], v[126:129], v[94:97], v[86:89]
	ds_read_b128 v[60:63], v138 offset:4608
	ds_read_b128 v[70:73], v138 offset:6912
	ds_read_b128 v[82:85], v138
	ds_read_b128 v[86:89], v138 offset:2304
	ds_read_b128 v[90:93], v138 offset:4672
	ds_read_b128 v[94:97], v138 offset:6976
	ds_read_b128 v[188:191], v138 offset:64
	ds_read_b128 v[230:233], v138 offset:2368
	s_waitcnt lgkmcnt(5)
	v_mfma_f32_16x16x32_bf16 v[82:85], v[60:63], v[82:85], v[98:101]
	s_waitcnt lgkmcnt(4)
	v_mfma_f32_16x16x32_bf16 v[70:73], v[70:73], v[86:89], v[98:101]
	s_waitcnt lgkmcnt(1)
	v_mfma_f32_16x16x32_bf16 v[82:85], v[90:93], v[188:191], v[82:85]
	s_waitcnt lgkmcnt(0)
	v_mfma_f32_16x16x32_bf16 v[70:73], v[94:97], v[230:233], v[70:73]
	v_mfma_f32_16x16x32_bf16 v[60:63], v[60:63], v[86:89], v[98:101]
	s_nop 4
	v_cndmask_b32_e64 v64, v85, 0, s[42:43]
	s_nop 0
	v_cndmask_b32_e64 v85, v73, 0, s[42:43]
	v_cndmask_b32_e64 v94, v72, 0, s[46:47]
	v_cndmask_b32_e64 v95, v71, 0, s[48:49]
	v_cndmask_b32_e64 v96, v70, 0, s[50:51]
	v_mfma_f32_16x16x32_bf16 v[70:73], v[90:93], v[230:233], v[60:63]
	v_cndmask_b32_e64 v84, v84, 0, s[46:47]
	v_cndmask_b32_e64 v83, v83, 0, s[48:49]
	v_cndmask_b32_e64 v82, v82, 0, s[50:51]
	v_cvt_pk_bf16_f32 v62, v82, v83
	v_cvt_pk_bf16_f32 v63, v84, v64
	v_mov_b32_e32 v64, v65
	s_nop 1
	v_cvt_pk_bf16_f32 v98, v70, v71
	v_cvt_pk_bf16_f32 v99, v72, v73
	ds_read_b64_tr_b16 v[72:73], v139 offset:11520
	ds_read_b64_tr_b16 v[70:71], v139 offset:9216
	ds_read_b64_tr_b16 v[90:91], v139 offset:9248
	v_cvt_pk_bf16_f32 v100, v96, v95
	v_cvt_pk_bf16_f32 v101, v94, v85
	s_waitcnt lgkmcnt(1)
	v_mfma_f32_16x16x32_bf16 v[82:85], v[62:65], v[70:73], v[114:117]
	ds_read_b64_tr_b16 v[92:93], v139 offset:11552
	ds_read_b64_tr_b16 v[94:95], v139 offset:9280
	ds_read_b64_tr_b16 v[96:97], v139 offset:11584
	ds_read_b64_tr_b16 v[114:115], v139 offset:9312
	ds_read_b64_tr_b16 v[116:117], v139 offset:11616
	v_mfma_f32_16x16x32_bf16 v[70:73], v[98:101], v[70:73], v[74:77]
	s_waitcnt lgkmcnt(4)
	v_mfma_f32_16x16x32_bf16 v[86:89], v[62:65], v[90:93], v[118:121]
	v_mfma_f32_16x16x32_bf16 v[74:77], v[98:101], v[90:93], v[178:181]
	s_waitcnt lgkmcnt(2)
	v_mfma_f32_16x16x32_bf16 v[90:93], v[62:65], v[94:97], v[122:125]
	v_mfma_f32_16x16x32_bf16 v[78:81], v[98:101], v[94:97], v[78:81]
	s_waitcnt lgkmcnt(0)
	v_mfma_f32_16x16x32_bf16 v[94:97], v[62:65], v[114:117], v[110:113]
	v_add_u32_e32 v64, v137, v136
	v_mfma_f32_16x16x32_bf16 v[60:63], v[98:101], v[114:117], v[126:129]
	ds_read_b64_tr_b16 v[98:99], v140 offset:9216
	ds_read_b64_tr_b16 v[100:101], v140 offset:9792
	ds_read_b64_tr_b16 v[110:111], v140 offset:9248
	ds_read_b64_tr_b16 v[112:113], v140 offset:9824
	ds_read_b64_tr_b16 v[114:115], v140 offset:9280
	ds_read_b64_tr_b16 v[116:117], v140 offset:9856
	ds_read_b64_tr_b16 v[118:119], v140 offset:9312
	ds_read_b64_tr_b16 v[120:121], v140 offset:9888
	ds_read_b64_tr_b16 v[124:125], v140 offset:5184
	ds_read_b64_tr_b16 v[122:123], v140 offset:4608
	ds_read_b64_tr_b16 v[126:127], v140 offset:4640
	ds_read_b128 v[128:131], v64 offset:13824
	s_waitcnt lgkmcnt(2)
; __device__ __forceinline__ float bf2f(bf16_t b) { return __uint_as_float(((unsigned)b) << 16); }
; template <int MODE>
; __device__ __forceinline__ void hgrn_mfma(const Ctx& C, int l, int z, int b, int hd, int c, f32x4 (&Sacc)[4][4], float& dectot, unsigned char* wl, float lb) {
;     ...
;             for (int kt = 0; kt < 4; ++kt) { const bf16_t* kp = Kb + (8 * quad + (fr >> 2)) * HPT + 16 * kt + 4 * (fr & 3);
;                 union { bf16x8 v; s16x4 h[2]; } ka; ka.h[0] = lds_tr(kp); ka.h[1] = lds_tr(kp + 4 * HPT);
;                 const f32x4 d4 = *(const f32x4*)(dl + 16 * kt + 4 * quad);
; #pragma unroll
;                 for (int vt = 0; vt < 4; ++vt) { Sacc[kt][vt] = __builtin_amdgcn_mfma_f32_16x16x32_bf16(ka.v, vB[vt], Sacc[kt][vt], 0, 0, 0); Sacc[kt][vt] *= d4; } }
;     ...
;                 bf16_t tmpv[4][4], gtv[4][4];
; #pragma unroll
;                 for (int r = 0; r < 4; ++r) { const int st = c * 128 + sc * 32 + 16 * tt + 4 * quad + r; const int tq = z ? 4095 - st : st;
;                     const size_t tok = (size_t)(b * SEQ + tq); const bf16_t* yp = ya + tok * 256 + hd * 64 + fr; const bf16_t* gp = pa + tok * 1280 + 1024 + hd * 64 + fr;
; #pragma unroll
;                     for (int vt = 0; vt < 4; ++vt) { tmpv[r][vt] = yp[16 * vt]; gtv[r][vt] = gp[16 * vt]; } }
; #pragma unroll
;                 for (int r = 0; r < 4; ++r) { const int st = c * 128 + sc * 32 + 16 * tt + 4 * quad + r; const int tq = z ? 4095 - st : st;
;                     bf16_t* yp = ya + (size_t)(b * SEQ + tq) * 256 + hd * 64 + fr;
;                     float o[4]; float ss = 0.f;
; #pragma unroll
;                     for (int vt = 0; vt < 4; ++vt) { o[vt] = Oacc[tt][vt][r] + bf2f(tmpv[r][vt]); ss += o[vt] * o[vt]; }
;                     ss += __shfl_xor(ss, 1); ss += __shfl_xor(ss, 2); ss += __shfl_xor(ss, 4); ss += __shfl_xor(ss, 8);
	v_mfma_f32_16x16x32_bf16 v[0:3], v[122:125], v[98:101], v[0:3]
	v_mfma_f32_16x16x32_bf16 v[4:7], v[122:125], v[110:113], v[4:7]
	s_waitcnt lgkmcnt(0)
	s_nop 5
	v_pk_mul_f32 v[0:1], v[128:129], v[0:1]
	v_pk_mul_f32 v[2:3], v[130:131], v[2:3]
	v_mfma_f32_16x16x32_bf16 v[8:11], v[122:125], v[114:117], v[8:11]
	v_mfma_f32_16x16x32_bf16 v[12:15], v[122:125], v[118:121], v[12:15]
	v_mul_f32_e64 v4, v128, v4
	v_mul_f32_e64 v5, v129, v5
	s_nop 4
	v_pk_mul_f32 v[8:9], v[128:129], v[8:9]
	v_pk_mul_f32 v[6:7], v[130:131], v[6:7]
	v_pk_mul_f32 v[10:11], v[130:131], v[10:11]
	v_pk_mul_f32 v[12:13], v[128:129], v[12:13]
	ds_read_b64_tr_b16 v[128:129], v140 offset:5216
	ds_read_b128 v[122:125], v64 offset:13888
	s_waitcnt lgkmcnt(1)
	v_mfma_f32_16x16x32_bf16 v[16:19], v[126:129], v[98:101], v[16:19]
	v_mul_f32_e64 v14, v130, v14
	v_mul_f32_e64 v15, v131, v15
	v_mfma_f32_16x16x32_bf16 v[20:23], v[126:129], v[110:113], v[20:23]
	s_waitcnt lgkmcnt(0)
	s_nop 3
	v_pk_mul_f32 v[18:19], v[124:125], v[18:19]
	v_pk_mul_f32 v[16:17], v[122:123], v[16:17]
	v_mfma_f32_16x16x32_bf16 v[24:27], v[126:129], v[114:117], v[24:27]
	v_mfma_f32_16x16x32_bf16 v[28:31], v[126:129], v[118:121], v[28:31]
	v_mul_f32_e64 v22, v124, v22
	v_mul_f32_e64 v23, v125, v23
	v_pk_mul_f32 v[20:21], v[122:123], v[20:21]
	s_nop 3
	v_pk_mul_f32 v[26:27], v[124:125], v[26:27]
	v_pk_mul_f32 v[24:25], v[122:123], v[24:25]
	v_pk_mul_f32 v[30:31], v[124:125], v[30:31]
	v_pk_mul_f32 v[28:29], v[122:123], v[28:29]
	ds_read_b64_tr_b16 v[122:123], v140 offset:4672
	ds_read_b64_tr_b16 v[124:125], v140 offset:5248
	ds_read_b128 v[126:129], v64 offset:13952
	s_waitcnt lgkmcnt(1)
	v_mfma_f32_16x16x32_bf16 v[32:35], v[122:125], v[98:101], v[32:35]
	v_mfma_f32_16x16x32_bf16 v[36:39], v[122:125], v[110:113], v[36:39]
	s_waitcnt lgkmcnt(0)
	s_nop 5
	v_pk_mul_f32 v[34:35], v[128:129], v[34:35]
	v_pk_mul_f32 v[32:33], v[126:127], v[32:33]
	v_mfma_f32_16x16x32_bf16 v[40:43], v[122:125], v[114:117], v[40:43]
	v_mfma_f32_16x16x32_bf16 v[44:47], v[122:125], v[118:121], v[44:47]
	v_mul_f32_e64 v38, v128, v38
	v_mul_f32_e64 v39, v129, v39
	v_pk_mul_f32 v[36:37], v[126:127], v[36:37]
	s_nop 3
	v_pk_mul_f32 v[42:43], v[128:129], v[42:43]
	v_pk_mul_f32 v[40:41], v[126:127], v[40:41]
	v_pk_mul_f32 v[46:47], v[128:129], v[46:47]
	v_pk_mul_f32 v[44:45], v[126:127], v[44:45]
	ds_read_b64_tr_b16 v[122:123], v140 offset:4704
	ds_read_b64_tr_b16 v[124:125], v140 offset:5280
	ds_read_b128 v[126:129], v64 offset:14016
	s_waitcnt lgkmcnt(1)
	v_mfma_f32_16x16x32_bf16 v[48:51], v[122:125], v[98:101], v[48:51]
	v_and_b32_e32 v99, 64, v221
	v_xor_b32_e32 v64, 1, v221
	v_add_u32_e32 v99, 64, v99
	v_cmp_lt_i32_e32 vcc, v64, v99
	v_add_u32_e32 v98, s75, v214
	v_mfma_f32_16x16x32_bf16 v[56:59], v[122:125], v[114:117], v[56:59]
	v_cndmask_b32_e32 v64, v221, v64, vcc
	v_lshlrev_b32_e32 v231, 2, v64
	v_xor_b32_e32 v64, 2, v221
	v_cmp_lt_i32_e32 vcc, v64, v99
	v_mfma_f32_16x16x32_bf16 v[52:55], v[122:125], v[110:113], v[52:55]
	v_or_b32_e32 v116, 3, v98
	v_cndmask_b32_e32 v64, v221, v64, vcc
	v_lshlrev_b32_e32 v230, 2, v64
	v_xor_b32_e32 v64, 4, v221
	v_cmp_lt_i32_e32 vcc, v64, v99
	v_mfma_f32_16x16x32_bf16 v[66:69], v[122:125], v[118:121], v[66:69]
	v_ashrrev_i32_e32 v117, 31, v116
	v_cndmask_b32_e32 v64, v221, v64, vcc
	v_lshlrev_b32_e32 v229, 2, v64
	v_xor_b32_e32 v64, 8, v221
	v_cmp_lt_i32_e32 vcc, v64, v99
	v_ashrrev_i32_e32 v99, 31, v98
	v_lshlrev_b64 v[100:101], 9, v[98:99]
	v_lshl_add_u64 v[114:115], v[106:107], 0, v[100:101]
	v_or_b32_e32 v100, 1, v98
	v_ashrrev_i32_e32 v101, 31, v100
	v_lshlrev_b64 v[110:111], 9, v[100:101]
	v_mad_i64_i32 v[124:125], s[0:1], v100, s62, v[108:109]
	v_or_b32_e32 v100, 2, v98
	v_ashrrev_i32_e32 v101, 31, v100
	v_lshl_add_u64 v[112:113], v[106:107], 0, v[110:111]
	v_lshlrev_b64 v[110:111], 9, v[100:101]
	v_mad_i64_i32 v[120:121], s[0:1], v100, s62, v[108:109]
	v_lshlrev_b64 v[100:101], 9, v[116:117]
	s_waitcnt lgkmcnt(0)
	v_pk_mul_f32 v[48:49], v[126:127], v[48:49]
	v_pk_mul_f32 v[52:53], v[126:127], v[52:53]
	v_pk_mul_f32 v[56:57], v[126:127], v[56:57]
	v_pk_mul_f32 v[66:67], v[126:127], v[66:67]
	v_mad_i64_i32 v[126:127], s[0:1], v98, s62, v[108:109]
	v_lshl_add_u64 v[110:111], v[106:107], 0, v[110:111]
	v_lshl_add_u64 v[100:101], v[106:107], 0, v[100:101]
	global_load_ushort v118, v[114:115], off
	global_load_ushort v119, v[114:115], off offset:32
	global_load_ushort v130, v[114:115], off offset:64
	global_load_ushort v131, v[114:115], off offset:96
	global_load_ushort v244, v[112:113], off
	global_load_ushort v245, v[112:113], off offset:32
	global_load_ushort v242, v[112:113], off offset:64
	global_load_ushort v243, v[112:113], off offset:96
	global_load_ushort v237, v[110:111], off
	global_load_ushort v238, v[110:111], off offset:32
	global_load_ushort v235, v[110:111], off offset:64
	global_load_ushort v236, v[110:111], off offset:96
	global_load_ushort v233, v[100:101], off
	global_load_ushort v234, v[100:101], off offset:32
	global_load_ushort v99, v[100:101], off offset:64
	global_load_ushort v232, v[100:101], off offset:96
	v_mov_b32_e32 v122, v82
	global_load_ushort v82, v[126:127], off offset:2048
	v_mov_b32_e32 v123, v86
	v_cndmask_b32_e32 v64, v221, v64, vcc
	v_pk_mul_f32 v[50:51], v[128:129], v[50:51]
	v_pk_mul_f32 v[54:55], v[128:129], v[54:55]
	v_pk_mul_f32 v[58:59], v[128:129], v[58:59]
	v_pk_mul_f32 v[68:69], v[128:129], v[68:69]
	v_lshlrev_b32_e32 v64, 2, v64
	v_mad_i64_i32 v[116:117], s[0:1], v116, s62, v[108:109]
	s_waitcnt vmcnt(16)
	v_lshlrev_b32_e32 v118, 16, v118
	s_waitcnt vmcnt(15)
	v_lshlrev_b32_e32 v119, 16, v119
	v_pk_add_f32 v[122:123], v[122:123], v[118:119]
	s_waitcnt vmcnt(14)
; __device__ __forceinline__ bf16_t f2bf(float f) { return (bf16_t)(cvt_pk_bf16(f, 0.f) & 0xffffu); }
; __device__ __forceinline__ float bf2f(bf16_t b) { return __uint_as_float(((unsigned)b) << 16); }
; __device__ __forceinline__ float sigmoidf_(float x) { return 1.0f / (1.0f + __expf(-x)); }
; __device__ __forceinline__ float siluf_(float x) { return x * sigmoidf_(x); }
; template <int MODE>
; __device__ __forceinline__ void hgrn_mfma(const Ctx& C, int l, int z, int b, int hd, int c, f32x4 (&Sacc)[4][4], float& dectot, unsigned char* wl, float lb) {
;     ...
;                 for (int r = 0; r < 4; ++r) { const int st = c * 128 + sc * 32 + 16 * tt + 4 * quad + r; const int tq = z ? 4095 - st : st;
;                     bf16_t* yp = ya + (size_t)(b * SEQ + tq) * 256 + hd * 64 + fr;
;                     float o[4]; float ss = 0.f;
; #pragma unroll
;                     for (int vt = 0; vt < 4; ++vt) { o[vt] = Oacc[tt][vt][r] + bf2f(tmpv[r][vt]); ss += o[vt] * o[vt]; }
;                     ss += __shfl_xor(ss, 1); ss += __shfl_xor(ss, 2); ss += __shfl_xor(ss, 4); ss += __shfl_xor(ss, 8);
;                     const float rs = rsqrtf(ss * (1.f / 64.f) + 1e-6f);
; #pragma unroll
;                     for (int vt = 0; vt < 4; ++vt) yp[16 * vt] = f2bf(o[vt] * rs * gnv[vt] * siluf_(bf2f(gtv[r][vt]))); }
	v_lshlrev_b32_e32 v118, 16, v130
	v_mov_b32_e32 v130, v90
	s_waitcnt vmcnt(13)
	v_lshlrev_b32_e32 v119, 16, v131
	v_mov_b32_e32 v131, v94
	v_pk_mul_f32 v[128:129], v[122:123], v[122:123]
	s_waitcnt vmcnt(0)
	v_lshlrev_b32_e32 v82, 16, v82
	v_mul_f32_e32 v86, 0xbfb8aa3b, v82
	v_exp_f32_e32 v86, v86
	v_pk_add_f32 v[118:119], v[130:131], v[118:119]
	v_add_f32_e32 v86, 1.0, v86
	v_pk_mul_f32 v[130:131], v[118:119], v[118:119]
	v_rcp_f32_e32 v86, v86
	s_nop 0
	v_mul_f32_e32 v246, v86, v82
	global_load_ushort v82, v[126:127], off offset:2080
	s_waitcnt vmcnt(0)
	v_lshlrev_b32_e32 v82, 16, v82
	v_mul_f32_e32 v86, 0xbfb8aa3b, v82
	v_exp_f32_e32 v86, v86
	s_nop 0
	v_add_f32_e32 v86, 1.0, v86
	s_nop 0
	v_rcp_f32_e32 v86, v86
	s_nop 0
	v_mul_f32_e32 v239, v86, v82
	global_load_ushort v82, v[126:127], off offset:2112
	s_waitcnt vmcnt(0)
	v_lshlrev_b32_e32 v82, 16, v82
	v_mul_f32_e32 v86, 0xbfb8aa3b, v82
	v_exp_f32_e32 v86, v86
	s_nop 0
	v_add_f32_e32 v86, 1.0, v86
	s_nop 0
	v_rcp_f32_e32 v86, v86
	s_nop 0
	v_mul_f32_e32 v240, v86, v82
	global_load_ushort v82, v[126:127], off offset:2144
	s_waitcnt vmcnt(0)
	v_lshlrev_b32_e32 v82, 16, v82
	v_mul_f32_e32 v86, 0xbfb8aa3b, v82
	v_exp_f32_e32 v86, v86
	s_nop 0
	v_add_f32_e32 v86, 1.0, v86
	s_nop 0
	v_rcp_f32_e32 v86, v86
	s_nop 0
	v_mul_f32_e32 v241, v86, v82
	v_lshlrev_b32_e32 v127, 16, v245
	v_lshlrev_b32_e32 v126, 16, v244
	v_mov_b32_e32 v86, v83
	v_pk_add_f32 v[126:127], v[86:87], v[126:127]
	v_lshlrev_b32_e32 v87, 16, v243
	v_lshlrev_b32_e32 v86, 16, v242
	v_mov_b32_e32 v94, v91
	v_pk_mul_f32 v[82:83], v[126:127], v[126:127]
	v_pk_add_f32 v[86:87], v[94:95], v[86:87]
	v_mov_b32_e32 v94, v82
	v_pk_mul_f32 v[90:91], v[86:87], v[86:87]
	v_mov_b32_e32 v95, v128
	v_mov_b32_e32 v128, v83
	v_pk_add_f32 v[82:83], v[94:95], v[128:129]
	v_mov_b32_e32 v94, v90
	v_mov_b32_e32 v95, v130
	v_pk_add_f32 v[82:83], v[82:83], v[94:95]
	v_mov_b32_e32 v130, v91
	v_pk_add_f32 v[82:83], v[82:83], v[130:131]
	ds_bpermute_b32 v91, v231, v83
	ds_bpermute_b32 v90, v231, v82
	s_waitcnt lgkmcnt(0)
	v_pk_add_f32 v[82:83], v[82:83], v[90:91]
	ds_bpermute_b32 v91, v230, v83
	ds_bpermute_b32 v90, v230, v82
	s_waitcnt lgkmcnt(0)
	v_pk_add_f32 v[82:83], v[82:83], v[90:91]
	ds_bpermute_b32 v91, v229, v83
	ds_bpermute_b32 v90, v229, v82
	s_waitcnt lgkmcnt(0)
	v_pk_add_f32 v[82:83], v[82:83], v[90:91]
	ds_bpermute_b32 v91, v64, v83
	ds_bpermute_b32 v90, v64, v82
	s_waitcnt lgkmcnt(0)
	v_pk_add_f32 v[90:91], v[82:83], v[90:91]
	v_mov_b64_e32 v[82:83], s[66:67]
	v_pk_fma_f32 v[90:91], v[90:91], s[2:3], v[82:83] op_sel_hi:[1,0,0]
	s_nop 0
	v_mul_f32_e32 v94, 0x4b800000, v91
	v_cmp_gt_f32_e64 s[0:1], s54, v91
	v_cmp_gt_f32_e32 vcc, s54, v90
	s_nop 0
	v_cndmask_b32_e64 v91, v91, v94, s[0:1]
	v_rsq_f32_e32 v91, v91
	s_nop 0
	v_mul_f32_e32 v94, 0x45800000, v91
	v_cndmask_b32_e64 v91, v91, v94, s[0:1]
	v_mul_f32_e32 v94, v122, v91
	global_load_ushort v95, v[124:125], off offset:2048
	global_load_ushort v128, v[124:125], off offset:2080
	global_load_ushort v129, v[124:125], off offset:2112
	global_load_ushort v130, v[124:125], off offset:2144
	global_load_ushort v131, v[120:121], off offset:2048
	global_load_ushort v178, v[120:121], off offset:2080
	s_nop 0
	global_load_ushort v125, v[120:121], off offset:2112
	global_load_ushort v124, v[120:121], off offset:2144
	global_load_ushort v122, v[116:117], off offset:2048
	s_nop 0
	global_load_ushort v121, v[116:117], off offset:2080
	global_load_ushort v120, v[116:117], off offset:2112
	s_nop 0
	global_load_ushort v116, v[116:117], off offset:2144
	v_mul_f32_e32 v94, v209, v94
	v_mul_f32_e32 v94, v246, v94
	v_cvt_pk_bf16_f32 v94, v94, s0
	global_store_short v[114:115], v94, off
	v_mul_f32_e32 v94, v123, v91
	v_mul_f32_e32 v94, v210, v94
	v_mul_f32_e32 v94, v239, v94
	v_cvt_pk_bf16_f32 v94, v94, s0
	global_store_short v[114:115], v94, off offset:32
	v_mul_f32_e32 v94, v118, v91
	v_mul_f32_e32 v94, v211, v94
	v_mul_f32_e32 v94, v240, v94
	v_cvt_pk_bf16_f32 v94, v94, s0
	global_store_short v[114:115], v94, off offset:64
	v_mul_f32_e32 v91, v119, v91
	v_mul_f32_e32 v91, v212, v91
	v_mul_f32_e32 v91, v241, v91
	v_cvt_pk_bf16_f32 v91, v91, s0
	global_store_short v[114:115], v91, off offset:96
	v_mul_f32_e32 v91, 0x4b800000, v90
	v_cndmask_b32_e32 v90, v90, v91, vcc
	v_rsq_f32_e32 v90, v90
	s_waitcnt vmcnt(15)
	v_lshlrev_b32_e32 v94, 16, v95
	v_mul_f32_e32 v95, 0xbfb8aa3b, v94
	v_exp_f32_e32 v95, v95
	v_mul_f32_e32 v91, 0x45800000, v90
	v_cndmask_b32_e32 v90, v90, v91, vcc
	v_mul_f32_e32 v91, v126, v90
	v_add_f32_e32 v95, 1.0, v95
	v_mul_f32_e32 v91, v209, v91
	v_mul_f32_e32 v86, v86, v90
	v_mul_f32_e32 v86, v211, v86
	v_rcp_f32_e32 v95, v95
	s_nop 0
	v_mul_f32_e32 v94, v95, v94
	v_mul_f32_e32 v91, v94, v91
	s_waitcnt vmcnt(14)
	v_lshlrev_b32_e32 v94, 16, v128
	v_mul_f32_e32 v95, 0xbfb8aa3b, v94
	v_exp_f32_e32 v95, v95
	v_cvt_pk_bf16_f32 v91, v91, s0
	global_store_short v[112:113], v91, off
	v_mul_f32_e32 v91, v127, v90
	v_add_f32_e32 v95, 1.0, v95
	v_mul_f32_e32 v91, v210, v91
	v_rcp_f32_e32 v95, v95
	s_nop 0
	v_mul_f32_e32 v94, v95, v94
	v_mul_f32_e32 v91, v94, v91
	v_cvt_pk_bf16_f32 v91, v91, s0
	global_store_short v[112:113], v91, off offset:32
	s_waitcnt vmcnt(15)
	v_lshlrev_b32_e32 v91, 16, v129
	v_mul_f32_e32 v94, 0xbfb8aa3b, v91
	v_exp_f32_e32 v94, v94
	s_nop 0
	v_add_f32_e32 v94, 1.0, v94
	s_nop 0
	v_rcp_f32_e32 v94, v94
	s_nop 0
	v_mul_f32_e32 v91, v94, v91
	v_mul_f32_e32 v86, v91, v86
	v_cvt_pk_bf16_f32 v86, v86, s0
	global_store_short v[112:113], v86, off offset:64
	v_mul_f32_e32 v86, v87, v90
	s_waitcnt vmcnt(15)
; __device__ __forceinline__ bf16_t f2bf(float f) { return (bf16_t)(cvt_pk_bf16(f, 0.f) & 0xffffu); }
; __device__ __forceinline__ float bf2f(bf16_t b) { return __uint_as_float(((unsigned)b) << 16); }
; __device__ __forceinline__ float sigmoidf_(float x) { return 1.0f / (1.0f + __expf(-x)); }
; __device__ __forceinline__ float siluf_(float x) { return x * sigmoidf_(x); }
; template <int MODE>
; __device__ __forceinline__ void hgrn_mfma(const Ctx& C, int l, int z, int b, int hd, int c, f32x4 (&Sacc)[4][4], float& dectot, unsigned char* wl, float lb) {
;     ...
;                 for (int r = 0; r < 4; ++r) { const int st = c * 128 + sc * 32 + 16 * tt + 4 * quad + r; const int tq = z ? 4095 - st : st;
;                     bf16_t* yp = ya + (size_t)(b * SEQ + tq) * 256 + hd * 64 + fr;
;                     float o[4]; float ss = 0.f;
; #pragma unroll
;                     for (int vt = 0; vt < 4; ++vt) { o[vt] = Oacc[tt][vt][r] + bf2f(tmpv[r][vt]); ss += o[vt] * o[vt]; }
;                     ss += __shfl_xor(ss, 1); ss += __shfl_xor(ss, 2); ss += __shfl_xor(ss, 4); ss += __shfl_xor(ss, 8);
;                     const float rs = rsqrtf(ss * (1.f / 64.f) + 1e-6f);
; #pragma unroll
;                     for (int vt = 0; vt < 4; ++vt) yp[16 * vt] = f2bf(o[vt] * rs * gnv[vt] * siluf_(bf2f(gtv[r][vt]))); }
	v_lshlrev_b32_e32 v87, 16, v130
	v_mul_f32_e32 v90, 0xbfb8aa3b, v87
	v_exp_f32_e32 v90, v90
	v_mul_f32_e32 v86, v212, v86
	v_add_f32_e32 v90, 1.0, v90
	s_nop 0
	v_rcp_f32_e32 v90, v90
	s_nop 0
	v_mul_f32_e32 v87, v90, v87
	v_mov_b32_e32 v90, v84
	s_waitcnt vmcnt(14)
	v_lshlrev_b32_e32 v84, 16, v131
	v_mov_b32_e32 v91, v88
	v_mul_f32_e32 v88, 0xbfb8aa3b, v84
	v_exp_f32_e32 v88, v88
	v_mul_f32_e32 v86, v87, v86
	v_cvt_pk_bf16_f32 v86, v86, s0
	v_mov_b32_e32 v94, v92
	v_add_f32_e32 v88, 1.0, v88
	v_mov_b32_e32 v95, v96
	global_store_short v[112:113], v86, off offset:96
	v_lshlrev_b32_e32 v87, 16, v238
	v_lshlrev_b32_e32 v86, 16, v237
	v_rcp_f32_e32 v88, v88
	s_nop 0
	v_mul_f32_e32 v117, v88, v84
	s_waitcnt vmcnt(14)
	v_lshlrev_b32_e32 v84, 16, v178
	v_mul_f32_e32 v88, 0xbfb8aa3b, v84
	v_exp_f32_e32 v88, v88
	v_pk_add_f32 v[90:91], v[90:91], v[86:87]
	v_lshlrev_b32_e32 v87, 16, v236
	v_lshlrev_b32_e32 v86, 16, v235
	v_add_f32_e32 v88, 1.0, v88
	v_pk_mul_f32 v[112:113], v[90:91], v[90:91]
	v_pk_add_f32 v[86:87], v[94:95], v[86:87]
	v_rcp_f32_e32 v88, v88
	s_nop 0
	v_mul_f32_e32 v118, v88, v84
	s_waitcnt vmcnt(13)
	v_lshlrev_b32_e32 v84, 16, v125
	v_mul_f32_e32 v88, 0xbfb8aa3b, v84
	v_exp_f32_e32 v88, v88
	v_pk_mul_f32 v[94:95], v[86:87], v[86:87]
	v_add_f32_e32 v88, 1.0, v88
	s_nop 0
	v_rcp_f32_e32 v88, v88
	s_nop 0
	v_mul_f32_e32 v119, v88, v84
	s_waitcnt vmcnt(12)
	v_lshlrev_b32_e32 v84, 16, v124
	v_mul_f32_e32 v88, 0xbfb8aa3b, v84
	v_exp_f32_e32 v88, v88
	s_nop 0
	v_add_f32_e32 v88, 1.0, v88
	s_nop 0
	v_rcp_f32_e32 v88, v88
	s_nop 0
	v_mul_f32_e32 v123, v88, v84
	v_lshlrev_b32_e32 v115, 16, v234
	v_lshlrev_b32_e32 v114, 16, v233
	v_mov_b32_e32 v88, v85
	v_pk_add_f32 v[88:89], v[88:89], v[114:115]
	v_lshlrev_b32_e32 v85, 16, v232
	v_lshlrev_b32_e32 v84, 16, v99
	v_mov_b32_e32 v96, v93
	v_pk_mul_f32 v[114:115], v[88:89], v[88:89]
	v_pk_add_f32 v[84:85], v[96:97], v[84:85]
	v_mov_b32_e32 v96, v114
	v_pk_mul_f32 v[92:93], v[84:85], v[84:85]
	v_mov_b32_e32 v97, v112
	v_mov_b32_e32 v112, v115
	v_pk_add_f32 v[96:97], v[96:97], v[112:113]
	v_mov_b32_e32 v112, v92
	v_mov_b32_e32 v113, v94
	v_pk_add_f32 v[96:97], v[96:97], v[112:113]
	v_mov_b32_e32 v94, v93
	v_pk_add_f32 v[92:93], v[96:97], v[94:95]
	ds_bpermute_b32 v95, v231, v93
	ds_bpermute_b32 v94, v231, v92
	v_mov_b32_e32 v99, v74
	s_waitcnt lgkmcnt(0)
	v_pk_add_f32 v[92:93], v[92:93], v[94:95]
	ds_bpermute_b32 v95, v230, v93
	ds_bpermute_b32 v94, v230, v92
	s_waitcnt lgkmcnt(0)
	v_pk_add_f32 v[92:93], v[92:93], v[94:95]
	ds_bpermute_b32 v95, v229, v93
	ds_bpermute_b32 v94, v229, v92
	s_waitcnt lgkmcnt(0)
	v_pk_add_f32 v[92:93], v[92:93], v[94:95]
	ds_bpermute_b32 v95, v64, v93
	ds_bpermute_b32 v94, v64, v92
	s_waitcnt lgkmcnt(0)
	v_pk_add_f32 v[92:93], v[92:93], v[94:95]
	s_nop 0
	v_pk_fma_f32 v[92:93], v[92:93], s[2:3], v[82:83] op_sel_hi:[1,0,0]
	s_nop 0
	v_mul_f32_e32 v94, 0x4b800000, v93
	v_cmp_gt_f32_e64 s[0:1], s54, v93
	v_cmp_gt_f32_e32 vcc, s54, v92
	s_nop 0
	v_cndmask_b32_e64 v93, v93, v94, s[0:1]
	v_rsq_f32_e32 v93, v93
	s_nop 0
	v_mul_f32_e32 v94, 0x45800000, v93
	v_cndmask_b32_e64 v93, v93, v94, s[0:1]
	v_mul_f32_e32 v86, v86, v93
	v_mul_f32_e32 v86, v211, v86
	v_mul_f32_e32 v86, v119, v86
	v_cvt_pk_bf16_f32 v86, v86, s0
	global_store_short v[110:111], v86, off offset:64
	v_mul_f32_e32 v86, v87, v93
	v_mul_f32_e32 v86, v212, v86
	v_mul_f32_e32 v86, v123, v86
	v_cvt_pk_bf16_f32 v86, v86, s0
	global_store_short v[110:111], v86, off offset:96
	v_mul_f32_e32 v86, 0x4b800000, v92
	v_mul_f32_e32 v90, v90, v93
	v_cndmask_b32_e32 v86, v92, v86, vcc
	v_mul_f32_e32 v90, v209, v90
	v_rsq_f32_e32 v86, v86
	v_mul_f32_e32 v90, v117, v90
	v_cvt_pk_bf16_f32 v90, v90, s0
	global_store_short v[110:111], v90, off
	v_mul_f32_e32 v90, v91, v93
	v_mul_f32_e32 v90, v210, v90
	v_mul_f32_e32 v87, 0x45800000, v86
	v_mul_f32_e32 v90, v118, v90
	v_cndmask_b32_e32 v86, v86, v87, vcc
	v_cvt_pk_bf16_f32 v90, v90, s0
	v_mul_f32_e32 v87, v88, v86
	s_waitcnt vmcnt(14)
	v_lshlrev_b32_e32 v88, 16, v122
	global_store_short v[110:111], v90, off offset:32
	v_mul_f32_e32 v90, 0xbfb8aa3b, v88
	v_exp_f32_e32 v90, v90
	v_mul_f32_e32 v87, v209, v87
	v_mul_f32_e32 v84, v84, v86
	v_mul_f32_e32 v84, v211, v84
	v_add_f32_e32 v90, 1.0, v90
	s_nop 0
	v_rcp_f32_e32 v90, v90
	s_nop 0
	v_mul_f32_e32 v88, v90, v88
	v_mul_f32_e32 v87, v88, v87
	v_cvt_pk_bf16_f32 v87, v87, s0
	s_waitcnt vmcnt(14)
	v_lshlrev_b32_e32 v88, 16, v121
	global_store_short v[100:101], v87, off
	v_mul_f32_e32 v87, v89, v86
	v_mul_f32_e32 v89, 0xbfb8aa3b, v88
	v_exp_f32_e32 v89, v89
	v_mul_f32_e32 v87, v210, v87
	v_add_f32_e32 v89, 1.0, v89
	s_nop 0
	v_rcp_f32_e32 v89, v89
	s_nop 0
	v_mul_f32_e32 v88, v89, v88
	v_mul_f32_e32 v87, v88, v87
	v_cvt_pk_bf16_f32 v87, v87, s0
	global_store_short v[100:101], v87, off offset:32
	s_waitcnt vmcnt(15)
	v_lshlrev_b32_e32 v87, 16, v120
	v_mul_f32_e32 v88, 0xbfb8aa3b, v87
	v_exp_f32_e32 v88, v88
	s_nop 0
	v_add_f32_e32 v88, 1.0, v88
	s_nop 0
	v_rcp_f32_e32 v88, v88
	s_nop 0
	v_mul_f32_e32 v87, v88, v87
	v_mul_f32_e32 v84, v87, v84
	v_cvt_pk_bf16_f32 v84, v84, s0
	global_store_short v[100:101], v84, off offset:64
	v_mul_f32_e32 v84, v85, v86
	s_waitcnt vmcnt(15)
; __device__ __forceinline__ bf16_t f2bf(float f) { return (bf16_t)(cvt_pk_bf16(f, 0.f) & 0xffffu); }
; __device__ __forceinline__ float bf2f(bf16_t b) { return __uint_as_float(((unsigned)b) << 16); }
; __device__ __forceinline__ float sigmoidf_(float x) { return 1.0f / (1.0f + __expf(-x)); }
; __device__ __forceinline__ float siluf_(float x) { return x * sigmoidf_(x); }
; template <int MODE>
; __device__ __forceinline__ void hgrn_mfma(const Ctx& C, int l, int z, int b, int hd, int c, f32x4 (&Sacc)[4][4], float& dectot, unsigned char* wl, float lb) {
;     ...
;                 for (int r = 0; r < 4; ++r) { const int st = c * 128 + sc * 32 + 16 * tt + 4 * quad + r; const int tq = z ? 4095 - st : st;
;                     bf16_t* yp = ya + (size_t)(b * SEQ + tq) * 256 + hd * 64 + fr;
; #pragma unroll
;                     for (int vt = 0; vt < 4; ++vt) yp[16 * vt] = f2bf(Oacc[tt][vt][r]); }
;         }
;         if (MODE == 2) {
; #pragma unroll
;             for (int tt = 0; tt < 2; ++tt) {
;                 bf16_t tmpv[4][4], gtv[4][4];
; #pragma unroll
;                 for (int r = 0; r < 4; ++r) { const int st = c * 128 + sc * 32 + 16 * tt + 4 * quad + r; const int tq = z ? 4095 - st : st;
;                     const size_t tok = (size_t)(b * SEQ + tq); const bf16_t* yp = ya + tok * 256 + hd * 64 + fr; const bf16_t* gp = pa + tok * 1280 + 1024 + hd * 64 + fr;
; #pragma unroll
;                     for (int vt = 0; vt < 4; ++vt) { tmpv[r][vt] = yp[16 * vt]; gtv[r][vt] = gp[16 * vt]; } }
; #pragma unroll
;                 for (int r = 0; r < 4; ++r) { const int st = c * 128 + sc * 32 + 16 * tt + 4 * quad + r; const int tq = z ? 4095 - st : st;
;                     bf16_t* yp = ya + (size_t)(b * SEQ + tq) * 256 + hd * 64 + fr;
;                     float o[4]; float ss = 0.f;
; #pragma unroll
;                     for (int vt = 0; vt < 4; ++vt) { o[vt] = Oacc[tt][vt][r] + bf2f(tmpv[r][vt]); ss += o[vt] * o[vt]; }
;                     ss += __shfl_xor(ss, 1); ss += __shfl_xor(ss, 2); ss += __shfl_xor(ss, 4); ss += __shfl_xor(ss, 8);
;                     const float rs = rsqrtf(ss * (1.f / 64.f) + 1e-6f);
; #pragma unroll
;                     for (int vt = 0; vt < 4; ++vt) yp[16 * vt] = f2bf(o[vt] * rs * gnv[vt] * siluf_(bf2f(gtv[r][vt]))); }
	v_lshlrev_b32_e32 v85, 16, v116
	v_mul_f32_e32 v86, 0xbfb8aa3b, v85
	v_exp_f32_e32 v86, v86
	v_mul_f32_e32 v84, v212, v84
	v_or_b32_e32 v92, 19, v98
	v_ashrrev_i32_e32 v93, 31, v92
	v_add_f32_e32 v86, 1.0, v86
	s_nop 0
	v_rcp_f32_e32 v86, v86
	s_nop 0
	v_mul_f32_e32 v85, v86, v85
	v_mul_f32_e32 v84, v85, v84
	v_cvt_pk_bf16_f32 v84, v84, s0
	global_store_short v[100:101], v84, off offset:96
	v_or_b32_e32 v84, 16, v98
	v_ashrrev_i32_e32 v85, 31, v84
	v_lshlrev_b64 v[86:87], 9, v[84:85]
	v_lshl_add_u64 v[90:91], v[106:107], 0, v[86:87]
	global_load_ushort v94, v[90:91], off
	global_load_ushort v95, v[90:91], off offset:32
	global_load_ushort v114, v[90:91], off offset:64
	global_load_ushort v115, v[90:91], off offset:96
	v_mad_i64_i32 v[110:111], s[0:1], v84, s62, v[108:109]
	v_or_b32_e32 v84, 17, v98
	v_ashrrev_i32_e32 v85, 31, v84
	v_lshlrev_b64 v[86:87], 9, v[84:85]
	v_mad_i64_i32 v[100:101], s[0:1], v84, s62, v[108:109]
	v_or_b32_e32 v84, 18, v98
	v_ashrrev_i32_e32 v85, 31, v84
	v_lshl_add_u64 v[88:89], v[106:107], 0, v[86:87]
	v_lshlrev_b64 v[86:87], 9, v[84:85]
	v_mad_i64_i32 v[96:97], s[0:1], v84, s62, v[108:109]
	v_lshlrev_b64 v[84:85], 9, v[92:93]
	v_lshl_add_u64 v[86:87], v[106:107], 0, v[86:87]
	v_lshl_add_u64 v[84:85], v[106:107], 0, v[84:85]
	v_mov_b32_e32 v98, v70
	global_load_ushort v127, v[88:89], off
	global_load_ushort v128, v[88:89], off offset:32
	global_load_ushort v125, v[88:89], off offset:64
	global_load_ushort v126, v[88:89], off offset:96
	global_load_ushort v122, v[86:87], off
	global_load_ushort v123, v[86:87], off offset:32
	global_load_ushort v120, v[86:87], off offset:64
	global_load_ushort v121, v[86:87], off offset:96
	global_load_ushort v118, v[84:85], off
	global_load_ushort v119, v[84:85], off offset:32
	global_load_ushort v116, v[84:85], off offset:64
	global_load_ushort v117, v[84:85], off offset:96
	v_mad_i64_i32 v[92:93], s[0:1], v92, s62, v[108:109]
	s_waitcnt vmcnt(15)
	v_lshlrev_b32_e32 v94, 16, v94
	s_waitcnt vmcnt(14)
	v_lshlrev_b32_e32 v95, 16, v95
	v_pk_add_f32 v[98:99], v[98:99], v[94:95]
	s_waitcnt vmcnt(12)
	v_lshlrev_b32_e32 v95, 16, v115
	v_mov_b32_e32 v115, v60
	global_load_ushort v60, v[110:111], off offset:2048
	v_lshlrev_b32_e32 v94, 16, v114
	v_mov_b32_e32 v114, v78
	v_pk_mul_f32 v[112:113], v[98:99], v[98:99]
	v_pk_add_f32 v[94:95], v[114:115], v[94:95]
	s_waitcnt vmcnt(0)
	v_lshlrev_b32_e32 v60, 16, v60
	v_mul_f32_e32 v70, 0xbfb8aa3b, v60
	v_exp_f32_e32 v70, v70
	v_pk_mul_f32 v[114:115], v[94:95], v[94:95]
	v_add_f32_e32 v70, 1.0, v70
	s_nop 0
	v_rcp_f32_e32 v70, v70
	s_nop 0
	v_mul_f32_e32 v129, v70, v60
	global_load_ushort v60, v[110:111], off offset:2080
	s_waitcnt vmcnt(0)
	v_lshlrev_b32_e32 v60, 16, v60
	v_mul_f32_e32 v70, 0xbfb8aa3b, v60
	v_exp_f32_e32 v70, v70
	s_nop 0
	v_add_f32_e32 v70, 1.0, v70
	s_nop 0
	v_rcp_f32_e32 v70, v70
	s_nop 0
	v_mul_f32_e32 v78, v70, v60
	global_load_ushort v60, v[110:111], off offset:2112
	s_waitcnt vmcnt(0)
	v_lshlrev_b32_e32 v60, 16, v60
	v_mul_f32_e32 v70, 0xbfb8aa3b, v60
	v_exp_f32_e32 v70, v70
	s_nop 0
	v_add_f32_e32 v70, 1.0, v70
	s_nop 0
	v_rcp_f32_e32 v70, v70
	s_nop 0
	v_mul_f32_e32 v124, v70, v60
	global_load_ushort v60, v[110:111], off offset:2144
	s_waitcnt vmcnt(0)
	v_lshlrev_b32_e32 v60, 16, v60
	v_mul_f32_e32 v70, 0xbfb8aa3b, v60
	v_exp_f32_e32 v70, v70
	s_nop 0
	v_add_f32_e32 v70, 1.0, v70
	s_nop 0
	v_rcp_f32_e32 v70, v70
	v_lshlrev_b32_e32 v131, 16, v128
	v_lshlrev_b32_e32 v130, 16, v127
	v_mov_b32_e32 v74, v71
	v_mul_f32_e32 v110, v70, v60
	v_pk_add_f32 v[70:71], v[74:75], v[130:131]
	v_lshlrev_b32_e32 v127, 16, v126
	v_lshlrev_b32_e32 v126, 16, v125
	v_mov_b32_e32 v60, v79
	v_pk_mul_f32 v[74:75], v[70:71], v[70:71]
	v_pk_add_f32 v[60:61], v[60:61], v[126:127]
	v_mov_b32_e32 v130, v74
	v_pk_mul_f32 v[126:127], v[60:61], v[60:61]
	v_mov_b32_e32 v131, v112
	v_mov_b32_e32 v112, v75
	v_pk_add_f32 v[74:75], v[130:131], v[112:113]
	v_mov_b32_e32 v112, v126
	v_mov_b32_e32 v113, v114
	v_pk_add_f32 v[74:75], v[74:75], v[112:113]
	v_mov_b32_e32 v114, v127
	v_pk_add_f32 v[74:75], v[74:75], v[114:115]
	ds_bpermute_b32 v113, v231, v75
	ds_bpermute_b32 v112, v231, v74
	s_waitcnt lgkmcnt(0)
	v_pk_add_f32 v[74:75], v[74:75], v[112:113]
	ds_bpermute_b32 v113, v230, v75
	ds_bpermute_b32 v112, v230, v74
	s_waitcnt lgkmcnt(0)
	v_pk_add_f32 v[74:75], v[74:75], v[112:113]
	ds_bpermute_b32 v113, v229, v75
	ds_bpermute_b32 v112, v229, v74
	s_waitcnt lgkmcnt(0)
	v_pk_add_f32 v[74:75], v[74:75], v[112:113]
	ds_bpermute_b32 v113, v64, v75
	ds_bpermute_b32 v112, v64, v74
	s_waitcnt lgkmcnt(0)
	v_pk_add_f32 v[74:75], v[74:75], v[112:113]
	s_nop 0
	v_pk_fma_f32 v[74:75], v[74:75], s[2:3], v[82:83] op_sel_hi:[1,0,0]
	s_nop 0
	v_mul_f32_e32 v79, 0x4b800000, v75
	v_cmp_gt_f32_e64 s[0:1], s54, v75
	v_cmp_gt_f32_e32 vcc, s54, v74
	s_nop 0
	v_cndmask_b32_e64 v75, v75, v79, s[0:1]
	v_rsq_f32_e32 v75, v75
	s_nop 0
	v_mul_f32_e32 v79, 0x45800000, v75
	v_cndmask_b32_e64 v75, v75, v79, s[0:1]
	v_mul_f32_e32 v79, v98, v75
	global_load_ushort v111, v[100:101], off offset:2048
	global_load_ushort v112, v[100:101], off offset:2080
	global_load_ushort v113, v[100:101], off offset:2112
	global_load_ushort v114, v[100:101], off offset:2144
	global_load_ushort v115, v[96:97], off offset:2048
	global_load_ushort v125, v[96:97], off offset:2080
	s_nop 0
	global_load_ushort v101, v[96:97], off offset:2112
	global_load_ushort v100, v[96:97], off offset:2144
	global_load_ushort v98, v[92:93], off offset:2048
	s_nop 0
	global_load_ushort v97, v[92:93], off offset:2080
	global_load_ushort v96, v[92:93], off offset:2112
	s_nop 0
	global_load_ushort v92, v[92:93], off offset:2144
	v_mul_f32_e32 v79, v209, v79
	v_mul_f32_e32 v79, v129, v79
	v_cvt_pk_bf16_f32 v79, v79, s0
	global_store_short v[90:91], v79, off
	v_mul_f32_e32 v79, v99, v75
	v_mul_f32_e32 v79, v210, v79
	v_mul_f32_e32 v78, v78, v79
	v_cvt_pk_bf16_f32 v78, v78, s0
	global_store_short v[90:91], v78, off offset:32
	v_mul_f32_e32 v78, v94, v75
	v_mul_f32_e32 v75, v95, v75
	v_mul_f32_e32 v75, v212, v75
	v_mul_f32_e32 v75, v110, v75
	v_cvt_pk_bf16_f32 v75, v75, s0
	global_store_short v[90:91], v75, off offset:96
	v_mul_f32_e32 v75, 0x4b800000, v74
	v_cndmask_b32_e32 v74, v74, v75, vcc
	v_rsq_f32_e32 v74, v74
	v_mul_f32_e32 v78, v211, v78
	v_mul_f32_e32 v78, v124, v78
	v_cvt_pk_bf16_f32 v78, v78, s0
	v_mul_f32_e32 v75, 0x45800000, v74
	v_cndmask_b32_e32 v74, v74, v75, vcc
	global_store_short v[90:91], v78, off offset:64
	v_mul_f32_e32 v70, v70, v74
	v_mul_f32_e32 v70, v209, v70
	v_mul_f32_e32 v60, v60, v74
	v_mul_f32_e32 v60, v211, v60
	s_waitcnt vmcnt(15)
; __device__ __forceinline__ bf16_t f2bf(float f) { return (bf16_t)(cvt_pk_bf16(f, 0.f) & 0xffffu); }
; __device__ __forceinline__ float bf2f(bf16_t b) { return __uint_as_float(((unsigned)b) << 16); }
; __device__ __forceinline__ float siluf_(float x) { return x * sigmoidf_(x); }
; __device__ __forceinline__ void wave_lds_fence() { asm volatile("s_waitcnt lgkmcnt(0)" ::: "memory"); __builtin_amdgcn_wave_barrier(); }
; template <int MODE>
; __device__ __forceinline__ void hgrn_mfma(const Ctx& C, int l, int z, int b, int hd, int c, f32x4 (&Sacc)[4][4], float& dectot, unsigned char* wl, float lb) {
;     ...
;         if (MODE == 2) {
; #pragma unroll
;             for (int tt = 0; tt < 2; ++tt) {
;                 bf16_t tmpv[4][4], gtv[4][4];
; #pragma unroll
;                 for (int r = 0; r < 4; ++r) { const int st = c * 128 + sc * 32 + 16 * tt + 4 * quad + r; const int tq = z ? 4095 - st : st;
;                     const size_t tok = (size_t)(b * SEQ + tq); const bf16_t* yp = ya + tok * 256 + hd * 64 + fr; const bf16_t* gp = pa + tok * 1280 + 1024 + hd * 64 + fr;
; #pragma unroll
;                     for (int vt = 0; vt < 4; ++vt) { tmpv[r][vt] = yp[16 * vt]; gtv[r][vt] = gp[16 * vt]; } }
; #pragma unroll
;                 for (int r = 0; r < 4; ++r) { const int st = c * 128 + sc * 32 + 16 * tt + 4 * quad + r; const int tq = z ? 4095 - st : st;
;                     bf16_t* yp = ya + (size_t)(b * SEQ + tq) * 256 + hd * 64 + fr;
;                     float o[4]; float ss = 0.f;
; #pragma unroll
;                     for (int vt = 0; vt < 4; ++vt) { o[vt] = Oacc[tt][vt][r] + bf2f(tmpv[r][vt]); ss += o[vt] * o[vt]; }
;                     ss += __shfl_xor(ss, 1); ss += __shfl_xor(ss, 2); ss += __shfl_xor(ss, 4); ss += __shfl_xor(ss, 8);
;                     const float rs = rsqrtf(ss * (1.f / 64.f) + 1e-6f);
; #pragma unroll
;                     for (int vt = 0; vt < 4; ++vt) yp[16 * vt] = f2bf(o[vt] * rs * gnv[vt] * siluf_(bf2f(gtv[r][vt]))); }
;                 asm volatile("" ::: "memory");
;             }
;         }
;         wave_lds_fence();
; __global__ void __launch_bounds__(NTHR, 2) fwd_megakernel(Params prm) {
;     ...
;         for (int it = bid * 8 + C.wave; it < 1024; it += G * 8) hgrn_pass3_item<0>(C, l, it);
	v_lshlrev_b32_e32 v75, 16, v111
	v_mul_f32_e32 v78, 0xbfb8aa3b, v75
	v_exp_f32_e32 v78, v78
	s_nop 0
	v_add_f32_e32 v78, 1.0, v78
	s_nop 0
	v_rcp_f32_e32 v78, v78
	s_nop 0
	v_mul_f32_e32 v75, v78, v75
	v_mul_f32_e32 v70, v75, v70
	v_cvt_pk_bf16_f32 v70, v70, s0
	global_store_short v[88:89], v70, off
	v_mul_f32_e32 v70, v71, v74
	s_waitcnt vmcnt(15)
	v_lshlrev_b32_e32 v71, 16, v112
	v_mul_f32_e32 v75, 0xbfb8aa3b, v71
	v_exp_f32_e32 v75, v75
	v_mul_f32_e32 v70, v210, v70
	v_add_f32_e32 v75, 1.0, v75
	s_nop 0
	v_rcp_f32_e32 v75, v75
	s_nop 0
	v_mul_f32_e32 v71, v75, v71
	v_mul_f32_e32 v70, v71, v70
	v_cvt_pk_bf16_f32 v70, v70, s0
	global_store_short v[88:89], v70, off offset:32
	s_waitcnt vmcnt(15)
	v_lshlrev_b32_e32 v70, 16, v113
	v_mul_f32_e32 v71, 0xbfb8aa3b, v70
	v_exp_f32_e32 v71, v71
	s_nop 0
	v_add_f32_e32 v71, 1.0, v71
	s_nop 0
	v_rcp_f32_e32 v71, v71
	s_nop 0
	v_mul_f32_e32 v70, v71, v70
	v_mul_f32_e32 v60, v70, v60
	v_cvt_pk_bf16_f32 v60, v60, s0
	global_store_short v[88:89], v60, off offset:64
	v_mul_f32_e32 v60, v61, v74
	s_waitcnt vmcnt(15)
	v_lshlrev_b32_e32 v61, 16, v114
	v_mul_f32_e32 v70, 0xbfb8aa3b, v61
	v_exp_f32_e32 v70, v70
	v_mul_f32_e32 v60, v212, v60
	v_add_f32_e32 v70, 1.0, v70
	s_nop 0
	v_rcp_f32_e32 v70, v70
	v_mov_b32_e32 v75, v62
	s_waitcnt vmcnt(14)
	v_lshlrev_b32_e32 v62, 16, v115
	v_mul_f32_e32 v61, v70, v61
	v_mov_b32_e32 v70, v72
	v_mul_f32_e32 v72, 0xbfb8aa3b, v62
	v_exp_f32_e32 v72, v72
	v_mul_f32_e32 v60, v61, v60
	v_cvt_pk_bf16_f32 v60, v60, s0
	v_mov_b32_e32 v71, v76
	v_add_f32_e32 v72, 1.0, v72
	v_mov_b32_e32 v74, v80
	global_store_short v[88:89], v60, off offset:96
	v_lshlrev_b32_e32 v61, 16, v123
	v_lshlrev_b32_e32 v60, 16, v122
	v_rcp_f32_e32 v72, v72
	s_nop 0
	v_mul_f32_e32 v90, v72, v62
	s_waitcnt vmcnt(14)
	v_lshlrev_b32_e32 v62, 16, v125
	v_mul_f32_e32 v72, 0xbfb8aa3b, v62
	v_exp_f32_e32 v72, v72
	v_pk_add_f32 v[70:71], v[70:71], v[60:61]
	v_lshlrev_b32_e32 v61, 16, v121
	v_lshlrev_b32_e32 v60, 16, v120
	v_add_f32_e32 v72, 1.0, v72
	v_pk_mul_f32 v[78:79], v[70:71], v[70:71]
	v_pk_add_f32 v[60:61], v[74:75], v[60:61]
	v_rcp_f32_e32 v72, v72
	s_nop 0
	v_mul_f32_e32 v91, v72, v62
	s_waitcnt vmcnt(13)
	v_lshlrev_b32_e32 v62, 16, v101
	v_mul_f32_e32 v72, 0xbfb8aa3b, v62
	v_exp_f32_e32 v72, v72
	v_pk_mul_f32 v[74:75], v[60:61], v[60:61]
	v_add_f32_e32 v72, 1.0, v72
	s_nop 0
	v_rcp_f32_e32 v72, v72
	s_nop 0
	v_mul_f32_e32 v93, v72, v62
	s_waitcnt vmcnt(12)
	v_lshlrev_b32_e32 v62, 16, v100
	v_mul_f32_e32 v72, 0xbfb8aa3b, v62
	v_exp_f32_e32 v72, v72
	s_nop 0
	v_add_f32_e32 v72, 1.0, v72
	s_nop 0
	v_rcp_f32_e32 v72, v72
	v_lshlrev_b32_e32 v89, 16, v119
	v_lshlrev_b32_e32 v88, 16, v118
	v_mov_b32_e32 v76, v73
	v_mul_f32_e32 v94, v72, v62
	v_pk_add_f32 v[72:73], v[76:77], v[88:89]
	v_lshlrev_b32_e32 v89, 16, v117
	v_lshlrev_b32_e32 v88, 16, v116
	v_mov_b32_e32 v62, v81
	v_pk_mul_f32 v[76:77], v[72:73], v[72:73]
	v_pk_add_f32 v[62:63], v[62:63], v[88:89]
	v_mov_b32_e32 v88, v76
	v_pk_mul_f32 v[80:81], v[62:63], v[62:63]
	v_mov_b32_e32 v89, v78
	v_mov_b32_e32 v78, v77
	v_pk_add_f32 v[76:77], v[88:89], v[78:79]
	v_mov_b32_e32 v78, v80
	v_mov_b32_e32 v79, v74
	v_pk_add_f32 v[76:77], v[76:77], v[78:79]
	v_mov_b32_e32 v74, v81
	v_pk_add_f32 v[74:75], v[76:77], v[74:75]
	ds_bpermute_b32 v77, v231, v75
	ds_bpermute_b32 v76, v231, v74
	s_waitcnt lgkmcnt(0)
	v_pk_add_f32 v[74:75], v[74:75], v[76:77]
	ds_bpermute_b32 v77, v230, v75
	ds_bpermute_b32 v76, v230, v74
	s_waitcnt lgkmcnt(0)
	v_pk_add_f32 v[74:75], v[74:75], v[76:77]
	ds_bpermute_b32 v77, v229, v75
	ds_bpermute_b32 v76, v229, v74
	s_waitcnt lgkmcnt(0)
	v_pk_add_f32 v[74:75], v[74:75], v[76:77]
	ds_bpermute_b32 v77, v64, v75
	ds_bpermute_b32 v76, v64, v74
	s_waitcnt lgkmcnt(0)
	v_pk_add_f32 v[74:75], v[74:75], v[76:77]
	s_nop 0
	v_pk_fma_f32 v[74:75], v[74:75], s[2:3], v[82:83] op_sel_hi:[1,0,0]
	s_nop 0
	v_mul_f32_e32 v64, 0x4b800000, v75
	v_cmp_gt_f32_e64 s[0:1], s54, v75
	v_cmp_gt_f32_e32 vcc, s54, v74
	s_nop 0
	v_cndmask_b32_e64 v64, v75, v64, s[0:1]
	v_rsq_f32_e32 v64, v64
	s_nop 0
	v_mul_f32_e32 v75, 0x45800000, v64
	v_cndmask_b32_e64 v64, v64, v75, s[0:1]
	v_mul_f32_e32 v60, v60, v64
	v_mul_f32_e32 v70, v70, v64
	v_mul_f32_e32 v60, v211, v60
	v_mul_f32_e32 v70, v209, v70
	v_mul_f32_e32 v60, v93, v60
	v_mul_f32_e32 v70, v90, v70
	v_cvt_pk_bf16_f32 v60, v60, s0
	v_cvt_pk_bf16_f32 v70, v70, s0
	global_store_short v[86:87], v60, off offset:64
	v_mul_f32_e32 v60, v61, v64
	global_store_short v[86:87], v70, off
	v_mul_f32_e32 v70, v71, v64
	v_mul_f32_e32 v60, v212, v60
	v_mul_f32_e32 v70, v210, v70
	v_mul_f32_e32 v60, v94, v60
	v_mul_f32_e32 v70, v91, v70
	v_cvt_pk_bf16_f32 v60, v60, s0
	v_cvt_pk_bf16_f32 v70, v70, s0
	global_store_short v[86:87], v60, off offset:96
	v_mul_f32_e32 v60, 0x4b800000, v74
	s_waitcnt vmcnt(14)
	v_lshlrev_b32_e32 v64, 16, v98
	global_store_short v[86:87], v70, off offset:32
	v_cndmask_b32_e32 v60, v74, v60, vcc
	v_mul_f32_e32 v70, 0xbfb8aa3b, v64
	v_rsq_f32_e32 v60, v60
	v_exp_f32_e32 v70, v70
	v_mul_f32_e32 v61, 0x45800000, v60
	v_add_f32_e32 v70, 1.0, v70
	v_cndmask_b32_e32 v60, v60, v61, vcc
	v_mul_f32_e32 v61, v72, v60
	v_mul_f32_e32 v61, v209, v61
	v_rcp_f32_e32 v70, v70
	s_nop 0
	v_mul_f32_e32 v64, v70, v64
	v_mul_f32_e32 v61, v64, v61
	s_waitcnt vmcnt(14)
	v_lshlrev_b32_e32 v64, 16, v97
	v_mul_f32_e32 v70, 0xbfb8aa3b, v64
	v_exp_f32_e32 v70, v70
	v_cvt_pk_bf16_f32 v61, v61, s0
	global_store_short v[84:85], v61, off
	v_mul_f32_e32 v61, v73, v60
	v_add_f32_e32 v70, 1.0, v70
	v_mul_f32_e32 v61, v210, v61
	v_rcp_f32_e32 v70, v70
	s_nop 0
	v_mul_f32_e32 v64, v70, v64
	v_mul_f32_e32 v61, v64, v61
	v_cvt_pk_bf16_f32 v61, v61, s0
	global_store_short v[84:85], v61, off offset:32
	v_mul_f32_e32 v61, v62, v60
	s_waitcnt vmcnt(15)
	v_lshlrev_b32_e32 v62, 16, v96
	v_mul_f32_e32 v64, 0xbfb8aa3b, v62
	v_exp_f32_e32 v64, v64
	v_mul_f32_e32 v61, v211, v61
	v_mul_f32_e32 v60, v63, v60
	v_mul_f32_e32 v60, v212, v60
	v_add_f32_e32 v64, 1.0, v64
	s_nop 0
	v_rcp_f32_e32 v64, v64
	s_nop 0
	v_mul_f32_e32 v62, v64, v62
	v_mul_f32_e32 v61, v62, v61
	v_cvt_pk_bf16_f32 v61, v61, s0
	global_store_short v[84:85], v61, off offset:64
	s_waitcnt vmcnt(15)
	v_lshlrev_b32_e32 v61, 16, v92
	v_mul_f32_e32 v62, 0xbfb8aa3b, v61
	v_exp_f32_e32 v62, v62
	s_nop 0
	v_add_f32_e32 v62, 1.0, v62
	s_nop 0
	v_rcp_f32_e32 v62, v62
	s_nop 0
	v_mul_f32_e32 v61, v62, v61
	v_mul_f32_e32 v60, v61, v60
	v_cvt_pk_bf16_f32 v60, v60, s0
	global_store_short v[84:85], v60, off offset:96
	s_waitcnt lgkmcnt(0)
	s_cbranch_scc0 .LBB0_742
	v_readlane_b32 s0, v254, 20
	s_add_i32 s73, s73, s0
	s_cmpk_gt_i32 s73, 0x3ff
	v_readlane_b32 s1, v254, 21
	s_cbranch_scc0 .LBB0_739

; __device__ __forceinline__ unsigned cvt_pk_bf16(float lo, float hi) { f32x2_t v = {lo, hi}; bf2_t r = __builtin_convertvector(v, bf2_t); return __builtin_bit_cast(unsigned, r); }
; __device__ __forceinline__ float bflo(unsigned u) { return __uint_as_float(u << 16); }
; __device__ __forceinline__ float bfhi(unsigned u) { return __uint_as_float(u & 0xffff0000u); }
; __device__ __forceinline__ void attn_combine(const Ctx& C) {
;     ...
;     for (int idx = C.bid * NTHR + C.tid; idx < M_TOK * 32; idx += C.G * NTHR) {
;         const int tok = idx >> 5, j = (idx >> 3) & 3, c8 = idx & 7;
;         const float l0 = lse[((size_t)0 * M_TOK + tok) * 4 + j], l1 = lse[((size_t)1 * M_TOK + tok) * 4 + j], l2 = lse[((size_t)2 * M_TOK + tok) * 4 + j];
;         const float mx = fmaxf(l0, fmaxf(l1, l2)); float w0 = __expf(l0 - mx), w1 = __expf(l1 - mx), w2 = __expf(l2 - mx); const float inv = 1.0f / (w0 + w1 + w2); w0 *= inv; w1 *= inv; w2 *= inv;
;         const bf16_t* row = pd + (size_t)tok * 2304 + j * 64 + c8 * 8;
;         const u32x4 o0 = *(const u32x4*)row, o1 = *(const u32x4*)(row + 256), o2 = *(const u32x4*)(row + 512);
;         u32x4 o;
;         o.x = cvt_pk_bf16(w0 * bflo(o0.x) + w1 * bflo(o1.x) + w2 * bflo(o2.x), w0 * bfhi(o0.x) + w1 * bfhi(o1.x) + w2 * bfhi(o2.x));
;         o.y = cvt_pk_bf16(w0 * bflo(o0.y) + w1 * bflo(o1.y) + w2 * bflo(o2.y), w0 * bfhi(o0.y) + w1 * bfhi(o1.y) + w2 * bfhi(o2.y));
;         o.z = cvt_pk_bf16(w0 * bflo(o0.z) + w1 * bflo(o1.z) + w2 * bflo(o2.z), w0 * bfhi(o0.z) + w1 * bfhi(o1.z) + w2 * bfhi(o2.z));
;         o.w = cvt_pk_bf16(w0 * bflo(o0.w) + w1 * bflo(o1.w) + w2 * bflo(o2.w), w0 * bfhi(o0.w) + w1 * bfhi(o1.w) + w2 * bfhi(o2.w));
;         *(u32x4*)(yd + (size_t)tok * 256 + j * 64 + c8 * 8) = o;
.LBB0_753:
	v_ashrrev_i32_e32 v0, 5, v3
	v_bfe_u32 v10, v3, 3, 2
	v_ashrrev_i32_e32 v1, 31, v0
	v_lshl_add_u64 v[4:5], v[0:1], 4, s[6:7]
	v_lshlrev_b32_e32 v64, 2, v10
	v_lshl_add_u64 v[4:5], v[4:5], 0, v[64:65]
	v_add_co_u32_e32 v8, vcc, 0x80000, v4
	global_load_dword v2, v[4:5], off
	s_nop 0
	v_addc_co_u32_e32 v9, vcc, 0, v5, vcc
	global_load_dword v6, v[8:9], off
	v_add_co_u32_e32 v4, vcc, s14, v4
	v_lshlrev_b32_e32 v64, 7, v10
	s_nop 0
	v_addc_co_u32_e32 v5, vcc, 0, v5, vcc
	global_load_dword v8, v[4:5], off
	v_and_b32_e32 v10, 56, v7
	v_lshlrev_b32_e32 v20, 1, v10
	v_mov_b32_e32 v21, v65
	s_waitcnt vmcnt(0)
	v_max3_f32 v9, v2, v6, v8
	v_sub_f32_e32 v2, v2, v9
	v_mul_f32_e32 v2, 0x3fb8aa3b, v2
	v_exp_f32_e32 v5, v2
	v_sub_f32_e32 v2, v6, v9
	v_mul_f32_e32 v2, 0x3fb8aa3b, v2
	v_exp_f32_e32 v4, v2
	v_sub_f32_e32 v2, v8, v9
	v_mul_f32_e32 v2, 0x3fb8aa3b, v2
	v_exp_f32_e32 v2, v2
	v_add_f32_e32 v6, v5, v4
	v_add_f32_e32 v6, v2, v6
	s_nop 0
	v_rcp_f32_e32 v6, v6
	v_mov_b64_e32 v[8:9], s[4:5]
	v_mad_i64_i32 v[8:9], s[12:13], v0, s92, v[8:9]
	v_lshl_add_u64 v[8:9], v[8:9], 0, v[64:65]
	v_lshl_add_u64 v[16:17], v[8:9], 0, v[20:21]
	global_load_dwordx4 v[8:11], v[16:17], off
	global_load_dwordx4 v[12:15], v[16:17], off offset:512
	s_nop 0
	global_load_dwordx4 v[16:19], v[16:17], off offset:1024
	v_pk_mul_f32 v[4:5], v[4:5], v[6:7] op_sel_hi:[1,0]
	v_mul_f32_e32 v2, v2, v6
	v_lshlrev_b64 v[0:1], 9, v[0:1]
	v_lshl_add_u64 v[0:1], s[8:9], 0, v[0:1]
	s_mov_b32 s12, 0xfffff
	v_lshl_add_u64 v[0:1], v[0:1], 0, v[64:65]
	v_lshl_add_u64 v[0:1], v[0:1], 0, v[20:21]
	v_add_u32_e32 v7, s41, v7
	s_waitcnt vmcnt(2)
	v_lshlrev_b32_e32 v24, 16, v8
	s_waitcnt vmcnt(1)
	v_and_b32_e32 v25, 0xffff0000, v12
	v_lshlrev_b32_e32 v22, 16, v12
	v_and_b32_e32 v23, 0xffff0000, v8
	v_pk_mul_f32 v[24:25], v[4:5], v[24:25] op_sel:[1,0] op_sel_hi:[0,1]
	s_waitcnt vmcnt(0)
	v_lshlrev_b32_e32 v26, 16, v16
	v_and_b32_e32 v27, 0xffff0000, v16
	v_pk_fma_f32 v[22:23], v[4:5], v[22:23], v[24:25]
	v_lshlrev_b32_e32 v12, 16, v9
	v_pk_fma_f32 v[22:23], v[2:3], v[26:27], v[22:23] op_sel_hi:[0,1,1]
	v_cvt_pk_bf16_f32 v8, v22, v23
	v_lshlrev_b32_e32 v22, 16, v13
	v_and_b32_e32 v13, 0xffff0000, v13
	v_and_b32_e32 v23, 0xffff0000, v9
	v_pk_mul_f32 v[12:13], v[4:5], v[12:13] op_sel:[1,0] op_sel_hi:[0,1]
	v_lshlrev_b32_e32 v16, 16, v17
	v_and_b32_e32 v17, 0xffff0000, v17
	v_pk_fma_f32 v[12:13], v[4:5], v[22:23], v[12:13]
	v_lshlrev_b32_e32 v22, 16, v18
	v_pk_fma_f32 v[12:13], v[2:3], v[16:17], v[12:13] op_sel_hi:[0,1,1]
	v_lshlrev_b32_e32 v16, 16, v10
	v_and_b32_e32 v17, 0xffff0000, v14
	v_cvt_pk_bf16_f32 v9, v12, v13
	v_lshlrev_b32_e32 v12, 16, v14
	v_and_b32_e32 v13, 0xffff0000, v10
	v_pk_mul_f32 v[16:17], v[4:5], v[16:17] op_sel:[1,0] op_sel_hi:[0,1]
	v_and_b32_e32 v23, 0xffff0000, v18
	v_pk_fma_f32 v[12:13], v[4:5], v[12:13], v[16:17]
	v_lshlrev_b32_e32 v14, 16, v11
	v_pk_fma_f32 v[12:13], v[2:3], v[22:23], v[12:13] op_sel_hi:[0,1,1]
	v_cvt_pk_bf16_f32 v10, v12, v13
	v_lshlrev_b32_e32 v12, 16, v15
	v_and_b32_e32 v15, 0xffff0000, v15
	v_and_b32_e32 v13, 0xffff0000, v11
	v_pk_mul_f32 v[14:15], v[4:5], v[14:15] op_sel:[1,0] op_sel_hi:[0,1]
	v_pk_fma_f32 v[4:5], v[4:5], v[12:13], v[14:15]
	v_lshlrev_b32_e32 v12, 16, v19
	v_and_b32_e32 v13, 0xffff0000, v19
	v_pk_fma_f32 v[4:5], v[2:3], v[12:13], v[4:5] op_sel_hi:[0,1,1]
	v_add_u32_e32 v3, s40, v3
	v_cmp_lt_i32_e32 vcc, s12, v3
	v_cvt_pk_bf16_f32 v11, v4, v5
	s_or_b64 s[10:11], vcc, s[10:11]
	global_store_dwordx4 v[0:1], v[8:11], off
	s_andn2_b64 exec, exec, s[10:11]
	s_cbranch_execnz .LBB0_753

; __device__ __forceinline__ unsigned cvt_pk_bf16(float lo, float hi) { f32x2_t v = {lo, hi}; bf2_t r = __builtin_convertvector(v, bf2_t); return __builtin_bit_cast(unsigned, r); }
; __device__ __forceinline__ float bflo(unsigned u) { return __uint_as_float(u << 16); }
; __device__ __forceinline__ float bfhi(unsigned u) { return __uint_as_float(u & 0xffff0000u); }
; __device__ __forceinline__ float sigmoidf_(float x) { return 1.0f / (1.0f + __expf(-x)); }
;     __device__ __forceinline__ void operator()(const f32x4 (&acc)[2][2][4][2], const Unit& u, int wr, int wc, int fr, int fq) const {
;     ...
;                     for (int bj = 0; bj < 2; ++bj) { pvv[mm][bj] = *(const u32x4*)(P + row * 4096 + colg + bj * HALF);
;                         if (j > 0) ovv[mm][bj] = *(const u32x4*)(mixed + row * 1024 + colm + bj * HALF); else ovv[mm][bj] = (u32x4){0u, 0u, 0u, 0u}; } }
; #pragma unroll
;                 for (int mm = 0; mm < 2; ++mm) { const int m = 2 * m2 + mm; const size_t row = (size_t)(row0 + ai * HALF + m * 16);
; #pragma unroll
;                     for (int bj = 0; bj < 2; ++bj) {
;                         const u32x4 pv = pvv[mm][bj], ov = ovv[mm][bj];
;                         bf16_t* mp = mixed + row * 1024 + colm + bj * HALF;
;                         const f32x4 a0 = acc[ai][bj][m][0] + bv[bj][0], a1 = acc[ai][bj][m][1] + bv[bj][1];
;                         float r[8];
;                         r[0] = sigmoidf_(a0[0]) * bflo(pv.x); r[1] = sigmoidf_(a0[1]) * bfhi(pv.x); r[2] = sigmoidf_(a0[2]) * bflo(pv.y); r[3] = sigmoidf_(a0[3]) * bfhi(pv.y);
;                         r[4] = sigmoidf_(a1[0]) * bflo(pv.z); r[5] = sigmoidf_(a1[1]) * bfhi(pv.z); r[6] = sigmoidf_(a1[2]) * bflo(pv.w); r[7] = sigmoidf_(a1[3]) * bfhi(pv.w);
;                         r[0] += bflo(ov.x); r[1] += bfhi(ov.x); r[2] += bflo(ov.y); r[3] += bfhi(ov.y); r[4] += bflo(ov.z); r[5] += bfhi(ov.z); r[6] += bflo(ov.w); r[7] += bfhi(ov.w);
;                         u32x4 w; w.x = cvt_pk_bf16(r[0], r[1]); w.y = cvt_pk_bf16(r[2], r[3]); w.z = cvt_pk_bf16(r[4], r[5]); w.w = cvt_pk_bf16(r[6], r[7]);
;                         *(u32x4*)mp = w; } }
.LBB0_909:
	s_waitcnt vmcnt(0)
	v_pk_add_f32 v[166:167], v[166:167], v[40:41]
	v_pk_add_f32 v[162:163], v[162:163], v[32:33]
	v_mul_f32_e32 v166, 0xbfb8aa3b, v166
	v_mul_f32_e32 v167, 0xbfb8aa3b, v167
	v_exp_f32_e32 v166, v166
	v_exp_f32_e32 v167, v167
	v_lshl_add_u64 v[178:179], s[6:7], 0, v[212:213]
	v_mul_f32_e32 v162, 0xbfb8aa3b, v162
	v_lshl_add_u64 v[212:213], v[178:179], 0, v[64:65]
	v_pk_add_f32 v[164:165], v[164:165], v[34:35]
	v_exp_f32_e32 v178, v162
	v_mul_f32_e32 v162, 0xbfb8aa3b, v163
	v_exp_f32_e32 v179, v162
	v_mul_f32_e32 v162, 0xbfb8aa3b, v164
	v_mul_f32_e32 v163, 0xbfb8aa3b, v165
	v_pk_add_f32 v[164:165], v[166:167], 1.0 op_sel_hi:[1,0]
	v_pk_add_f32 v[168:169], v[168:169], v[42:43]
	v_mul_f32_e32 v168, 0xbfb8aa3b, v168
	v_mul_f32_e32 v169, 0xbfb8aa3b, v169
	v_exp_f32_e32 v168, v168
	v_rcp_f32_e32 v165, v165
	v_exp_f32_e32 v169, v169
	v_exp_f32_e32 v162, v162
	v_exp_f32_e32 v163, v163
	v_rcp_f32_e32 v164, v164
	v_lshlrev_b32_e32 v166, 16, v170
	v_and_b32_e32 v167, 0xffff0000, v170
	v_lshlrev_b32_e32 v180, 16, v174
	v_and_b32_e32 v181, 0xffff0000, v174
	v_pk_fma_f32 v[164:165], v[164:165], v[166:167], v[180:181]
	v_pk_add_f32 v[166:167], v[168:169], 1.0 op_sel_hi:[1,0]
	v_pk_add_f32 v[162:163], v[162:163], 1.0 op_sel_hi:[1,0]
	v_pk_add_f32 v[142:143], v[142:143], v[28:29]
	v_pk_add_f32 v[138:139], v[138:139], v[24:25]
	v_mul_f32_e32 v142, 0xbfb8aa3b, v142
	v_rcp_f32_e32 v167, v167
	v_mul_f32_e32 v143, 0xbfb8aa3b, v143
	v_exp_f32_e32 v142, v142
	v_exp_f32_e32 v143, v143
	v_rcp_f32_e32 v166, v166
	v_lshlrev_b32_e32 v168, 16, v171
	v_and_b32_e32 v169, 0xffff0000, v171
	v_lshlrev_b32_e32 v170, 16, v175
	v_and_b32_e32 v171, 0xffff0000, v175
	v_pk_fma_f32 v[166:167], v[166:167], v[168:169], v[170:171]
	v_pk_add_f32 v[168:169], v[178:179], 1.0 op_sel_hi:[1,0]
	v_mul_f32_e32 v138, 0xbfb8aa3b, v138
	v_pk_add_f32 v[140:141], v[140:141], v[26:27]
	v_pk_add_f32 v[144:145], v[144:145], v[30:31]
	v_pk_add_f32 v[126:127], v[126:127], v[40:41]
	v_rcp_f32_e32 v169, v169
	v_mul_f32_e32 v144, 0xbfb8aa3b, v144
	v_mul_f32_e32 v145, 0xbfb8aa3b, v145
	v_exp_f32_e32 v144, v144
	v_rcp_f32_e32 v168, v168
	v_lshlrev_b32_e32 v170, 16, v172
	v_and_b32_e32 v171, 0xffff0000, v172
	v_lshlrev_b32_e32 v174, 16, v176
	v_and_b32_e32 v175, 0xffff0000, v176
	v_pk_fma_f32 v[168:169], v[168:169], v[170:171], v[174:175]
	v_exp_f32_e32 v145, v145
	v_mul_f32_e32 v126, 0xbfb8aa3b, v126
	v_mul_f32_e32 v127, 0xbfb8aa3b, v127
	v_rcp_f32_e32 v163, v163
	v_exp_f32_e32 v126, v126
	v_exp_f32_e32 v127, v127
	v_pk_add_f32 v[122:123], v[122:123], v[32:33]
	v_rcp_f32_e32 v162, v162
	v_lshlrev_b32_e32 v170, 16, v173
	v_and_b32_e32 v171, 0xffff0000, v173
	v_lshlrev_b32_e32 v172, 16, v177
	v_and_b32_e32 v173, 0xffff0000, v177
	v_pk_fma_f32 v[170:171], v[162:163], v[170:171], v[172:173]
	v_cvt_pk_bf16_f32 v162, v164, v165
	v_cvt_pk_bf16_f32 v163, v166, v167
	v_cvt_pk_bf16_f32 v164, v168, v169
	v_cvt_pk_bf16_f32 v165, v170, v171
	global_store_dwordx4 v[212:213], v[162:165], off
	v_mul_f32_e32 v122, 0xbfb8aa3b, v122
	v_pk_add_f32 v[124:125], v[124:125], v[34:35]
	v_exp_f32_e32 v162, v138
	v_mul_f32_e32 v138, 0xbfb8aa3b, v139
	v_exp_f32_e32 v163, v138
	v_mul_f32_e32 v138, 0xbfb8aa3b, v140
	v_mul_f32_e32 v139, 0xbfb8aa3b, v141
	v_pk_add_f32 v[140:141], v[142:143], 1.0 op_sel_hi:[1,0]
	v_exp_f32_e32 v138, v138
	v_exp_f32_e32 v139, v139
	v_pk_add_f32 v[128:129], v[128:129], v[42:43]
	v_pk_add_f32 v[118:119], v[118:119], v[28:29]
	v_rcp_f32_e32 v141, v141
	v_pk_add_f32 v[138:139], v[138:139], 1.0 op_sel_hi:[1,0]
	v_mul_f32_e32 v128, 0xbfb8aa3b, v128
	v_mul_f32_e32 v129, 0xbfb8aa3b, v129
	v_rcp_f32_e32 v140, v140
	v_lshlrev_b32_e32 v142, 16, v158
	v_and_b32_e32 v143, 0xffff0000, v158
	v_lshlrev_b32_e32 v164, 16, v154
	v_and_b32_e32 v165, 0xffff0000, v154
	v_pk_fma_f32 v[140:141], v[140:141], v[142:143], v[164:165]
	v_pk_add_f32 v[142:143], v[144:145], 1.0 op_sel_hi:[1,0]
	v_exp_f32_e32 v128, v128
	v_exp_f32_e32 v129, v129
	v_mul_f32_e32 v118, 0xbfb8aa3b, v118
	v_mul_f32_e32 v119, 0xbfb8aa3b, v119
	v_rcp_f32_e32 v143, v143
	v_exp_f32_e32 v118, v118
	v_exp_f32_e32 v119, v119
	v_pk_add_f32 v[114:115], v[114:115], v[24:25]
	v_rcp_f32_e32 v142, v142
	v_lshlrev_b32_e32 v144, 16, v159
	v_and_b32_e32 v145, 0xffff0000, v159
	v_lshlrev_b32_e32 v154, 16, v155
	v_and_b32_e32 v155, 0xffff0000, v155
	v_pk_fma_f32 v[142:143], v[142:143], v[144:145], v[154:155]
	v_pk_add_f32 v[144:145], v[162:163], 1.0 op_sel_hi:[1,0]
	v_mul_f32_e32 v114, 0xbfb8aa3b, v114
	v_pk_add_f32 v[116:117], v[116:117], v[26:27]
	v_pk_add_f32 v[120:121], v[120:121], v[30:31]
	v_rcp_f32_e32 v145, v145
	v_mul_f32_e32 v120, 0xbfb8aa3b, v120
	v_mul_f32_e32 v121, 0xbfb8aa3b, v121
	v_exp_f32_e32 v120, v120
	v_rcp_f32_e32 v144, v144
	v_lshlrev_b32_e32 v154, 16, v160
	v_and_b32_e32 v155, 0xffff0000, v160
; __device__ __forceinline__ unsigned cvt_pk_bf16(float lo, float hi) { f32x2_t v = {lo, hi}; bf2_t r = __builtin_convertvector(v, bf2_t); return __builtin_bit_cast(unsigned, r); }
; __device__ __forceinline__ float bflo(unsigned u) { return __uint_as_float(u << 16); }
; __device__ __forceinline__ float bfhi(unsigned u) { return __uint_as_float(u & 0xffff0000u); }
; __device__ __forceinline__ float sigmoidf_(float x) { return 1.0f / (1.0f + __expf(-x)); }
;     __device__ __forceinline__ void operator()(const f32x4 (&acc)[2][2][4][2], const Unit& u, int wr, int wc, int fr, int fq) const {
;     ...
;                 for (int mm = 0; mm < 2; ++mm) { const size_t row = (size_t)(row0 + ai * HALF + (2 * m2 + mm) * 16);
; #pragma unroll
;                     for (int bj = 0; bj < 2; ++bj) { pvv[mm][bj] = *(const u32x4*)(P + row * 4096 + colg + bj * HALF);
;                         if (j > 0) ovv[mm][bj] = *(const u32x4*)(mixed + row * 1024 + colm + bj * HALF); else ovv[mm][bj] = (u32x4){0u, 0u, 0u, 0u}; } }
; #pragma unroll
;                 for (int mm = 0; mm < 2; ++mm) { const int m = 2 * m2 + mm; const size_t row = (size_t)(row0 + ai * HALF + m * 16);
; #pragma unroll
;                     for (int bj = 0; bj < 2; ++bj) {
;                         const u32x4 pv = pvv[mm][bj], ov = ovv[mm][bj];
;                         bf16_t* mp = mixed + row * 1024 + colm + bj * HALF;
;                         const f32x4 a0 = acc[ai][bj][m][0] + bv[bj][0], a1 = acc[ai][bj][m][1] + bv[bj][1];
;                         float r[8];
;                         r[0] = sigmoidf_(a0[0]) * bflo(pv.x); r[1] = sigmoidf_(a0[1]) * bfhi(pv.x); r[2] = sigmoidf_(a0[2]) * bflo(pv.y); r[3] = sigmoidf_(a0[3]) * bfhi(pv.y);
;                         r[4] = sigmoidf_(a1[0]) * bflo(pv.z); r[5] = sigmoidf_(a1[1]) * bfhi(pv.z); r[6] = sigmoidf_(a1[2]) * bflo(pv.w); r[7] = sigmoidf_(a1[3]) * bfhi(pv.w);
;                         r[0] += bflo(ov.x); r[1] += bfhi(ov.x); r[2] += bflo(ov.y); r[3] += bfhi(ov.y); r[4] += bflo(ov.z); r[5] += bfhi(ov.z); r[6] += bflo(ov.w); r[7] += bfhi(ov.w);
;                         u32x4 w; w.x = cvt_pk_bf16(r[0], r[1]); w.y = cvt_pk_bf16(r[2], r[3]); w.z = cvt_pk_bf16(r[4], r[5]); w.w = cvt_pk_bf16(r[6], r[7]);
;                         *(u32x4*)mp = w; } }
	v_lshlrev_b32_e32 v158, 16, v156
	v_and_b32_e32 v159, 0xffff0000, v156
	v_pk_fma_f32 v[144:145], v[144:145], v[154:155], v[158:159]
	v_exp_f32_e32 v121, v121
	v_rcp_f32_e32 v139, v139
	s_nop 0
	v_rcp_f32_e32 v138, v138
	v_lshlrev_b32_e32 v154, 16, v161
	v_and_b32_e32 v155, 0xffff0000, v161
	v_lshlrev_b32_e32 v156, 16, v157
	v_and_b32_e32 v157, 0xffff0000, v157
	v_pk_fma_f32 v[154:155], v[138:139], v[154:155], v[156:157]
	v_cvt_pk_bf16_f32 v138, v140, v141
	v_cvt_pk_bf16_f32 v139, v142, v143
	v_cvt_pk_bf16_f32 v140, v144, v145
	v_cvt_pk_bf16_f32 v141, v154, v155
	global_store_dwordx4 v[212:213], v[138:141], off offset:256
	v_mov_b32_e32 v145, 0
	s_nop 0
	v_exp_f32_e32 v140, v122
	v_mul_f32_e32 v122, 0xbfb8aa3b, v123
	v_exp_f32_e32 v141, v122
	v_mul_f32_e32 v122, 0xbfb8aa3b, v124
	v_mul_f32_e32 v123, 0xbfb8aa3b, v125
	v_pk_add_f32 v[124:125], v[126:127], 1.0 op_sel_hi:[1,0]
	v_exp_f32_e32 v122, v122
	v_exp_f32_e32 v123, v123
	v_lshl_add_u64 v[138:139], s[6:7], 0, v[210:211]
	v_lshl_add_u64 v[138:139], v[138:139], 0, v[64:65]
	v_rcp_f32_e32 v125, v125
	v_pk_add_f32 v[122:123], v[122:123], 1.0 op_sel_hi:[1,0]
	v_rcp_f32_e32 v124, v124
	v_lshlrev_b32_e32 v126, 16, v146
	v_and_b32_e32 v127, 0xffff0000, v146
	v_lshlrev_b32_e32 v142, 16, v150
	v_and_b32_e32 v143, 0xffff0000, v150
	v_pk_fma_f32 v[124:125], v[124:125], v[126:127], v[142:143]
	v_pk_add_f32 v[126:127], v[128:129], 1.0 op_sel_hi:[1,0]
	s_nop 0
	s_nop 0
	v_rcp_f32_e32 v127, v127
	s_nop 0
	v_rcp_f32_e32 v126, v126
	v_lshlrev_b32_e32 v128, 16, v147
	v_and_b32_e32 v129, 0xffff0000, v147
	v_lshlrev_b32_e32 v142, 16, v151
	v_and_b32_e32 v143, 0xffff0000, v151
	v_pk_fma_f32 v[126:127], v[126:127], v[128:129], v[142:143]
	v_pk_add_f32 v[128:129], v[140:141], 1.0 op_sel_hi:[1,0]
	s_nop 0
	s_nop 0
	v_rcp_f32_e32 v129, v129
	s_nop 0
	v_rcp_f32_e32 v128, v128
	v_lshlrev_b32_e32 v140, 16, v148
	v_and_b32_e32 v141, 0xffff0000, v148
	v_lshlrev_b32_e32 v142, 16, v152
	v_and_b32_e32 v143, 0xffff0000, v152
	v_pk_fma_f32 v[128:129], v[128:129], v[140:141], v[142:143]
	s_nop 0
	v_rcp_f32_e32 v123, v123
	s_nop 0
	v_rcp_f32_e32 v122, v122
	v_lshlrev_b32_e32 v140, 16, v149
	v_and_b32_e32 v141, 0xffff0000, v149
	v_lshlrev_b32_e32 v142, 16, v153
	v_and_b32_e32 v143, 0xffff0000, v153
	v_pk_fma_f32 v[140:141], v[122:123], v[140:141], v[142:143]
	v_cvt_pk_bf16_f32 v122, v124, v125
	v_cvt_pk_bf16_f32 v123, v126, v127
	v_cvt_pk_bf16_f32 v124, v128, v129
	v_cvt_pk_bf16_f32 v125, v140, v141
	global_store_dwordx4 v[138:139], v[122:125], off
	v_mov_b32_e32 v142, 0
	v_mov_b32_e32 v143, 0
	v_exp_f32_e32 v122, v114
	v_mul_f32_e32 v114, 0xbfb8aa3b, v115
	v_exp_f32_e32 v123, v114
	v_mul_f32_e32 v114, 0xbfb8aa3b, v116
	v_mul_f32_e32 v115, 0xbfb8aa3b, v117
	v_pk_add_f32 v[116:117], v[118:119], 1.0 op_sel_hi:[1,0]
	v_exp_f32_e32 v114, v114
	v_exp_f32_e32 v115, v115
	v_mov_b32_e32 v144, 0
	v_rcp_f32_e32 v117, v117
	v_pk_add_f32 v[114:115], v[114:115], 1.0 op_sel_hi:[1,0]
	v_rcp_f32_e32 v116, v116
	v_lshlrev_b32_e32 v118, 16, v134
	v_and_b32_e32 v119, 0xffff0000, v134
	v_lshlrev_b32_e32 v124, 16, v130
	v_and_b32_e32 v125, 0xffff0000, v130
	v_pk_fma_f32 v[116:117], v[116:117], v[118:119], v[124:125]
	v_pk_add_f32 v[118:119], v[120:121], 1.0 op_sel_hi:[1,0]
	v_mov_b32_e32 v130, 0
	s_nop 0
	v_rcp_f32_e32 v119, v119
	s_nop 0
	v_rcp_f32_e32 v118, v118
	v_lshlrev_b32_e32 v120, 16, v135
	v_and_b32_e32 v121, 0xffff0000, v135
	v_lshlrev_b32_e32 v124, 16, v131
	v_and_b32_e32 v125, 0xffff0000, v131
	v_pk_fma_f32 v[118:119], v[118:119], v[120:121], v[124:125]
	v_pk_add_f32 v[120:121], v[122:123], 1.0 op_sel_hi:[1,0]
	s_nop 0
	s_nop 0
	v_rcp_f32_e32 v121, v121
	s_nop 0
	v_rcp_f32_e32 v120, v120
	v_lshlrev_b32_e32 v122, 16, v136
	v_and_b32_e32 v123, 0xffff0000, v136
	v_lshlrev_b32_e32 v124, 16, v132
	v_and_b32_e32 v125, 0xffff0000, v132
	v_pk_fma_f32 v[120:121], v[120:121], v[122:123], v[124:125]
	s_nop 0
	v_rcp_f32_e32 v115, v115
	s_nop 0
	v_rcp_f32_e32 v114, v114
	v_lshlrev_b32_e32 v122, 16, v137
	v_and_b32_e32 v123, 0xffff0000, v137
	v_lshlrev_b32_e32 v124, 16, v133
	v_and_b32_e32 v125, 0xffff0000, v133
	v_pk_fma_f32 v[122:123], v[114:115], v[122:123], v[124:125]
	v_cvt_pk_bf16_f32 v114, v116, v117
	v_cvt_pk_bf16_f32 v115, v118, v119
	v_cvt_pk_bf16_f32 v116, v120, v121
	v_cvt_pk_bf16_f32 v117, v122, v123
	global_store_dwordx4 v[138:139], v[114:117], off offset:256
	s_and_b64 vcc, exec, s[42:43]
	s_nop 0
	v_or_b32_e32 v114, 32, v206
	v_ashrrev_i32_e32 v115, 31, v114
	v_lshlrev_b64 v[116:117], 13, v[114:115]
	v_lshl_add_u64 v[116:117], v[204:205], 0, v[116:117]
	global_load_dwordx4 v[138:141], v[116:117], off
	v_lshlrev_b64 v[148:149], 11, v[114:115]
	v_lshl_add_u64 v[114:115], v[208:209], 0, v[148:149]
	s_cbranch_vccnz .LBB0_911
	global_load_dwordx4 v[142:145], v[114:115], off

; __device__ __forceinline__ unsigned cvt_pk_bf16(float lo, float hi) { f32x2_t v = {lo, hi}; bf2_t r = __builtin_convertvector(v, bf2_t); return __builtin_bit_cast(unsigned, r); }
; __device__ __forceinline__ float bflo(unsigned u) { return __uint_as_float(u << 16); }
; __device__ __forceinline__ float bfhi(unsigned u) { return __uint_as_float(u & 0xffff0000u); }
; __device__ __forceinline__ float sigmoidf_(float x) { return 1.0f / (1.0f + __expf(-x)); }
;     __device__ __forceinline__ void operator()(const f32x4 (&acc)[2][2][4][2], const Unit& u, int wr, int wc, int fr, int fq) const {
;     ...
;                     for (int bj = 0; bj < 2; ++bj) { pvv[mm][bj] = *(const u32x4*)(P + row * 4096 + colg + bj * HALF);
;                         if (j > 0) ovv[mm][bj] = *(const u32x4*)(mixed + row * 1024 + colm + bj * HALF); else ovv[mm][bj] = (u32x4){0u, 0u, 0u, 0u}; } }
; #pragma unroll
;                 for (int mm = 0; mm < 2; ++mm) { const int m = 2 * m2 + mm; const size_t row = (size_t)(row0 + ai * HALF + m * 16);
; #pragma unroll
;                     for (int bj = 0; bj < 2; ++bj) {
;                         const u32x4 pv = pvv[mm][bj], ov = ovv[mm][bj];
;                         bf16_t* mp = mixed + row * 1024 + colm + bj * HALF;
;                         const f32x4 a0 = acc[ai][bj][m][0] + bv[bj][0], a1 = acc[ai][bj][m][1] + bv[bj][1];
;                         float r[8];
;                         r[0] = sigmoidf_(a0[0]) * bflo(pv.x); r[1] = sigmoidf_(a0[1]) * bfhi(pv.x); r[2] = sigmoidf_(a0[2]) * bflo(pv.y); r[3] = sigmoidf_(a0[3]) * bfhi(pv.y);
;                         r[4] = sigmoidf_(a1[0]) * bflo(pv.z); r[5] = sigmoidf_(a1[1]) * bfhi(pv.z); r[6] = sigmoidf_(a1[2]) * bflo(pv.w); r[7] = sigmoidf_(a1[3]) * bfhi(pv.w);
;                         r[0] += bflo(ov.x); r[1] += bfhi(ov.x); r[2] += bflo(ov.y); r[3] += bfhi(ov.y); r[4] += bflo(ov.z); r[5] += bfhi(ov.z); r[6] += bflo(ov.w); r[7] += bfhi(ov.w);
;                         u32x4 w; w.x = cvt_pk_bf16(r[0], r[1]); w.y = cvt_pk_bf16(r[2], r[3]); w.z = cvt_pk_bf16(r[4], r[5]); w.w = cvt_pk_bf16(r[6], r[7]);
;                         *(u32x4*)mp = w; } }
.LBB0_917:
	v_pk_add_f32 v[110:111], v[110:111], v[40:41]
	v_pk_add_f32 v[106:107], v[106:107], v[32:33]
	v_mul_f32_e32 v110, 0xbfb8aa3b, v110
	v_mul_f32_e32 v111, 0xbfb8aa3b, v111
	v_exp_f32_e32 v110, v110
	v_exp_f32_e32 v111, v111
	v_mul_f32_e32 v106, 0xbfb8aa3b, v106
	v_pk_add_f32 v[108:109], v[108:109], v[34:35]
	v_exp_f32_e32 v150, v106
	v_mul_f32_e32 v106, 0xbfb8aa3b, v107
	v_exp_f32_e32 v151, v106
	v_mul_f32_e32 v106, 0xbfb8aa3b, v108
	v_mul_f32_e32 v107, 0xbfb8aa3b, v109
	v_pk_add_f32 v[108:109], v[110:111], 1.0 op_sel_hi:[1,0]
	v_pk_add_f32 v[112:113], v[112:113], v[42:43]
	v_mul_f32_e32 v112, 0xbfb8aa3b, v112
	v_mul_f32_e32 v113, 0xbfb8aa3b, v113
	v_exp_f32_e32 v112, v112
	v_rcp_f32_e32 v109, v109
	v_exp_f32_e32 v113, v113
	v_exp_f32_e32 v106, v106
	v_exp_f32_e32 v107, v107
	v_rcp_f32_e32 v108, v108
	s_waitcnt vmcnt(3)
	v_lshlrev_b32_e32 v110, 16, v138
	v_and_b32_e32 v111, 0xffff0000, v138
	v_lshlrev_b32_e32 v152, 16, v142
	v_and_b32_e32 v153, 0xffff0000, v142
	v_pk_fma_f32 v[108:109], v[108:109], v[110:111], v[152:153]
	v_pk_add_f32 v[110:111], v[112:113], 1.0 op_sel_hi:[1,0]
	v_pk_add_f32 v[106:107], v[106:107], 1.0 op_sel_hi:[1,0]
	v_pk_add_f32 v[102:103], v[102:103], v[28:29]
	v_lshl_add_u64 v[148:149], s[6:7], 0, v[148:149]
	v_mul_f32_e32 v102, 0xbfb8aa3b, v102
	v_rcp_f32_e32 v111, v111
	v_mul_f32_e32 v103, 0xbfb8aa3b, v103
	v_exp_f32_e32 v102, v102
	v_exp_f32_e32 v103, v103
	v_rcp_f32_e32 v110, v110
	v_lshlrev_b32_e32 v112, 16, v139
	v_and_b32_e32 v113, 0xffff0000, v139
	v_lshlrev_b32_e32 v138, 16, v143
	v_and_b32_e32 v139, 0xffff0000, v143
	v_pk_fma_f32 v[110:111], v[110:111], v[112:113], v[138:139]
	v_pk_add_f32 v[112:113], v[150:151], 1.0 op_sel_hi:[1,0]
	v_pk_add_f32 v[98:99], v[98:99], v[24:25]
	v_lshl_add_u64 v[148:149], v[148:149], 0, v[64:65]
	v_mul_f32_e32 v98, 0xbfb8aa3b, v98
	v_pk_add_f32 v[100:101], v[100:101], v[26:27]
	v_rcp_f32_e32 v113, v113
	v_pk_add_f32 v[104:105], v[104:105], v[30:31]
	v_pk_add_f32 v[94:95], v[94:95], v[40:41]
	v_mul_f32_e32 v104, 0xbfb8aa3b, v104
	v_rcp_f32_e32 v112, v112
	v_lshlrev_b32_e32 v138, 16, v140
	v_and_b32_e32 v139, 0xffff0000, v140
	v_lshlrev_b32_e32 v142, 16, v144
	v_and_b32_e32 v143, 0xffff0000, v144
	v_pk_fma_f32 v[112:113], v[112:113], v[138:139], v[142:143]
	v_mul_f32_e32 v105, 0xbfb8aa3b, v105
	v_exp_f32_e32 v104, v104
	v_exp_f32_e32 v105, v105
	v_rcp_f32_e32 v107, v107
	v_mul_f32_e32 v94, 0xbfb8aa3b, v94
	v_mul_f32_e32 v95, 0xbfb8aa3b, v95
	v_exp_f32_e32 v94, v94
	v_rcp_f32_e32 v106, v106
	v_lshlrev_b32_e32 v138, 16, v141
	v_and_b32_e32 v139, 0xffff0000, v141
	v_lshlrev_b32_e32 v140, 16, v145
	v_and_b32_e32 v141, 0xffff0000, v145
	v_pk_fma_f32 v[138:139], v[106:107], v[138:139], v[140:141]
	v_cvt_pk_bf16_f32 v106, v108, v109
	v_cvt_pk_bf16_f32 v107, v110, v111
	v_cvt_pk_bf16_f32 v108, v112, v113
	v_cvt_pk_bf16_f32 v109, v138, v139
	global_store_dwordx4 v[148:149], v[106:109], off
	v_exp_f32_e32 v95, v95
	v_pk_add_f32 v[90:91], v[90:91], v[32:33]
	v_exp_f32_e32 v106, v98
	v_mul_f32_e32 v98, 0xbfb8aa3b, v99
	v_exp_f32_e32 v107, v98
	v_mul_f32_e32 v98, 0xbfb8aa3b, v100
	v_mul_f32_e32 v99, 0xbfb8aa3b, v101
	v_pk_add_f32 v[100:101], v[102:103], 1.0 op_sel_hi:[1,0]
	v_exp_f32_e32 v98, v98
	v_exp_f32_e32 v99, v99
	v_mul_f32_e32 v90, 0xbfb8aa3b, v90
	v_pk_add_f32 v[92:93], v[92:93], v[34:35]
	v_rcp_f32_e32 v101, v101
	v_pk_add_f32 v[98:99], v[98:99], 1.0 op_sel_hi:[1,0]
	v_pk_add_f32 v[96:97], v[96:97], v[42:43]
	v_pk_add_f32 v[86:87], v[86:87], v[28:29]
	v_rcp_f32_e32 v100, v100
	s_waitcnt vmcnt(3)
; __device__ __forceinline__ unsigned cvt_pk_bf16(float lo, float hi) { f32x2_t v = {lo, hi}; bf2_t r = __builtin_convertvector(v, bf2_t); return __builtin_bit_cast(unsigned, r); }
; __device__ __forceinline__ float bflo(unsigned u) { return __uint_as_float(u << 16); }
; __device__ __forceinline__ float bfhi(unsigned u) { return __uint_as_float(u & 0xffff0000u); }
; __device__ __forceinline__ float sigmoidf_(float x) { return 1.0f / (1.0f + __expf(-x)); }
;     __device__ __forceinline__ void operator()(const f32x4 (&acc)[2][2][4][2], const Unit& u, int wr, int wc, int fr, int fq) const {
;     ...
;                 for (int mm = 0; mm < 2; ++mm) { const size_t row = (size_t)(row0 + ai * HALF + (2 * m2 + mm) * 16);
; #pragma unroll
;                     for (int bj = 0; bj < 2; ++bj) { pvv[mm][bj] = *(const u32x4*)(P + row * 4096 + colg + bj * HALF);
;                         if (j > 0) ovv[mm][bj] = *(const u32x4*)(mixed + row * 1024 + colm + bj * HALF); else ovv[mm][bj] = (u32x4){0u, 0u, 0u, 0u}; } }
; #pragma unroll
;                 for (int mm = 0; mm < 2; ++mm) { const int m = 2 * m2 + mm; const size_t row = (size_t)(row0 + ai * HALF + m * 16);
; #pragma unroll
;                     for (int bj = 0; bj < 2; ++bj) {
;                         const u32x4 pv = pvv[mm][bj], ov = ovv[mm][bj];
;                         bf16_t* mp = mixed + row * 1024 + colm + bj * HALF;
;                         const f32x4 a0 = acc[ai][bj][m][0] + bv[bj][0], a1 = acc[ai][bj][m][1] + bv[bj][1];
;                         float r[8];
;                         r[0] = sigmoidf_(a0[0]) * bflo(pv.x); r[1] = sigmoidf_(a0[1]) * bfhi(pv.x); r[2] = sigmoidf_(a0[2]) * bflo(pv.y); r[3] = sigmoidf_(a0[3]) * bfhi(pv.y);
;                         r[4] = sigmoidf_(a1[0]) * bflo(pv.z); r[5] = sigmoidf_(a1[1]) * bfhi(pv.z); r[6] = sigmoidf_(a1[2]) * bflo(pv.w); r[7] = sigmoidf_(a1[3]) * bfhi(pv.w);
;                         r[0] += bflo(ov.x); r[1] += bfhi(ov.x); r[2] += bflo(ov.y); r[3] += bfhi(ov.y); r[4] += bflo(ov.z); r[5] += bfhi(ov.z); r[6] += bflo(ov.w); r[7] += bfhi(ov.w);
;                         u32x4 w; w.x = cvt_pk_bf16(r[0], r[1]); w.y = cvt_pk_bf16(r[2], r[3]); w.z = cvt_pk_bf16(r[4], r[5]); w.w = cvt_pk_bf16(r[6], r[7]);
;                         *(u32x4*)mp = w; } }
	v_lshlrev_b32_e32 v102, 16, v134
	v_and_b32_e32 v103, 0xffff0000, v134
	v_lshlrev_b32_e32 v108, 16, v130
	v_and_b32_e32 v109, 0xffff0000, v130
	v_pk_fma_f32 v[100:101], v[100:101], v[102:103], v[108:109]
	v_pk_add_f32 v[102:103], v[104:105], 1.0 op_sel_hi:[1,0]
	v_mul_f32_e32 v96, 0xbfb8aa3b, v96
	v_mul_f32_e32 v97, 0xbfb8aa3b, v97
	v_exp_f32_e32 v96, v96
	v_exp_f32_e32 v97, v97
	v_rcp_f32_e32 v103, v103
	v_mul_f32_e32 v86, 0xbfb8aa3b, v86
	v_mul_f32_e32 v87, 0xbfb8aa3b, v87
	v_exp_f32_e32 v86, v86
	v_rcp_f32_e32 v102, v102
	v_lshlrev_b32_e32 v104, 16, v135
	v_and_b32_e32 v105, 0xffff0000, v135
	v_lshlrev_b32_e32 v108, 16, v131
	v_and_b32_e32 v109, 0xffff0000, v131
	v_pk_fma_f32 v[102:103], v[102:103], v[104:105], v[108:109]
	v_pk_add_f32 v[104:105], v[106:107], 1.0 op_sel_hi:[1,0]
	v_exp_f32_e32 v87, v87
	v_pk_add_f32 v[82:83], v[82:83], v[24:25]
	v_pk_add_f32 v[84:85], v[84:85], v[26:27]
	v_mul_f32_e32 v82, 0xbfb8aa3b, v82
	v_rcp_f32_e32 v105, v105
	v_pk_add_f32 v[88:89], v[88:89], v[30:31]
	v_mov_b32_e32 v111, 0
	v_mul_f32_e32 v88, 0xbfb8aa3b, v88
	v_rcp_f32_e32 v104, v104
	v_lshlrev_b32_e32 v106, 16, v136
	v_and_b32_e32 v107, 0xffff0000, v136
	v_lshlrev_b32_e32 v108, 16, v132
	v_and_b32_e32 v109, 0xffff0000, v132
	v_pk_fma_f32 v[104:105], v[104:105], v[106:107], v[108:109]
	v_mul_f32_e32 v89, 0xbfb8aa3b, v89
	v_exp_f32_e32 v88, v88
	v_exp_f32_e32 v89, v89
	v_rcp_f32_e32 v99, v99
	v_mov_b32_e32 v112, 0
	v_mov_b32_e32 v113, 0
	v_rcp_f32_e32 v98, v98
	v_lshlrev_b32_e32 v106, 16, v137
	v_and_b32_e32 v107, 0xffff0000, v137
	v_lshlrev_b32_e32 v108, 16, v133
	v_and_b32_e32 v109, 0xffff0000, v133
	v_pk_fma_f32 v[106:107], v[98:99], v[106:107], v[108:109]
	v_cvt_pk_bf16_f32 v98, v100, v101
	v_cvt_pk_bf16_f32 v99, v102, v103
	v_cvt_pk_bf16_f32 v100, v104, v105
	v_cvt_pk_bf16_f32 v101, v106, v107
	global_store_dwordx4 v[148:149], v[98:101], off offset:256
	v_mov_b32_e32 v110, 0
	s_nop 0
	v_exp_f32_e32 v100, v90
	v_mul_f32_e32 v90, 0xbfb8aa3b, v91
	v_exp_f32_e32 v101, v90
	v_mul_f32_e32 v90, 0xbfb8aa3b, v92
	v_mul_f32_e32 v91, 0xbfb8aa3b, v93
	v_pk_add_f32 v[92:93], v[94:95], 1.0 op_sel_hi:[1,0]
	v_exp_f32_e32 v90, v90
	v_exp_f32_e32 v91, v91
	v_lshl_add_u64 v[98:99], s[6:7], 0, v[146:147]
	v_lshl_add_u64 v[98:99], v[98:99], 0, v[64:65]
	v_rcp_f32_e32 v93, v93
	v_pk_add_f32 v[90:91], v[90:91], 1.0 op_sel_hi:[1,0]
	v_rcp_f32_e32 v92, v92
	s_waitcnt vmcnt(3)
	v_lshlrev_b32_e32 v94, 16, v122
	v_and_b32_e32 v95, 0xffff0000, v122
	v_lshlrev_b32_e32 v102, 16, v126
	v_and_b32_e32 v103, 0xffff0000, v126
	v_pk_fma_f32 v[92:93], v[92:93], v[94:95], v[102:103]
	v_pk_add_f32 v[94:95], v[96:97], 1.0 op_sel_hi:[1,0]
	s_nop 0
	s_nop 0
	v_rcp_f32_e32 v95, v95
	s_nop 0
	v_rcp_f32_e32 v94, v94
	v_lshlrev_b32_e32 v96, 16, v123
	v_and_b32_e32 v97, 0xffff0000, v123
	v_lshlrev_b32_e32 v102, 16, v127
	v_and_b32_e32 v103, 0xffff0000, v127
	v_pk_fma_f32 v[94:95], v[94:95], v[96:97], v[102:103]
	v_pk_add_f32 v[96:97], v[100:101], 1.0 op_sel_hi:[1,0]
	s_nop 0
	s_nop 0
	v_rcp_f32_e32 v97, v97
	s_nop 0
	v_rcp_f32_e32 v96, v96
	v_lshlrev_b32_e32 v100, 16, v124
	v_and_b32_e32 v101, 0xffff0000, v124
	v_lshlrev_b32_e32 v102, 16, v128
	v_and_b32_e32 v103, 0xffff0000, v128
	v_pk_fma_f32 v[96:97], v[96:97], v[100:101], v[102:103]
	s_nop 0
	v_rcp_f32_e32 v91, v91
	s_nop 0
	v_rcp_f32_e32 v90, v90
	v_lshlrev_b32_e32 v100, 16, v125
	v_and_b32_e32 v101, 0xffff0000, v125
	v_lshlrev_b32_e32 v102, 16, v129
	v_and_b32_e32 v103, 0xffff0000, v129
	v_pk_fma_f32 v[100:101], v[90:91], v[100:101], v[102:103]
	v_cvt_pk_bf16_f32 v90, v92, v93
	v_cvt_pk_bf16_f32 v91, v94, v95
	v_cvt_pk_bf16_f32 v92, v96, v97
	v_cvt_pk_bf16_f32 v93, v100, v101
	global_store_dwordx4 v[98:99], v[90:93], off
	s_nop 1
	v_exp_f32_e32 v90, v82
	v_mul_f32_e32 v82, 0xbfb8aa3b, v83
	v_exp_f32_e32 v91, v82
	v_mul_f32_e32 v82, 0xbfb8aa3b, v84
	v_mul_f32_e32 v83, 0xbfb8aa3b, v85
	v_pk_add_f32 v[84:85], v[86:87], 1.0 op_sel_hi:[1,0]
	v_exp_f32_e32 v82, v82
	v_exp_f32_e32 v83, v83
	v_rcp_f32_e32 v85, v85
	v_pk_add_f32 v[82:83], v[82:83], 1.0 op_sel_hi:[1,0]
	v_rcp_f32_e32 v84, v84
	s_waitcnt vmcnt(3)
	v_lshlrev_b32_e32 v86, 16, v118
	v_and_b32_e32 v87, 0xffff0000, v118
	v_lshlrev_b32_e32 v92, 16, v114
	v_and_b32_e32 v93, 0xffff0000, v114
	v_pk_fma_f32 v[84:85], v[84:85], v[86:87], v[92:93]
	v_pk_add_f32 v[86:87], v[88:89], 1.0 op_sel_hi:[1,0]
	s_nop 0
	s_nop 0
	v_rcp_f32_e32 v87, v87
	s_nop 0
	v_rcp_f32_e32 v86, v86
	v_lshlrev_b32_e32 v88, 16, v119
	v_and_b32_e32 v89, 0xffff0000, v119
	v_lshlrev_b32_e32 v92, 16, v115
	v_and_b32_e32 v93, 0xffff0000, v115
	v_pk_fma_f32 v[86:87], v[86:87], v[88:89], v[92:93]
	v_pk_add_f32 v[88:89], v[90:91], 1.0 op_sel_hi:[1,0]
	s_nop 0
	s_nop 0
	v_rcp_f32_e32 v89, v89
	s_nop 0
	v_rcp_f32_e32 v88, v88
	v_lshlrev_b32_e32 v90, 16, v120
	v_and_b32_e32 v91, 0xffff0000, v120
	v_lshlrev_b32_e32 v92, 16, v116
	v_and_b32_e32 v93, 0xffff0000, v116
	v_pk_fma_f32 v[88:89], v[88:89], v[90:91], v[92:93]
	s_nop 0
	v_rcp_f32_e32 v83, v83
	s_nop 0
	v_rcp_f32_e32 v82, v82
	v_lshlrev_b32_e32 v90, 16, v121
	v_and_b32_e32 v91, 0xffff0000, v121
	v_lshlrev_b32_e32 v92, 16, v117
	v_and_b32_e32 v93, 0xffff0000, v117
	v_pk_fma_f32 v[90:91], v[82:83], v[90:91], v[92:93]
	v_cvt_pk_bf16_f32 v82, v84, v85
	v_cvt_pk_bf16_f32 v83, v86, v87
	v_cvt_pk_bf16_f32 v84, v88, v89
	v_cvt_pk_bf16_f32 v85, v90, v91
	global_store_dwordx4 v[98:99], v[82:85], off offset:256
	v_mov_b32_e32 v98, 0
	s_and_b64 vcc, exec, s[42:43]
	v_add_u32_e32 v82, 0x80, v206
	v_ashrrev_i32_e32 v83, 31, v82
	v_lshlrev_b64 v[84:85], 13, v[82:83]
	v_lshl_add_u64 v[84:85], v[204:205], 0, v[84:85]
	global_load_dwordx4 v[106:109], v[84:85], off
	v_lshlrev_b64 v[116:117], 11, v[82:83]
	v_lshl_add_u64 v[82:83], v[208:209], 0, v[116:117]
	s_cbranch_vccnz .LBB0_919
	global_load_dwordx4 v[110:113], v[82:83], off

; __device__ __forceinline__ unsigned cvt_pk_bf16(float lo, float hi) { f32x2_t v = {lo, hi}; bf2_t r = __builtin_convertvector(v, bf2_t); return __builtin_bit_cast(unsigned, r); }
; __device__ __forceinline__ float bflo(unsigned u) { return __uint_as_float(u << 16); }
; __device__ __forceinline__ float bfhi(unsigned u) { return __uint_as_float(u & 0xffff0000u); }
; __device__ __forceinline__ float sigmoidf_(float x) { return 1.0f / (1.0f + __expf(-x)); }
;     __device__ __forceinline__ void operator()(const f32x4 (&acc)[2][2][4][2], const Unit& u, int wr, int wc, int fr, int fq) const {
;     ...
;                     for (int bj = 0; bj < 2; ++bj) { pvv[mm][bj] = *(const u32x4*)(P + row * 4096 + colg + bj * HALF);
;                         if (j > 0) ovv[mm][bj] = *(const u32x4*)(mixed + row * 1024 + colm + bj * HALF); else ovv[mm][bj] = (u32x4){0u, 0u, 0u, 0u}; } }
; #pragma unroll
;                 for (int mm = 0; mm < 2; ++mm) { const int m = 2 * m2 + mm; const size_t row = (size_t)(row0 + ai * HALF + m * 16);
; #pragma unroll
;                     for (int bj = 0; bj < 2; ++bj) {
;                         const u32x4 pv = pvv[mm][bj], ov = ovv[mm][bj];
;                         bf16_t* mp = mixed + row * 1024 + colm + bj * HALF;
;                         const f32x4 a0 = acc[ai][bj][m][0] + bv[bj][0], a1 = acc[ai][bj][m][1] + bv[bj][1];
;                         float r[8];
;                         r[0] = sigmoidf_(a0[0]) * bflo(pv.x); r[1] = sigmoidf_(a0[1]) * bfhi(pv.x); r[2] = sigmoidf_(a0[2]) * bflo(pv.y); r[3] = sigmoidf_(a0[3]) * bfhi(pv.y);
;                         r[4] = sigmoidf_(a1[0]) * bflo(pv.z); r[5] = sigmoidf_(a1[1]) * bfhi(pv.z); r[6] = sigmoidf_(a1[2]) * bflo(pv.w); r[7] = sigmoidf_(a1[3]) * bfhi(pv.w);
;                         r[0] += bflo(ov.x); r[1] += bfhi(ov.x); r[2] += bflo(ov.y); r[3] += bfhi(ov.y); r[4] += bflo(ov.z); r[5] += bfhi(ov.z); r[6] += bflo(ov.w); r[7] += bfhi(ov.w);
;                         u32x4 w; w.x = cvt_pk_bf16(r[0], r[1]); w.y = cvt_pk_bf16(r[2], r[3]); w.z = cvt_pk_bf16(r[4], r[5]); w.w = cvt_pk_bf16(r[6], r[7]);
;                         *(u32x4*)mp = w; } }
.LBB0_925:
	v_pk_add_f32 v[78:79], v[78:79], v[40:41]
	v_pk_add_f32 v[74:75], v[74:75], v[32:33]
	v_mul_f32_e32 v78, 0xbfb8aa3b, v78
	v_mul_f32_e32 v79, 0xbfb8aa3b, v79
	v_exp_f32_e32 v78, v78
	v_exp_f32_e32 v79, v79
	v_mul_f32_e32 v74, 0xbfb8aa3b, v74
	v_pk_add_f32 v[76:77], v[76:77], v[34:35]
	v_exp_f32_e32 v118, v74
	v_mul_f32_e32 v74, 0xbfb8aa3b, v75
	v_exp_f32_e32 v119, v74
	v_mul_f32_e32 v74, 0xbfb8aa3b, v76
	v_mul_f32_e32 v75, 0xbfb8aa3b, v77
	v_pk_add_f32 v[76:77], v[78:79], 1.0 op_sel_hi:[1,0]
	v_pk_add_f32 v[80:81], v[80:81], v[42:43]
	v_mul_f32_e32 v80, 0xbfb8aa3b, v80
	v_mul_f32_e32 v81, 0xbfb8aa3b, v81
	v_exp_f32_e32 v80, v80
	v_rcp_f32_e32 v77, v77
	v_exp_f32_e32 v81, v81
	v_exp_f32_e32 v74, v74
	v_exp_f32_e32 v75, v75
	v_rcp_f32_e32 v76, v76
	s_waitcnt vmcnt(3)
	v_lshlrev_b32_e32 v78, 16, v106
	v_and_b32_e32 v79, 0xffff0000, v106
	v_lshlrev_b32_e32 v120, 16, v110
	v_and_b32_e32 v121, 0xffff0000, v110
	v_pk_fma_f32 v[76:77], v[76:77], v[78:79], v[120:121]
	v_pk_add_f32 v[78:79], v[80:81], 1.0 op_sel_hi:[1,0]
	v_pk_add_f32 v[74:75], v[74:75], 1.0 op_sel_hi:[1,0]
	v_pk_add_f32 v[70:71], v[70:71], v[28:29]
	v_lshl_add_u64 v[116:117], s[6:7], 0, v[116:117]
	v_mul_f32_e32 v70, 0xbfb8aa3b, v70
	v_rcp_f32_e32 v79, v79
	v_mul_f32_e32 v71, 0xbfb8aa3b, v71
	v_exp_f32_e32 v70, v70
	v_exp_f32_e32 v71, v71
	v_rcp_f32_e32 v78, v78
	v_lshlrev_b32_e32 v80, 16, v107
	v_and_b32_e32 v81, 0xffff0000, v107
	v_lshlrev_b32_e32 v106, 16, v111
	v_and_b32_e32 v107, 0xffff0000, v111
	v_pk_fma_f32 v[78:79], v[78:79], v[80:81], v[106:107]
	v_pk_add_f32 v[80:81], v[118:119], 1.0 op_sel_hi:[1,0]
	v_pk_add_f32 v[66:67], v[66:67], v[24:25]
	v_lshl_add_u64 v[116:117], v[116:117], 0, v[64:65]
	v_mul_f32_e32 v66, 0xbfb8aa3b, v66
	v_pk_add_f32 v[68:69], v[68:69], v[26:27]
	v_rcp_f32_e32 v81, v81
	v_pk_add_f32 v[72:73], v[72:73], v[30:31]
	v_pk_add_f32 v[60:61], v[60:61], v[40:41]
	v_mul_f32_e32 v72, 0xbfb8aa3b, v72
	v_rcp_f32_e32 v80, v80
	v_lshlrev_b32_e32 v106, 16, v108
	v_and_b32_e32 v107, 0xffff0000, v108
	v_lshlrev_b32_e32 v110, 16, v112
	v_and_b32_e32 v111, 0xffff0000, v112
	v_pk_fma_f32 v[80:81], v[80:81], v[106:107], v[110:111]
	v_mul_f32_e32 v73, 0xbfb8aa3b, v73
	v_exp_f32_e32 v72, v72
	v_exp_f32_e32 v73, v73
	v_rcp_f32_e32 v75, v75
	v_mul_f32_e32 v60, 0xbfb8aa3b, v60
	v_mul_f32_e32 v61, 0xbfb8aa3b, v61
	v_exp_f32_e32 v60, v60
	v_rcp_f32_e32 v74, v74
	v_lshlrev_b32_e32 v106, 16, v109
	v_and_b32_e32 v107, 0xffff0000, v109
	v_lshlrev_b32_e32 v108, 16, v113
	v_and_b32_e32 v109, 0xffff0000, v113
	v_pk_fma_f32 v[106:107], v[74:75], v[106:107], v[108:109]
	v_cvt_pk_bf16_f32 v74, v76, v77
	v_cvt_pk_bf16_f32 v75, v78, v79
	v_cvt_pk_bf16_f32 v76, v80, v81
	v_cvt_pk_bf16_f32 v77, v106, v107
	global_store_dwordx4 v[116:117], v[74:77], off
	v_exp_f32_e32 v61, v61
	v_pk_add_f32 v[56:57], v[56:57], v[32:33]
	v_exp_f32_e32 v74, v66
	v_mul_f32_e32 v66, 0xbfb8aa3b, v67
	v_exp_f32_e32 v75, v66
	v_mul_f32_e32 v66, 0xbfb8aa3b, v68
	v_mul_f32_e32 v67, 0xbfb8aa3b, v69
	v_pk_add_f32 v[68:69], v[70:71], 1.0 op_sel_hi:[1,0]
	v_exp_f32_e32 v66, v66
	v_exp_f32_e32 v67, v67
	v_mul_f32_e32 v56, 0xbfb8aa3b, v56
	v_pk_add_f32 v[58:59], v[58:59], v[34:35]
	v_rcp_f32_e32 v69, v69
	v_pk_add_f32 v[66:67], v[66:67], 1.0 op_sel_hi:[1,0]
	v_pk_add_f32 v[62:63], v[62:63], v[42:43]
	v_pk_add_f32 v[52:53], v[52:53], v[28:29]
	v_rcp_f32_e32 v68, v68
	s_waitcnt vmcnt(3)
; __device__ __forceinline__ unsigned cvt_pk_bf16(float lo, float hi) { f32x2_t v = {lo, hi}; bf2_t r = __builtin_convertvector(v, bf2_t); return __builtin_bit_cast(unsigned, r); }
; __device__ __forceinline__ float bflo(unsigned u) { return __uint_as_float(u << 16); }
; __device__ __forceinline__ float bfhi(unsigned u) { return __uint_as_float(u & 0xffff0000u); }
; __device__ __forceinline__ float sigmoidf_(float x) { return 1.0f / (1.0f + __expf(-x)); }
;     __device__ __forceinline__ void operator()(const f32x4 (&acc)[2][2][4][2], const Unit& u, int wr, int wc, int fr, int fq) const {
;     ...
;                 for (int mm = 0; mm < 2; ++mm) { const size_t row = (size_t)(row0 + ai * HALF + (2 * m2 + mm) * 16);
; #pragma unroll
;                     for (int bj = 0; bj < 2; ++bj) { pvv[mm][bj] = *(const u32x4*)(P + row * 4096 + colg + bj * HALF);
;                         if (j > 0) ovv[mm][bj] = *(const u32x4*)(mixed + row * 1024 + colm + bj * HALF); else ovv[mm][bj] = (u32x4){0u, 0u, 0u, 0u}; } }
; #pragma unroll
;                 for (int mm = 0; mm < 2; ++mm) { const int m = 2 * m2 + mm; const size_t row = (size_t)(row0 + ai * HALF + m * 16);
; #pragma unroll
;                     for (int bj = 0; bj < 2; ++bj) {
;                         const u32x4 pv = pvv[mm][bj], ov = ovv[mm][bj];
;                         bf16_t* mp = mixed + row * 1024 + colm + bj * HALF;
;                         const f32x4 a0 = acc[ai][bj][m][0] + bv[bj][0], a1 = acc[ai][bj][m][1] + bv[bj][1];
;                         float r[8];
;                         r[0] = sigmoidf_(a0[0]) * bflo(pv.x); r[1] = sigmoidf_(a0[1]) * bfhi(pv.x); r[2] = sigmoidf_(a0[2]) * bflo(pv.y); r[3] = sigmoidf_(a0[3]) * bfhi(pv.y);
;                         r[4] = sigmoidf_(a1[0]) * bflo(pv.z); r[5] = sigmoidf_(a1[1]) * bfhi(pv.z); r[6] = sigmoidf_(a1[2]) * bflo(pv.w); r[7] = sigmoidf_(a1[3]) * bfhi(pv.w);
;                         r[0] += bflo(ov.x); r[1] += bfhi(ov.x); r[2] += bflo(ov.y); r[3] += bfhi(ov.y); r[4] += bflo(ov.z); r[5] += bfhi(ov.z); r[6] += bflo(ov.w); r[7] += bfhi(ov.w);
;                         u32x4 w; w.x = cvt_pk_bf16(r[0], r[1]); w.y = cvt_pk_bf16(r[2], r[3]); w.z = cvt_pk_bf16(r[4], r[5]); w.w = cvt_pk_bf16(r[6], r[7]);
;                         *(u32x4*)mp = w; } }
	v_lshlrev_b32_e32 v70, 16, v102
	v_and_b32_e32 v71, 0xffff0000, v102
	v_lshlrev_b32_e32 v76, 16, v98
	v_and_b32_e32 v77, 0xffff0000, v98
	v_pk_fma_f32 v[68:69], v[68:69], v[70:71], v[76:77]
	v_pk_add_f32 v[70:71], v[72:73], 1.0 op_sel_hi:[1,0]
	v_mul_f32_e32 v62, 0xbfb8aa3b, v62
	v_mul_f32_e32 v63, 0xbfb8aa3b, v63
	v_exp_f32_e32 v62, v62
	v_exp_f32_e32 v63, v63
	v_rcp_f32_e32 v71, v71
	v_mul_f32_e32 v52, 0xbfb8aa3b, v52
	v_mul_f32_e32 v53, 0xbfb8aa3b, v53
	v_exp_f32_e32 v52, v52
	v_rcp_f32_e32 v70, v70
	v_lshlrev_b32_e32 v72, 16, v103
	v_and_b32_e32 v73, 0xffff0000, v103
	v_lshlrev_b32_e32 v76, 16, v99
	v_and_b32_e32 v77, 0xffff0000, v99
	v_pk_fma_f32 v[70:71], v[70:71], v[72:73], v[76:77]
	v_pk_add_f32 v[72:73], v[74:75], 1.0 op_sel_hi:[1,0]
	v_exp_f32_e32 v53, v53
	v_pk_add_f32 v[48:49], v[48:49], v[24:25]
	v_pk_add_f32 v[50:51], v[50:51], v[26:27]
	v_mul_f32_e32 v48, 0xbfb8aa3b, v48
	v_rcp_f32_e32 v73, v73
	v_pk_add_f32 v[54:55], v[54:55], v[30:31]
	v_mov_b32_e32 v79, 0
	v_mul_f32_e32 v54, 0xbfb8aa3b, v54
	v_rcp_f32_e32 v72, v72
	v_lshlrev_b32_e32 v74, 16, v104
	v_and_b32_e32 v75, 0xffff0000, v104
	v_lshlrev_b32_e32 v76, 16, v100
	v_and_b32_e32 v77, 0xffff0000, v100
	v_pk_fma_f32 v[72:73], v[72:73], v[74:75], v[76:77]
	v_mul_f32_e32 v55, 0xbfb8aa3b, v55
	v_exp_f32_e32 v54, v54
	v_exp_f32_e32 v55, v55
	v_rcp_f32_e32 v67, v67
	v_mov_b32_e32 v80, 0
	v_mov_b32_e32 v81, 0
	v_rcp_f32_e32 v66, v66
	v_lshlrev_b32_e32 v74, 16, v105
	v_and_b32_e32 v75, 0xffff0000, v105
	v_lshlrev_b32_e32 v76, 16, v101
	v_and_b32_e32 v77, 0xffff0000, v101
	v_pk_fma_f32 v[74:75], v[66:67], v[74:75], v[76:77]
	v_cvt_pk_bf16_f32 v66, v68, v69
	v_cvt_pk_bf16_f32 v67, v70, v71
	v_cvt_pk_bf16_f32 v68, v72, v73
	v_cvt_pk_bf16_f32 v69, v74, v75
	global_store_dwordx4 v[116:117], v[66:69], off offset:256
	v_mov_b32_e32 v78, 0
	s_nop 0
	v_exp_f32_e32 v68, v56
	v_mul_f32_e32 v56, 0xbfb8aa3b, v57
	v_exp_f32_e32 v69, v56
	v_mul_f32_e32 v56, 0xbfb8aa3b, v58
	v_mul_f32_e32 v57, 0xbfb8aa3b, v59
	v_pk_add_f32 v[58:59], v[60:61], 1.0 op_sel_hi:[1,0]
	v_exp_f32_e32 v56, v56
	v_exp_f32_e32 v57, v57
	v_lshl_add_u64 v[66:67], s[6:7], 0, v[114:115]
	v_lshl_add_u64 v[66:67], v[66:67], 0, v[64:65]
	v_rcp_f32_e32 v59, v59
	v_pk_add_f32 v[56:57], v[56:57], 1.0 op_sel_hi:[1,0]
	v_rcp_f32_e32 v58, v58
	s_waitcnt vmcnt(3)
	v_lshlrev_b32_e32 v60, 16, v90
	v_and_b32_e32 v61, 0xffff0000, v90
	v_lshlrev_b32_e32 v70, 16, v94
	v_and_b32_e32 v71, 0xffff0000, v94
	v_pk_fma_f32 v[58:59], v[58:59], v[60:61], v[70:71]
	v_pk_add_f32 v[60:61], v[62:63], 1.0 op_sel_hi:[1,0]
	s_nop 0
	s_nop 0
	v_rcp_f32_e32 v61, v61
	s_nop 0
	v_rcp_f32_e32 v60, v60
	v_lshlrev_b32_e32 v62, 16, v91
	v_and_b32_e32 v63, 0xffff0000, v91
	v_lshlrev_b32_e32 v70, 16, v95
	v_and_b32_e32 v71, 0xffff0000, v95
	v_pk_fma_f32 v[60:61], v[60:61], v[62:63], v[70:71]
	v_pk_add_f32 v[62:63], v[68:69], 1.0 op_sel_hi:[1,0]
	s_nop 0
	s_nop 0
	v_rcp_f32_e32 v63, v63
	s_nop 0
	v_rcp_f32_e32 v62, v62
	v_lshlrev_b32_e32 v68, 16, v92
	v_and_b32_e32 v69, 0xffff0000, v92
	v_lshlrev_b32_e32 v70, 16, v96
	v_and_b32_e32 v71, 0xffff0000, v96
	v_pk_fma_f32 v[62:63], v[62:63], v[68:69], v[70:71]
	s_nop 0
	v_rcp_f32_e32 v57, v57
	s_nop 0
	v_rcp_f32_e32 v56, v56
	v_lshlrev_b32_e32 v68, 16, v93
	v_and_b32_e32 v69, 0xffff0000, v93
	v_lshlrev_b32_e32 v70, 16, v97
	v_and_b32_e32 v71, 0xffff0000, v97
	v_pk_fma_f32 v[68:69], v[56:57], v[68:69], v[70:71]
	v_cvt_pk_bf16_f32 v56, v58, v59
	v_cvt_pk_bf16_f32 v57, v60, v61
	v_cvt_pk_bf16_f32 v58, v62, v63
	v_cvt_pk_bf16_f32 v59, v68, v69
	global_store_dwordx4 v[66:67], v[56:59], off
	s_nop 1
	v_exp_f32_e32 v56, v48
	v_mul_f32_e32 v48, 0xbfb8aa3b, v49
	v_exp_f32_e32 v57, v48
	v_mul_f32_e32 v48, 0xbfb8aa3b, v50
	v_mul_f32_e32 v49, 0xbfb8aa3b, v51
	v_pk_add_f32 v[50:51], v[52:53], 1.0 op_sel_hi:[1,0]
	v_exp_f32_e32 v48, v48
	v_exp_f32_e32 v49, v49
	v_rcp_f32_e32 v51, v51
	v_pk_add_f32 v[48:49], v[48:49], 1.0 op_sel_hi:[1,0]
	v_rcp_f32_e32 v50, v50
	s_waitcnt vmcnt(3)
	v_lshlrev_b32_e32 v52, 16, v86
	v_and_b32_e32 v53, 0xffff0000, v86
	v_lshlrev_b32_e32 v58, 16, v82
	v_and_b32_e32 v59, 0xffff0000, v82
	v_pk_fma_f32 v[50:51], v[50:51], v[52:53], v[58:59]
	v_pk_add_f32 v[52:53], v[54:55], 1.0 op_sel_hi:[1,0]
	s_nop 0
	s_nop 0
	v_rcp_f32_e32 v53, v53
	s_nop 0
	v_rcp_f32_e32 v52, v52
	v_lshlrev_b32_e32 v54, 16, v87
	v_and_b32_e32 v55, 0xffff0000, v87
	v_lshlrev_b32_e32 v58, 16, v83
	v_and_b32_e32 v59, 0xffff0000, v83
	v_pk_fma_f32 v[52:53], v[52:53], v[54:55], v[58:59]
	v_pk_add_f32 v[54:55], v[56:57], 1.0 op_sel_hi:[1,0]
	s_nop 0
	s_nop 0
	v_rcp_f32_e32 v55, v55
	s_nop 0
	v_rcp_f32_e32 v54, v54
	v_lshlrev_b32_e32 v56, 16, v88
	v_and_b32_e32 v57, 0xffff0000, v88
	v_lshlrev_b32_e32 v58, 16, v84
	v_and_b32_e32 v59, 0xffff0000, v84
	v_pk_fma_f32 v[54:55], v[54:55], v[56:57], v[58:59]
	s_nop 0
	v_rcp_f32_e32 v49, v49
	s_nop 0
	v_rcp_f32_e32 v48, v48
	v_lshlrev_b32_e32 v56, 16, v89
	v_and_b32_e32 v57, 0xffff0000, v89
	v_lshlrev_b32_e32 v58, 16, v85
	v_and_b32_e32 v59, 0xffff0000, v85
	v_pk_fma_f32 v[56:57], v[48:49], v[56:57], v[58:59]
	v_cvt_pk_bf16_f32 v48, v50, v51
	v_cvt_pk_bf16_f32 v49, v52, v53
	v_cvt_pk_bf16_f32 v50, v54, v55
	v_cvt_pk_bf16_f32 v51, v56, v57
	global_store_dwordx4 v[66:67], v[48:51], off offset:256
	v_mov_b32_e32 v66, 0
	s_and_b64 vcc, exec, s[42:43]
	v_add_u32_e32 v48, 0xa0, v206
	v_ashrrev_i32_e32 v49, 31, v48
	v_lshlrev_b64 v[50:51], 13, v[48:49]
	v_lshl_add_u64 v[50:51], v[204:205], 0, v[50:51]
	global_load_dwordx4 v[74:77], v[50:51], off
	v_lshlrev_b64 v[84:85], 11, v[48:49]
	v_lshl_add_u64 v[48:49], v[208:209], 0, v[84:85]
	s_cbranch_vccnz .LBB0_927
	global_load_dwordx4 v[78:81], v[48:49], off

; __device__ __forceinline__ unsigned cvt_pk_bf16(float lo, float hi) { f32x2_t v = {lo, hi}; bf2_t r = __builtin_convertvector(v, bf2_t); return __builtin_bit_cast(unsigned, r); }
; __device__ __forceinline__ float bflo(unsigned u) { return __uint_as_float(u << 16); }
; __device__ __forceinline__ float bfhi(unsigned u) { return __uint_as_float(u & 0xffff0000u); }
; __device__ __forceinline__ float sigmoidf_(float x) { return 1.0f / (1.0f + __expf(-x)); }
;     __device__ __forceinline__ void operator()(const f32x4 (&acc)[2][2][4][2], const Unit& u, int wr, int wc, int fr, int fq) const {
;     ...
;                     for (int bj = 0; bj < 2; ++bj) { pvv[mm][bj] = *(const u32x4*)(P + row * 4096 + colg + bj * HALF);
;                         if (j > 0) ovv[mm][bj] = *(const u32x4*)(mixed + row * 1024 + colm + bj * HALF); else ovv[mm][bj] = (u32x4){0u, 0u, 0u, 0u}; } }
; #pragma unroll
;                 for (int mm = 0; mm < 2; ++mm) { const int m = 2 * m2 + mm; const size_t row = (size_t)(row0 + ai * HALF + m * 16);
; #pragma unroll
;                     for (int bj = 0; bj < 2; ++bj) {
;                         const u32x4 pv = pvv[mm][bj], ov = ovv[mm][bj];
;                         bf16_t* mp = mixed + row * 1024 + colm + bj * HALF;
;                         const f32x4 a0 = acc[ai][bj][m][0] + bv[bj][0], a1 = acc[ai][bj][m][1] + bv[bj][1];
;                         float r[8];
;                         r[0] = sigmoidf_(a0[0]) * bflo(pv.x); r[1] = sigmoidf_(a0[1]) * bfhi(pv.x); r[2] = sigmoidf_(a0[2]) * bflo(pv.y); r[3] = sigmoidf_(a0[3]) * bfhi(pv.y);
;                         r[4] = sigmoidf_(a1[0]) * bflo(pv.z); r[5] = sigmoidf_(a1[1]) * bfhi(pv.z); r[6] = sigmoidf_(a1[2]) * bflo(pv.w); r[7] = sigmoidf_(a1[3]) * bfhi(pv.w);
;                         r[0] += bflo(ov.x); r[1] += bfhi(ov.x); r[2] += bflo(ov.y); r[3] += bfhi(ov.y); r[4] += bflo(ov.z); r[5] += bfhi(ov.z); r[6] += bflo(ov.w); r[7] += bfhi(ov.w);
;                         u32x4 w; w.x = cvt_pk_bf16(r[0], r[1]); w.y = cvt_pk_bf16(r[2], r[3]); w.z = cvt_pk_bf16(r[4], r[5]); w.w = cvt_pk_bf16(r[6], r[7]);
;                         *(u32x4*)mp = w; } }
.LBB0_933:
	v_pk_add_f32 v[44:45], v[44:45], v[40:41]
	v_pk_add_f32 v[36:37], v[36:37], v[32:33]
	v_mul_f32_e32 v44, 0xbfb8aa3b, v44
	v_mul_f32_e32 v45, 0xbfb8aa3b, v45
	v_exp_f32_e32 v44, v44
	v_exp_f32_e32 v45, v45
	v_mul_f32_e32 v36, 0xbfb8aa3b, v36
	v_pk_add_f32 v[38:39], v[38:39], v[34:35]
	v_exp_f32_e32 v86, v36
	v_mul_f32_e32 v36, 0xbfb8aa3b, v37
	v_exp_f32_e32 v87, v36
	v_mul_f32_e32 v36, 0xbfb8aa3b, v38
	v_mul_f32_e32 v37, 0xbfb8aa3b, v39
	v_pk_add_f32 v[38:39], v[44:45], 1.0 op_sel_hi:[1,0]
	v_pk_add_f32 v[46:47], v[46:47], v[42:43]
	v_mul_f32_e32 v46, 0xbfb8aa3b, v46
	v_mul_f32_e32 v47, 0xbfb8aa3b, v47
	v_exp_f32_e32 v46, v46
	v_rcp_f32_e32 v39, v39
	v_exp_f32_e32 v47, v47
	v_exp_f32_e32 v36, v36
	v_exp_f32_e32 v37, v37
	v_rcp_f32_e32 v38, v38
	s_waitcnt vmcnt(3)
	v_lshlrev_b32_e32 v44, 16, v74
	v_and_b32_e32 v45, 0xffff0000, v74
	v_lshlrev_b32_e32 v88, 16, v78
	v_and_b32_e32 v89, 0xffff0000, v78
	v_pk_fma_f32 v[38:39], v[38:39], v[44:45], v[88:89]
	v_pk_add_f32 v[44:45], v[46:47], 1.0 op_sel_hi:[1,0]
	v_pk_add_f32 v[36:37], v[36:37], 1.0 op_sel_hi:[1,0]
	v_pk_add_f32 v[20:21], v[20:21], v[28:29]
	v_lshl_add_u64 v[84:85], s[6:7], 0, v[84:85]
	v_mul_f32_e32 v20, 0xbfb8aa3b, v20
	v_rcp_f32_e32 v45, v45
	v_mul_f32_e32 v21, 0xbfb8aa3b, v21
	v_exp_f32_e32 v20, v20
	v_exp_f32_e32 v21, v21
	v_rcp_f32_e32 v44, v44
	v_lshlrev_b32_e32 v46, 16, v75
	v_and_b32_e32 v47, 0xffff0000, v75
	v_lshlrev_b32_e32 v74, 16, v79
	v_and_b32_e32 v75, 0xffff0000, v79
	v_pk_fma_f32 v[44:45], v[44:45], v[46:47], v[74:75]
	v_pk_add_f32 v[46:47], v[86:87], 1.0 op_sel_hi:[1,0]
	v_pk_add_f32 v[16:17], v[16:17], v[24:25]
	v_lshl_add_u64 v[84:85], v[84:85], 0, v[64:65]
	v_mul_f32_e32 v16, 0xbfb8aa3b, v16
	v_pk_add_f32 v[18:19], v[18:19], v[26:27]
	v_rcp_f32_e32 v47, v47
	v_pk_add_f32 v[22:23], v[22:23], v[30:31]
	v_pk_add_f32 v[12:13], v[12:13], v[40:41]
	v_mul_f32_e32 v22, 0xbfb8aa3b, v22
	v_rcp_f32_e32 v46, v46
	v_lshlrev_b32_e32 v74, 16, v76
	v_and_b32_e32 v75, 0xffff0000, v76
	v_lshlrev_b32_e32 v78, 16, v80
	v_and_b32_e32 v79, 0xffff0000, v80
	v_pk_fma_f32 v[46:47], v[46:47], v[74:75], v[78:79]
	v_mul_f32_e32 v23, 0xbfb8aa3b, v23
	v_exp_f32_e32 v22, v22
	v_exp_f32_e32 v23, v23
	v_rcp_f32_e32 v37, v37
	v_mul_f32_e32 v12, 0xbfb8aa3b, v12
	v_mul_f32_e32 v13, 0xbfb8aa3b, v13
	v_exp_f32_e32 v12, v12
	v_rcp_f32_e32 v36, v36
	v_lshlrev_b32_e32 v74, 16, v77
	v_and_b32_e32 v75, 0xffff0000, v77
	v_lshlrev_b32_e32 v76, 16, v81
	v_and_b32_e32 v77, 0xffff0000, v81
	v_pk_fma_f32 v[74:75], v[36:37], v[74:75], v[76:77]
	v_cvt_pk_bf16_f32 v36, v38, v39
	v_cvt_pk_bf16_f32 v37, v44, v45
	v_cvt_pk_bf16_f32 v38, v46, v47
	v_cvt_pk_bf16_f32 v39, v74, v75
	global_store_dwordx4 v[84:85], v[36:39], off
	v_exp_f32_e32 v13, v13
	v_pk_add_f32 v[8:9], v[8:9], v[32:33]
	v_exp_f32_e32 v36, v16
	v_mul_f32_e32 v16, 0xbfb8aa3b, v17
	v_exp_f32_e32 v37, v16
	v_mul_f32_e32 v16, 0xbfb8aa3b, v18
	v_mul_f32_e32 v17, 0xbfb8aa3b, v19
	v_pk_add_f32 v[18:19], v[20:21], 1.0 op_sel_hi:[1,0]
	v_exp_f32_e32 v16, v16
	v_exp_f32_e32 v17, v17
	v_mul_f32_e32 v8, 0xbfb8aa3b, v8
	v_pk_add_f32 v[10:11], v[10:11], v[34:35]
	v_rcp_f32_e32 v19, v19
	v_pk_add_f32 v[16:17], v[16:17], 1.0 op_sel_hi:[1,0]
	v_pk_add_f32 v[14:15], v[14:15], v[42:43]
	v_pk_add_f32 v[4:5], v[4:5], v[28:29]
	v_rcp_f32_e32 v18, v18
	s_waitcnt vmcnt(3)
; __device__ __forceinline__ unsigned cvt_pk_bf16(float lo, float hi) { f32x2_t v = {lo, hi}; bf2_t r = __builtin_convertvector(v, bf2_t); return __builtin_bit_cast(unsigned, r); }
; __device__ __forceinline__ float bflo(unsigned u) { return __uint_as_float(u << 16); }
; __device__ __forceinline__ float bfhi(unsigned u) { return __uint_as_float(u & 0xffff0000u); }
; __device__ __forceinline__ float sigmoidf_(float x) { return 1.0f / (1.0f + __expf(-x)); }
;     __device__ __forceinline__ void operator()(const f32x4 (&acc)[2][2][4][2], const Unit& u, int wr, int wc, int fr, int fq) const {
;     ...
;                 for (int mm = 0; mm < 2; ++mm) { const int m = 2 * m2 + mm; const size_t row = (size_t)(row0 + ai * HALF + m * 16);
; #pragma unroll
;                     for (int bj = 0; bj < 2; ++bj) {
;                         const u32x4 pv = pvv[mm][bj], ov = ovv[mm][bj];
;                         bf16_t* mp = mixed + row * 1024 + colm + bj * HALF;
;                         const f32x4 a0 = acc[ai][bj][m][0] + bv[bj][0], a1 = acc[ai][bj][m][1] + bv[bj][1];
;                         float r[8];
;                         r[0] = sigmoidf_(a0[0]) * bflo(pv.x); r[1] = sigmoidf_(a0[1]) * bfhi(pv.x); r[2] = sigmoidf_(a0[2]) * bflo(pv.y); r[3] = sigmoidf_(a0[3]) * bfhi(pv.y);
;                         r[4] = sigmoidf_(a1[0]) * bflo(pv.z); r[5] = sigmoidf_(a1[1]) * bfhi(pv.z); r[6] = sigmoidf_(a1[2]) * bflo(pv.w); r[7] = sigmoidf_(a1[3]) * bfhi(pv.w);
;                         r[0] += bflo(ov.x); r[1] += bfhi(ov.x); r[2] += bflo(ov.y); r[3] += bfhi(ov.y); r[4] += bflo(ov.z); r[5] += bfhi(ov.z); r[6] += bflo(ov.w); r[7] += bfhi(ov.w);
;                         u32x4 w; w.x = cvt_pk_bf16(r[0], r[1]); w.y = cvt_pk_bf16(r[2], r[3]); w.z = cvt_pk_bf16(r[4], r[5]); w.w = cvt_pk_bf16(r[6], r[7]);
;                         *(u32x4*)mp = w; } }
	v_lshlrev_b32_e32 v20, 16, v70
	v_and_b32_e32 v21, 0xffff0000, v70
	v_lshlrev_b32_e32 v38, 16, v66
	v_and_b32_e32 v39, 0xffff0000, v66
	v_pk_fma_f32 v[18:19], v[18:19], v[20:21], v[38:39]
	v_pk_add_f32 v[20:21], v[22:23], 1.0 op_sel_hi:[1,0]
	v_mul_f32_e32 v14, 0xbfb8aa3b, v14
	v_mul_f32_e32 v15, 0xbfb8aa3b, v15
	v_exp_f32_e32 v14, v14
	v_exp_f32_e32 v15, v15
	v_rcp_f32_e32 v21, v21
	v_mul_f32_e32 v4, 0xbfb8aa3b, v4
	v_mul_f32_e32 v5, 0xbfb8aa3b, v5
	v_exp_f32_e32 v4, v4
	v_rcp_f32_e32 v20, v20
	v_lshlrev_b32_e32 v22, 16, v71
	v_and_b32_e32 v23, 0xffff0000, v71
	v_lshlrev_b32_e32 v38, 16, v67
	v_and_b32_e32 v39, 0xffff0000, v67
	v_pk_fma_f32 v[20:21], v[20:21], v[22:23], v[38:39]
	v_pk_add_f32 v[22:23], v[36:37], 1.0 op_sel_hi:[1,0]
	v_exp_f32_e32 v5, v5
	v_pk_add_f32 v[0:1], v[0:1], v[24:25]
	v_pk_add_f32 v[2:3], v[2:3], v[26:27]
	v_mul_f32_e32 v0, 0xbfb8aa3b, v0
	v_rcp_f32_e32 v23, v23
	v_pk_add_f32 v[6:7], v[6:7], v[30:31]
	v_rcp_f32_e32 v22, v22
	v_lshlrev_b32_e32 v36, 16, v72
	v_and_b32_e32 v37, 0xffff0000, v72
	v_lshlrev_b32_e32 v38, 16, v68
	v_and_b32_e32 v39, 0xffff0000, v68
	v_pk_fma_f32 v[22:23], v[22:23], v[36:37], v[38:39]
	v_mul_f32_e32 v6, 0xbfb8aa3b, v6
	v_mul_f32_e32 v7, 0xbfb8aa3b, v7
	v_exp_f32_e32 v6, v6
	v_rcp_f32_e32 v17, v17
	v_exp_f32_e32 v7, v7
	v_rcp_f32_e32 v16, v16
	v_lshlrev_b32_e32 v36, 16, v73
	v_and_b32_e32 v37, 0xffff0000, v73
	v_lshlrev_b32_e32 v38, 16, v69
	v_and_b32_e32 v39, 0xffff0000, v69
	v_pk_fma_f32 v[36:37], v[16:17], v[36:37], v[38:39]
	v_cvt_pk_bf16_f32 v16, v18, v19
	v_cvt_pk_bf16_f32 v17, v20, v21
	v_cvt_pk_bf16_f32 v18, v22, v23
	v_cvt_pk_bf16_f32 v19, v36, v37
	global_store_dwordx4 v[84:85], v[16:19], off offset:256
	s_nop 1
	v_exp_f32_e32 v18, v8
	v_mul_f32_e32 v8, 0xbfb8aa3b, v9
	v_exp_f32_e32 v19, v8
	v_mul_f32_e32 v8, 0xbfb8aa3b, v10
	v_mul_f32_e32 v9, 0xbfb8aa3b, v11
	v_pk_add_f32 v[10:11], v[12:13], 1.0 op_sel_hi:[1,0]
	v_exp_f32_e32 v8, v8
	v_exp_f32_e32 v9, v9
	v_lshl_add_u64 v[16:17], s[6:7], 0, v[82:83]
	v_lshl_add_u64 v[16:17], v[16:17], 0, v[64:65]
	v_rcp_f32_e32 v11, v11
	v_pk_add_f32 v[8:9], v[8:9], 1.0 op_sel_hi:[1,0]
	v_rcp_f32_e32 v10, v10
	s_waitcnt vmcnt(3)
	v_lshlrev_b32_e32 v12, 16, v56
	v_and_b32_e32 v13, 0xffff0000, v56
	v_lshlrev_b32_e32 v20, 16, v60
	v_and_b32_e32 v21, 0xffff0000, v60
	v_pk_fma_f32 v[10:11], v[10:11], v[12:13], v[20:21]
	v_pk_add_f32 v[12:13], v[14:15], 1.0 op_sel_hi:[1,0]
	s_nop 0
	s_nop 0
	v_rcp_f32_e32 v13, v13
	s_nop 0
	v_rcp_f32_e32 v12, v12
	v_lshlrev_b32_e32 v14, 16, v57
	v_and_b32_e32 v15, 0xffff0000, v57
	v_lshlrev_b32_e32 v20, 16, v61
	v_and_b32_e32 v21, 0xffff0000, v61
	v_pk_fma_f32 v[12:13], v[12:13], v[14:15], v[20:21]
	v_pk_add_f32 v[14:15], v[18:19], 1.0 op_sel_hi:[1,0]
	s_nop 0
	s_nop 0
	v_rcp_f32_e32 v15, v15
	s_nop 0
	v_rcp_f32_e32 v14, v14
	v_lshlrev_b32_e32 v18, 16, v58
	v_and_b32_e32 v19, 0xffff0000, v58
	v_lshlrev_b32_e32 v20, 16, v62
	v_and_b32_e32 v21, 0xffff0000, v62
	v_pk_fma_f32 v[14:15], v[14:15], v[18:19], v[20:21]
	s_nop 0
	v_rcp_f32_e32 v9, v9
	s_nop 0
	v_rcp_f32_e32 v8, v8
	v_lshlrev_b32_e32 v18, 16, v59
	v_and_b32_e32 v19, 0xffff0000, v59
	v_lshlrev_b32_e32 v20, 16, v63
	v_and_b32_e32 v21, 0xffff0000, v63
	v_pk_fma_f32 v[18:19], v[8:9], v[18:19], v[20:21]
	v_cvt_pk_bf16_f32 v8, v10, v11
	v_cvt_pk_bf16_f32 v9, v12, v13
	v_cvt_pk_bf16_f32 v10, v14, v15
	v_cvt_pk_bf16_f32 v11, v18, v19
	global_store_dwordx4 v[16:17], v[8:11], off
	s_nop 1
	v_exp_f32_e32 v8, v0
	v_mul_f32_e32 v0, 0xbfb8aa3b, v1
	v_exp_f32_e32 v9, v0
	v_mul_f32_e32 v0, 0xbfb8aa3b, v2
	v_mul_f32_e32 v1, 0xbfb8aa3b, v3
	v_pk_add_f32 v[2:3], v[4:5], 1.0 op_sel_hi:[1,0]
	v_exp_f32_e32 v0, v0
	v_exp_f32_e32 v1, v1
	v_rcp_f32_e32 v3, v3
	v_pk_add_f32 v[0:1], v[0:1], 1.0 op_sel_hi:[1,0]
	v_rcp_f32_e32 v2, v2
	s_waitcnt vmcnt(3)
	v_lshlrev_b32_e32 v4, 16, v52
	v_and_b32_e32 v5, 0xffff0000, v52
	v_lshlrev_b32_e32 v10, 16, v48
	v_and_b32_e32 v11, 0xffff0000, v48
	v_pk_fma_f32 v[2:3], v[2:3], v[4:5], v[10:11]
	v_pk_add_f32 v[4:5], v[6:7], 1.0 op_sel_hi:[1,0]
	s_nop 0
	s_nop 0
	v_rcp_f32_e32 v5, v5
	s_nop 0
	v_rcp_f32_e32 v4, v4
	v_lshlrev_b32_e32 v6, 16, v53
	v_and_b32_e32 v7, 0xffff0000, v53
	v_lshlrev_b32_e32 v10, 16, v49
	v_and_b32_e32 v11, 0xffff0000, v49
	v_pk_fma_f32 v[4:5], v[4:5], v[6:7], v[10:11]
	v_pk_add_f32 v[6:7], v[8:9], 1.0 op_sel_hi:[1,0]
	s_nop 0
	s_nop 0
	v_rcp_f32_e32 v7, v7
	s_nop 0
	v_rcp_f32_e32 v6, v6
	v_lshlrev_b32_e32 v8, 16, v54
	v_and_b32_e32 v9, 0xffff0000, v54
	v_lshlrev_b32_e32 v10, 16, v50
	v_and_b32_e32 v11, 0xffff0000, v50
	v_pk_fma_f32 v[6:7], v[6:7], v[8:9], v[10:11]
	s_nop 0
	v_rcp_f32_e32 v1, v1
	s_mov_b64 s[38:39], -1
	v_rcp_f32_e32 v0, v0
	v_lshlrev_b32_e32 v8, 16, v55
	v_and_b32_e32 v9, 0xffff0000, v55
	v_lshlrev_b32_e32 v10, 16, v51
	v_and_b32_e32 v11, 0xffff0000, v51
	v_pk_fma_f32 v[8:9], v[0:1], v[8:9], v[10:11]
	v_cvt_pk_bf16_f32 v0, v2, v3
	v_cvt_pk_bf16_f32 v1, v4, v5
	v_cvt_pk_bf16_f32 v2, v6, v7
	v_cvt_pk_bf16_f32 v3, v8, v9
	global_store_dwordx4 v[16:17], v[0:3], off offset:256
	s_andn2_b64 vcc, exec, s[16:17]
	s_cbranch_vccnz .LBB0_889
	s_andn2_b64 vcc, exec, s[0:1]
	s_cbranch_vccnz .LBB0_888
	s_barrier
	s_branch .LBB0_888

; __device__ __forceinline__ unsigned cvt_pk_bf16(float lo, float hi) { f32x2_t v = {lo, hi}; bf2_t r = __builtin_convertvector(v, bf2_t); return __builtin_bit_cast(unsigned, r); }
; __device__ __forceinline__ float sigmoidf_(float x) { return 1.0f / (1.0f + __expf(-x)); }
; __device__ __forceinline__ float siluf_(float x) { return x * sigmoidf_(x); }
;     __device__ __forceinline__ void operator()(const f32x4 (&acc)[2][2][4][2], const Unit& u, int wr, int wc, int fr, int fq) const {
;         const int row0 = u.pm * BM + wr * 64 + fr, col0 = u.pn * HALF + wc * 32 + 8 * fq;
; #pragma unroll
;         for (int ai = 0; ai < 2; ++ai)
; #pragma unroll
;             for (int m = 0; m < 4; ++m) { bf16_t* rowp = U + (size_t)(row0 + ai * HALF + m * 16) * DFF + col0;
;                 const f32x4 g0 = acc[ai][0][m][0], g1 = acc[ai][0][m][1], h0 = acc[ai][1][m][0], h1 = acc[ai][1][m][1];
;                 u32x4 w; w.x = cvt_pk_bf16(siluf_(g0[0]) * h0[0], siluf_(g0[1]) * h0[1]); w.y = cvt_pk_bf16(siluf_(g0[2]) * h0[2], siluf_(g0[3]) * h0[3]);
;                 w.z = cvt_pk_bf16(siluf_(g1[0]) * h1[0], siluf_(g1[1]) * h1[1]); w.w = cvt_pk_bf16(siluf_(g1[2]) * h1[2], siluf_(g1[3]) * h1[3]);
;                 *(u32x4*)rowp = w; }
.LBB0_1129:
	v_mul_f32_e32 v151, 0xbfb8aa3b, v126
	v_exp_f32_e32 v152, v151
	v_mul_f32_e32 v151, 0xbfb8aa3b, v127
	v_exp_f32_e32 v153, v151
	v_lshl_or_b32 v142, s53, 7, v148
	v_lshl_add_u32 v150, s67, 8, v146
	v_ashrrev_i32_e32 v143, 31, v142
	v_pk_add_f32 v[152:153], v[152:153], 1.0 op_sel_hi:[1,0]
	v_mov_b64_e32 v[140:141], s[4:5]
	s_movk_i32 s9, 0x1600
	v_mad_i64_i32 v[144:145], s[16:17], v150, s9, v[140:141]
	v_rcp_f32_e32 v153, v153
	v_lshlrev_b64 v[142:143], 1, v[142:143]
	v_lshl_add_u64 v[144:145], v[144:145], 0, v[142:143]
	v_rcp_f32_e32 v152, v152
	s_nop 0
	v_pk_mul_f32 v[126:127], v[126:127], v[152:153]
	s_nop 0
	v_pk_mul_f32 v[122:123], v[126:127], v[122:123]
	s_nop 0
	v_cvt_pk_bf16_f32 v122, v122, v123
	v_mul_f32_e32 v123, 0xbfb8aa3b, v128
	v_exp_f32_e32 v126, v123
	v_mul_f32_e32 v123, 0xbfb8aa3b, v129
	v_exp_f32_e32 v127, v123
	s_nop 0
	v_pk_add_f32 v[126:127], v[126:127], 1.0 op_sel_hi:[1,0]
	s_nop 0
	s_nop 0
	v_rcp_f32_e32 v127, v127
	s_nop 0
	v_rcp_f32_e32 v126, v126
	s_nop 0
	v_pk_mul_f32 v[126:127], v[128:129], v[126:127]
	s_nop 0
	v_pk_mul_f32 v[124:125], v[126:127], v[124:125]
	s_nop 0
	v_cvt_pk_bf16_f32 v123, v124, v125
	v_mul_f32_e32 v124, 0xbfb8aa3b, v118
	v_mul_f32_e32 v125, 0xbfb8aa3b, v119
	v_exp_f32_e32 v124, v124
	v_exp_f32_e32 v125, v125
	s_nop 0
	v_pk_add_f32 v[124:125], v[124:125], 1.0 op_sel_hi:[1,0]
	s_nop 0
	s_nop 0
	v_rcp_f32_e32 v125, v125
	s_nop 0
	v_rcp_f32_e32 v124, v124
	s_nop 0
	v_pk_mul_f32 v[118:119], v[118:119], v[124:125]
	s_nop 0
	v_pk_mul_f32 v[114:115], v[118:119], v[114:115]
	s_nop 0
	v_cvt_pk_bf16_f32 v124, v114, v115
	v_mul_f32_e32 v114, 0xbfb8aa3b, v120
	v_mul_f32_e32 v115, 0xbfb8aa3b, v121
	v_exp_f32_e32 v114, v114
	v_exp_f32_e32 v115, v115
	s_nop 0
	v_pk_add_f32 v[114:115], v[114:115], 1.0 op_sel_hi:[1,0]
	s_nop 0
	s_nop 0
	v_rcp_f32_e32 v115, v115
	s_nop 0
	v_rcp_f32_e32 v114, v114
	s_nop 0
	v_pk_mul_f32 v[114:115], v[120:121], v[114:115]
	s_nop 0
	v_pk_mul_f32 v[114:115], v[114:115], v[116:117]
	v_mul_f32_e32 v116, 0xbfb8aa3b, v110
	v_mul_f32_e32 v117, 0xbfb8aa3b, v111
	v_exp_f32_e32 v116, v116
	v_exp_f32_e32 v117, v117
	v_cvt_pk_bf16_f32 v125, v114, v115
	global_store_dwordx4 v[144:145], v[122:125], off
	v_or_b32_e32 v114, 16, v150
	v_pk_add_f32 v[116:117], v[116:117], 1.0 op_sel_hi:[1,0]
	v_mad_i64_i32 v[114:115], s[16:17], v114, s9, v[140:141]
	v_lshl_add_u64 v[114:115], v[114:115], 0, v[142:143]
	v_rcp_f32_e32 v117, v117
	s_nop 0
	v_rcp_f32_e32 v116, v116
	s_nop 0
	v_pk_mul_f32 v[110:111], v[110:111], v[116:117]
	s_nop 0
	v_pk_mul_f32 v[106:107], v[110:111], v[106:107]
	s_nop 0
	v_cvt_pk_bf16_f32 v106, v106, v107
	v_mul_f32_e32 v107, 0xbfb8aa3b, v112
	v_exp_f32_e32 v110, v107
	v_mul_f32_e32 v107, 0xbfb8aa3b, v113
	v_exp_f32_e32 v111, v107
	s_nop 0
	v_pk_add_f32 v[110:111], v[110:111], 1.0 op_sel_hi:[1,0]
	s_nop 0
	s_nop 0
	v_rcp_f32_e32 v111, v111
	s_nop 0
	v_rcp_f32_e32 v110, v110
	s_nop 0
	v_pk_mul_f32 v[110:111], v[112:113], v[110:111]
	s_nop 0
	v_pk_mul_f32 v[108:109], v[110:111], v[108:109]
	s_nop 0
	v_cvt_pk_bf16_f32 v107, v108, v109
	v_mul_f32_e32 v108, 0xbfb8aa3b, v102
	v_mul_f32_e32 v109, 0xbfb8aa3b, v103
	v_exp_f32_e32 v108, v108
	v_exp_f32_e32 v109, v109
	s_nop 0
	v_pk_add_f32 v[108:109], v[108:109], 1.0 op_sel_hi:[1,0]
	s_nop 0
	s_nop 0
	v_rcp_f32_e32 v109, v109
	s_nop 0
	v_rcp_f32_e32 v108, v108
	s_nop 0
	v_pk_mul_f32 v[102:103], v[102:103], v[108:109]
	s_nop 0
	v_pk_mul_f32 v[98:99], v[102:103], v[98:99]
	s_nop 0
	v_cvt_pk_bf16_f32 v108, v98, v99
	v_mul_f32_e32 v98, 0xbfb8aa3b, v104
	v_mul_f32_e32 v99, 0xbfb8aa3b, v105
	v_exp_f32_e32 v98, v98
	v_exp_f32_e32 v99, v99
	s_nop 0
	v_pk_add_f32 v[98:99], v[98:99], 1.0 op_sel_hi:[1,0]
	s_nop 0
	s_nop 0
	v_rcp_f32_e32 v99, v99
	s_nop 0
	v_rcp_f32_e32 v98, v98
	s_nop 0
	v_pk_mul_f32 v[98:99], v[104:105], v[98:99]
	s_nop 0
	v_pk_mul_f32 v[98:99], v[98:99], v[100:101]
	v_mul_f32_e32 v100, 0xbfb8aa3b, v94
	v_mul_f32_e32 v101, 0xbfb8aa3b, v95
	v_exp_f32_e32 v100, v100
	v_exp_f32_e32 v101, v101
	v_cvt_pk_bf16_f32 v109, v98, v99
	global_store_dwordx4 v[114:115], v[106:109], off
	v_or_b32_e32 v98, 32, v150
	v_pk_add_f32 v[100:101], v[100:101], 1.0 op_sel_hi:[1,0]
	v_mad_i64_i32 v[98:99], s[16:17], v98, s9, v[140:141]
	v_lshl_add_u64 v[98:99], v[98:99], 0, v[142:143]
	v_rcp_f32_e32 v101, v101
	s_nop 0
	v_rcp_f32_e32 v100, v100
	s_nop 0
	v_pk_mul_f32 v[94:95], v[94:95], v[100:101]
	s_nop 0
	v_pk_mul_f32 v[90:91], v[94:95], v[90:91]
	s_nop 0
	v_cvt_pk_bf16_f32 v90, v90, v91
	v_mul_f32_e32 v91, 0xbfb8aa3b, v96
	v_exp_f32_e32 v94, v91
	v_mul_f32_e32 v91, 0xbfb8aa3b, v97
	v_exp_f32_e32 v95, v91
	s_nop 0
	v_pk_add_f32 v[94:95], v[94:95], 1.0 op_sel_hi:[1,0]
	s_nop 0
	s_nop 0
	v_rcp_f32_e32 v95, v95
	s_nop 0
	v_rcp_f32_e32 v94, v94
	s_nop 0
	v_pk_mul_f32 v[94:95], v[96:97], v[94:95]
	s_nop 0
	v_pk_mul_f32 v[92:93], v[94:95], v[92:93]
	s_nop 0
	v_cvt_pk_bf16_f32 v91, v92, v93
	v_mul_f32_e32 v92, 0xbfb8aa3b, v86
	v_mul_f32_e32 v93, 0xbfb8aa3b, v87
	v_exp_f32_e32 v92, v92
	v_exp_f32_e32 v93, v93
	s_nop 0
	v_pk_add_f32 v[92:93], v[92:93], 1.0 op_sel_hi:[1,0]
	s_nop 0
	s_nop 0
	v_rcp_f32_e32 v93, v93
	s_nop 0
	v_rcp_f32_e32 v92, v92
	s_nop 0
	v_pk_mul_f32 v[86:87], v[86:87], v[92:93]
	s_nop 0
	v_pk_mul_f32 v[82:83], v[86:87], v[82:83]
	s_nop 0
	v_cvt_pk_bf16_f32 v92, v82, v83
	v_mul_f32_e32 v82, 0xbfb8aa3b, v88
	v_mul_f32_e32 v83, 0xbfb8aa3b, v89
	v_exp_f32_e32 v82, v82
	v_exp_f32_e32 v83, v83
	s_nop 0
	v_pk_add_f32 v[82:83], v[82:83], 1.0 op_sel_hi:[1,0]
	s_nop 0
	s_nop 0
	v_rcp_f32_e32 v83, v83
	s_nop 0
	v_rcp_f32_e32 v82, v82
	s_nop 0
	v_pk_mul_f32 v[82:83], v[88:89], v[82:83]
	s_nop 0
	v_pk_mul_f32 v[82:83], v[82:83], v[84:85]
; __device__ __forceinline__ unsigned cvt_pk_bf16(float lo, float hi) { f32x2_t v = {lo, hi}; bf2_t r = __builtin_convertvector(v, bf2_t); return __builtin_bit_cast(unsigned, r); }
; __device__ __forceinline__ float sigmoidf_(float x) { return 1.0f / (1.0f + __expf(-x)); }
; __device__ __forceinline__ float siluf_(float x) { return x * sigmoidf_(x); }
;     __device__ __forceinline__ void operator()(const f32x4 (&acc)[2][2][4][2], const Unit& u, int wr, int wc, int fr, int fq) const {
;         const int row0 = u.pm * BM + wr * 64 + fr, col0 = u.pn * HALF + wc * 32 + 8 * fq;
; #pragma unroll
;         for (int ai = 0; ai < 2; ++ai)
; #pragma unroll
;             for (int m = 0; m < 4; ++m) { bf16_t* rowp = U + (size_t)(row0 + ai * HALF + m * 16) * DFF + col0;
;                 const f32x4 g0 = acc[ai][0][m][0], g1 = acc[ai][0][m][1], h0 = acc[ai][1][m][0], h1 = acc[ai][1][m][1];
;                 u32x4 w; w.x = cvt_pk_bf16(siluf_(g0[0]) * h0[0], siluf_(g0[1]) * h0[1]); w.y = cvt_pk_bf16(siluf_(g0[2]) * h0[2], siluf_(g0[3]) * h0[3]);
;                 w.z = cvt_pk_bf16(siluf_(g1[0]) * h1[0], siluf_(g1[1]) * h1[1]); w.w = cvt_pk_bf16(siluf_(g1[2]) * h1[2], siluf_(g1[3]) * h1[3]);
;                 *(u32x4*)rowp = w; }
	v_mul_f32_e32 v84, 0xbfb8aa3b, v78
	v_mul_f32_e32 v85, 0xbfb8aa3b, v79
	v_exp_f32_e32 v84, v84
	v_exp_f32_e32 v85, v85
	v_cvt_pk_bf16_f32 v93, v82, v83
	global_store_dwordx4 v[98:99], v[90:93], off
	v_or_b32_e32 v82, 48, v150
	v_pk_add_f32 v[84:85], v[84:85], 1.0 op_sel_hi:[1,0]
	v_mad_i64_i32 v[82:83], s[16:17], v82, s9, v[140:141]
	v_lshl_add_u64 v[82:83], v[82:83], 0, v[142:143]
	v_rcp_f32_e32 v85, v85
	s_nop 0
	v_rcp_f32_e32 v84, v84
	s_nop 0
	v_pk_mul_f32 v[78:79], v[78:79], v[84:85]
	s_nop 0
	v_pk_mul_f32 v[74:75], v[78:79], v[74:75]
	s_nop 0
	v_cvt_pk_bf16_f32 v74, v74, v75
	v_mul_f32_e32 v75, 0xbfb8aa3b, v80
	v_exp_f32_e32 v78, v75
	v_mul_f32_e32 v75, 0xbfb8aa3b, v81
	v_exp_f32_e32 v79, v75
	s_nop 0
	v_pk_add_f32 v[78:79], v[78:79], 1.0 op_sel_hi:[1,0]
	s_nop 0
	s_nop 0
	v_rcp_f32_e32 v79, v79
	s_nop 0
	v_rcp_f32_e32 v78, v78
	s_nop 0
	v_pk_mul_f32 v[78:79], v[80:81], v[78:79]
	s_nop 0
	v_pk_mul_f32 v[76:77], v[78:79], v[76:77]
	s_nop 0
	v_cvt_pk_bf16_f32 v75, v76, v77
	v_mul_f32_e32 v76, 0xbfb8aa3b, v70
	v_mul_f32_e32 v77, 0xbfb8aa3b, v71
	v_exp_f32_e32 v76, v76
	v_exp_f32_e32 v77, v77
	s_nop 0
	v_pk_add_f32 v[76:77], v[76:77], 1.0 op_sel_hi:[1,0]
	s_nop 0
	s_nop 0
	v_rcp_f32_e32 v77, v77
	s_nop 0
	v_rcp_f32_e32 v76, v76
	s_nop 0
	v_pk_mul_f32 v[70:71], v[70:71], v[76:77]
	s_nop 0
	v_pk_mul_f32 v[66:67], v[70:71], v[66:67]
	s_nop 0
	v_cvt_pk_bf16_f32 v76, v66, v67
	v_mul_f32_e32 v66, 0xbfb8aa3b, v72
	v_mul_f32_e32 v67, 0xbfb8aa3b, v73
	v_exp_f32_e32 v66, v66
	v_exp_f32_e32 v67, v67
	s_nop 0
	v_pk_add_f32 v[66:67], v[66:67], 1.0 op_sel_hi:[1,0]
	s_nop 0
	s_nop 0
	v_rcp_f32_e32 v67, v67
	s_nop 0
	v_rcp_f32_e32 v66, v66
	s_nop 0
	v_pk_mul_f32 v[66:67], v[72:73], v[66:67]
	s_nop 0
	v_pk_mul_f32 v[66:67], v[66:67], v[68:69]
	v_mul_f32_e32 v68, 0xbfb8aa3b, v60
	v_mul_f32_e32 v69, 0xbfb8aa3b, v61
	v_exp_f32_e32 v68, v68
	v_exp_f32_e32 v69, v69
	v_cvt_pk_bf16_f32 v77, v66, v67
	global_store_dwordx4 v[82:83], v[74:77], off
	v_add_u32_e32 v66, 0x80, v150
	v_pk_add_f32 v[68:69], v[68:69], 1.0 op_sel_hi:[1,0]
	v_mad_i64_i32 v[66:67], s[16:17], v66, s9, v[140:141]
	v_lshl_add_u64 v[66:67], v[66:67], 0, v[142:143]
	v_rcp_f32_e32 v69, v69
	s_nop 0
	v_rcp_f32_e32 v68, v68
	s_nop 0
	v_pk_mul_f32 v[60:61], v[60:61], v[68:69]
	s_nop 0
	v_pk_mul_f32 v[56:57], v[60:61], v[56:57]
	s_nop 0
	v_cvt_pk_bf16_f32 v56, v56, v57
	v_mul_f32_e32 v57, 0xbfb8aa3b, v62
	v_exp_f32_e32 v60, v57
	v_mul_f32_e32 v57, 0xbfb8aa3b, v63
	v_exp_f32_e32 v61, v57
	s_nop 0
	v_pk_add_f32 v[60:61], v[60:61], 1.0 op_sel_hi:[1,0]
	s_nop 0
	s_nop 0
	v_rcp_f32_e32 v61, v61
	s_nop 0
	v_rcp_f32_e32 v60, v60
	s_nop 0
	v_pk_mul_f32 v[60:61], v[62:63], v[60:61]
	s_nop 0
	v_pk_mul_f32 v[58:59], v[60:61], v[58:59]
	s_nop 0
	v_cvt_pk_bf16_f32 v57, v58, v59
	v_mul_f32_e32 v58, 0xbfb8aa3b, v52
	v_mul_f32_e32 v59, 0xbfb8aa3b, v53
	v_exp_f32_e32 v58, v58
	v_exp_f32_e32 v59, v59
	s_nop 0
	v_pk_add_f32 v[58:59], v[58:59], 1.0 op_sel_hi:[1,0]
	s_nop 0
	s_nop 0
	v_rcp_f32_e32 v59, v59
	s_nop 0
	v_rcp_f32_e32 v58, v58
	s_nop 0
	v_pk_mul_f32 v[52:53], v[52:53], v[58:59]
	s_nop 0
	v_pk_mul_f32 v[48:49], v[52:53], v[48:49]
	s_nop 0
	v_cvt_pk_bf16_f32 v58, v48, v49
	v_mul_f32_e32 v48, 0xbfb8aa3b, v54
	v_mul_f32_e32 v49, 0xbfb8aa3b, v55
	v_exp_f32_e32 v48, v48
	v_exp_f32_e32 v49, v49
	s_nop 0
	v_pk_add_f32 v[48:49], v[48:49], 1.0 op_sel_hi:[1,0]
	s_nop 0
	s_nop 0
	v_rcp_f32_e32 v49, v49
	s_nop 0
	v_rcp_f32_e32 v48, v48
	s_nop 0
	v_pk_mul_f32 v[48:49], v[54:55], v[48:49]
	s_nop 0
	v_pk_mul_f32 v[48:49], v[48:49], v[50:51]
	v_mul_f32_e32 v50, 0xbfb8aa3b, v44
	v_mul_f32_e32 v51, 0xbfb8aa3b, v45
	v_exp_f32_e32 v50, v50
	v_exp_f32_e32 v51, v51
	v_cvt_pk_bf16_f32 v59, v48, v49
	global_store_dwordx4 v[66:67], v[56:59], off
	v_add_u32_e32 v48, 0x90, v150
	v_pk_add_f32 v[50:51], v[50:51], 1.0 op_sel_hi:[1,0]
	v_mad_i64_i32 v[48:49], s[16:17], v48, s9, v[140:141]
	v_lshl_add_u64 v[48:49], v[48:49], 0, v[142:143]
	v_rcp_f32_e32 v51, v51
	s_nop 0
	v_rcp_f32_e32 v50, v50
	s_nop 0
	v_pk_mul_f32 v[44:45], v[44:45], v[50:51]
	s_nop 0
	v_pk_mul_f32 v[40:41], v[44:45], v[40:41]
	s_nop 0
	v_cvt_pk_bf16_f32 v40, v40, v41
	v_mul_f32_e32 v41, 0xbfb8aa3b, v46
	v_exp_f32_e32 v44, v41
	v_mul_f32_e32 v41, 0xbfb8aa3b, v47
	v_exp_f32_e32 v45, v41
	s_nop 0
	v_pk_add_f32 v[44:45], v[44:45], 1.0 op_sel_hi:[1,0]
	s_nop 0
	s_nop 0
	v_rcp_f32_e32 v45, v45
	s_nop 0
	v_rcp_f32_e32 v44, v44
	s_nop 0
	v_pk_mul_f32 v[44:45], v[46:47], v[44:45]
	s_nop 0
	v_pk_mul_f32 v[42:43], v[44:45], v[42:43]
	s_nop 0
; __device__ __forceinline__ unsigned cvt_pk_bf16(float lo, float hi) { f32x2_t v = {lo, hi}; bf2_t r = __builtin_convertvector(v, bf2_t); return __builtin_bit_cast(unsigned, r); }
; __device__ __forceinline__ float sigmoidf_(float x) { return 1.0f / (1.0f + __expf(-x)); }
; __device__ __forceinline__ float siluf_(float x) { return x * sigmoidf_(x); }
;     __device__ __forceinline__ void operator()(const f32x4 (&acc)[2][2][4][2], const Unit& u, int wr, int wc, int fr, int fq) const {
;         const int row0 = u.pm * BM + wr * 64 + fr, col0 = u.pn * HALF + wc * 32 + 8 * fq;
; #pragma unroll
;         for (int ai = 0; ai < 2; ++ai)
; #pragma unroll
;             for (int m = 0; m < 4; ++m) { bf16_t* rowp = U + (size_t)(row0 + ai * HALF + m * 16) * DFF + col0;
;                 const f32x4 g0 = acc[ai][0][m][0], g1 = acc[ai][0][m][1], h0 = acc[ai][1][m][0], h1 = acc[ai][1][m][1];
;                 u32x4 w; w.x = cvt_pk_bf16(siluf_(g0[0]) * h0[0], siluf_(g0[1]) * h0[1]); w.y = cvt_pk_bf16(siluf_(g0[2]) * h0[2], siluf_(g0[3]) * h0[3]);
;                 w.z = cvt_pk_bf16(siluf_(g1[0]) * h1[0], siluf_(g1[1]) * h1[1]); w.w = cvt_pk_bf16(siluf_(g1[2]) * h1[2], siluf_(g1[3]) * h1[3]);
;                 *(u32x4*)rowp = w; }
	v_cvt_pk_bf16_f32 v41, v42, v43
	v_mul_f32_e32 v42, 0xbfb8aa3b, v36
	v_mul_f32_e32 v43, 0xbfb8aa3b, v37
	v_exp_f32_e32 v42, v42
	v_exp_f32_e32 v43, v43
	s_nop 0
	v_pk_add_f32 v[42:43], v[42:43], 1.0 op_sel_hi:[1,0]
	s_nop 0
	s_nop 0
	v_rcp_f32_e32 v43, v43
	s_nop 0
	v_rcp_f32_e32 v42, v42
	s_nop 0
	v_pk_mul_f32 v[36:37], v[36:37], v[42:43]
	s_nop 0
	v_pk_mul_f32 v[32:33], v[36:37], v[32:33]
	s_nop 0
	v_cvt_pk_bf16_f32 v42, v32, v33
	v_mul_f32_e32 v32, 0xbfb8aa3b, v38
	v_mul_f32_e32 v33, 0xbfb8aa3b, v39
	v_exp_f32_e32 v32, v32
	v_exp_f32_e32 v33, v33
	s_nop 0
	v_pk_add_f32 v[32:33], v[32:33], 1.0 op_sel_hi:[1,0]
	s_nop 0
	s_nop 0
	v_rcp_f32_e32 v33, v33
	s_nop 0
	v_rcp_f32_e32 v32, v32
	s_nop 0
	v_pk_mul_f32 v[32:33], v[38:39], v[32:33]
	s_nop 0
	v_pk_mul_f32 v[32:33], v[32:33], v[34:35]
	v_mul_f32_e32 v34, 0xbfb8aa3b, v28
	v_mul_f32_e32 v35, 0xbfb8aa3b, v29
	v_exp_f32_e32 v34, v34
	v_exp_f32_e32 v35, v35
	v_cvt_pk_bf16_f32 v43, v32, v33
	global_store_dwordx4 v[48:49], v[40:43], off
	v_add_u32_e32 v32, 0xa0, v150
	v_pk_add_f32 v[34:35], v[34:35], 1.0 op_sel_hi:[1,0]
	v_mad_i64_i32 v[32:33], s[16:17], v32, s9, v[140:141]
	v_lshl_add_u64 v[32:33], v[32:33], 0, v[142:143]
	v_rcp_f32_e32 v35, v35
	s_nop 0
	v_rcp_f32_e32 v34, v34
	s_nop 0
	v_pk_mul_f32 v[28:29], v[28:29], v[34:35]
	s_nop 0
	v_pk_mul_f32 v[24:25], v[28:29], v[24:25]
	s_nop 0
	v_cvt_pk_bf16_f32 v24, v24, v25
	v_mul_f32_e32 v25, 0xbfb8aa3b, v30
	v_exp_f32_e32 v28, v25
	v_mul_f32_e32 v25, 0xbfb8aa3b, v31
	v_exp_f32_e32 v29, v25
	s_nop 0
	v_pk_add_f32 v[28:29], v[28:29], 1.0 op_sel_hi:[1,0]
	s_nop 0
	s_nop 0
	v_rcp_f32_e32 v29, v29
	s_nop 0
	v_rcp_f32_e32 v28, v28
	s_nop 0
	v_pk_mul_f32 v[28:29], v[30:31], v[28:29]
	s_nop 0
	v_pk_mul_f32 v[26:27], v[28:29], v[26:27]
	s_nop 0
	v_cvt_pk_bf16_f32 v25, v26, v27
	v_mul_f32_e32 v26, 0xbfb8aa3b, v20
	v_mul_f32_e32 v27, 0xbfb8aa3b, v21
	v_exp_f32_e32 v26, v26
	v_exp_f32_e32 v27, v27
	s_nop 0
	v_pk_add_f32 v[26:27], v[26:27], 1.0 op_sel_hi:[1,0]
	s_nop 0
	s_nop 0
	v_rcp_f32_e32 v27, v27
	s_nop 0
	v_rcp_f32_e32 v26, v26
	s_nop 0
	v_pk_mul_f32 v[20:21], v[20:21], v[26:27]
	s_nop 0
	v_pk_mul_f32 v[16:17], v[20:21], v[16:17]
	s_nop 0
	v_cvt_pk_bf16_f32 v26, v16, v17
	v_mul_f32_e32 v16, 0xbfb8aa3b, v22
	v_mul_f32_e32 v17, 0xbfb8aa3b, v23
	v_exp_f32_e32 v16, v16
	v_exp_f32_e32 v17, v17
	s_nop 0
	v_pk_add_f32 v[16:17], v[16:17], 1.0 op_sel_hi:[1,0]
	s_nop 0
	s_nop 0
	v_rcp_f32_e32 v17, v17
	s_nop 0
	v_rcp_f32_e32 v16, v16
	s_nop 0
	v_pk_mul_f32 v[16:17], v[22:23], v[16:17]
	s_nop 0
	v_pk_mul_f32 v[16:17], v[16:17], v[18:19]
	v_mul_f32_e32 v18, 0xbfb8aa3b, v12
	v_mul_f32_e32 v19, 0xbfb8aa3b, v13
	v_exp_f32_e32 v18, v18
	v_exp_f32_e32 v19, v19
	v_cvt_pk_bf16_f32 v27, v16, v17
	global_store_dwordx4 v[32:33], v[24:27], off
	v_add_u32_e32 v16, 0xb0, v150
	v_pk_add_f32 v[18:19], v[18:19], 1.0 op_sel_hi:[1,0]
	v_mad_i64_i32 v[16:17], s[16:17], v16, s9, v[140:141]
	v_lshl_add_u64 v[16:17], v[16:17], 0, v[142:143]
	v_rcp_f32_e32 v19, v19
	s_nop 0
	v_rcp_f32_e32 v18, v18
	s_nop 0
	v_pk_mul_f32 v[12:13], v[12:13], v[18:19]
	s_nop 0
	v_pk_mul_f32 v[8:9], v[12:13], v[8:9]
	s_nop 0
	v_cvt_pk_bf16_f32 v8, v8, v9
	v_mul_f32_e32 v9, 0xbfb8aa3b, v14
	v_exp_f32_e32 v12, v9
	v_mul_f32_e32 v9, 0xbfb8aa3b, v15
	v_exp_f32_e32 v13, v9
	s_nop 0
	v_pk_add_f32 v[12:13], v[12:13], 1.0 op_sel_hi:[1,0]
	s_nop 0
	s_nop 0
	v_rcp_f32_e32 v13, v13
	s_nop 0
	v_rcp_f32_e32 v12, v12
	s_nop 0
	v_pk_mul_f32 v[12:13], v[14:15], v[12:13]
	s_nop 0
	v_pk_mul_f32 v[10:11], v[12:13], v[10:11]
	s_nop 0
	v_cvt_pk_bf16_f32 v9, v10, v11
	v_mul_f32_e32 v10, 0xbfb8aa3b, v4
	v_mul_f32_e32 v11, 0xbfb8aa3b, v5
	v_exp_f32_e32 v10, v10
	v_exp_f32_e32 v11, v11
	s_nop 0
	v_pk_add_f32 v[10:11], v[10:11], 1.0 op_sel_hi:[1,0]
	s_nop 0
	s_nop 0
	v_rcp_f32_e32 v11, v11
	s_nop 0
	v_rcp_f32_e32 v10, v10
	s_nop 0
	v_pk_mul_f32 v[4:5], v[4:5], v[10:11]
	s_nop 0
	v_pk_mul_f32 v[0:1], v[4:5], v[0:1]
	s_nop 0
	v_cvt_pk_bf16_f32 v10, v0, v1
	v_mul_f32_e32 v0, 0xbfb8aa3b, v6
	v_mul_f32_e32 v1, 0xbfb8aa3b, v7
	v_exp_f32_e32 v0, v0
	v_exp_f32_e32 v1, v1
	s_nop 0
	v_pk_add_f32 v[0:1], v[0:1], 1.0 op_sel_hi:[1,0]
	s_nop 0
	s_nop 0
	v_rcp_f32_e32 v1, v1
	s_mov_b64 s[16:17], -1
	v_rcp_f32_e32 v0, v0
	s_nop 0
	v_pk_mul_f32 v[0:1], v[6:7], v[0:1]
	s_andn2_b64 vcc, exec, s[42:43]
	v_pk_mul_f32 v[0:1], v[0:1], v[2:3]
	s_nop 0
	v_cvt_pk_bf16_f32 v11, v0, v1
	global_store_dwordx4 v[16:17], v[8:11], off
	s_cbranch_vccnz .LBB0_1122
	s_andn2_b64 vcc, exec, s[0:1]
	s_cbranch_vccnz .LBB0_1121
	s_barrier
	s_branch .LBB0_1121
